# ALIGN barrier of the leading half moved behind its first six epilogue stores (was four)
# baseline (speedup 1.0000x reference)
; __device__ __forceinline__ unsigned cvt_pk_bf16(float lo, float hi) { unsigned r; asm volatile("v_cvt_pk_bf16_f32 %0, %1, %2" : "=v"(r) : "v"(lo), "v"(hi)); return r; }
;     __device__ __forceinline__ void operator()(const Acc& acc, const Unit& u, int wr, int wc, int fr, int fq) const {
;         asm volatile("" : "+v"(fr), "+v"(fq));
; #pragma unroll
;         for (int ai = 0; ai < 2; ++ai)
; #pragma unroll
;             for (int m = 0; m < 4; ++m) {
;                 const int row_in = ai * HALF + wr * 64 + m * 16 + fr, c = u.pm * BM + row_in;
;                 const int tok = ((c & ((1 << lL) - 1)) << ld) + (c >> lL);
;                 f32x4 t0 = (f32x4){1.f, 0.f, 1.f, 0.f}, t1 = t0;
;                 if (wc == 0) { const f32x4* cp = csa + ((size_t)tok * 16 + 4 * fq) / 2; t0 = cp[0]; t1 = cp[1]; }
;                 bf16_t* rowp = O + u.coff + (size_t)row_in * D + wc * 32 + ((fq & 1) ? 16 + 4 * (fq - 1) : 4 * fq);
; #pragma unroll
;                 for (int bj = 0; bj < 2; ++bj) {
;                     const f32x4 x1 = acc[ai][bj][m][0], x2 = acc[ai][bj][m][1];
;                     float o1[4], o2[4];
;                     const float cc[4] = {t0[0], t0[2], t1[0], t1[2]}, ss[4] = {t0[1], t0[3], t1[1], t1[3]};
; #pragma unroll
;                     for (int j = 0; j < 4; ++j) { o1[j] = x1[j] * cc[j] - x2[j] * ss[j]; o2[j] = x2[j] * cc[j] + x1[j] * ss[j]; }
;                     const unsigned lo0 = cvt_pk_bf16(o1[0], o1[1]), lo1 = cvt_pk_bf16(o1[2], o1[3]), hi0 = cvt_pk_bf16(o2[0], o2[1]), hi1 = cvt_pk_bf16(o2[2], o2[3]);
;                     const auto s0 = __builtin_amdgcn_permlane16_swap(lo0, hi0, false, false), s1 = __builtin_amdgcn_permlane16_swap(lo1, hi1, false, false);
;                     *(u32x4*)(rowp + bj * HALF) = (u32x4){s0[0], s1[0], s0[1], s1[1]};
;                 }
;             }
.LBB0_232:
	v_mov_b32_e32 v108, v92
	v_mov_b32_e32 v109, v88
	v_pk_mul_f32 v[108:109], v[108:109], v[102:103]
	v_ashrrev_i32_e32 v107, 31, v106
	v_sub_f32_e32 v110, v108, v109
	v_mov_b32_e32 v108, v88
	v_mov_b32_e32 v109, v92
	v_pk_mul_f32 v[108:109], v[108:109], v[102:103]
	v_mov_b32_e32 v88, v93
	v_mov_b32_e32 v92, v89
	v_add_f32_e32 v111, v109, v108
	v_pk_mul_f32 v[108:109], v[88:89], v[104:105]
	v_pk_mul_f32 v[88:89], v[92:93], v[104:105]
	v_sub_f32_e32 v108, v108, v109
	v_add_f32_e32 v92, v89, v88
	v_mov_b32_e32 v88, v94
	v_mov_b32_e32 v89, v90
	v_pk_mul_f32 v[88:89], v[88:89], v[98:99]
	v_lshlrev_b64 v[106:107], 12, v[106:107]
	v_sub_f32_e32 v93, v88, v89
	v_mov_b32_e32 v88, v90
	v_mov_b32_e32 v89, v94
	v_pk_mul_f32 v[88:89], v[88:89], v[98:99]
	v_mov_b32_e32 v90, v95
	v_add_f32_e32 v109, v89, v88
	v_pk_mul_f32 v[88:89], v[90:91], v[100:101]
	v_mov_b32_e32 v94, v91
	v_sub_f32_e32 v90, v88, v89
	v_pk_mul_f32 v[88:89], v[94:95], v[100:101]
	v_lshl_add_u64 v[106:107], s[44:45], 0, v[106:107]
	v_add_f32_e32 v91, v89, v88
	v_lshl_add_u64 v[106:107], v[106:107], 0, s[60:61]
	v_cvt_pk_bf16_f32 v88, v110, v108
	v_cvt_pk_bf16_f32 v89, v93, v90
	v_cvt_pk_bf16_f32 v90, v111, v92
	v_cvt_pk_bf16_f32 v91, v109, v91
	v_lshl_add_u64 v[106:107], v[166:167], 1, v[106:107]
	v_permlane16_swap_b32_e32 v88, v90
	v_permlane16_swap_b32_e32 v89, v91
	global_store_dwordx4 v[106:107], v[88:91], off
	s_and_b64 vcc, exec, s[42:43]
	s_nop 0
	v_mov_b32_e32 v88, v84
	v_mov_b32_e32 v89, v80
	v_pk_mul_f32 v[88:89], v[88:89], v[102:103]
	s_nop 0
	v_sub_f32_e32 v90, v88, v89
	v_mov_b32_e32 v88, v80
	v_mov_b32_e32 v89, v84
	v_pk_mul_f32 v[88:89], v[88:89], v[102:103]
	v_mov_b32_e32 v80, v85
	v_mov_b32_e32 v84, v81
	v_add_f32_e32 v91, v89, v88
	v_pk_mul_f32 v[88:89], v[80:81], v[104:105]
	v_pk_mul_f32 v[80:81], v[84:85], v[104:105]
	v_sub_f32_e32 v88, v88, v89
	v_add_f32_e32 v84, v81, v80
	v_mov_b32_e32 v80, v86
	v_mov_b32_e32 v81, v82
	v_pk_mul_f32 v[80:81], v[80:81], v[98:99]
	s_nop 0
	v_sub_f32_e32 v85, v80, v81
	v_mov_b32_e32 v80, v82
	v_mov_b32_e32 v81, v86
	v_pk_mul_f32 v[80:81], v[80:81], v[98:99]
	v_mov_b32_e32 v82, v87
	v_add_f32_e32 v89, v81, v80
	v_pk_mul_f32 v[80:81], v[82:83], v[100:101]
	v_mov_b32_e32 v86, v83
	v_sub_f32_e32 v82, v80, v81
	v_pk_mul_f32 v[80:81], v[86:87], v[100:101]
	v_mov_b32_e32 v98, 1.0
	v_add_f32_e32 v83, v81, v80
	v_cvt_pk_bf16_f32 v80, v90, v88
	v_cvt_pk_bf16_f32 v81, v85, v82
	v_cvt_pk_bf16_f32 v82, v91, v84
	v_cvt_pk_bf16_f32 v83, v89, v83
	v_add_u32_e32 v84, 48, v164
	v_permlane16_swap_b32_e32 v80, v82
	v_permlane16_swap_b32_e32 v81, v83
	global_store_dwordx4 v[106:107], v[80:83], off offset:256
	s_cmp_lg_u64 s[28:29], 0
	s_cbranch_scc0 .Llate_align_0
	s_barrier
.Llate_align_0:
	v_mov_b32_e32 v99, 0
	s_nop 0
	v_mov_b32_e32 v80, 1.0
	v_mov_b32_e32 v81, 0
	v_mov_b32_e32 v82, 1.0
	v_mov_b32_e32 v83, 0
	s_cbranch_vccnz .LBB0_234
	s_waitcnt vmcnt(14)
	v_mov_b32_e32 v96, v216
	v_mov_b32_e32 v97, v217
	v_mov_b32_e32 v98, v218
	v_mov_b32_e32 v99, v219
	v_mov_b32_e32 v80, v220
	v_mov_b32_e32 v81, v221
	v_mov_b32_e32 v82, v222
	v_mov_b32_e32 v83, v223

; __device__ __forceinline__ unsigned cvt_pk_bf16(float lo, float hi) { unsigned r; asm volatile("v_cvt_pk_bf16_f32 %0, %1, %2" : "=v"(r) : "v"(lo), "v"(hi)); return r; }
; __device__ __forceinline__ float silu_f(float v) { return v / (1.0f + __expf(-v)); }
; #define PG8_BAR __builtin_amdgcn_s_barrier()
; template <class Epi, class Map>
; __device__ __forceinline__ void gemm_phase(LAS unsigned char* lds, const Gemm g, const Sched<Map>& S, const Epi& E) {
;     ...
;         if (!has_next) break;
; #pragma unroll
;         for (int a = 0; a < 2; ++a)
; #pragma unroll
;             for (int b = 0; b < 2; ++b)
; #pragma unroll
;                 for (int m = 0; m < 4; ++m)
; #pragma unroll
;                     for (int n = 0; n < 2; ++n) acc[a][b][m][n] = (f32x4){0.f, 0.f, 0.f, 0.f};
;         cur = nxt; cA = nA; cB = nB; ++ui;
;         if (wr == 1) PG8_BAR;
;     __device__ __forceinline__ void operator()(const Acc& acc, const Unit& u, int wr, int wc, int fr, int fq) const {
;         asm volatile("" : "+v"(fr), "+v"(fq));
;         bf16_t* base = O + u.coff + (size_t)(wr * 64 + fr) * ldc + wc * 32 + 8 * fq;
; #pragma unroll
;         for (int ai = 0; ai < 2; ++ai)
; #pragma unroll
;             for (int m = 0; m < 4; ++m) { bf16_t* rowp = base + (size_t)(ai * HALF + m * 16) * ldc;
; #pragma unroll
;                 for (int bj = 0; bj < 2; ++bj) { f32x4 v0 = acc[ai][bj][m][0], v1 = acc[ai][bj][m][1];
;                     if (ACT == 1) {
; #pragma unroll
;                         for (int j = 0; j < 4; ++j) { v0[j] = silu_f(v0[j]); v1[j] = silu_f(v1[j]); } }
;                     if (ACT == 2) {
; #pragma unroll
;                         for (int j = 0; j < 4; ++j) { const float a = fmaxf(v0[j], 0.f), b = fmaxf(v1[j], 0.f); v0[j] = a * a; v1[j] = b * b; } }
;                     u32x4 w; w.x = cvt_pk_bf16(v0[0], v0[1]); w.y = cvt_pk_bf16(v0[2], v0[3]); w.z = cvt_pk_bf16(v1[0], v1[1]); w.w = cvt_pk_bf16(v1[2], v1[3]);
;                     *(u32x4*)(rowp + bj * HALF) = w; } }
.LBB0_264:
	v_mov_b32_e32 v138, v140
	v_mov_b32_e32 v158, v141
	s_lshl_b64 s[34:35], s[60:61], 1
	v_add_u32_e32 v138, s14, v138
	s_add_u32 s34, s12, s34
	v_ashrrev_i32_e32 v139, 31, v138
	s_addc_u32 s35, s13, s35
	v_lshlrev_b64 v[138:139], 15, v[138:139]
	v_lshl_add_u64 v[138:139], s[34:35], 0, v[138:139]
	s_mov_b32 s25, s61
	v_lshlrev_b32_e32 v158, 3, v158
	v_lshl_add_u64 v[138:139], v[138:139], 0, s[24:25]
	v_ashrrev_i32_e32 v159, 31, v158
	v_lshl_add_u64 v[138:139], v[158:159], 1, v[138:139]
	s_mov_b32 s25, 0x80000
	v_cvt_pk_bf16_f32 v124, v124, v125
	v_cvt_pk_bf16_f32 v125, v126, v127
	v_cvt_pk_bf16_f32 v126, v120, v121
	v_cvt_pk_bf16_f32 v127, v122, v123
	global_store_dwordx4 v[138:139], v[124:127], off
	v_cvt_pk_bf16_f32 v112, v112, v113
	v_cvt_pk_bf16_f32 v113, v114, v115
	v_cvt_pk_bf16_f32 v114, v104, v105
	v_cvt_pk_bf16_f32 v115, v106, v107
	global_store_dwordx4 v[138:139], v[112:115], off offset:256
	v_cvt_pk_bf16_f32 v104, v116, v117
	v_cvt_pk_bf16_f32 v105, v118, v119
	v_cvt_pk_bf16_f32 v106, v108, v109
	v_add_co_u32_e32 v108, vcc, s25, v138
	v_cvt_pk_bf16_f32 v107, v110, v111
	s_mov_b32 s25, 0x180000
	s_nop 0
	v_addc_co_u32_e32 v109, vcc, 0, v139, vcc
	global_store_dwordx4 v[108:109], v[104:107], off
	v_cvt_pk_bf16_f32 v96, v96, v97
	v_cvt_pk_bf16_f32 v97, v98, v99
	v_cvt_pk_bf16_f32 v98, v88, v89
	v_cvt_pk_bf16_f32 v99, v90, v91
	global_store_dwordx4 v[108:109], v[96:99], off offset:256
	v_cvt_pk_bf16_f32 v88, v100, v101
	v_cvt_pk_bf16_f32 v89, v102, v103
	v_cvt_pk_bf16_f32 v90, v92, v93
	v_add_co_u32_e32 v92, vcc, s72, v138
	v_cvt_pk_bf16_f32 v91, v94, v95
	s_mov_b64 s[34:35], -1
	s_nop 0
	v_addc_co_u32_e32 v93, vcc, 0, v139, vcc
	global_store_dwordx4 v[92:93], v[88:91], off
	v_cvt_pk_bf16_f32 v80, v80, v81
	v_cvt_pk_bf16_f32 v81, v82, v83
	v_cvt_pk_bf16_f32 v82, v72, v73
	v_cvt_pk_bf16_f32 v83, v74, v75
	global_store_dwordx4 v[92:93], v[80:83], off offset:256
	s_cmp_lg_u64 s[20:21], 0
	s_cbranch_scc0 .Llate_align_1
	s_barrier
.Llate_align_1:
	v_cvt_pk_bf16_f32 v72, v84, v85
	v_cvt_pk_bf16_f32 v73, v86, v87
	v_cvt_pk_bf16_f32 v74, v76, v77
	v_add_co_u32_e32 v76, vcc, s25, v138
	s_mov_b32 s25, 0x400000
	s_nop 0
	v_addc_co_u32_e32 v77, vcc, 0, v139, vcc
	v_cvt_pk_bf16_f32 v75, v78, v79
	global_store_dwordx4 v[76:77], v[72:75], off
	v_cvt_pk_bf16_f32 v68, v68, v69
	v_cvt_pk_bf16_f32 v69, v70, v71
	v_cvt_pk_bf16_f32 v70, v64, v65
	v_cvt_pk_bf16_f32 v71, v66, v67
	global_store_dwordx4 v[76:77], v[68:71], off offset:256
	v_cvt_pk_bf16_f32 v60, v60, v61
	v_cvt_pk_bf16_f32 v61, v62, v63
	v_cvt_pk_bf16_f32 v62, v56, v57
	v_add_co_u32_e32 v56, vcc, s25, v138
	s_mov_b32 s25, 0x480000
	s_nop 0
	v_addc_co_u32_e32 v57, vcc, 0, v139, vcc
	v_cvt_pk_bf16_f32 v63, v58, v59
	global_store_dwordx4 v[56:57], v[60:63], off
	v_cvt_pk_bf16_f32 v48, v48, v49
	v_cvt_pk_bf16_f32 v49, v50, v51
	v_cvt_pk_bf16_f32 v50, v40, v41
	v_cvt_pk_bf16_f32 v51, v42, v43
	global_store_dwordx4 v[56:57], v[48:51], off offset:256
	v_cvt_pk_bf16_f32 v40, v52, v53
	v_cvt_pk_bf16_f32 v41, v54, v55
	v_cvt_pk_bf16_f32 v42, v44, v45
	v_add_co_u32_e32 v44, vcc, s25, v138
	s_mov_b32 s25, 0x500000
	s_nop 0
	v_addc_co_u32_e32 v45, vcc, 0, v139, vcc
	v_cvt_pk_bf16_f32 v43, v46, v47
	global_store_dwordx4 v[44:45], v[40:43], off
	v_cvt_pk_bf16_f32 v32, v32, v33
	v_cvt_pk_bf16_f32 v33, v34, v35
	v_cvt_pk_bf16_f32 v34, v24, v25
	v_cvt_pk_bf16_f32 v35, v26, v27
	global_store_dwordx4 v[44:45], v[32:35], off offset:256
	v_cvt_pk_bf16_f32 v24, v36, v37
	v_cvt_pk_bf16_f32 v25, v38, v39
	v_cvt_pk_bf16_f32 v26, v28, v29
	v_add_co_u32_e32 v28, vcc, s25, v138
	s_mov_b32 s25, 0x580000
	s_nop 0
	v_addc_co_u32_e32 v29, vcc, 0, v139, vcc
	v_cvt_pk_bf16_f32 v27, v30, v31
	global_store_dwordx4 v[28:29], v[24:27], off
	v_cvt_pk_bf16_f32 v16, v16, v17
	v_cvt_pk_bf16_f32 v17, v18, v19
	v_cvt_pk_bf16_f32 v18, v8, v9
	v_cvt_pk_bf16_f32 v19, v10, v11
	global_store_dwordx4 v[28:29], v[16:19], off offset:256
	v_cvt_pk_bf16_f32 v8, v20, v21
	v_cvt_pk_bf16_f32 v9, v22, v23
	v_cvt_pk_bf16_f32 v10, v12, v13
	v_add_co_u32_e32 v12, vcc, s25, v138
	v_cvt_pk_bf16_f32 v11, v14, v15
	s_nop 1
	v_addc_co_u32_e32 v13, vcc, 0, v139, vcc
	s_andn2_b64 vcc, exec, s[40:41]
	global_store_dwordx4 v[12:13], v[8:11], off
	v_cvt_pk_bf16_f32 v4, v4, v5
	v_cvt_pk_bf16_f32 v5, v6, v7
	v_cvt_pk_bf16_f32 v6, v0, v1
	v_cvt_pk_bf16_f32 v7, v2, v3
	global_store_dwordx4 v[12:13], v[4:7], off offset:256
	s_cbranch_vccnz .LBB0_253
	s_andn2_b64 vcc, exec, s[18:19]
	s_cbranch_vccnz .LBB0_252
	s_barrier
	s_branch .LBB0_252

;     __device__ __forceinline__ void operator()(const Acc& acc, const Unit& u, int wr, int wc, int fr, int fq) const {
;         asm volatile("" : "+v"(fr), "+v"(fq));
;         const int row0 = u.pm * BM + wr * 64 + fr, col0 = u.pn * BM + wc * 32 + 4 * fq;
;         const float* gp = gate + (size_t)(u.pm >> 6) * gate_bstride + col0;
;         f32x4 gv[2][2];
; #pragma unroll
;         for (int bj = 0; bj < 2; ++bj)
; #pragma unroll
;             for (int n = 0; n < 2; ++n) gv[bj][n] = *(const f32x4*)(gp + bj * HALF + n * 16);
; #pragma unroll
;         for (int aim = 0; aim < 4; ++aim) { const int ai = aim >> 1, m0 = (aim & 1) * 2;
;             f32x4 bs[2][2][2];
; #pragma unroll
;             for (int mm = 0; mm < 2; ++mm) { const size_t off = (size_t)(row0 + ai * HALF + (m0 + mm) * 16) * D + col0;
; #pragma unroll
;                 for (int bj = 0; bj < 2; ++bj)
; #pragma unroll
;                     for (int n = 0; n < 2; ++n) bs[mm][bj][n] = *(const f32x4*)(base + off + bj * HALF + n * 16); }
; #pragma unroll
;             for (int mm = 0; mm < 2; ++mm) { const size_t off = (size_t)(row0 + ai * HALF + (m0 + mm) * 16) * D + col0;
; #pragma unroll
;                 for (int bj = 0; bj < 2; ++bj)
; #pragma unroll
;                     for (int n = 0; n < 2; ++n) *(f32x4*)(out + off + bj * HALF + n * 16) = bs[mm][bj][n] + gv[bj][n] * acc[ai][bj][m0 + mm][n]; }
;             asm volatile("" ::: "memory"); }
;     }
.LBB0_408:
	v_mov_b32_e32 v64, v172
	v_mov_b32_e32 v168, v159
	s_lshl_b32 s28, s37, 8
	s_or_b32 s28, s28, s9
	v_lshl_add_u32 v64, v64, 2, s28
	s_ashr_i32 s28, s36, 6
	s_mul_hi_i32 s29, s28, 0xc000
	s_mul_i32 s28, s28, 0xc000
	s_add_u32 s28, s6, s28
	v_ashrrev_i32_e32 v65, 31, v64
	s_addc_u32 s29, s7, s29
	v_lshlrev_b64 v[166:167], 2, v[64:65]
	v_lshl_add_u64 v[64:65], s[28:29], 0, v[166:167]
	s_lshl_b32 s28, s36, 8
	s_add_i32 s28, s28, s8
	v_add_u32_e32 v170, s28, v168
	v_readlane_b32 s28, v245, 51
	v_readlane_b32 s29, v245, 52
	v_ashrrev_i32_e32 v171, 31, v170
	v_lshlrev_b64 v[170:171], 13, v[170:171]
	v_lshl_add_u64 v[168:169], s[28:29], 0, v[166:167]
	v_lshl_add_u64 v[180:181], v[168:169], 0, v[170:171]
	s_mov_b64 s[30:31], 0x20000
	global_load_dwordx4 v[108:111], v[64:65], off
	global_load_dwordx4 v[72:75], v[64:65], off offset:64
	global_load_dwordx4 v[68:71], v[64:65], off offset:512
	s_nop 0
	global_load_dwordx4 v[64:67], v[64:65], off offset:576
	s_nop 0
	global_load_dwordx4 v[176:179], v[180:181], off
	global_load_dwordx4 v[192:195], v[180:181], off offset:64
	global_load_dwordx4 v[196:199], v[180:181], off offset:512
	global_load_dwordx4 v[200:203], v[180:181], off offset:576
	v_lshl_add_u64 v[180:181], v[170:171], 0, s[30:31]
	v_lshl_add_u64 v[216:217], v[168:169], 0, v[180:181]
	global_load_dwordx4 v[204:207], v[216:217], off
	global_load_dwordx4 v[208:211], v[216:217], off offset:64
	global_load_dwordx4 v[212:215], v[216:217], off offset:512
	s_nop 0
	global_load_dwordx4 v[216:219], v[216:217], off offset:576
	s_mov_b64 s[30:31], 0x40000
	s_andn2_b64 vcc, exec, s[38:39]
	s_waitcnt vmcnt(0)
	v_pk_fma_f32 v[140:141], v[140:141], v[108:109], v[176:177]
	v_lshl_add_u64 v[176:177], s[28:29], 0, v[170:171]
	v_lshl_add_u64 v[176:177], v[176:177], 0, v[166:167]
	v_pk_fma_f32 v[126:127], v[126:127], v[70:71], v[198:199]
	v_pk_fma_f32 v[124:125], v[124:125], v[68:69], v[196:197]
	global_store_dwordx4 v[176:177], v[124:127], off offset:512
	v_pk_fma_f32 v[122:123], v[122:123], v[66:67], v[202:203]
	v_pk_fma_f32 v[120:121], v[120:121], v[64:65], v[200:201]
	v_lshl_add_u64 v[124:125], s[28:29], 0, v[180:181]
	global_store_dwordx4 v[176:177], v[120:123], off offset:576
	v_lshl_add_u64 v[124:125], v[124:125], 0, v[166:167]
	v_pk_fma_f32 v[142:143], v[142:143], v[110:111], v[178:179]
	v_pk_fma_f32 v[122:123], v[134:135], v[110:111], v[206:207]
	v_pk_fma_f32 v[120:121], v[132:133], v[108:109], v[204:205]
	v_pk_fma_f32 v[138:139], v[138:139], v[74:75], v[194:195]
	v_pk_fma_f32 v[136:137], v[136:137], v[72:73], v[192:193]
	global_store_dwordx4 v[124:125], v[120:123], off
	v_pk_fma_f32 v[118:119], v[118:119], v[70:71], v[214:215]
	v_pk_fma_f32 v[116:117], v[116:117], v[68:69], v[212:213]
	v_pk_fma_f32 v[122:123], v[130:131], v[74:75], v[210:211]
	v_pk_fma_f32 v[120:121], v[128:129], v[72:73], v[208:209]
	v_pk_fma_f32 v[114:115], v[114:115], v[66:67], v[218:219]
	v_pk_fma_f32 v[112:113], v[112:113], v[64:65], v[216:217]
	global_store_dwordx4 v[176:177], v[140:143], off
	global_store_dwordx4 v[176:177], v[136:139], off offset:64
	global_store_dwordx4 v[124:125], v[120:123], off offset:64
	s_cmp_lg_u64 s[18:19], 0
	s_cbranch_scc0 .Llate_align_2
	s_barrier
.Llate_align_2:
	global_store_dwordx4 v[124:125], v[116:119], off offset:512
	global_store_dwordx4 v[124:125], v[112:115], off offset:576
	v_lshl_add_u64 v[176:177], v[170:171], 0, s[30:31]
	v_lshl_add_u64 v[124:125], v[168:169], 0, v[176:177]
	s_mov_b64 s[30:31], 0x60000
	global_load_dwordx4 v[112:115], v[124:125], off
	global_load_dwordx4 v[116:119], v[124:125], off offset:64
	global_load_dwordx4 v[120:123], v[124:125], off offset:512
	s_nop 0
	global_load_dwordx4 v[124:127], v[124:125], off offset:576
	v_lshl_add_u64 v[178:179], v[170:171], 0, s[30:31]
	v_lshl_add_u64 v[140:141], v[168:169], 0, v[178:179]
	global_load_dwordx4 v[128:131], v[140:141], off
	global_load_dwordx4 v[132:135], v[140:141], off offset:64
	global_load_dwordx4 v[136:139], v[140:141], off offset:512
	s_nop 0
	global_load_dwordx4 v[140:143], v[140:141], off offset:576
	s_mov_b64 s[30:31], 0x100000
	s_waitcnt vmcnt(7)
	v_pk_fma_f32 v[104:105], v[104:105], v[108:109], v[112:113]
	v_lshl_add_u64 v[112:113], s[28:29], 0, v[176:177]
	v_lshl_add_u64 v[112:113], v[112:113], 0, v[166:167]
	s_waitcnt vmcnt(5)
	v_pk_fma_f32 v[90:91], v[90:91], v[70:71], v[122:123]
	v_pk_fma_f32 v[88:89], v[88:89], v[68:69], v[120:121]
	global_store_dwordx4 v[112:113], v[88:91], off offset:512
	s_waitcnt vmcnt(5)
	v_pk_fma_f32 v[86:87], v[86:87], v[66:67], v[126:127]
	v_pk_fma_f32 v[84:85], v[84:85], v[64:65], v[124:125]
	v_lshl_add_u64 v[88:89], s[28:29], 0, v[178:179]
	global_store_dwordx4 v[112:113], v[84:87], off offset:576
	v_lshl_add_u64 v[88:89], v[88:89], 0, v[166:167]
	v_pk_fma_f32 v[106:107], v[106:107], v[110:111], v[114:115]
	s_waitcnt vmcnt(5)
	v_pk_fma_f32 v[86:87], v[98:99], v[110:111], v[130:131]
	v_pk_fma_f32 v[84:85], v[96:97], v[108:109], v[128:129]
	v_pk_fma_f32 v[102:103], v[102:103], v[74:75], v[118:119]
	v_pk_fma_f32 v[100:101], v[100:101], v[72:73], v[116:117]
	global_store_dwordx4 v[88:89], v[84:87], off
	s_waitcnt vmcnt(4)
;     __device__ __forceinline__ void operator()(const Acc& acc, const Unit& u, int wr, int wc, int fr, int fq) const {
;         asm volatile("" : "+v"(fr), "+v"(fq));
;         const int row0 = u.pm * BM + wr * 64 + fr, col0 = u.pn * BM + wc * 32 + 4 * fq;
;         const float* gp = gate + (size_t)(u.pm >> 6) * gate_bstride + col0;
;         f32x4 gv[2][2];
; #pragma unroll
;         for (int bj = 0; bj < 2; ++bj)
; #pragma unroll
;             for (int n = 0; n < 2; ++n) gv[bj][n] = *(const f32x4*)(gp + bj * HALF + n * 16);
; #pragma unroll
;         for (int aim = 0; aim < 4; ++aim) { const int ai = aim >> 1, m0 = (aim & 1) * 2;
;             f32x4 bs[2][2][2];
; #pragma unroll
;             for (int mm = 0; mm < 2; ++mm) { const size_t off = (size_t)(row0 + ai * HALF + (m0 + mm) * 16) * D + col0;
; #pragma unroll
;                 for (int bj = 0; bj < 2; ++bj)
; #pragma unroll
;                     for (int n = 0; n < 2; ++n) bs[mm][bj][n] = *(const f32x4*)(base + off + bj * HALF + n * 16); }
; #pragma unroll
;             for (int mm = 0; mm < 2; ++mm) { const size_t off = (size_t)(row0 + ai * HALF + (m0 + mm) * 16) * D + col0;
; #pragma unroll
;                 for (int bj = 0; bj < 2; ++bj)
; #pragma unroll
;                     for (int n = 0; n < 2; ++n) *(f32x4*)(out + off + bj * HALF + n * 16) = bs[mm][bj][n] + gv[bj][n] * acc[ai][bj][m0 + mm][n]; }
;             asm volatile("" ::: "memory"); }
;     }
	v_pk_fma_f32 v[82:83], v[82:83], v[70:71], v[138:139]
	v_pk_fma_f32 v[80:81], v[80:81], v[68:69], v[136:137]
	v_pk_fma_f32 v[86:87], v[94:95], v[74:75], v[134:135]
	v_pk_fma_f32 v[84:85], v[92:93], v[72:73], v[132:133]
	s_waitcnt vmcnt(3)
	v_pk_fma_f32 v[78:79], v[78:79], v[66:67], v[142:143]
	v_pk_fma_f32 v[76:77], v[76:77], v[64:65], v[140:141]
	global_store_dwordx4 v[112:113], v[104:107], off
	global_store_dwordx4 v[112:113], v[100:103], off offset:64
	global_store_dwordx4 v[88:89], v[84:87], off offset:64
	global_store_dwordx4 v[88:89], v[80:83], off offset:512
	global_store_dwordx4 v[88:89], v[76:79], off offset:576
	v_lshl_add_u64 v[112:113], v[170:171], 0, s[30:31]
	v_lshl_add_u64 v[88:89], v[168:169], 0, v[112:113]
	s_mov_b64 s[30:31], 0x120000
	global_load_dwordx4 v[76:79], v[88:89], off
	global_load_dwordx4 v[80:83], v[88:89], off offset:64
	global_load_dwordx4 v[84:87], v[88:89], off offset:512
	s_nop 0
	global_load_dwordx4 v[88:91], v[88:89], off offset:576
	v_lshl_add_u64 v[114:115], v[170:171], 0, s[30:31]
	v_lshl_add_u64 v[104:105], v[168:169], 0, v[114:115]
	global_load_dwordx4 v[92:95], v[104:105], off
	global_load_dwordx4 v[96:99], v[104:105], off offset:64
	global_load_dwordx4 v[100:103], v[104:105], off offset:512
	s_nop 0
	global_load_dwordx4 v[104:107], v[104:105], off offset:576
	s_mov_b64 s[30:31], 0x140000
	s_waitcnt vmcnt(7)
	v_pk_fma_f32 v[60:61], v[60:61], v[108:109], v[76:77]
	v_lshl_add_u64 v[76:77], s[28:29], 0, v[112:113]
	v_lshl_add_u64 v[76:77], v[76:77], 0, v[166:167]
	s_waitcnt vmcnt(5)
	v_pk_fma_f32 v[46:47], v[46:47], v[70:71], v[86:87]
	v_pk_fma_f32 v[44:45], v[44:45], v[68:69], v[84:85]
	global_store_dwordx4 v[76:77], v[44:47], off offset:512
	s_waitcnt vmcnt(5)
	v_pk_fma_f32 v[42:43], v[42:43], v[66:67], v[90:91]
	v_pk_fma_f32 v[40:41], v[40:41], v[64:65], v[88:89]
	v_lshl_add_u64 v[44:45], s[28:29], 0, v[114:115]
	global_store_dwordx4 v[76:77], v[40:43], off offset:576
	v_lshl_add_u64 v[44:45], v[44:45], 0, v[166:167]
	v_pk_fma_f32 v[62:63], v[62:63], v[110:111], v[78:79]
	s_waitcnt vmcnt(5)
	v_pk_fma_f32 v[42:43], v[54:55], v[110:111], v[94:95]
	v_pk_fma_f32 v[40:41], v[52:53], v[108:109], v[92:93]
	v_pk_fma_f32 v[58:59], v[58:59], v[74:75], v[82:83]
	v_pk_fma_f32 v[56:57], v[56:57], v[72:73], v[80:81]
	global_store_dwordx4 v[44:45], v[40:43], off
	s_waitcnt vmcnt(4)
	v_pk_fma_f32 v[38:39], v[38:39], v[70:71], v[102:103]
	v_pk_fma_f32 v[36:37], v[36:37], v[68:69], v[100:101]
	v_pk_fma_f32 v[42:43], v[50:51], v[74:75], v[98:99]
	v_pk_fma_f32 v[40:41], v[48:49], v[72:73], v[96:97]
	s_waitcnt vmcnt(3)
	v_pk_fma_f32 v[34:35], v[34:35], v[66:67], v[106:107]
	v_pk_fma_f32 v[32:33], v[32:33], v[64:65], v[104:105]
	global_store_dwordx4 v[76:77], v[60:63], off
	global_store_dwordx4 v[76:77], v[56:59], off offset:64
	global_store_dwordx4 v[44:45], v[40:43], off offset:64
	global_store_dwordx4 v[44:45], v[36:39], off offset:512
	global_store_dwordx4 v[44:45], v[32:35], off offset:576
	v_lshl_add_u64 v[76:77], v[170:171], 0, s[30:31]
	s_mov_b64 s[30:31], 0x160000
	v_lshl_add_u64 v[44:45], v[168:169], 0, v[76:77]
	v_lshl_add_u64 v[78:79], v[170:171], 0, s[30:31]
	global_load_dwordx4 v[32:35], v[44:45], off
	global_load_dwordx4 v[36:39], v[44:45], off offset:64
	global_load_dwordx4 v[40:43], v[44:45], off offset:512
	s_nop 0
	global_load_dwordx4 v[44:47], v[44:45], off offset:576
	v_lshl_add_u64 v[60:61], v[168:169], 0, v[78:79]
	global_load_dwordx4 v[48:51], v[60:61], off
	global_load_dwordx4 v[52:55], v[60:61], off offset:64
	global_load_dwordx4 v[56:59], v[60:61], off offset:512
	s_nop 0
	global_load_dwordx4 v[60:63], v[60:61], off offset:576
	s_waitcnt vmcnt(7)
	v_pk_fma_f32 v[28:29], v[28:29], v[108:109], v[32:33]
	v_lshl_add_u64 v[32:33], s[28:29], 0, v[76:77]
	v_lshl_add_u64 v[32:33], v[32:33], 0, v[166:167]
	s_waitcnt vmcnt(5)
	v_pk_fma_f32 v[18:19], v[18:19], v[70:71], v[42:43]
	v_pk_fma_f32 v[16:17], v[16:17], v[68:69], v[40:41]
	global_store_dwordx4 v[32:33], v[16:19], off offset:512
	s_waitcnt vmcnt(5)
	v_pk_fma_f32 v[14:15], v[14:15], v[66:67], v[46:47]
	v_pk_fma_f32 v[12:13], v[12:13], v[64:65], v[44:45]
	v_lshl_add_u64 v[16:17], s[28:29], 0, v[78:79]
	v_pk_fma_f32 v[30:31], v[30:31], v[110:111], v[34:35]
	v_pk_fma_f32 v[26:27], v[26:27], v[74:75], v[38:39]
	v_pk_fma_f32 v[24:25], v[24:25], v[72:73], v[36:37]
	global_store_dwordx4 v[32:33], v[12:15], off offset:576
	v_lshl_add_u64 v[16:17], v[16:17], 0, v[166:167]
	s_waitcnt vmcnt(4)
	v_pk_fma_f32 v[10:11], v[10:11], v[74:75], v[54:55]
	v_pk_fma_f32 v[14:15], v[22:23], v[110:111], v[50:51]
	v_pk_fma_f32 v[12:13], v[20:21], v[108:109], v[48:49]
	v_pk_fma_f32 v[8:9], v[8:9], v[72:73], v[52:53]
	s_waitcnt vmcnt(3)
	v_pk_fma_f32 v[6:7], v[6:7], v[70:71], v[58:59]
	v_pk_fma_f32 v[4:5], v[4:5], v[68:69], v[56:57]
	s_waitcnt vmcnt(2)
	v_pk_fma_f32 v[2:3], v[2:3], v[66:67], v[62:63]
	v_pk_fma_f32 v[0:1], v[0:1], v[64:65], v[60:61]
	global_store_dwordx4 v[32:33], v[28:31], off
	global_store_dwordx4 v[32:33], v[24:27], off offset:64
	global_store_dwordx4 v[16:17], v[12:15], off
	global_store_dwordx4 v[16:17], v[8:11], off offset:64
	global_store_dwordx4 v[16:17], v[4:7], off offset:512
	global_store_dwordx4 v[16:17], v[0:3], off offset:576
	s_mov_b64 s[28:29], -1
	s_cbranch_vccnz .LBB0_397
	s_andn2_b64 vcc, exec, s[16:17]
	s_cbranch_vccnz .LBB0_396
	s_barrier
	s_branch .LBB0_396

; __device__ __forceinline__ unsigned cvt_pk_bf16(float lo, float hi) { unsigned r; asm volatile("v_cvt_pk_bf16_f32 %0, %1, %2" : "=v"(r) : "v"(lo), "v"(hi)); return r; }
;     __device__ __forceinline__ void operator()(const Acc& acc, const Unit& u, int wr, int wc, int fr, int fq) const {
;     ...
;             for (int m = 0; m < 4; ++m) {
;                 const int row_in = ai * HALF + wr * 64 + m * 16 + fr, s = u.pm * BM + row_in;
;                 const float rs = mode == 0 ? exp2f((float)(row_in + 1) * lg) : 0.0625f;
;                 const f32x4* cp = cs + ((size_t)s * 128 + wc * 32 + 8 * fq) / 2;
;                 f32x4 t[4];
; #pragma unroll
;                 for (int i = 0; i < 4; ++i) t[i] = cp[i];
;                 float o1[8], o2[8];
; #pragma unroll
;                 for (int n = 0; n < 2; ++n)
; #pragma unroll
;                     for (int j = 0; j < 4; ++j) { const int e = n * 4 + j; const float co = t[e >> 1][(e & 1) * 2], si = t[e >> 1][(e & 1) * 2 + 1];
;                         const float x1 = acc[ai][0][m][n][j], x2 = acc[ai][1][m][n][j];
;                         o1[e] = (x1 * co - x2 * si) * rs; o2[e] = (x2 * co + x1 * si) * rs; }
;                 bf16_t* rowp = O + u.coff + (size_t)row_in * ldc + wc * 32 + 8 * fq;
;                 u32x4 w; w.x = cvt_pk_bf16(o1[0], o1[1]); w.y = cvt_pk_bf16(o1[2], o1[3]); w.z = cvt_pk_bf16(o1[4], o1[5]); w.w = cvt_pk_bf16(o1[6], o1[7]);
;                 *(u32x4*)rowp = w;
;                 w.x = cvt_pk_bf16(o2[0], o2[1]); w.y = cvt_pk_bf16(o2[2], o2[3]); w.z = cvt_pk_bf16(o2[4], o2[5]); w.w = cvt_pk_bf16(o2[6], o2[7]);
;                 *(u32x4*)(rowp + HALF) = w;
;                 if (mode == 1) {
;                     const float z = exp2f((float)(255 - row_in) * lg);
;                     bf16_t* kz = KZ + u.coff + (size_t)(wc * 32 + 8 * fq) * 256 + row_in;
; #pragma unroll
;                     for (int e = 0; e < 8; e += 2) { const unsigned p1 = cvt_pk_bf16(o1[e] * z, o1[e + 1] * z), p2 = cvt_pk_bf16(o2[e] * z, o2[e + 1] * z);
;                         kz[(size_t)e * 256] = (bf16_t)(p1 & 0xffffu); kz[(size_t)(e + 1) * 256] = (bf16_t)(p1 >> 16);
;                         kz[(size_t)(e + HALF) * 256] = (bf16_t)(p2 & 0xffffu); kz[(size_t)(e + 1 + HALF) * 256] = (bf16_t)(p2 >> 16); }
;                 }
.Lrq_copy_2:
	v_add_u32_e32 v97, 33, v142
	v_cvt_f32_i32_e32 v97, v97
	v_add_u32_e32 v100, 32, v142
	v_add_u32_e32 v96, s20, v100
	v_mov_b32_e32 v116, v88
	v_mul_f32_e32 v98, v170, v97
	v_cmp_gt_f32_e32 vcc, s75, v98
	v_mov_b32_e32 v117, v92
	s_nop 0
	v_cndmask_b32_e32 v98, 0, v190, vcc
	v_fmac_f32_e32 v98, v170, v97
	v_exp_f32_e32 v97, v98
	v_cndmask_b32_e32 v98, 0, v189, vcc
	s_and_b64 vcc, exec, s[42:43]
	v_ldexp_f32 v101, v97, v98
	v_ashrrev_i32_e32 v97, 31, v96
	v_lshlrev_b64 v[96:97], 7, v[96:97]
	v_lshl_add_u64 v[96:97], v[96:97], 0, v[164:165]
	v_lshl_add_u64 v[102:103], v[96:97], 3, s[16:17]
	v_mov_b32_e32 v96, v196
	v_mov_b32_e32 v97, v197
	v_mov_b32_e32 v98, v198
	v_mov_b32_e32 v99, v199
	v_mov_b32_e32 v104, v200
	v_mov_b32_e32 v105, v201
	v_mov_b32_e32 v106, v202
	v_mov_b32_e32 v107, v203
	v_mov_b32_e32 v108, v204
	v_mov_b32_e32 v109, v205
	v_mov_b32_e32 v110, v206
	v_mov_b32_e32 v111, v207
	v_mov_b32_e32 v112, v208
	v_mov_b32_e32 v113, v209
	v_mov_b32_e32 v114, v210
	v_mov_b32_e32 v115, v211
	v_add_u32_e32 v228, 48, v142
	v_add_u32_e32 v228, s20, v228
	v_ashrrev_i32_e32 v229, 31, v228
	v_lshlrev_b64 v[228:229], 7, v[228:229]
	v_lshl_add_u64 v[228:229], v[228:229], 0, v[164:165]
	v_lshl_add_u64 v[228:229], v[228:229], 3, s[16:17]
	global_load_dwordx4 v[212:215], v[228:229], off offset:48
	global_load_dwordx4 v[216:219], v[228:229], off offset:32
	global_load_dwordx4 v[220:223], v[228:229], off offset:16
	global_load_dwordx4 v[224:227], v[228:229], off
	v_mov_b32_e32 v102, v92
	v_mov_b32_e32 v103, v88
	v_cndmask_b32_e64 v101, v191, v101, s[44:45]
	v_mov_b32_e32 v92, v89
	v_pk_mul_f32 v[102:103], v[102:103], v[112:113]
	v_pk_mul_f32 v[112:113], v[116:117], v[112:113]
	v_sub_f32_e32 v102, v102, v103
	v_add_f32_e32 v88, v113, v112
	v_mul_f32_e32 v103, v101, v88
	v_mov_b32_e32 v88, v93
	v_pk_mul_f32 v[112:113], v[88:89], v[114:115]
	v_pk_mul_f32 v[92:93], v[92:93], v[114:115]
	v_sub_f32_e32 v88, v112, v113
	v_add_f32_e32 v89, v93, v92
	v_mov_b32_e32 v92, v94
	v_mov_b32_e32 v93, v90
	v_mov_b32_e32 v112, v90
	v_mov_b32_e32 v113, v94
	v_pk_mul_f32 v[92:93], v[92:93], v[108:109]
	v_pk_mul_f32 v[108:109], v[112:113], v[108:109]
	v_sub_f32_e32 v92, v92, v93
	v_add_f32_e32 v90, v109, v108
	v_mul_f32_e32 v93, v101, v90
	v_mov_b32_e32 v90, v95
	v_mov_b32_e32 v94, v91
	v_pk_mul_f32 v[108:109], v[90:91], v[110:111]
	v_pk_mul_f32 v[94:95], v[94:95], v[110:111]
	v_sub_f32_e32 v90, v108, v109
	v_add_f32_e32 v91, v95, v94
	v_mov_b32_e32 v94, v80
	v_mov_b32_e32 v95, v84
	v_mov_b32_e32 v108, v84
	v_mov_b32_e32 v109, v80
	v_pk_mul_f32 v[94:95], v[94:95], v[104:105]
	v_pk_mul_f32 v[104:105], v[108:109], v[104:105]
	v_mov_b32_e32 v84, v81
	v_add_f32_e32 v80, v105, v104
	v_pk_mul_f32 v[104:105], v[84:85], v[106:107]
	v_sub_f32_e32 v94, v94, v95
	v_mul_f32_e32 v95, v101, v80
	v_sub_f32_e32 v80, v104, v105
	v_mul_f32_e32 v84, v101, v80
	v_mov_b32_e32 v80, v85
	v_mov_b32_e32 v104, v82
	v_mov_b32_e32 v105, v86
	v_pk_mul_f32 v[80:81], v[80:81], v[106:107]
	v_pk_mul_f32 v[104:105], v[104:105], v[96:97]
	v_add_f32_e32 v80, v81, v80
	v_sub_f32_e32 v81, v104, v105
	v_mov_b32_e32 v104, v86
	v_mov_b32_e32 v105, v82
	v_pk_mul_f32 v[96:97], v[104:105], v[96:97]
	v_mov_b32_e32 v86, v83
	v_add_f32_e32 v82, v97, v96
	v_pk_mul_f32 v[96:97], v[86:87], v[98:99]
	v_mul_f32_e32 v85, v101, v82
	v_sub_f32_e32 v82, v96, v97
	v_mul_f32_e32 v86, v101, v82
	v_mov_b32_e32 v82, v87
	v_pk_mul_f32 v[82:83], v[82:83], v[98:99]
	v_mul_f32_e32 v102, v101, v102
	v_add_f32_e32 v82, v83, v82
	v_mul_f32_e32 v88, v101, v88
	v_mul_f32_e32 v89, v101, v89
	v_mul_f32_e32 v92, v101, v92
	v_mul_f32_e32 v90, v101, v90
	v_mul_f32_e32 v91, v101, v91
	v_mul_f32_e32 v94, v101, v94
	v_mul_f32_e32 v80, v101, v80
	v_mul_f32_e32 v81, v101, v81
	v_mul_f32_e32 v82, v101, v82
	v_ashrrev_i32_e32 v101, 31, v100
	v_lshlrev_b64 v[96:97], s38, v[100:101]
	v_lshl_add_u64 v[96:97], v[96:97], 1, s[36:37]
	v_lshl_add_u64 v[96:97], v[96:97], 0, s[60:61]
	v_lshl_add_u64 v[100:101], v[162:163], 1, v[96:97]
	v_cvt_pk_bf16_f32 v96, v102, v88
	v_cvt_pk_bf16_f32 v97, v92, v90
	v_cvt_pk_bf16_f32 v98, v94, v84
	v_cvt_pk_bf16_f32 v99, v81, v86
	global_store_dwordx4 v[100:101], v[96:99], off
	s_nop 1
	v_cvt_pk_bf16_f32 v96, v103, v89
	v_cvt_pk_bf16_f32 v97, v93, v91
	v_cvt_pk_bf16_f32 v98, v95, v80
	v_cvt_pk_bf16_f32 v99, v85, v82
	global_store_dwordx4 v[100:101], v[96:99], off offset:256
	s_cmp_lg_u64 s[52:53], 0
	s_cbranch_scc0 .Llate_align_3
	s_barrier
.Llate_align_3:
	s_cbranch_vccnz .LBB0_561
	v_sub_u32_e32 v83, 0xdf, v142
	v_cvt_f32_i32_e32 v83, v83
	s_add_u32 s2, s76, s86
	s_addc_u32 s3, s64, s87
	v_lshl_add_u64 v[96:97], s[2:3], 0, v[160:161]
	v_mul_f32_e32 v87, v170, v83
	v_cmp_gt_f32_e32 vcc, s75, v87
	v_lshl_add_u64 v[96:97], v[142:143], 1, v[96:97]
	s_nop 0
	v_cndmask_b32_e32 v87, 0, v190, vcc
	v_fmac_f32_e32 v87, v170, v83
	v_exp_f32_e32 v83, v87
	v_cndmask_b32_e32 v87, 0, v189, vcc
	v_ldexp_f32 v83, v83, v87
	v_mul_f32_e32 v87, v83, v102
	v_mul_f32_e32 v88, v83, v88
	v_cvt_pk_bf16_f32 v87, v87, v88
	v_mul_f32_e32 v88, v83, v103
	v_mul_f32_e32 v89, v83, v89
	v_cvt_pk_bf16_f32 v98, v88, v89
	v_add_co_u32_e32 v88, vcc, s33, v96
	global_store_short v[96:97], v87, off offset:64
	global_store_short_d16_hi v[96:97], v87, off offset:576
	v_addc_co_u32_e32 v89, vcc, 0, v97, vcc
	v_mul_f32_e32 v87, v83, v92
	v_mul_f32_e32 v90, v83, v90
	global_store_short v[88:89], v98, off offset:64
	global_store_short_d16_hi v[88:89], v98, off offset:576
	v_cvt_pk_bf16_f32 v87, v87, v90
	v_mul_f32_e32 v90, v83, v93
	v_mul_f32_e32 v91, v83, v91
	v_cvt_pk_bf16_f32 v90, v90, v91
	global_store_short v[96:97], v87, off offset:1088
	global_store_short_d16_hi v[96:97], v87, off offset:1600
	global_store_short v[88:89], v90, off offset:1088
	global_store_short_d16_hi v[88:89], v90, off offset:1600
	v_mul_f32_e32 v87, v83, v94
	v_mul_f32_e32 v84, v83, v84
	v_mul_f32_e32 v80, v83, v80
	v_cvt_pk_bf16_f32 v84, v87, v84
	v_mul_f32_e32 v87, v83, v95
	v_cvt_pk_bf16_f32 v80, v87, v80
	global_store_short v[96:97], v84, off offset:2112
	global_store_short_d16_hi v[96:97], v84, off offset:2624
	global_store_short v[88:89], v80, off offset:2112
	global_store_short_d16_hi v[88:89], v80, off offset:2624
	v_mul_f32_e32 v80, v83, v81
	v_mul_f32_e32 v81, v83, v86
	v_cvt_pk_bf16_f32 v80, v80, v81
	v_mul_f32_e32 v81, v83, v85
	v_mul_f32_e32 v82, v83, v82
	v_cvt_pk_bf16_f32 v81, v81, v82
	global_store_short v[96:97], v80, off offset:3136
	global_store_short_d16_hi v[96:97], v80, off offset:3648
	global_store_short v[88:89], v81, off offset:3136
	global_store_short_d16_hi v[88:89], v81, off offset:3648
	s_waitcnt vmcnt(18)
	s_branch .Lrq_copy_3

; __device__ __forceinline__ unsigned cvt_pk_bf16(float lo, float hi) { unsigned r; asm volatile("v_cvt_pk_bf16_f32 %0, %1, %2" : "=v"(r) : "v"(lo), "v"(hi)); return r; }
; __device__ __forceinline__ float silu_f(float v) { return v / (1.0f + __expf(-v)); }
;     __device__ __forceinline__ void operator()(const Acc& acc, const Unit& u, int wr, int wc, int fr, int fq) const {
;         asm volatile("" : "+v"(fr), "+v"(fq));
;         bf16_t* base = O + u.coff + (size_t)(wr * 64 + fr) * ldc + wc * 32 + 8 * fq;
; #pragma unroll
;         for (int ai = 0; ai < 2; ++ai)
; #pragma unroll
;             for (int m = 0; m < 4; ++m) { bf16_t* rowp = base + (size_t)(ai * HALF + m * 16) * ldc;
; #pragma unroll
;                 for (int bj = 0; bj < 2; ++bj) { f32x4 v0 = acc[ai][bj][m][0], v1 = acc[ai][bj][m][1];
;                     if (ACT == 1) {
; #pragma unroll
;                         for (int j = 0; j < 4; ++j) { v0[j] = silu_f(v0[j]); v1[j] = silu_f(v1[j]); } }
;                     if (ACT == 2) {
; #pragma unroll
;                         for (int j = 0; j < 4; ++j) { const float a = fmaxf(v0[j], 0.f), b = fmaxf(v1[j], 0.f); v0[j] = a * a; v1[j] = b * b; } }
;                     u32x4 w; w.x = cvt_pk_bf16(v0[0], v0[1]); w.y = cvt_pk_bf16(v0[2], v0[3]); w.z = cvt_pk_bf16(v1[0], v1[1]); w.w = cvt_pk_bf16(v1[2], v1[3]);
;                     *(u32x4*)(rowp + bj * HALF) = w; } }
;     }
.LBB0_590:
	v_mov_b32_e32 v160, v141
	v_mov_b32_e32 v138, v140
	s_lshl_b64 s[12:13], s[60:61], 1
	v_readlane_b32 s14, v246, 43
	v_add_u32_e32 v138, s5, v138
	s_add_u32 s12, s14, s12
	v_readlane_b32 s14, v246, 44
	v_ashrrev_i32_e32 v139, 31, v138
	s_addc_u32 s13, s14, s13
	v_lshlrev_b64 v[138:139], 10, v[138:139]
	v_lshl_add_u64 v[138:139], s[12:13], 0, v[138:139]
	s_mov_b32 s21, s61
	v_lshlrev_b32_e32 v160, 3, v160
	v_lshl_add_u64 v[138:139], v[138:139], 0, s[20:21]
	v_ashrrev_i32_e32 v161, 31, v160
	v_lshl_add_u64 v[138:139], v[160:161], 1, v[138:139]
	s_movk_i32 s12, 0x4000
	v_cvt_pk_bf16_f32 v124, v124, v125
	v_cvt_pk_bf16_f32 v125, v126, v127
	v_cvt_pk_bf16_f32 v126, v120, v121
	v_cvt_pk_bf16_f32 v127, v122, v123
	global_store_dwordx4 v[138:139], v[124:127], off
	v_cvt_pk_bf16_f32 v112, v112, v113
	v_cvt_pk_bf16_f32 v113, v114, v115
	v_cvt_pk_bf16_f32 v114, v104, v105
	v_cvt_pk_bf16_f32 v115, v106, v107
	global_store_dwordx4 v[138:139], v[112:115], off offset:256
	v_cvt_pk_bf16_f32 v104, v116, v117
	v_cvt_pk_bf16_f32 v105, v118, v119
	v_cvt_pk_bf16_f32 v106, v108, v109
	v_add_co_u32_e32 v108, vcc, s12, v138
	s_mov_b32 s12, 0x8000
	s_nop 0
	v_addc_co_u32_e32 v109, vcc, 0, v139, vcc
	v_cvt_pk_bf16_f32 v107, v110, v111
	global_store_dwordx4 v[108:109], v[104:107], off
	v_cvt_pk_bf16_f32 v96, v96, v97
	v_cvt_pk_bf16_f32 v97, v98, v99
	v_cvt_pk_bf16_f32 v98, v88, v89
	v_cvt_pk_bf16_f32 v99, v90, v91
	global_store_dwordx4 v[108:109], v[96:99], off offset:256
	v_cvt_pk_bf16_f32 v88, v100, v101
	v_cvt_pk_bf16_f32 v89, v102, v103
	v_cvt_pk_bf16_f32 v90, v92, v93
	v_add_co_u32_e32 v92, vcc, s12, v138
	s_mov_b32 s12, 0xc000
	s_nop 0
	v_addc_co_u32_e32 v93, vcc, 0, v139, vcc
	v_cvt_pk_bf16_f32 v91, v94, v95
	global_store_dwordx4 v[92:93], v[88:91], off
	v_cvt_pk_bf16_f32 v80, v80, v81
	v_cvt_pk_bf16_f32 v81, v82, v83
	v_cvt_pk_bf16_f32 v82, v72, v73
	v_cvt_pk_bf16_f32 v83, v74, v75
	global_store_dwordx4 v[92:93], v[80:83], off offset:256
	s_cmp_lg_u64 s[18:19], 0
	s_cbranch_scc0 .Llate_align_4
	s_barrier
.Llate_align_4:
	v_cvt_pk_bf16_f32 v72, v84, v85
	v_cvt_pk_bf16_f32 v73, v86, v87
	v_cvt_pk_bf16_f32 v74, v76, v77
	v_add_co_u32_e32 v76, vcc, s12, v138
	s_mov_b32 s12, 0x20000
	s_nop 0
	v_addc_co_u32_e32 v77, vcc, 0, v139, vcc
	v_cvt_pk_bf16_f32 v75, v78, v79
	global_store_dwordx4 v[76:77], v[72:75], off
	v_cvt_pk_bf16_f32 v68, v68, v69
	v_cvt_pk_bf16_f32 v69, v70, v71
	v_cvt_pk_bf16_f32 v70, v64, v65
	v_cvt_pk_bf16_f32 v71, v66, v67
	global_store_dwordx4 v[76:77], v[68:71], off offset:256
	v_cvt_pk_bf16_f32 v60, v60, v61
	v_cvt_pk_bf16_f32 v61, v62, v63
	v_cvt_pk_bf16_f32 v62, v56, v57
	v_add_co_u32_e32 v56, vcc, s12, v138
	s_mov_b32 s12, 0x24000
	s_nop 0
	v_addc_co_u32_e32 v57, vcc, 0, v139, vcc
	v_cvt_pk_bf16_f32 v63, v58, v59
	global_store_dwordx4 v[56:57], v[60:63], off
	v_cvt_pk_bf16_f32 v48, v48, v49
	v_cvt_pk_bf16_f32 v49, v50, v51
	v_cvt_pk_bf16_f32 v50, v40, v41
	v_cvt_pk_bf16_f32 v51, v42, v43
	global_store_dwordx4 v[56:57], v[48:51], off offset:256
	v_cvt_pk_bf16_f32 v40, v52, v53
	v_cvt_pk_bf16_f32 v41, v54, v55
	v_cvt_pk_bf16_f32 v42, v44, v45
	v_add_co_u32_e32 v44, vcc, s12, v138
	s_mov_b32 s12, 0x28000
	s_nop 0
	v_addc_co_u32_e32 v45, vcc, 0, v139, vcc
	v_cvt_pk_bf16_f32 v43, v46, v47
	global_store_dwordx4 v[44:45], v[40:43], off
	v_cvt_pk_bf16_f32 v32, v32, v33
	v_cvt_pk_bf16_f32 v33, v34, v35
	v_cvt_pk_bf16_f32 v34, v24, v25
	v_cvt_pk_bf16_f32 v35, v26, v27
	global_store_dwordx4 v[44:45], v[32:35], off offset:256
	v_cvt_pk_bf16_f32 v24, v36, v37
	v_cvt_pk_bf16_f32 v25, v38, v39
	v_cvt_pk_bf16_f32 v26, v28, v29
	v_add_co_u32_e32 v28, vcc, s12, v138
	s_mov_b32 s12, 0x2c000
	s_nop 0
	v_addc_co_u32_e32 v29, vcc, 0, v139, vcc
	v_cvt_pk_bf16_f32 v27, v30, v31
	global_store_dwordx4 v[28:29], v[24:27], off
	v_cvt_pk_bf16_f32 v16, v16, v17
	v_cvt_pk_bf16_f32 v17, v18, v19
	v_cvt_pk_bf16_f32 v18, v8, v9
	v_cvt_pk_bf16_f32 v19, v10, v11
	global_store_dwordx4 v[28:29], v[16:19], off offset:256
	v_cvt_pk_bf16_f32 v8, v20, v21
	v_cvt_pk_bf16_f32 v9, v22, v23
	v_cvt_pk_bf16_f32 v10, v12, v13
	v_add_co_u32_e32 v12, vcc, s12, v138
	s_mov_b64 s[30:31], -1
	s_nop 0
	v_addc_co_u32_e32 v13, vcc, 0, v139, vcc
	s_andn2_b64 vcc, exec, s[42:43]
	v_cvt_pk_bf16_f32 v11, v14, v15
	global_store_dwordx4 v[12:13], v[8:11], off
	v_cvt_pk_bf16_f32 v4, v4, v5
	v_cvt_pk_bf16_f32 v5, v6, v7
	v_cvt_pk_bf16_f32 v6, v0, v1
	v_cvt_pk_bf16_f32 v7, v2, v3
	global_store_dwordx4 v[12:13], v[4:7], off offset:256
	s_cbranch_vccnz .LBB0_579
	s_andn2_b64 vcc, exec, s[16:17]
	s_cbranch_vccnz .LBB0_578
	s_barrier
	s_branch .LBB0_578

; __device__ __forceinline__ unsigned cvt_pk_bf16(float lo, float hi) { unsigned r; asm volatile("v_cvt_pk_bf16_f32 %0, %1, %2" : "=v"(r) : "v"(lo), "v"(hi)); return r; }
;     __device__ __forceinline__ void operator()(const Acc& acc, const Unit& u, int wr, int wc, int fr, int fq) const {
;     ...
;         const float lg = l2g[u.pm >> 6];
; #pragma unroll
;         for (int bj = 0; bj < 2; ++bj) {
;             const int j0 = bj * HALF + wc * 32 + 8 * fq;
;             float f[8];
; #pragma unroll
;             for (int e = 0; e < 8; ++e) f[e] = exp2f(-(float)(j0 + e + 1) * lg);
; #pragma unroll
;             for (int ai = 0; ai < 2; ++ai)
; #pragma unroll
;                 for (int m = 0; m < 4; ++m) {
;                     const int i = ai * HALF + wr * 64 + m * 16 + fr;
;                     float o[8];
; #pragma unroll
;                     for (int n = 0; n < 2; ++n)
; #pragma unroll
;                         for (int j = 0; j < 4; ++j) { const int e = n * 4 + j; o[e] = (i >= j0 + e) ? acc[ai][bj][m][n][j] * f[e] : 0.f; }
;                     u32x4 w; w.x = cvt_pk_bf16(o[0], o[1]); w.y = cvt_pk_bf16(o[2], o[3]); w.z = cvt_pk_bf16(o[4], o[5]); w.w = cvt_pk_bf16(o[6], o[7]);
;                     *(u32x4*)(O + u.coff + (size_t)i * 512 + j0) = w;
.LBB0_662:
	s_ashr_i32 s14, s14, 6
	s_ashr_i32 s15, s14, 31
	s_lshl_b64 s[14:15], s[14:15], 2
	v_readlane_b32 s28, v248, 2
	v_readlane_b32 s29, v248, 3
	s_add_u32 s14, s28, s14
	v_mov_b32_e32 v134, v139
	v_mov_b32_e32 v135, v138
	s_addc_u32 s15, s29, s15
	global_load_dword v142, v145, s[14:15]
	v_lshl_add_u32 v136, v134, 3, s6
	v_add_u32_e32 v134, s5, v135
	v_or_b32_e32 v135, 1, v136
	v_cvt_f32_i32_e32 v135, v135
	v_or_b32_e32 v160, 2, v136
	v_or_b32_e32 v162, 3, v136
	v_or_b32_e32 v164, 4, v136
	v_or_b32_e32 v166, 5, v136
	v_or_b32_e32 v168, 6, v136
	v_or_b32_e32 v170, 7, v136
	s_lshl_b64 s[14:15], s[60:61], 1
	v_readlane_b32 s28, v245, 30
	v_readlane_b32 s29, v245, 31
	s_add_u32 s28, s28, s14
	s_addc_u32 s29, s29, s15
	s_waitcnt vmcnt(0)
	v_mul_f32_e64 v137, v142, -v135
	v_cmp_gt_f32_e32 vcc, s75, v137
	s_nop 1
	v_cndmask_b32_e32 v137, 0, v190, vcc
	v_fma_f32 v135, v142, -v135, v137
	v_exp_f32_e32 v135, v135
	v_cndmask_b32_e32 v137, 0, v189, vcc
	v_ldexp_f32 v143, v135, v137
	v_cvt_f32_i32_e32 v135, v160
	v_mul_f32_e32 v124, v124, v143
	v_mul_f32_e32 v116, v116, v143
	v_mul_f32_e32 v108, v108, v143
	v_mul_f32_e64 v137, v142, -v135
	v_cmp_gt_f32_e32 vcc, s75, v137
	v_mul_f32_e32 v100, v100, v143
	v_mul_f32_e32 v92, v92, v143
	v_cndmask_b32_e32 v137, 0, v190, vcc
	v_fma_f32 v135, v142, -v135, v137
	v_exp_f32_e32 v135, v135
	v_cndmask_b32_e32 v137, 0, v189, vcc
	v_mul_f32_e32 v84, v84, v143
	v_mul_f32_e32 v76, v76, v143
	v_ldexp_f32 v161, v135, v137
	v_cvt_f32_i32_e32 v135, v162
	v_mul_f32_e32 v125, v125, v161
	v_mul_f32_e32 v117, v117, v161
	v_mul_f32_e32 v109, v109, v161
	v_mul_f32_e64 v137, v142, -v135
	v_cmp_gt_f32_e32 vcc, s75, v137
	v_mul_f32_e32 v101, v101, v161
	v_mul_f32_e32 v93, v93, v161
	v_cndmask_b32_e32 v137, 0, v190, vcc
	v_fma_f32 v135, v142, -v135, v137
	v_exp_f32_e32 v135, v135
	v_cndmask_b32_e32 v137, 0, v189, vcc
	v_mul_f32_e32 v85, v85, v161
	v_mul_f32_e32 v77, v77, v161
	v_ldexp_f32 v163, v135, v137
	v_cvt_f32_i32_e32 v135, v164
	v_mul_f32_e32 v126, v126, v163
	v_mul_f32_e32 v118, v118, v163
	v_mul_f32_e32 v110, v110, v163
	v_mul_f32_e64 v137, v142, -v135
	v_cmp_gt_f32_e32 vcc, s75, v137
	v_mul_f32_e32 v102, v102, v163
	v_mul_f32_e32 v94, v94, v163
	v_cndmask_b32_e32 v137, 0, v190, vcc
	v_fma_f32 v135, v142, -v135, v137
	v_exp_f32_e32 v135, v135
	v_cndmask_b32_e32 v137, 0, v189, vcc
	v_mul_f32_e32 v86, v86, v163
	v_mul_f32_e32 v78, v78, v163
	v_ldexp_f32 v165, v135, v137
	v_cvt_f32_i32_e32 v135, v166
	v_mul_f32_e32 v127, v127, v165
	v_mul_f32_e32 v119, v119, v165
	v_mul_f32_e32 v111, v111, v165
	v_mul_f32_e64 v137, v142, -v135
	v_cmp_gt_f32_e32 vcc, s75, v137
	v_mul_f32_e32 v103, v103, v165
	v_mul_f32_e32 v95, v95, v165
	v_cndmask_b32_e32 v137, 0, v190, vcc
	v_fma_f32 v135, v142, -v135, v137
	v_exp_f32_e32 v135, v135
	v_cndmask_b32_e32 v137, 0, v189, vcc
	v_mul_f32_e32 v87, v87, v165
	v_mul_f32_e32 v79, v79, v165
	v_ldexp_f32 v167, v135, v137
	v_cvt_f32_i32_e32 v135, v168
	v_mul_f32_e32 v120, v120, v167
	v_mul_f32_e32 v112, v112, v167
	v_mul_f32_e32 v104, v104, v167
	v_mul_f32_e64 v137, v142, -v135
	v_cmp_gt_f32_e32 vcc, s75, v137
	v_mul_f32_e32 v96, v96, v167
	v_mul_f32_e32 v88, v88, v167
	v_cndmask_b32_e32 v137, 0, v190, vcc
	v_fma_f32 v135, v142, -v135, v137
	v_exp_f32_e32 v135, v135
	v_cndmask_b32_e32 v137, 0, v189, vcc
	v_mul_f32_e32 v80, v80, v167
	v_mul_f32_e32 v72, v72, v167
	v_ldexp_f32 v169, v135, v137
	v_cvt_f32_i32_e32 v135, v170
	v_mul_f32_e32 v121, v121, v169
	v_mul_f32_e32 v113, v113, v169
	v_mul_f32_e32 v105, v105, v169
	v_mul_f32_e64 v137, v142, -v135
	v_cmp_gt_f32_e32 vcc, s75, v137
	v_mul_f32_e32 v97, v97, v169
	v_mul_f32_e32 v89, v89, v169
	v_cndmask_b32_e32 v137, 0, v190, vcc
	v_fma_f32 v135, v142, -v135, v137
	v_exp_f32_e32 v135, v135
	v_cndmask_b32_e32 v137, 0, v189, vcc
	v_mul_f32_e32 v81, v81, v169
	v_mul_f32_e32 v73, v73, v169
	v_ldexp_f32 v171, v135, v137
	v_add_u32_e32 v135, 8, v136
	v_cvt_f32_i32_e32 v135, v135
	v_mul_f32_e32 v122, v122, v171
	v_mul_f32_e32 v114, v114, v171
	v_mul_f32_e32 v106, v106, v171
	v_mul_f32_e64 v137, v142, -v135
	v_cmp_gt_f32_e32 vcc, s75, v137
	v_mul_f32_e32 v98, v98, v171
	v_mul_f32_e32 v90, v90, v171
	v_cndmask_b32_e32 v137, 0, v190, vcc
	v_fma_f32 v135, v142, -v135, v137
	v_cndmask_b32_e32 v137, 0, v189, vcc
	v_cmp_ge_i32_e32 vcc, v134, v136
	v_exp_f32_e32 v135, v135
	v_mul_f32_e32 v82, v82, v171
	v_cndmask_b32_e32 v124, 0, v124, vcc
	v_cmp_gt_i32_e32 vcc, v134, v136
	v_ldexp_f32 v172, v135, v137
	v_ashrrev_i32_e32 v135, 31, v134
	v_cndmask_b32_e32 v125, 0, v125, vcc
	v_cmp_ge_i32_e32 vcc, v134, v160
	v_ashrrev_i32_e32 v137, 31, v136
	v_mul_f32_e32 v123, v123, v172
	v_cndmask_b32_e32 v126, 0, v126, vcc
	v_cmp_ge_i32_e32 vcc, v134, v162
	v_cvt_pk_bf16_f32 v174, v124, v125
	v_lshlrev_b64 v[124:125], 1, v[136:137]
	v_mul_f32_e32 v115, v115, v172
	v_cndmask_b32_e32 v127, 0, v127, vcc
	v_cmp_ge_i32_e32 vcc, v134, v164
	v_cvt_pk_bf16_f32 v175, v126, v127
	v_mul_f32_e32 v107, v107, v172
	v_mul_f32_e32 v99, v99, v172
	v_cndmask_b32_e32 v120, 0, v120, vcc
	v_cmp_ge_i32_e32 vcc, v134, v166
	v_mul_f32_e32 v91, v91, v172
	v_mul_f32_e32 v83, v83, v172
	v_cndmask_b32_e32 v121, 0, v121, vcc
	v_cmp_ge_i32_e32 vcc, v134, v168
	v_cvt_pk_bf16_f32 v176, v120, v121
	v_lshlrev_b64 v[120:121], 10, v[134:135]
	v_lshl_add_u64 v[120:121], s[28:29], 0, v[120:121]
	v_cndmask_b32_e32 v122, 0, v122, vcc
	v_cmp_ge_i32_e32 vcc, v134, v170
	v_mul_f32_e32 v74, v74, v171
	v_mul_f32_e32 v75, v75, v172
	v_cndmask_b32_e32 v123, 0, v123, vcc
	v_cvt_pk_bf16_f32 v177, v122, v123
	v_lshl_add_u64 v[122:123], v[120:121], 0, v[124:125]
	v_add_u32_e32 v120, 16, v134
	v_cmp_ge_i32_e32 vcc, v120, v136
; __device__ __forceinline__ unsigned cvt_pk_bf16(float lo, float hi) { unsigned r; asm volatile("v_cvt_pk_bf16_f32 %0, %1, %2" : "=v"(r) : "v"(lo), "v"(hi)); return r; }
;     __device__ __forceinline__ void operator()(const Acc& acc, const Unit& u, int wr, int wc, int fr, int fq) const {
;     ...
;                 for (int m = 0; m < 4; ++m) {
;                     const int i = ai * HALF + wr * 64 + m * 16 + fr;
;                     float o[8];
; #pragma unroll
;                     for (int n = 0; n < 2; ++n)
; #pragma unroll
;                         for (int j = 0; j < 4; ++j) { const int e = n * 4 + j; o[e] = (i >= j0 + e) ? acc[ai][bj][m][n][j] * f[e] : 0.f; }
;                     u32x4 w; w.x = cvt_pk_bf16(o[0], o[1]); w.y = cvt_pk_bf16(o[2], o[3]); w.z = cvt_pk_bf16(o[4], o[5]); w.w = cvt_pk_bf16(o[6], o[7]);
;                     *(u32x4*)(O + u.coff + (size_t)i * 512 + j0) = w;
	v_ashrrev_i32_e32 v121, 31, v120
	global_store_dwordx4 v[122:123], v[174:177], off
	v_cndmask_b32_e32 v116, 0, v116, vcc
	v_cmp_gt_i32_e32 vcc, v120, v136
	v_mul_f32_e32 v68, v68, v143
	v_mul_f32_e32 v69, v69, v161
	v_cndmask_b32_e32 v117, 0, v117, vcc
	v_cmp_ge_i32_e32 vcc, v120, v160
	v_cvt_pk_bf16_f32 v116, v116, v117
	v_mul_f32_e32 v70, v70, v163
	v_mul_f32_e32 v71, v71, v165
	v_cndmask_b32_e32 v118, 0, v118, vcc
	v_cmp_ge_i32_e32 vcc, v120, v162
	v_mul_f32_e32 v64, v64, v167
	v_mul_f32_e32 v65, v65, v169
	v_cndmask_b32_e32 v119, 0, v119, vcc
	v_cmp_ge_i32_e32 vcc, v120, v164
	v_cvt_pk_bf16_f32 v117, v118, v119
	v_mul_f32_e32 v66, v66, v171
	s_nop 0
	v_cndmask_b32_e32 v112, 0, v112, vcc
	v_cmp_ge_i32_e32 vcc, v120, v166
	s_nop 1
	v_cndmask_b32_e32 v113, 0, v113, vcc
	v_cmp_ge_i32_e32 vcc, v120, v168
	v_cvt_pk_bf16_f32 v118, v112, v113
	v_lshlrev_b64 v[112:113], 10, v[120:121]
	v_lshl_add_u64 v[112:113], s[28:29], 0, v[112:113]
	v_cndmask_b32_e32 v114, 0, v114, vcc
	v_cmp_ge_i32_e32 vcc, v120, v170
	s_nop 1
	v_cndmask_b32_e32 v115, 0, v115, vcc
	v_cvt_pk_bf16_f32 v119, v114, v115
	v_lshl_add_u64 v[114:115], v[112:113], 0, v[124:125]
	v_add_u32_e32 v112, 32, v134
	v_cmp_ge_i32_e32 vcc, v112, v136
	v_ashrrev_i32_e32 v113, 31, v112
	global_store_dwordx4 v[114:115], v[116:119], off
	v_cndmask_b32_e32 v108, 0, v108, vcc
	v_cmp_gt_i32_e32 vcc, v112, v136
	s_nop 1
	v_cndmask_b32_e32 v109, 0, v109, vcc
	v_cmp_ge_i32_e32 vcc, v112, v160
	v_cvt_pk_bf16_f32 v108, v108, v109
	s_nop 1
	v_cndmask_b32_e32 v110, 0, v110, vcc
	v_cmp_ge_i32_e32 vcc, v112, v162
	s_nop 1
	v_cndmask_b32_e32 v111, 0, v111, vcc
	v_cmp_ge_i32_e32 vcc, v112, v164
	v_cvt_pk_bf16_f32 v109, v110, v111
	s_nop 1
	v_cndmask_b32_e32 v104, 0, v104, vcc
	v_cmp_ge_i32_e32 vcc, v112, v166
	s_nop 1
	v_cndmask_b32_e32 v105, 0, v105, vcc
	v_cmp_ge_i32_e32 vcc, v112, v168
	v_cvt_pk_bf16_f32 v110, v104, v105
	v_lshlrev_b64 v[104:105], 10, v[112:113]
	v_lshl_add_u64 v[104:105], s[28:29], 0, v[104:105]
	v_cndmask_b32_e32 v106, 0, v106, vcc
	v_cmp_ge_i32_e32 vcc, v112, v170
	s_nop 1
	v_cndmask_b32_e32 v107, 0, v107, vcc
	v_cvt_pk_bf16_f32 v111, v106, v107
	v_lshl_add_u64 v[106:107], v[104:105], 0, v[124:125]
	v_add_u32_e32 v104, 48, v134
	v_cmp_ge_i32_e32 vcc, v104, v136
	v_ashrrev_i32_e32 v105, 31, v104
	global_store_dwordx4 v[106:107], v[108:111], off
	v_cndmask_b32_e32 v100, 0, v100, vcc
	v_cmp_gt_i32_e32 vcc, v104, v136
	s_nop 1
	v_cndmask_b32_e32 v101, 0, v101, vcc
	v_cmp_ge_i32_e32 vcc, v104, v160
	v_cvt_pk_bf16_f32 v100, v100, v101
	s_nop 1
	v_cndmask_b32_e32 v102, 0, v102, vcc
	v_cmp_ge_i32_e32 vcc, v104, v162
	s_nop 1
	v_cndmask_b32_e32 v103, 0, v103, vcc
	v_cmp_ge_i32_e32 vcc, v104, v164
	v_cvt_pk_bf16_f32 v101, v102, v103
	s_nop 1
	v_cndmask_b32_e32 v96, 0, v96, vcc
	v_cmp_ge_i32_e32 vcc, v104, v166
	s_nop 1
	v_cndmask_b32_e32 v97, 0, v97, vcc
	v_cmp_ge_i32_e32 vcc, v104, v168
	v_cvt_pk_bf16_f32 v102, v96, v97
	v_lshlrev_b64 v[96:97], 10, v[104:105]
	v_lshl_add_u64 v[96:97], s[28:29], 0, v[96:97]
	v_cndmask_b32_e32 v98, 0, v98, vcc
	v_cmp_ge_i32_e32 vcc, v104, v170
	s_nop 1
	v_cndmask_b32_e32 v99, 0, v99, vcc
	v_cvt_pk_bf16_f32 v103, v98, v99
	v_lshl_add_u64 v[98:99], v[96:97], 0, v[124:125]
	v_add_u32_e32 v96, 0x80, v134
	v_cmp_ge_i32_e32 vcc, v96, v136
	v_ashrrev_i32_e32 v97, 31, v96
	global_store_dwordx4 v[98:99], v[100:103], off
	v_cndmask_b32_e32 v92, 0, v92, vcc
	v_cmp_gt_i32_e32 vcc, v96, v136
	s_nop 1
	v_cndmask_b32_e32 v93, 0, v93, vcc
	v_cmp_ge_i32_e32 vcc, v96, v160
	v_cvt_pk_bf16_f32 v92, v92, v93
	s_nop 1
	v_cndmask_b32_e32 v94, 0, v94, vcc
	v_cmp_ge_i32_e32 vcc, v96, v162
	s_nop 1
	v_cndmask_b32_e32 v95, 0, v95, vcc
	v_cmp_ge_i32_e32 vcc, v96, v164
	v_cvt_pk_bf16_f32 v93, v94, v95
	s_nop 1
	v_cndmask_b32_e32 v88, 0, v88, vcc
	v_cmp_ge_i32_e32 vcc, v96, v166
	s_nop 1
	v_cndmask_b32_e32 v89, 0, v89, vcc
	v_cmp_ge_i32_e32 vcc, v96, v168
	v_cvt_pk_bf16_f32 v94, v88, v89
	v_lshlrev_b64 v[88:89], 10, v[96:97]
	v_lshl_add_u64 v[88:89], s[28:29], 0, v[88:89]
	v_cndmask_b32_e32 v90, 0, v90, vcc
	v_cmp_ge_i32_e32 vcc, v96, v170
	s_nop 1
	v_cndmask_b32_e32 v91, 0, v91, vcc
	v_cvt_pk_bf16_f32 v95, v90, v91
	v_lshl_add_u64 v[90:91], v[88:89], 0, v[124:125]
	v_add_u32_e32 v88, 0x90, v134
	v_cmp_ge_i32_e32 vcc, v88, v136
	v_ashrrev_i32_e32 v89, 31, v88
	global_store_dwordx4 v[90:91], v[92:95], off
	v_cndmask_b32_e32 v84, 0, v84, vcc
	v_cmp_gt_i32_e32 vcc, v88, v136
	s_nop 1
	v_cndmask_b32_e32 v85, 0, v85, vcc
	v_cmp_ge_i32_e32 vcc, v88, v160
	v_cvt_pk_bf16_f32 v84, v84, v85
	s_nop 1
	v_cndmask_b32_e32 v86, 0, v86, vcc
	v_cmp_ge_i32_e32 vcc, v88, v162
	s_nop 1
	v_cndmask_b32_e32 v87, 0, v87, vcc
	v_cmp_ge_i32_e32 vcc, v88, v164
	v_cvt_pk_bf16_f32 v85, v86, v87
	s_nop 1
	v_cndmask_b32_e32 v80, 0, v80, vcc
	v_cmp_ge_i32_e32 vcc, v88, v166
	s_nop 1
	v_cndmask_b32_e32 v81, 0, v81, vcc
	v_cmp_ge_i32_e32 vcc, v88, v168
	v_cvt_pk_bf16_f32 v86, v80, v81
	v_lshlrev_b64 v[80:81], 10, v[88:89]
	v_lshl_add_u64 v[80:81], s[28:29], 0, v[80:81]
	v_cndmask_b32_e32 v82, 0, v82, vcc
	v_cmp_ge_i32_e32 vcc, v88, v170
	s_nop 1
	v_cndmask_b32_e32 v83, 0, v83, vcc
	v_cvt_pk_bf16_f32 v87, v82, v83
	v_lshl_add_u64 v[82:83], v[80:81], 0, v[124:125]
	v_add_u32_e32 v80, 0xa0, v134
	v_cmp_ge_i32_e32 vcc, v80, v136
	v_ashrrev_i32_e32 v81, 31, v80
	global_store_dwordx4 v[82:83], v[84:87], off
	s_cmp_lg_u64 s[18:19], 0
	s_cbranch_scc0 .Llate_align_5
	s_barrier
; __device__ __forceinline__ unsigned cvt_pk_bf16(float lo, float hi) { unsigned r; asm volatile("v_cvt_pk_bf16_f32 %0, %1, %2" : "=v"(r) : "v"(lo), "v"(hi)); return r; }
;     __device__ __forceinline__ void operator()(const Acc& acc, const Unit& u, int wr, int wc, int fr, int fq) const {
;     ...
;         for (int bj = 0; bj < 2; ++bj) {
;             const int j0 = bj * HALF + wc * 32 + 8 * fq;
;             float f[8];
; #pragma unroll
;             for (int e = 0; e < 8; ++e) f[e] = exp2f(-(float)(j0 + e + 1) * lg);
; #pragma unroll
;             for (int ai = 0; ai < 2; ++ai)
; #pragma unroll
;                 for (int m = 0; m < 4; ++m) {
;                     const int i = ai * HALF + wr * 64 + m * 16 + fr;
;                     float o[8];
; #pragma unroll
;                     for (int n = 0; n < 2; ++n)
; #pragma unroll
;                         for (int j = 0; j < 4; ++j) { const int e = n * 4 + j; o[e] = (i >= j0 + e) ? acc[ai][bj][m][n][j] * f[e] : 0.f; }
;                     u32x4 w; w.x = cvt_pk_bf16(o[0], o[1]); w.y = cvt_pk_bf16(o[2], o[3]); w.z = cvt_pk_bf16(o[4], o[5]); w.w = cvt_pk_bf16(o[6], o[7]);
;                     *(u32x4*)(O + u.coff + (size_t)i * 512 + j0) = w;
.Llate_align_5:
	v_cndmask_b32_e32 v76, 0, v76, vcc
	v_cmp_gt_i32_e32 vcc, v80, v136
	s_nop 1
	v_cndmask_b32_e32 v77, 0, v77, vcc
	v_cmp_ge_i32_e32 vcc, v80, v160
	v_cvt_pk_bf16_f32 v76, v76, v77
	s_nop 1
	v_cndmask_b32_e32 v78, 0, v78, vcc
	v_cmp_ge_i32_e32 vcc, v80, v162
	s_nop 1
	v_cndmask_b32_e32 v79, 0, v79, vcc
	v_cmp_ge_i32_e32 vcc, v80, v164
	v_cvt_pk_bf16_f32 v77, v78, v79
	s_nop 1
	v_cndmask_b32_e32 v72, 0, v72, vcc
	v_cmp_ge_i32_e32 vcc, v80, v166
	s_nop 1
	v_cndmask_b32_e32 v73, 0, v73, vcc
	v_cmp_ge_i32_e32 vcc, v80, v168
	v_cvt_pk_bf16_f32 v78, v72, v73
	v_lshlrev_b64 v[72:73], 10, v[80:81]
	v_lshl_add_u64 v[72:73], s[28:29], 0, v[72:73]
	v_cndmask_b32_e32 v74, 0, v74, vcc
	v_cmp_ge_i32_e32 vcc, v80, v170
	s_nop 1
	v_cndmask_b32_e32 v75, 0, v75, vcc
	v_cvt_pk_bf16_f32 v79, v74, v75
	v_lshl_add_u64 v[74:75], v[72:73], 0, v[124:125]
	v_add_u32_e32 v72, 0xb0, v134
	v_cmp_ge_i32_e32 vcc, v72, v136
	global_store_dwordx4 v[74:75], v[76:79], off
	s_nop 0
	v_cndmask_b32_e32 v68, 0, v68, vcc
	v_cmp_gt_i32_e32 vcc, v72, v136
	s_nop 1
	v_cndmask_b32_e32 v69, 0, v69, vcc
	v_cmp_ge_i32_e32 vcc, v72, v160
	s_nop 1
	v_cndmask_b32_e32 v70, 0, v70, vcc
	v_cmp_ge_i32_e32 vcc, v72, v162
	s_nop 1
	v_cndmask_b32_e32 v71, 0, v71, vcc
	v_cmp_ge_i32_e32 vcc, v72, v164
	s_nop 1
	v_cndmask_b32_e32 v64, 0, v64, vcc
	v_cmp_ge_i32_e32 vcc, v72, v166
	s_nop 1
	v_cndmask_b32_e32 v65, 0, v65, vcc
	v_cmp_ge_i32_e32 vcc, v72, v168
	s_nop 1
	v_cndmask_b32_e32 v73, 0, v66, vcc
	v_mul_f32_e32 v66, v67, v172
	v_cmp_ge_i32_e32 vcc, v72, v170
	s_nop 1
	v_cndmask_b32_e32 v76, 0, v66, vcc
	v_cvt_pk_bf16_f32 v66, v68, v69
	v_cvt_pk_bf16_f32 v67, v70, v71
	v_cvt_pk_bf16_f32 v68, v64, v65
	v_cvt_pk_bf16_f32 v69, v73, v76
	v_ashrrev_i32_e32 v73, 31, v72
	v_lshlrev_b64 v[64:65], 10, v[72:73]
	v_lshl_add_u64 v[64:65], s[28:29], 0, v[64:65]
	v_lshl_add_u64 v[64:65], v[64:65], 0, v[124:125]
	global_store_dwordx4 v[64:65], v[66:69], off
	s_mov_b64 s[28:29], -1
	s_nop 0
	v_add_u32_e32 v67, 0x81, v136
	v_cvt_f32_i32_e32 v67, v67
	v_add_u32_e32 v66, 0x80, v136
	v_mul_f32_e64 v68, v142, -v67
	v_cmp_gt_f32_e32 vcc, s75, v68
	s_nop 1
	v_cndmask_b32_e32 v68, 0, v190, vcc
	v_fma_f32 v67, v142, -v67, v68
	v_exp_f32_e32 v67, v67
	v_cndmask_b32_e32 v68, 0, v189, vcc
	v_ldexp_f32 v67, v67, v68
	v_add_u32_e32 v68, 0x82, v136
	v_cvt_f32_i32_e32 v69, v68
	v_mul_f32_e32 v60, v60, v67
	v_mul_f32_e32 v52, v52, v67
	v_mul_f32_e32 v44, v44, v67
	v_mul_f32_e64 v70, v142, -v69
	v_cmp_gt_f32_e32 vcc, s75, v70
	v_mul_f32_e32 v36, v36, v67
	v_mul_f32_e32 v28, v28, v67
	v_cndmask_b32_e32 v70, 0, v190, vcc
	v_fma_f32 v69, v142, -v69, v70
	v_exp_f32_e32 v69, v69
	v_cndmask_b32_e32 v70, 0, v189, vcc
	v_mul_f32_e32 v20, v20, v67
	v_mul_f32_e32 v12, v12, v67
	v_ldexp_f32 v69, v69, v70
	v_add_u32_e32 v70, 0x83, v136
	v_cvt_f32_i32_e32 v71, v70
	v_mul_f32_e32 v61, v61, v69
	v_mul_f32_e32 v53, v53, v69
	v_mul_f32_e32 v45, v45, v69
	v_mul_f32_e64 v73, v142, -v71
	v_cmp_gt_f32_e32 vcc, s75, v73
	v_mul_f32_e32 v37, v37, v69
	v_mul_f32_e32 v29, v29, v69
	v_cndmask_b32_e32 v73, 0, v190, vcc
	v_fma_f32 v71, v142, -v71, v73
	v_exp_f32_e32 v71, v71
	v_cndmask_b32_e32 v73, 0, v189, vcc
	v_mul_f32_e32 v21, v21, v69
	v_mul_f32_e32 v13, v13, v69
	v_ldexp_f32 v71, v71, v73
	v_add_u32_e32 v73, 0x84, v136
	v_cvt_f32_i32_e32 v76, v73
	v_mul_f32_e32 v62, v62, v71
	v_mul_f32_e32 v54, v54, v71
	v_mul_f32_e32 v46, v46, v71
	v_mul_f32_e64 v77, v142, -v76
	v_cmp_gt_f32_e32 vcc, s75, v77
	v_mul_f32_e32 v38, v38, v71
	v_mul_f32_e32 v30, v30, v71
	v_cndmask_b32_e32 v77, 0, v190, vcc
	v_fma_f32 v76, v142, -v76, v77
	v_exp_f32_e32 v76, v76
	v_cndmask_b32_e32 v77, 0, v189, vcc
	v_mul_f32_e32 v22, v22, v71
	v_mul_f32_e32 v14, v14, v71
	v_ldexp_f32 v76, v76, v77
	v_add_u32_e32 v77, 0x85, v136
	v_cvt_f32_i32_e32 v78, v77
	v_mul_f32_e32 v63, v63, v76
	v_mul_f32_e32 v55, v55, v76
	v_mul_f32_e32 v47, v47, v76
	v_mul_f32_e64 v79, v142, -v78
	v_cmp_gt_f32_e32 vcc, s75, v79
	v_mul_f32_e32 v39, v39, v76
	v_mul_f32_e32 v31, v31, v76
	v_cndmask_b32_e32 v79, 0, v190, vcc
	v_fma_f32 v78, v142, -v78, v79
	v_exp_f32_e32 v78, v78
	v_cndmask_b32_e32 v79, 0, v189, vcc
	v_mul_f32_e32 v23, v23, v76
	v_mul_f32_e32 v15, v15, v76
	v_ldexp_f32 v78, v78, v79
	v_add_u32_e32 v79, 0x86, v136
	v_cvt_f32_i32_e32 v81, v79
	v_mul_f32_e32 v56, v56, v78
	v_mul_f32_e32 v48, v48, v78
	v_mul_f32_e32 v40, v40, v78
	v_mul_f32_e64 v84, v142, -v81
	v_cmp_gt_f32_e32 vcc, s75, v84
	v_mul_f32_e32 v32, v32, v78
	v_mul_f32_e32 v24, v24, v78
	v_cndmask_b32_e32 v84, 0, v190, vcc
	v_fma_f32 v81, v142, -v81, v84
	v_exp_f32_e32 v81, v81
	v_cndmask_b32_e32 v84, 0, v189, vcc
	v_mul_f32_e32 v16, v16, v78
	v_mul_f32_e32 v8, v8, v78
	v_ldexp_f32 v81, v81, v84
	v_add_u32_e32 v84, 0x87, v136
	v_cvt_f32_i32_e32 v85, v84
	v_mul_f32_e32 v4, v4, v67
	v_mul_f32_e32 v5, v5, v69
	v_mul_f32_e32 v6, v6, v71
	v_mul_f32_e64 v86, v142, -v85
	v_cmp_gt_f32_e32 vcc, s75, v86
	v_mul_f32_e32 v7, v7, v76
	v_mul_f32_e32 v0, v0, v78
	v_cndmask_b32_e32 v86, 0, v190, vcc
	v_fma_f32 v85, v142, -v85, v86
	v_exp_f32_e32 v85, v85
	v_cndmask_b32_e32 v86, 0, v189, vcc
	v_ldexp_f32 v85, v85, v86
	v_add_u32_e32 v86, 0x88, v136
	v_cvt_f32_i32_e32 v86, v86
	v_mul_f32_e64 v87, v142, -v86
	v_cmp_gt_f32_e32 vcc, s75, v87
	s_nop 1
	v_cndmask_b32_e32 v87, 0, v190, vcc
	v_fma_f32 v86, v142, -v86, v87
	v_cndmask_b32_e32 v87, 0, v189, vcc
	v_cmp_ge_i32_e32 vcc, v134, v66
	v_exp_f32_e32 v86, v86
	s_nop 0
	v_cndmask_b32_e32 v60, 0, v60, vcc
	v_cmp_gt_i32_e32 vcc, v134, v66
	v_ldexp_f32 v86, v86, v87
	s_nop 0
	v_cndmask_b32_e32 v61, 0, v61, vcc
	v_cmp_ge_i32_e32 vcc, v134, v68
	s_nop 1
	v_cndmask_b32_e32 v62, 0, v62, vcc
; __device__ __forceinline__ unsigned cvt_pk_bf16(float lo, float hi) { unsigned r; asm volatile("v_cvt_pk_bf16_f32 %0, %1, %2" : "=v"(r) : "v"(lo), "v"(hi)); return r; }
; #define PG8_BAR __builtin_amdgcn_s_barrier()
; template <class Epi, class Map>
; __device__ __forceinline__ void gemm_phase(LAS unsigned char* lds, const Gemm g, const Sched<Map>& S, const Epi& E) {
;     ...
;         if (!has_next) break;
; #pragma unroll
;         for (int a = 0; a < 2; ++a)
; #pragma unroll
;             for (int b = 0; b < 2; ++b)
; #pragma unroll
;                 for (int m = 0; m < 4; ++m)
; #pragma unroll
;                     for (int n = 0; n < 2; ++n) acc[a][b][m][n] = (f32x4){0.f, 0.f, 0.f, 0.f};
;         cur = nxt; cA = nA; cB = nB; ++ui;
;         if (wr == 1) PG8_BAR;
;     __device__ __forceinline__ void operator()(const Acc& acc, const Unit& u, int wr, int wc, int fr, int fq) const {
;     ...
;                 for (int m = 0; m < 4; ++m) {
;                     const int i = ai * HALF + wr * 64 + m * 16 + fr;
;                     float o[8];
; #pragma unroll
;                     for (int n = 0; n < 2; ++n)
; #pragma unroll
;                         for (int j = 0; j < 4; ++j) { const int e = n * 4 + j; o[e] = (i >= j0 + e) ? acc[ai][bj][m][n][j] * f[e] : 0.f; }
;                     u32x4 w; w.x = cvt_pk_bf16(o[0], o[1]); w.y = cvt_pk_bf16(o[2], o[3]); w.z = cvt_pk_bf16(o[4], o[5]); w.w = cvt_pk_bf16(o[6], o[7]);
;                     *(u32x4*)(O + u.coff + (size_t)i * 512 + j0) = w;
	v_cmp_ge_i32_e32 vcc, v134, v70
	s_nop 1
	v_cndmask_b32_e32 v63, 0, v63, vcc
	v_cmp_ge_i32_e32 vcc, v134, v73
	s_nop 1
	v_cndmask_b32_e32 v87, 0, v56, vcc
	v_mul_f32_e32 v56, v57, v81
	v_cmp_ge_i32_e32 vcc, v134, v77
	s_nop 1
	v_cndmask_b32_e32 v89, 0, v56, vcc
	v_mul_f32_e32 v56, v58, v85
	v_cmp_ge_i32_e32 vcc, v134, v79
	s_nop 1
	v_cndmask_b32_e32 v92, 0, v56, vcc
	v_mul_f32_e32 v56, v59, v86
	v_cmp_ge_i32_e32 vcc, v134, v84
	s_nop 1
	v_cndmask_b32_e32 v59, 0, v56, vcc
	v_cmp_ge_i32_e32 vcc, v120, v66
	v_cvt_pk_bf16_f32 v56, v60, v61
	v_cvt_pk_bf16_f32 v57, v62, v63
	v_cvt_pk_bf16_f32 v58, v87, v89
	v_cvt_pk_bf16_f32 v59, v92, v59
	global_store_dwordx4 v[122:123], v[56:59], off offset:256
	s_nop 0
	v_cndmask_b32_e32 v52, 0, v52, vcc
	v_cmp_gt_i32_e32 vcc, v120, v66
	s_nop 1
	v_cndmask_b32_e32 v53, 0, v53, vcc
	v_cmp_ge_i32_e32 vcc, v120, v68
	s_nop 1
	v_cndmask_b32_e32 v54, 0, v54, vcc
	v_cmp_ge_i32_e32 vcc, v120, v70
	s_nop 1
	v_cndmask_b32_e32 v55, 0, v55, vcc
	v_cmp_ge_i32_e32 vcc, v120, v73
	s_nop 1
	v_cndmask_b32_e32 v56, 0, v48, vcc
	v_mul_f32_e32 v48, v49, v81
	v_cmp_ge_i32_e32 vcc, v120, v77
	s_nop 1
	v_cndmask_b32_e32 v57, 0, v48, vcc
	v_mul_f32_e32 v48, v50, v85
	v_cmp_ge_i32_e32 vcc, v120, v79
	s_nop 1
	v_cndmask_b32_e32 v58, 0, v48, vcc
	v_mul_f32_e32 v48, v51, v86
	v_cmp_ge_i32_e32 vcc, v120, v84
	s_nop 1
	v_cndmask_b32_e32 v51, 0, v48, vcc
	v_cmp_ge_i32_e32 vcc, v112, v66
	v_cvt_pk_bf16_f32 v48, v52, v53
	v_cvt_pk_bf16_f32 v49, v54, v55
	v_cvt_pk_bf16_f32 v50, v56, v57
	v_cvt_pk_bf16_f32 v51, v58, v51
	global_store_dwordx4 v[114:115], v[48:51], off offset:256
	s_nop 0
	v_cndmask_b32_e32 v44, 0, v44, vcc
	v_cmp_gt_i32_e32 vcc, v112, v66
	s_nop 1
	v_cndmask_b32_e32 v45, 0, v45, vcc
	v_cmp_ge_i32_e32 vcc, v112, v68
	s_nop 1
	v_cndmask_b32_e32 v46, 0, v46, vcc
	v_cmp_ge_i32_e32 vcc, v112, v70
	s_nop 1
	v_cndmask_b32_e32 v47, 0, v47, vcc
	v_cmp_ge_i32_e32 vcc, v112, v73
	s_nop 1
	v_cndmask_b32_e32 v48, 0, v40, vcc
	v_mul_f32_e32 v40, v41, v81
	v_cmp_ge_i32_e32 vcc, v112, v77
	s_nop 1
	v_cndmask_b32_e32 v49, 0, v40, vcc
	v_mul_f32_e32 v40, v42, v85
	v_cmp_ge_i32_e32 vcc, v112, v79
	s_nop 1
	v_cndmask_b32_e32 v50, 0, v40, vcc
	v_mul_f32_e32 v40, v43, v86
	v_cmp_ge_i32_e32 vcc, v112, v84
	s_nop 1
	v_cndmask_b32_e32 v43, 0, v40, vcc
	v_cmp_ge_i32_e32 vcc, v104, v66
	v_cvt_pk_bf16_f32 v40, v44, v45
	v_cvt_pk_bf16_f32 v41, v46, v47
	v_cvt_pk_bf16_f32 v42, v48, v49
	v_cvt_pk_bf16_f32 v43, v50, v43
	global_store_dwordx4 v[106:107], v[40:43], off offset:256
	s_nop 0
	v_cndmask_b32_e32 v36, 0, v36, vcc
	v_cmp_gt_i32_e32 vcc, v104, v66
	s_nop 1
	v_cndmask_b32_e32 v37, 0, v37, vcc
	v_cmp_ge_i32_e32 vcc, v104, v68
	s_nop 1
	v_cndmask_b32_e32 v38, 0, v38, vcc
	v_cmp_ge_i32_e32 vcc, v104, v70
	s_nop 1
	v_cndmask_b32_e32 v39, 0, v39, vcc
	v_cmp_ge_i32_e32 vcc, v104, v73
	s_nop 1
	v_cndmask_b32_e32 v40, 0, v32, vcc
	v_mul_f32_e32 v32, v33, v81
	v_cmp_ge_i32_e32 vcc, v104, v77
	s_nop 1
	v_cndmask_b32_e32 v41, 0, v32, vcc
	v_mul_f32_e32 v32, v34, v85
	v_cmp_ge_i32_e32 vcc, v104, v79
	s_nop 1
	v_cndmask_b32_e32 v42, 0, v32, vcc
	v_mul_f32_e32 v32, v35, v86
	v_cmp_ge_i32_e32 vcc, v104, v84
	s_nop 1
	v_cndmask_b32_e32 v35, 0, v32, vcc
	v_cmp_ge_i32_e32 vcc, v96, v66
	v_cvt_pk_bf16_f32 v32, v36, v37
	v_cvt_pk_bf16_f32 v33, v38, v39
	v_cvt_pk_bf16_f32 v34, v40, v41
	v_cvt_pk_bf16_f32 v35, v42, v35
	global_store_dwordx4 v[98:99], v[32:35], off offset:256
	s_nop 0
	v_cndmask_b32_e32 v28, 0, v28, vcc
	v_cmp_gt_i32_e32 vcc, v96, v66
	s_nop 1
	v_cndmask_b32_e32 v29, 0, v29, vcc
	v_cmp_ge_i32_e32 vcc, v96, v68
	s_nop 1
	v_cndmask_b32_e32 v30, 0, v30, vcc
	v_cmp_ge_i32_e32 vcc, v96, v70
	s_nop 1
	v_cndmask_b32_e32 v31, 0, v31, vcc
	v_cmp_ge_i32_e32 vcc, v96, v73
	s_nop 1
	v_cndmask_b32_e32 v32, 0, v24, vcc
	v_mul_f32_e32 v24, v25, v81
	v_cmp_ge_i32_e32 vcc, v96, v77
	s_nop 1
	v_cndmask_b32_e32 v33, 0, v24, vcc
	v_mul_f32_e32 v24, v26, v85
	v_cmp_ge_i32_e32 vcc, v96, v79
	s_nop 1
	v_cndmask_b32_e32 v34, 0, v24, vcc
	v_mul_f32_e32 v24, v27, v86
	v_cmp_ge_i32_e32 vcc, v96, v84
	s_nop 1
	v_cndmask_b32_e32 v27, 0, v24, vcc
	v_cmp_ge_i32_e32 vcc, v88, v66
	v_cvt_pk_bf16_f32 v24, v28, v29
	v_cvt_pk_bf16_f32 v25, v30, v31
	v_cvt_pk_bf16_f32 v26, v32, v33
	v_cvt_pk_bf16_f32 v27, v34, v27
	global_store_dwordx4 v[90:91], v[24:27], off offset:256
	s_nop 0
	v_cndmask_b32_e32 v20, 0, v20, vcc
	v_cmp_gt_i32_e32 vcc, v88, v66
	s_nop 1
	v_cndmask_b32_e32 v21, 0, v21, vcc
	v_cmp_ge_i32_e32 vcc, v88, v68
	s_nop 1
	v_cndmask_b32_e32 v22, 0, v22, vcc
	v_cmp_ge_i32_e32 vcc, v88, v70
	s_nop 1
	v_cndmask_b32_e32 v23, 0, v23, vcc
	v_cmp_ge_i32_e32 vcc, v88, v73
	s_nop 1
	v_cndmask_b32_e32 v24, 0, v16, vcc
	v_mul_f32_e32 v16, v17, v81
	v_cmp_ge_i32_e32 vcc, v88, v77
	s_nop 1
	v_cndmask_b32_e32 v25, 0, v16, vcc
	v_mul_f32_e32 v16, v18, v85
	v_cmp_ge_i32_e32 vcc, v88, v79
	s_nop 1
	v_cndmask_b32_e32 v26, 0, v16, vcc
	v_mul_f32_e32 v16, v19, v86
	v_cmp_ge_i32_e32 vcc, v88, v84
	s_nop 1
	v_cndmask_b32_e32 v19, 0, v16, vcc
	v_cmp_ge_i32_e32 vcc, v80, v66
	v_cvt_pk_bf16_f32 v16, v20, v21
	v_cvt_pk_bf16_f32 v17, v22, v23
	v_cvt_pk_bf16_f32 v18, v24, v25
	v_cvt_pk_bf16_f32 v19, v26, v19
	global_store_dwordx4 v[82:83], v[16:19], off offset:256
	s_nop 0
	v_cndmask_b32_e32 v12, 0, v12, vcc
	v_cmp_gt_i32_e32 vcc, v80, v66
	s_nop 1
	v_cndmask_b32_e32 v13, 0, v13, vcc
	v_cmp_ge_i32_e32 vcc, v80, v68
	s_nop 1
	v_cndmask_b32_e32 v14, 0, v14, vcc
	v_cmp_ge_i32_e32 vcc, v80, v70
	s_nop 1
	v_cndmask_b32_e32 v15, 0, v15, vcc
	v_cmp_ge_i32_e32 vcc, v80, v73
	s_nop 1
	v_cndmask_b32_e32 v16, 0, v8, vcc
	v_mul_f32_e32 v8, v9, v81
	v_cmp_ge_i32_e32 vcc, v80, v77
	s_nop 1
	v_cndmask_b32_e32 v17, 0, v8, vcc
	v_mul_f32_e32 v8, v10, v85
	v_cmp_ge_i32_e32 vcc, v80, v79
	s_nop 1
	v_cndmask_b32_e32 v18, 0, v8, vcc
	v_mul_f32_e32 v8, v11, v86
	v_cmp_ge_i32_e32 vcc, v80, v84
	s_nop 1
	v_cndmask_b32_e32 v11, 0, v8, vcc
	v_cmp_ge_i32_e32 vcc, v72, v66
	v_cvt_pk_bf16_f32 v8, v12, v13
	v_cvt_pk_bf16_f32 v9, v14, v15
	v_cvt_pk_bf16_f32 v10, v16, v17
	v_cvt_pk_bf16_f32 v11, v18, v11
	global_store_dwordx4 v[74:75], v[8:11], off offset:256
	s_nop 0
	v_cndmask_b32_e32 v4, 0, v4, vcc
	v_cmp_gt_i32_e32 vcc, v72, v66
	s_nop 1
	v_cndmask_b32_e32 v5, 0, v5, vcc
	v_cmp_ge_i32_e32 vcc, v72, v68
	s_nop 1
	v_cndmask_b32_e32 v6, 0, v6, vcc
	v_cmp_ge_i32_e32 vcc, v72, v70
	s_nop 1
	v_cndmask_b32_e32 v7, 0, v7, vcc
	v_cmp_ge_i32_e32 vcc, v72, v73
	s_nop 1
	v_cndmask_b32_e32 v8, 0, v0, vcc
	v_mul_f32_e32 v0, v1, v81
	v_cmp_ge_i32_e32 vcc, v72, v77
	s_nop 1
	v_cndmask_b32_e32 v9, 0, v0, vcc
	v_mul_f32_e32 v0, v2, v85
	v_cmp_ge_i32_e32 vcc, v72, v79
	s_nop 1
	v_cndmask_b32_e32 v10, 0, v0, vcc
	v_mul_f32_e32 v0, v3, v86
	v_cmp_ge_i32_e32 vcc, v72, v84
	s_nop 1
	v_cndmask_b32_e32 v3, 0, v0, vcc
	s_andn2_b64 vcc, exec, s[42:43]
	v_cvt_pk_bf16_f32 v0, v4, v5
	v_cvt_pk_bf16_f32 v1, v6, v7
	v_cvt_pk_bf16_f32 v2, v8, v9
	v_cvt_pk_bf16_f32 v3, v10, v3
	global_store_dwordx4 v[64:65], v[0:3], off offset:256
	s_cbranch_vccnz .LBB0_651
	s_andn2_b64 vcc, exec, s[16:17]
	s_cbranch_vccnz .LBB0_650
	s_barrier
	s_branch .LBB0_650

; __device__ __forceinline__ unsigned cvt_pk_bf16(float lo, float hi) { unsigned r; asm volatile("v_cvt_pk_bf16_f32 %0, %1, %2" : "=v"(r) : "v"(lo), "v"(hi)); return r; }
; __device__ __forceinline__ float silu_f(float v) { return v / (1.0f + __expf(-v)); }
;     __device__ __forceinline__ void operator()(const Acc& acc, const Unit& u, int wr, int wc, int fr, int fq) const {
;         asm volatile("" : "+v"(fr), "+v"(fq));
;         bf16_t* base = O + u.coff + (size_t)(wr * 64 + fr) * ldc + wc * 32 + 8 * fq;
; #pragma unroll
;         for (int ai = 0; ai < 2; ++ai)
; #pragma unroll
;             for (int m = 0; m < 4; ++m) { bf16_t* rowp = base + (size_t)(ai * HALF + m * 16) * ldc;
; #pragma unroll
;                 for (int bj = 0; bj < 2; ++bj) { f32x4 v0 = acc[ai][bj][m][0], v1 = acc[ai][bj][m][1];
;                     if (ACT == 1) {
; #pragma unroll
;                         for (int j = 0; j < 4; ++j) { v0[j] = silu_f(v0[j]); v1[j] = silu_f(v1[j]); } }
;                     if (ACT == 2) {
; #pragma unroll
;                         for (int j = 0; j < 4; ++j) { const float a = fmaxf(v0[j], 0.f), b = fmaxf(v1[j], 0.f); v0[j] = a * a; v1[j] = b * b; } }
;                     u32x4 w; w.x = cvt_pk_bf16(v0[0], v0[1]); w.y = cvt_pk_bf16(v0[2], v0[3]); w.z = cvt_pk_bf16(v1[0], v1[1]); w.w = cvt_pk_bf16(v1[2], v1[3]);
;                     *(u32x4*)(rowp + bj * HALF) = w; } }
;     }
.LBB0_682:
	v_mov_b32_e32 v134, v136
	v_mov_b32_e32 v140, v137
	s_lshl_b64 s[12:13], s[60:61], 1
	v_readlane_b32 s14, v246, 43
	v_add_u32_e32 v134, s5, v134
	s_add_u32 s12, s14, s12
	v_readlane_b32 s14, v246, 44
	v_ashrrev_i32_e32 v135, 31, v134
	s_addc_u32 s13, s14, s13
	v_lshlrev_b64 v[134:135], 10, v[134:135]
	v_lshl_add_u64 v[134:135], s[12:13], 0, v[134:135]
	s_mov_b32 s21, s61
	v_lshlrev_b32_e32 v140, 3, v140
	v_lshl_add_u64 v[134:135], v[134:135], 0, s[20:21]
	v_ashrrev_i32_e32 v141, 31, v140
	v_lshl_add_u64 v[134:135], v[140:141], 1, v[134:135]
	s_movk_i32 s12, 0x4000
	v_cvt_pk_bf16_f32 v124, v124, v125
	v_cvt_pk_bf16_f32 v125, v126, v127
	v_cvt_pk_bf16_f32 v126, v120, v121
	v_cvt_pk_bf16_f32 v127, v122, v123
	global_store_dwordx4 v[134:135], v[124:127], off
	v_cvt_pk_bf16_f32 v112, v112, v113
	v_cvt_pk_bf16_f32 v113, v114, v115
	v_cvt_pk_bf16_f32 v114, v104, v105
	v_cvt_pk_bf16_f32 v115, v106, v107
	global_store_dwordx4 v[134:135], v[112:115], off offset:256
	v_cvt_pk_bf16_f32 v104, v116, v117
	v_cvt_pk_bf16_f32 v105, v118, v119
	v_cvt_pk_bf16_f32 v106, v108, v109
	v_add_co_u32_e32 v108, vcc, s12, v134
	s_mov_b32 s12, 0x8000
	s_nop 0
	v_addc_co_u32_e32 v109, vcc, 0, v135, vcc
	v_cvt_pk_bf16_f32 v107, v110, v111
	global_store_dwordx4 v[108:109], v[104:107], off
	v_cvt_pk_bf16_f32 v96, v96, v97
	v_cvt_pk_bf16_f32 v97, v98, v99
	v_cvt_pk_bf16_f32 v98, v88, v89
	v_cvt_pk_bf16_f32 v99, v90, v91
	global_store_dwordx4 v[108:109], v[96:99], off offset:256
	v_cvt_pk_bf16_f32 v88, v100, v101
	v_cvt_pk_bf16_f32 v89, v102, v103
	v_cvt_pk_bf16_f32 v90, v92, v93
	v_add_co_u32_e32 v92, vcc, s12, v134
	s_mov_b32 s12, 0xc000
	s_nop 0
	v_addc_co_u32_e32 v93, vcc, 0, v135, vcc
	v_cvt_pk_bf16_f32 v91, v94, v95
	global_store_dwordx4 v[92:93], v[88:91], off
	v_cvt_pk_bf16_f32 v80, v80, v81
	v_cvt_pk_bf16_f32 v81, v82, v83
	v_cvt_pk_bf16_f32 v82, v72, v73
	v_cvt_pk_bf16_f32 v83, v74, v75
	global_store_dwordx4 v[92:93], v[80:83], off offset:256
	s_cmp_lg_u64 s[18:19], 0
	s_cbranch_scc0 .Llate_align_6
	s_barrier
.Llate_align_6:
	v_cvt_pk_bf16_f32 v72, v84, v85
	v_cvt_pk_bf16_f32 v73, v86, v87
	v_cvt_pk_bf16_f32 v74, v76, v77
	v_add_co_u32_e32 v76, vcc, s12, v134
	s_mov_b32 s12, 0x20000
	s_nop 0
	v_addc_co_u32_e32 v77, vcc, 0, v135, vcc
	v_cvt_pk_bf16_f32 v75, v78, v79
	global_store_dwordx4 v[76:77], v[72:75], off
	v_cvt_pk_bf16_f32 v68, v68, v69
	v_cvt_pk_bf16_f32 v69, v70, v71
	v_cvt_pk_bf16_f32 v70, v64, v65
	v_cvt_pk_bf16_f32 v71, v66, v67
	global_store_dwordx4 v[76:77], v[68:71], off offset:256
	v_cvt_pk_bf16_f32 v60, v60, v61
	v_cvt_pk_bf16_f32 v61, v62, v63
	v_cvt_pk_bf16_f32 v62, v56, v57
	v_add_co_u32_e32 v56, vcc, s12, v134
	s_mov_b32 s12, 0x24000
	s_nop 0
	v_addc_co_u32_e32 v57, vcc, 0, v135, vcc
	v_cvt_pk_bf16_f32 v63, v58, v59
	global_store_dwordx4 v[56:57], v[60:63], off
	v_cvt_pk_bf16_f32 v48, v48, v49
	v_cvt_pk_bf16_f32 v49, v50, v51
	v_cvt_pk_bf16_f32 v50, v40, v41
	v_cvt_pk_bf16_f32 v51, v42, v43
	global_store_dwordx4 v[56:57], v[48:51], off offset:256
	v_cvt_pk_bf16_f32 v40, v52, v53
	v_cvt_pk_bf16_f32 v41, v54, v55
	v_cvt_pk_bf16_f32 v42, v44, v45
	v_add_co_u32_e32 v44, vcc, s12, v134
	s_mov_b32 s12, 0x28000
	s_nop 0
	v_addc_co_u32_e32 v45, vcc, 0, v135, vcc
	v_cvt_pk_bf16_f32 v43, v46, v47
	global_store_dwordx4 v[44:45], v[40:43], off
	v_cvt_pk_bf16_f32 v32, v32, v33
	v_cvt_pk_bf16_f32 v33, v34, v35
	v_cvt_pk_bf16_f32 v34, v24, v25
	v_cvt_pk_bf16_f32 v35, v26, v27
	global_store_dwordx4 v[44:45], v[32:35], off offset:256
	v_cvt_pk_bf16_f32 v24, v36, v37
	v_cvt_pk_bf16_f32 v25, v38, v39
	v_cvt_pk_bf16_f32 v26, v28, v29
	v_add_co_u32_e32 v28, vcc, s12, v134
	s_mov_b32 s12, 0x2c000
	s_nop 0
	v_addc_co_u32_e32 v29, vcc, 0, v135, vcc
	v_cvt_pk_bf16_f32 v27, v30, v31
	global_store_dwordx4 v[28:29], v[24:27], off
	v_cvt_pk_bf16_f32 v16, v16, v17
	v_cvt_pk_bf16_f32 v17, v18, v19
	v_cvt_pk_bf16_f32 v18, v8, v9
	v_cvt_pk_bf16_f32 v19, v10, v11
	global_store_dwordx4 v[28:29], v[16:19], off offset:256
	v_cvt_pk_bf16_f32 v8, v20, v21
	v_cvt_pk_bf16_f32 v9, v22, v23
	v_cvt_pk_bf16_f32 v10, v12, v13
	v_add_co_u32_e32 v12, vcc, s12, v134
	s_mov_b64 s[30:31], -1
	s_nop 0
	v_addc_co_u32_e32 v13, vcc, 0, v135, vcc
	s_andn2_b64 vcc, exec, s[42:43]
	v_cvt_pk_bf16_f32 v11, v14, v15
	global_store_dwordx4 v[12:13], v[8:11], off
	v_cvt_pk_bf16_f32 v4, v4, v5
	v_cvt_pk_bf16_f32 v5, v6, v7
	v_cvt_pk_bf16_f32 v6, v0, v1
	v_cvt_pk_bf16_f32 v7, v2, v3
	global_store_dwordx4 v[12:13], v[4:7], off offset:256
	s_cbranch_vccnz .LBB0_671
	s_andn2_b64 vcc, exec, s[16:17]
	s_cbranch_vccnz .LBB0_670
	s_barrier
	s_branch .LBB0_670

; __device__ __forceinline__ unsigned cvt_pk_bf16(float lo, float hi) { unsigned r; asm volatile("v_cvt_pk_bf16_f32 %0, %1, %2" : "=v"(r) : "v"(lo), "v"(hi)); return r; }
;     __device__ __forceinline__ void operator()(const Acc& acc, const Unit& u, int wr, int wc, int fr, int fq) const {
;     ...
;         const int h = u.pm >> 6, nchunk = u.pm & 63, et = u.pn;
; #pragma unroll
;         for (int ai = 0; ai < 2; ++ai) {
;             float S1[4], S2[4];
; #pragma unroll
;             for (int m = 0; m < 4; ++m) {
;                 const int row_in = ai * HALF + wr * 64 + m * 16 + fr;
;                 float s1 = 0.f, s2 = 0.f;
; #pragma unroll
;                 for (int bj = 0; bj < 2; ++bj) {
;                     const f32x4 v0 = acc[ai][bj][m][0], v1 = acc[ai][bj][m][1];
; #pragma unroll
;                     for (int j = 0; j < 4; ++j) { s1 += v0[j] + v1[j]; s2 += v0[j] * v0[j] + v1[j] * v1[j]; }
;                     u32x4 w; w.x = cvt_pk_bf16(v0[0], v0[1]); w.y = cvt_pk_bf16(v0[2], v0[3]); w.z = cvt_pk_bf16(v1[0], v1[1]); w.w = cvt_pk_bf16(v1[2], v1[3]);
;                     *(u32x4*)(O + u.coff + (size_t)row_in * RV + bj * HALF + wc * 32 + 8 * fq) = w;
;                 }
;                 s1 += __shfl_xor(s1, 16); s1 += __shfl_xor(s1, 32); s2 += __shfl_xor(s2, 16); s2 += __shfl_xor(s2, 32);
;                 S1[m] = s1; S2[m] = s2;
.LBB0_811:
	v_mov_b32_e32 v138, v143
	v_mov_b32_e32 v139, v142
	s_ashr_i32 s34, s15, 6
	s_lshl_b32 s15, s15, 8
	v_add_u32_e32 v140, s5, v139
	v_lshlrev_b32_e32 v162, 3, v138
	v_cmp_eq_u32_e32 vcc, 0, v138
	v_cmp_eq_u32_e64 s[44:45], 1, v138
	v_cmp_eq_u32_e64 s[46:47], 2, v138
	v_lshlrev_b32_e32 v138, 4, v138
	s_and_b32 s15, s15, 0x3f00
	s_ashr_i32 s35, s34, 31
	s_lshl_b32 s50, s14, 2
	v_add3_u32 v138, v138, s15, v140
	s_ashr_i32 s51, s50, 31
	s_lshl_b64 s[34:35], s[34:35], 6
	v_pk_add_f32 v[168:169], v[124:125], v[120:121]
	s_lshl_b64 s[14:15], s[60:61], 1
	v_readlane_b32 s36, v246, 17
	v_ashrrev_i32_e32 v141, 31, v140
	v_add_f32_e32 v139, 0, v168
	v_readlane_b32 s37, v246, 18
	s_add_u32 s36, s36, s14
	v_lshlrev_b64 v[164:165], 13, v[140:141]
	v_add_f32_e32 v139, v169, v139
	v_pk_mul_f32 v[168:169], v[122:123], v[122:123]
	v_pk_mul_f32 v[170:171], v[120:121], v[120:121]
	s_addc_u32 s37, s37, s15
	v_ashrrev_i32_e32 v163, 31, v162
	v_pk_add_f32 v[166:167], v[126:127], v[122:123]
	v_pk_fma_f32 v[168:169], v[126:127], v[126:127], v[168:169]
	v_pk_fma_f32 v[170:171], v[124:125], v[124:125], v[170:171]
	v_cvt_pk_bf16_f32 v124, v124, v125
	v_cvt_pk_bf16_f32 v125, v126, v127
	v_cvt_pk_bf16_f32 v126, v120, v121
	v_lshl_add_u64 v[120:121], s[36:37], 0, v[164:165]
	s_mov_b32 s21, s61
	v_add_f32_e32 v139, v166, v139
	v_cvt_pk_bf16_f32 v127, v122, v123
	v_lshl_add_u64 v[122:123], v[120:121], 0, s[20:21]
	v_lshlrev_b64 v[120:121], 1, v[162:163]
	v_add_f32_e32 v139, v167, v139
	v_lshl_add_u64 v[166:167], v[122:123], 0, v[120:121]
	global_store_dwordx4 v[166:167], v[124:127], off
	v_pk_add_f32 v[122:123], v[92:93], v[88:89]
	v_cvt_pk_bf16_f32 v162, v92, v93
	v_cvt_pk_bf16_f32 v163, v94, v95
	v_cvt_pk_bf16_f32 v164, v88, v89
	v_cvt_pk_bf16_f32 v165, v90, v91
	s_nop 0
	v_pk_mul_f32 v[124:125], v[92:93], v[92:93]
	v_add_f32_e32 v122, v139, v122
	v_pk_fma_f32 v[124:125], v[88:89], v[88:89], v[124:125]
	v_and_b32_e32 v89, 64, v183
	v_xor_b32_e32 v88, 16, v183
	v_add_u32_e32 v89, 64, v89
	v_cmp_lt_i32_e64 s[48:49], v88, v89
	v_add_f32_e32 v122, v123, v122
	v_add_f32_e32 v123, v170, v171
	v_cndmask_b32_e64 v88, v183, v88, s[48:49]
	v_add_f32_e32 v123, v168, v123
	v_lshlrev_b32_e32 v93, 2, v88
	v_xor_b32_e32 v88, 32, v183
	v_add_f32_e32 v123, v169, v123
	v_cmp_lt_i32_e64 s[48:49], v88, v89
	v_add_f32_e32 v126, v123, v124
	v_pk_add_f32 v[124:125], v[124:125], v[126:127] op_sel_hi:[1,0]
	v_cndmask_b32_e64 v88, v183, v88, s[48:49]
	v_lshlrev_b32_e32 v92, 2, v88
	v_add_u32_e32 v88, 16, v140
	v_mov_b32_e32 v126, v94
	v_mov_b32_e32 v127, v90
	v_mul_f32_e32 v124, v94, v94
	global_store_dwordx4 v[166:167], v[162:165], off offset:256
	v_ashrrev_i32_e32 v89, 31, v88
	v_pk_fma_f32 v[126:127], v[126:127], v[126:127], v[124:125] op_sel_hi:[1,1,0]
	v_pk_add_f32 v[164:165], v[116:117], v[112:113]
	v_lshlrev_b64 v[88:89], 13, v[88:89]
	v_add_f32_e32 v124, 0, v164
	v_pk_add_f32 v[162:163], v[118:119], v[114:115]
	v_add_f32_e32 v124, v165, v124
	v_lshl_add_u64 v[88:89], s[36:37], 0, v[88:89]
	v_add_f32_e32 v124, v162, v124
	v_lshl_add_u64 v[88:89], v[88:89], 0, s[20:21]
	v_pk_mul_f32 v[166:167], v[112:113], v[112:113]
	v_add_f32_e32 v124, v163, v124
	v_lshl_add_u64 v[162:163], v[88:89], 0, v[120:121]
	v_pk_add_f32 v[88:89], v[84:85], v[80:81]
	v_pk_mul_f32 v[164:165], v[114:115], v[114:115]
	v_pk_fma_f32 v[166:167], v[116:117], v[116:117], v[166:167]
	v_add_f32_e32 v88, v124, v88
	v_pk_fma_f32 v[164:165], v[118:119], v[118:119], v[164:165]
	v_add_f32_e32 v88, v89, v88
	v_add_f32_e32 v89, v166, v167
	v_cvt_pk_bf16_f32 v116, v116, v117
	v_cvt_pk_bf16_f32 v117, v118, v119
	v_cvt_pk_bf16_f32 v118, v112, v113
	v_pk_mul_f32 v[112:113], v[84:85], v[84:85]
	v_add_f32_e32 v89, v164, v89
	v_pk_fma_f32 v[112:113], v[80:81], v[80:81], v[112:113]
	v_add_f32_e32 v89, v165, v89
	v_cvt_pk_bf16_f32 v119, v114, v115
	v_add_f32_e32 v114, v89, v112
	global_store_dwordx4 v[162:163], v[116:119], off
	v_mul_f32_e32 v89, v83, v83
	v_mul_f32_e32 v123, v91, v91
	v_pk_add_f32 v[116:117], v[112:113], v[114:115] op_sel_hi:[1,0]
	v_mov_b32_e32 v112, v86
	v_mov_b32_e32 v113, v82
	v_mul_f32_e32 v114, v86, v86
	v_pk_fma_f32 v[118:119], v[112:113], v[112:113], v[114:115] op_sel_hi:[1,1,0]
	v_cvt_pk_bf16_f32 v112, v84, v85
	v_cvt_pk_bf16_f32 v113, v86, v87
	v_cvt_pk_bf16_f32 v114, v80, v81
	v_cvt_pk_bf16_f32 v115, v82, v83
	global_store_dwordx4 v[162:163], v[112:115], off offset:256
	v_pk_add_f32 v[84:85], v[110:111], v[106:107]
	v_add_u32_e32 v80, 32, v140
	v_pk_add_f32 v[112:113], v[108:109], v[104:105]
	v_pk_mul_f32 v[114:115], v[104:105], v[104:105]
	v_add_f32_e32 v112, 0, v112
	v_add_f32_e32 v116, v113, v112
	v_add_f32_e32 v84, v84, v116
	v_add_f32_e32 v116, v85, v84
	v_pk_add_f32 v[84:85], v[76:77], v[72:73]
	v_ashrrev_i32_e32 v81, 31, v80
	v_pk_mul_f32 v[112:113], v[106:107], v[106:107]
	v_pk_fma_f32 v[114:115], v[108:109], v[108:109], v[114:115]
	v_add_f32_e32 v84, v116, v84
	v_lshlrev_b64 v[80:81], 13, v[80:81]
	v_pk_fma_f32 v[112:113], v[110:111], v[110:111], v[112:113]
	v_add_f32_e32 v84, v85, v84
	v_add_f32_e32 v85, v114, v115
	v_cvt_pk_bf16_f32 v108, v108, v109
	v_cvt_pk_bf16_f32 v109, v110, v111
	v_cvt_pk_bf16_f32 v110, v104, v105
	v_lshl_add_u64 v[80:81], s[36:37], 0, v[80:81]
	v_pk_mul_f32 v[104:105], v[76:77], v[76:77]
	v_add_f32_e32 v85, v112, v85
	v_lshl_add_u64 v[80:81], v[80:81], 0, s[20:21]
	v_pk_fma_f32 v[104:105], v[72:73], v[72:73], v[104:105]
	v_add_f32_e32 v85, v113, v85
	v_cvt_pk_bf16_f32 v111, v106, v107
	v_lshl_add_u64 v[80:81], v[80:81], 0, v[120:121]
	v_add_f32_e32 v106, v85, v104
	global_store_dwordx4 v[80:81], v[108:111], off
	v_mov_b32_e32 v118, v87
	v_mov_b32_e32 v116, v83
	v_pk_add_f32 v[108:109], v[104:105], v[106:107] op_sel_hi:[1,0]
	v_mov_b32_e32 v104, v78
	v_mov_b32_e32 v105, v74
	v_mul_f32_e32 v106, v78, v78
	v_pk_fma_f32 v[110:111], v[104:105], v[104:105], v[106:107] op_sel_hi:[1,1,0]
	v_cvt_pk_bf16_f32 v104, v76, v77
	v_cvt_pk_bf16_f32 v105, v78, v79
	v_cvt_pk_bf16_f32 v106, v72, v73
	v_cvt_pk_bf16_f32 v107, v74, v75
	global_store_dwordx4 v[80:81], v[104:107], off offset:256
	s_cmp_lg_u64 s[18:19], 0
	s_cbranch_scc0 .Llate_align_7
	s_barrier
; __device__ __forceinline__ unsigned cvt_pk_bf16(float lo, float hi) { unsigned r; asm volatile("v_cvt_pk_bf16_f32 %0, %1, %2" : "=v"(r) : "v"(lo), "v"(hi)); return r; }
;     __device__ __forceinline__ void operator()(const Acc& acc, const Unit& u, int wr, int wc, int fr, int fq) const {
;     ...
;             for (int m = 0; m < 4; ++m) {
;                 const int row_in = ai * HALF + wr * 64 + m * 16 + fr;
;                 float s1 = 0.f, s2 = 0.f;
; #pragma unroll
;                 for (int bj = 0; bj < 2; ++bj) {
;                     const f32x4 v0 = acc[ai][bj][m][0], v1 = acc[ai][bj][m][1];
; #pragma unroll
;                     for (int j = 0; j < 4; ++j) { s1 += v0[j] + v1[j]; s2 += v0[j] * v0[j] + v1[j] * v1[j]; }
;                     u32x4 w; w.x = cvt_pk_bf16(v0[0], v0[1]); w.y = cvt_pk_bf16(v0[2], v0[3]); w.z = cvt_pk_bf16(v1[0], v1[1]); w.w = cvt_pk_bf16(v1[2], v1[3]);
;                     *(u32x4*)(O + u.coff + (size_t)row_in * RV + bj * HALF + wc * 32 + 8 * fq) = w;
;                 }
;                 s1 += __shfl_xor(s1, 16); s1 += __shfl_xor(s1, 32); s2 += __shfl_xor(s2, 16); s2 += __shfl_xor(s2, 32);
;                 S1[m] = s1; S2[m] = s2;
;             }
;             const float t1 = fq == 0 ? S1[0] : fq == 1 ? S1[1] : fq == 2 ? S1[2] : S1[3], t2 = fq == 0 ? S2[0] : fq == 1 ? S2[1] : fq == 2 ? S2[2] : S2[3];
;             const int row_st = ai * HALF + wr * 64 + fq * 16 + fr;
;             stats[((size_t)(nchunk * 256 + row_st) * 8 + h) * 8 + et * 4 + wc] = (f32x2){t1, t2};
;         }
.Llate_align_7:
	v_pk_add_f32 v[80:81], v[100:101], v[96:97]
	v_pk_add_f32 v[76:77], v[102:103], v[98:99]
	v_add_f32_e32 v80, 0, v80
	v_add_f32_e32 v106, v81, v80
	v_add_f32_e32 v76, v76, v106
	v_pk_mul_f32 v[104:105], v[96:97], v[96:97]
	v_add_f32_e32 v106, v77, v76
	v_pk_add_f32 v[76:77], v[68:69], v[64:65]
	v_pk_mul_f32 v[80:81], v[98:99], v[98:99]
	v_pk_fma_f32 v[104:105], v[100:101], v[100:101], v[104:105]
	v_add_f32_e32 v76, v106, v76
	v_add_u32_e32 v72, 48, v140
	v_pk_fma_f32 v[80:81], v[102:103], v[102:103], v[80:81]
	v_add_f32_e32 v76, v77, v76
	v_add_f32_e32 v77, v104, v105
	v_ashrrev_i32_e32 v73, 31, v72
	v_cvt_pk_bf16_f32 v100, v100, v101
	v_cvt_pk_bf16_f32 v101, v102, v103
	v_cvt_pk_bf16_f32 v102, v96, v97
	v_pk_mul_f32 v[96:97], v[68:69], v[68:69]
	v_add_f32_e32 v77, v80, v77
	v_lshlrev_b64 v[72:73], 13, v[72:73]
	v_pk_fma_f32 v[96:97], v[64:65], v[64:65], v[96:97]
	v_add_f32_e32 v77, v81, v77
	v_lshl_add_u64 v[72:73], s[36:37], 0, v[72:73]
	v_add_f32_e32 v80, v77, v96
	v_lshl_add_u64 v[72:73], v[72:73], 0, s[20:21]
	v_pk_add_f32 v[80:81], v[96:97], v[80:81] op_sel_hi:[1,0]
	v_lshl_add_u64 v[72:73], v[72:73], 0, v[120:121]
	v_mov_b32_e32 v96, v70
	v_mov_b32_e32 v97, v66
	v_mul_f32_e32 v80, v70, v70
	v_pk_add_f32 v[82:83], v[86:87], v[82:83]
	v_pk_mul_f32 v[86:87], v[86:87], v[86:87]
	v_cvt_pk_bf16_f32 v103, v98, v99
	global_store_dwordx4 v[72:73], v[100:103], off
	v_mov_b32_e32 v83, v87
	v_pk_add_f32 v[82:83], v[82:83], v[88:89]
	v_pk_fma_f32 v[100:101], v[96:97], v[96:97], v[80:81] op_sel_hi:[1,1,0]
	v_cvt_pk_bf16_f32 v96, v68, v69
	v_cvt_pk_bf16_f32 v97, v70, v71
	v_cvt_pk_bf16_f32 v98, v64, v65
	v_cvt_pk_bf16_f32 v99, v66, v67
	global_store_dwordx4 v[72:73], v[96:99], off offset:256
	v_pk_add_f32 v[68:69], v[94:95], v[90:91]
	v_pk_mul_f32 v[72:73], v[94:95], v[94:95]
	v_mul_f32_e32 v85, v75, v75
	v_mov_b32_e32 v69, v73
	v_pk_add_f32 v[72:73], v[118:119], v[116:117]
	v_mov_b32_e32 v110, v79
	v_pk_add_f32 v[72:73], v[82:83], v[72:73]
	ds_bpermute_b32 v82, v93, v72
	ds_bpermute_b32 v83, v93, v73
	v_mov_b32_e32 v108, v75
	v_pk_add_f32 v[74:75], v[78:79], v[74:75]
	v_pk_mul_f32 v[78:79], v[78:79], v[78:79]
	v_mul_f32_e32 v77, v67, v67
	s_waitcnt lgkmcnt(0)
	v_pk_add_f32 v[72:73], v[72:73], v[82:83]
	ds_bpermute_b32 v82, v92, v72
	ds_bpermute_b32 v83, v92, v73
	v_mov_b32_e32 v75, v79
	v_pk_add_f32 v[74:75], v[74:75], v[84:85]
	v_mov_b32_e32 v100, v71
	v_mov_b32_e32 v80, v67
	s_waitcnt lgkmcnt(0)
	v_pk_add_f32 v[72:73], v[72:73], v[82:83]
	v_pk_add_f32 v[82:83], v[110:111], v[108:109]
	v_pk_add_f32 v[66:67], v[70:71], v[66:67]
	v_pk_add_f32 v[74:75], v[74:75], v[82:83]
	ds_bpermute_b32 v78, v93, v74
	ds_bpermute_b32 v79, v93, v75
	v_pk_mul_f32 v[70:71], v[70:71], v[70:71]
	v_mov_b32_e32 v126, v95
	v_mov_b32_e32 v67, v71
	v_pk_add_f32 v[66:67], v[66:67], v[76:77]
	s_waitcnt lgkmcnt(0)
	v_pk_add_f32 v[74:75], v[74:75], v[78:79]
	ds_bpermute_b32 v78, v92, v74
	ds_bpermute_b32 v79, v92, v75
	v_mov_b32_e32 v124, v91
	v_pk_add_f32 v[64:65], v[126:127], v[124:125]
	v_pk_add_f32 v[68:69], v[68:69], v[122:123]
	v_ashrrev_i32_e32 v139, 31, v138
	s_waitcnt lgkmcnt(0)
	v_pk_add_f32 v[74:75], v[74:75], v[78:79]
	v_pk_add_f32 v[78:79], v[100:101], v[80:81]
	v_pk_add_f32 v[64:65], v[68:69], v[64:65]
	v_pk_add_f32 v[66:67], v[66:67], v[78:79]
	ds_bpermute_b32 v70, v93, v66
	ds_bpermute_b32 v71, v93, v67
	ds_bpermute_b32 v68, v93, v64
	ds_bpermute_b32 v69, v93, v65
	v_readlane_b32 s14, v248, 11
	v_readlane_b32 s15, v248, 12
	s_waitcnt lgkmcnt(0)
	v_pk_add_f32 v[66:67], v[66:67], v[70:71]
	ds_bpermute_b32 v70, v92, v66
	ds_bpermute_b32 v71, v92, v67
	v_pk_add_f32 v[64:65], v[64:65], v[68:69]
	ds_bpermute_b32 v68, v92, v64
	ds_bpermute_b32 v69, v92, v65
	s_lshl_b64 s[48:49], s[50:51], 3
	s_waitcnt lgkmcnt(0)
	v_pk_add_f32 v[66:67], v[66:67], v[70:71]
	s_mov_b32 s25, s61
	v_cndmask_b32_e64 v67, v67, v75, s[46:47]
	v_cndmask_b32_e64 v66, v66, v74, s[46:47]
	v_pk_add_f32 v[64:65], v[64:65], v[68:69]
	v_cndmask_b32_e64 v66, v66, v72, s[44:45]
	v_cndmask_b32_e64 v67, v67, v73, s[44:45]
	v_cndmask_b32_e32 v65, v67, v65, vcc
	v_cndmask_b32_e32 v64, v66, v64, vcc
	v_lshlrev_b64 v[66:67], 9, v[138:139]
	v_lshl_add_u64 v[66:67], s[14:15], 0, v[66:67]
	v_lshl_add_u64 v[66:67], v[66:67], 0, s[34:35]
	v_lshl_add_u64 v[66:67], v[66:67], 0, s[48:49]
	v_lshl_add_u64 v[66:67], v[66:67], 0, s[24:25]
	global_store_dwordx2 v[66:67], v[64:65], off
	v_add_u32_e32 v64, 0x80, v140
	v_pk_add_f32 v[68:69], v[60:61], v[56:57]
	v_ashrrev_i32_e32 v65, 31, v64
	v_add_f32_e32 v68, 0, v68
	v_lshlrev_b64 v[64:65], 13, v[64:65]
	v_add_f32_e32 v72, v69, v68
	v_pk_mul_f32 v[68:69], v[58:59], v[58:59]
	v_pk_mul_f32 v[70:71], v[56:57], v[56:57]
	v_pk_add_f32 v[66:67], v[62:63], v[58:59]
	v_pk_fma_f32 v[68:69], v[62:63], v[62:63], v[68:69]
	v_pk_fma_f32 v[70:71], v[60:61], v[60:61], v[70:71]
	v_cvt_pk_bf16_f32 v60, v60, v61
	v_cvt_pk_bf16_f32 v61, v62, v63
	v_cvt_pk_bf16_f32 v62, v56, v57
	v_lshl_add_u64 v[56:57], s[36:37], 0, v[64:65]
	v_add_f32_e32 v66, v66, v72
	v_lshl_add_u64 v[56:57], v[56:57], 0, s[20:21]
	v_add_f32_e32 v72, v67, v66
	v_lshl_add_u64 v[66:67], v[56:57], 0, v[120:121]
	v_pk_add_f32 v[56:57], v[28:29], v[24:25]
	v_cvt_pk_bf16_f32 v63, v58, v59
	v_pk_mul_f32 v[58:59], v[28:29], v[28:29]
	v_add_f32_e32 v56, v72, v56
	v_add_f32_e32 v56, v57, v56
	v_add_f32_e32 v57, v70, v71
	v_add_f32_e32 v57, v68, v57
	v_pk_fma_f32 v[58:59], v[24:25], v[24:25], v[58:59]
	v_add_f32_e32 v57, v69, v57
	global_store_dwordx4 v[66:67], v[60:63], off
	s_nop 1
	v_add_f32_e32 v60, v57, v58
	v_pk_add_f32 v[58:59], v[58:59], v[60:61] op_sel_hi:[1,0]
	v_cvt_pk_bf16_f32 v62, v28, v29
; __device__ __forceinline__ unsigned cvt_pk_bf16(float lo, float hi) { unsigned r; asm volatile("v_cvt_pk_bf16_f32 %0, %1, %2" : "=v"(r) : "v"(lo), "v"(hi)); return r; }
;     __device__ __forceinline__ void operator()(const Acc& acc, const Unit& u, int wr, int wc, int fr, int fq) const {
;     ...
;             for (int m = 0; m < 4; ++m) {
;                 const int row_in = ai * HALF + wr * 64 + m * 16 + fr;
;                 float s1 = 0.f, s2 = 0.f;
; #pragma unroll
;                 for (int bj = 0; bj < 2; ++bj) {
;                     const f32x4 v0 = acc[ai][bj][m][0], v1 = acc[ai][bj][m][1];
; #pragma unroll
;                     for (int j = 0; j < 4; ++j) { s1 += v0[j] + v1[j]; s2 += v0[j] * v0[j] + v1[j] * v1[j]; }
;                     u32x4 w; w.x = cvt_pk_bf16(v0[0], v0[1]); w.y = cvt_pk_bf16(v0[2], v0[3]); w.z = cvt_pk_bf16(v1[0], v1[1]); w.w = cvt_pk_bf16(v1[2], v1[3]);
;                     *(u32x4*)(O + u.coff + (size_t)row_in * RV + bj * HALF + wc * 32 + 8 * fq) = w;
;                 }
;                 s1 += __shfl_xor(s1, 16); s1 += __shfl_xor(s1, 32); s2 += __shfl_xor(s2, 16); s2 += __shfl_xor(s2, 32);
;                 S1[m] = s1; S2[m] = s2;
	v_cvt_pk_bf16_f32 v63, v30, v31
	v_cvt_pk_bf16_f32 v64, v24, v25
	v_add_u32_e32 v24, 0x90, v140
	v_mov_b32_e32 v60, v30
	v_mov_b32_e32 v61, v26
	v_mul_f32_e32 v58, v30, v30
	v_cvt_pk_bf16_f32 v65, v26, v27
	global_store_dwordx4 v[66:67], v[62:65], off offset:256
	v_ashrrev_i32_e32 v25, 31, v24
	v_pk_fma_f32 v[60:61], v[60:61], v[60:61], v[58:59] op_sel_hi:[1,1,0]
	v_pk_add_f32 v[62:63], v[52:53], v[48:49]
	v_lshlrev_b64 v[24:25], 13, v[24:25]
	v_add_f32_e32 v58, 0, v62
	v_pk_add_f32 v[28:29], v[54:55], v[50:51]
	v_add_f32_e32 v58, v63, v58
	v_lshl_add_u64 v[24:25], s[36:37], 0, v[24:25]
	v_add_f32_e32 v28, v28, v58
	v_lshl_add_u64 v[24:25], v[24:25], 0, s[20:21]
	v_pk_mul_f32 v[64:65], v[48:49], v[48:49]
	v_add_f32_e32 v58, v29, v28
	v_lshl_add_u64 v[28:29], v[24:25], 0, v[120:121]
	v_pk_add_f32 v[24:25], v[20:21], v[16:17]
	v_pk_mul_f32 v[62:63], v[50:51], v[50:51]
	v_pk_fma_f32 v[64:65], v[52:53], v[52:53], v[64:65]
	v_add_f32_e32 v24, v58, v24
	v_pk_fma_f32 v[62:63], v[54:55], v[54:55], v[62:63]
	v_add_f32_e32 v24, v25, v24
	v_add_f32_e32 v25, v64, v65
	v_cvt_pk_bf16_f32 v52, v52, v53
	v_cvt_pk_bf16_f32 v53, v54, v55
	v_cvt_pk_bf16_f32 v54, v48, v49
	v_pk_mul_f32 v[48:49], v[20:21], v[20:21]
	v_add_f32_e32 v25, v62, v25
	v_pk_fma_f32 v[48:49], v[16:17], v[16:17], v[48:49]
	v_add_f32_e32 v25, v63, v25
	v_cvt_pk_bf16_f32 v55, v50, v51
	v_add_f32_e32 v50, v25, v48
	global_store_dwordx4 v[28:29], v[52:55], off
	v_mul_f32_e32 v25, v19, v19
	v_mul_f32_e32 v57, v27, v27
	v_pk_add_f32 v[52:53], v[48:49], v[50:51] op_sel_hi:[1,0]
	v_mov_b32_e32 v48, v22
	v_mov_b32_e32 v49, v18
	v_mul_f32_e32 v50, v22, v22
	v_pk_fma_f32 v[54:55], v[48:49], v[48:49], v[50:51] op_sel_hi:[1,1,0]
	v_cvt_pk_bf16_f32 v48, v20, v21
	v_cvt_pk_bf16_f32 v49, v22, v23
	v_cvt_pk_bf16_f32 v50, v16, v17
	v_cvt_pk_bf16_f32 v51, v18, v19
	global_store_dwordx4 v[28:29], v[48:51], off offset:256
	v_pk_add_f32 v[28:29], v[44:45], v[40:41]
	v_pk_add_f32 v[20:21], v[46:47], v[42:43]
	v_add_f32_e32 v28, 0, v28
	v_add_f32_e32 v50, v29, v28
	v_add_f32_e32 v20, v20, v50
	v_pk_mul_f32 v[48:49], v[40:41], v[40:41]
	v_add_f32_e32 v50, v21, v20
	v_pk_add_f32 v[20:21], v[12:13], v[8:9]
	v_pk_mul_f32 v[28:29], v[42:43], v[42:43]
	v_pk_fma_f32 v[48:49], v[44:45], v[44:45], v[48:49]
	v_add_f32_e32 v20, v50, v20
	v_add_u32_e32 v16, 0xa0, v140
	v_pk_fma_f32 v[28:29], v[46:47], v[46:47], v[28:29]
	v_add_f32_e32 v20, v21, v20
	v_add_f32_e32 v21, v48, v49
	v_ashrrev_i32_e32 v17, 31, v16
	v_cvt_pk_bf16_f32 v44, v44, v45
	v_cvt_pk_bf16_f32 v45, v46, v47
	v_cvt_pk_bf16_f32 v46, v40, v41
	v_pk_mul_f32 v[40:41], v[12:13], v[12:13]
	v_add_f32_e32 v21, v28, v21
	v_lshlrev_b64 v[16:17], 13, v[16:17]
	v_pk_fma_f32 v[40:41], v[8:9], v[8:9], v[40:41]
	v_add_f32_e32 v21, v29, v21
	v_lshl_add_u64 v[16:17], s[36:37], 0, v[16:17]
	v_add_f32_e32 v28, v21, v40
	v_lshl_add_u64 v[16:17], v[16:17], 0, s[20:21]
	v_pk_add_f32 v[28:29], v[40:41], v[28:29] op_sel_hi:[1,0]
	v_lshl_add_u64 v[16:17], v[16:17], 0, v[120:121]
	v_mov_b32_e32 v40, v14
	v_mov_b32_e32 v41, v10
	v_mul_f32_e32 v28, v14, v14
	v_cvt_pk_bf16_f32 v47, v42, v43
	global_store_dwordx4 v[16:17], v[44:47], off
	v_mov_b32_e32 v54, v23
	v_mov_b32_e32 v52, v19
	v_pk_fma_f32 v[44:45], v[40:41], v[40:41], v[28:29] op_sel_hi:[1,1,0]
	v_cvt_pk_bf16_f32 v40, v12, v13
	v_cvt_pk_bf16_f32 v41, v14, v15
	v_cvt_pk_bf16_f32 v42, v8, v9
	v_cvt_pk_bf16_f32 v43, v10, v11
	global_store_dwordx4 v[16:17], v[40:43], off offset:256
	v_pk_add_f32 v[16:17], v[36:37], v[32:33]
	v_pk_add_f32 v[12:13], v[38:39], v[34:35]
	v_add_f32_e32 v16, 0, v16
	v_add_f32_e32 v28, v17, v16
	v_add_f32_e32 v12, v12, v28
	v_pk_mul_f32 v[40:41], v[32:33], v[32:33]
	v_add_f32_e32 v28, v13, v12
	v_pk_add_f32 v[12:13], v[4:5], v[0:1]
	v_pk_mul_f32 v[16:17], v[34:35], v[34:35]
	v_pk_fma_f32 v[40:41], v[36:37], v[36:37], v[40:41]
	v_add_f32_e32 v12, v28, v12
	v_add_u32_e32 v8, 0xb0, v140
	v_pk_fma_f32 v[16:17], v[38:39], v[38:39], v[16:17]
	v_add_f32_e32 v12, v13, v12
	v_add_f32_e32 v13, v40, v41
	v_ashrrev_i32_e32 v9, 31, v8
	v_cvt_pk_bf16_f32 v36, v36, v37
	v_cvt_pk_bf16_f32 v37, v38, v39
	v_cvt_pk_bf16_f32 v38, v32, v33
	v_pk_mul_f32 v[32:33], v[4:5], v[4:5]
	v_add_f32_e32 v13, v16, v13
	v_lshlrev_b64 v[8:9], 13, v[8:9]
	v_pk_fma_f32 v[32:33], v[0:1], v[0:1], v[32:33]
	v_add_f32_e32 v13, v17, v13
	v_lshl_add_u64 v[8:9], s[36:37], 0, v[8:9]
	v_add_f32_e32 v16, v13, v32
	v_lshl_add_u64 v[8:9], v[8:9], 0, s[20:21]
	v_pk_add_f32 v[16:17], v[32:33], v[16:17] op_sel_hi:[1,0]
	v_lshl_add_u64 v[8:9], v[8:9], 0, v[120:121]
	v_mov_b32_e32 v32, v6
	v_mov_b32_e32 v33, v2
	v_mul_f32_e32 v16, v6, v6
	v_pk_add_f32 v[18:19], v[22:23], v[18:19]
	v_pk_mul_f32 v[22:23], v[22:23], v[22:23]
	v_cvt_pk_bf16_f32 v39, v34, v35
	global_store_dwordx4 v[8:9], v[36:39], off
	v_mov_b32_e32 v19, v23
	v_pk_add_f32 v[18:19], v[18:19], v[24:25]
	v_pk_fma_f32 v[36:37], v[32:33], v[32:33], v[16:17] op_sel_hi:[1,1,0]
	v_cvt_pk_bf16_f32 v32, v4, v5
	v_cvt_pk_bf16_f32 v33, v6, v7
	v_cvt_pk_bf16_f32 v34, v0, v1
	v_cvt_pk_bf16_f32 v35, v2, v3
	global_store_dwordx4 v[8:9], v[32:35], off offset:256
	v_pk_add_f32 v[4:5], v[30:31], v[26:27]
	v_pk_mul_f32 v[8:9], v[30:31], v[30:31]
	v_mul_f32_e32 v21, v11, v11
	v_mov_b32_e32 v5, v9
	v_pk_add_f32 v[8:9], v[54:55], v[52:53]
	v_mov_b32_e32 v44, v15
	v_pk_add_f32 v[8:9], v[18:19], v[8:9]
	ds_bpermute_b32 v18, v93, v8
	ds_bpermute_b32 v19, v93, v9
	v_mov_b32_e32 v28, v11
	v_pk_add_f32 v[10:11], v[14:15], v[10:11]
	v_pk_mul_f32 v[14:15], v[14:15], v[14:15]
	v_mul_f32_e32 v13, v3, v3
	s_waitcnt lgkmcnt(0)
;     __device__ __forceinline__ void operator()(const Acc& acc, const Unit& u, int wr, int wc, int fr, int fq) const {
;     ...
;                 s1 += __shfl_xor(s1, 16); s1 += __shfl_xor(s1, 32); s2 += __shfl_xor(s2, 16); s2 += __shfl_xor(s2, 32);
;                 S1[m] = s1; S2[m] = s2;
;             }
;             const float t1 = fq == 0 ? S1[0] : fq == 1 ? S1[1] : fq == 2 ? S1[2] : S1[3], t2 = fq == 0 ? S2[0] : fq == 1 ? S2[1] : fq == 2 ? S2[2] : S2[3];
;             const int row_st = ai * HALF + wr * 64 + fq * 16 + fr;
;             stats[((size_t)(nchunk * 256 + row_st) * 8 + h) * 8 + et * 4 + wc] = (f32x2){t1, t2};
;         }
	v_pk_add_f32 v[8:9], v[8:9], v[18:19]
	ds_bpermute_b32 v18, v92, v8
	ds_bpermute_b32 v19, v92, v9
	v_mov_b32_e32 v11, v15
	v_pk_add_f32 v[10:11], v[10:11], v[20:21]
	v_mov_b32_e32 v36, v7
	v_mov_b32_e32 v16, v3
	s_waitcnt lgkmcnt(0)
	v_pk_add_f32 v[8:9], v[8:9], v[18:19]
	v_pk_add_f32 v[18:19], v[44:45], v[28:29]
	v_pk_add_f32 v[2:3], v[6:7], v[2:3]
	v_pk_add_f32 v[10:11], v[10:11], v[18:19]
	ds_bpermute_b32 v14, v93, v10
	ds_bpermute_b32 v15, v93, v11
	v_pk_mul_f32 v[6:7], v[6:7], v[6:7]
	v_mov_b32_e32 v60, v31
	v_mov_b32_e32 v3, v7
	v_pk_add_f32 v[2:3], v[2:3], v[12:13]
	s_waitcnt lgkmcnt(0)
	v_pk_add_f32 v[10:11], v[10:11], v[14:15]
	ds_bpermute_b32 v14, v92, v10
	ds_bpermute_b32 v15, v92, v11
	v_mov_b32_e32 v58, v27
	v_pk_add_f32 v[0:1], v[60:61], v[58:59]
	v_pk_add_f32 v[4:5], v[4:5], v[56:57]
	s_waitcnt lgkmcnt(0)
	v_pk_add_f32 v[10:11], v[10:11], v[14:15]
	v_pk_add_f32 v[14:15], v[36:37], v[16:17]
	v_pk_add_f32 v[0:1], v[4:5], v[0:1]
	v_pk_add_f32 v[2:3], v[2:3], v[14:15]
	ds_bpermute_b32 v6, v93, v2
	ds_bpermute_b32 v7, v93, v3
	ds_bpermute_b32 v4, v93, v0
	ds_bpermute_b32 v5, v93, v1
	s_waitcnt lgkmcnt(0)
	v_pk_add_f32 v[2:3], v[2:3], v[6:7]
	ds_bpermute_b32 v6, v92, v2
	ds_bpermute_b32 v7, v92, v3
	v_pk_add_f32 v[0:1], v[0:1], v[4:5]
	ds_bpermute_b32 v4, v92, v0
	ds_bpermute_b32 v5, v92, v1
	s_waitcnt lgkmcnt(0)
	v_pk_add_f32 v[2:3], v[2:3], v[6:7]
	s_nop 0
	v_cndmask_b32_e64 v2, v2, v10, s[46:47]
	v_cndmask_b32_e64 v3, v3, v11, s[46:47]
	v_pk_add_f32 v[0:1], v[0:1], v[4:5]
	v_cndmask_b32_e64 v2, v2, v8, s[44:45]
	v_cndmask_b32_e64 v3, v3, v9, s[44:45]
	v_cndmask_b32_e32 v0, v2, v0, vcc
	v_add_u32_e32 v2, 0x80, v138
	v_cndmask_b32_e32 v1, v3, v1, vcc
	v_ashrrev_i32_e32 v3, 31, v2
	v_lshlrev_b64 v[2:3], 9, v[2:3]
	v_lshl_add_u64 v[2:3], s[14:15], 0, v[2:3]
	v_lshl_add_u64 v[2:3], v[2:3], 0, s[34:35]
	v_lshl_add_u64 v[2:3], v[2:3], 0, s[48:49]
	v_lshl_add_u64 v[2:3], v[2:3], 0, s[24:25]
	s_mov_b64 s[34:35], -1
	s_andn2_b64 vcc, exec, s[42:43]
	global_store_dwordx2 v[2:3], v[0:1], off
	s_cbranch_vccnz .LBB0_800
	s_andn2_b64 vcc, exec, s[16:17]
	s_cbranch_vccnz .LBB0_799
	s_barrier
	s_branch .LBB0_799

; __device__ __forceinline__ unsigned cvt_pk_bf16(float lo, float hi) { unsigned r; asm volatile("v_cvt_pk_bf16_f32 %0, %1, %2" : "=v"(r) : "v"(lo), "v"(hi)); return r; }
; __device__ __forceinline__ float bf_lo(unsigned w) { return __uint_as_float(w << 16); }
; __device__ __forceinline__ float bf_hi(unsigned w) { return __uint_as_float(w & 0xffff0000u); }
;     __device__ __forceinline__ void operator()(const Acc& acc, const Unit& u, int wr, int wc, int fr, int fq) const {
;     ...
;         const int h = u.pn >> 1;
; #pragma unroll
;         for (int ai = 0; ai < 2; ++ai)
; #pragma unroll
;             for (int m = 0; m < 4; ++m) {
;                 const int row_in = ai * HALF + wr * 64 + m * 16 + fr, s = u.pm * BM + row_in;
;                 const f32x4 tq = ((const f32x4*)(stats + ((size_t)s * 8 + h) * 8))[fq];
;                 const size_t off = (size_t)s * RV + u.pn * BM + wc * 32 + 8 * fq;
;                 const u32x4 o0 = *(const u32x4*)(O + off), o1 = *(const u32x4*)(O + off + HALF);
;                 float s1 = tq[0] + tq[2], s2 = tq[1] + tq[3];
;                 { const auto r1 = __builtin_amdgcn_permlane16_swap(__float_as_uint(s1), __float_as_uint(s1), false, false); s1 = __uint_as_float(r1[0]) + __uint_as_float(r1[1]);
;                   const auto r2 = __builtin_amdgcn_permlane16_swap(__float_as_uint(s2), __float_as_uint(s2), false, false); s2 = __uint_as_float(r2[0]) + __uint_as_float(r2[1]);
;                   const auto r3 = __builtin_amdgcn_permlane32_swap(__float_as_uint(s1), __float_as_uint(s1), false, false); s1 = __uint_as_float(r3[0]) + __uint_as_float(r3[1]);
;                   const auto r4 = __builtin_amdgcn_permlane32_swap(__float_as_uint(s2), __float_as_uint(s2), false, false); s2 = __uint_as_float(r4[0]) + __uint_as_float(r4[1]); }
;                 const float mu = s1 * (1.0f / 512.0f), var = fmaxf(s2 * (1.0f / 512.0f) - mu * mu, 0.f), rstd = rsqrtf(var + EPS);
; #pragma unroll
;                 for (int bj = 0; bj < 2; ++bj) { const u32x4 ov = bj == 0 ? o0 : o1; const unsigned ow[4] = {ov.x, ov.y, ov.z, ov.w}; unsigned r[4];
; #pragma unroll
;                     for (int p = 0; p < 4; ++p) { const f32x4 v = acc[ai][bj][m][p >> 1]; const float g0 = silu_f(v[(p & 1) * 2]), g1 = silu_f(v[(p & 1) * 2 + 1]);
;                         r[p] = cvt_pk_bf16(g0 * ((bf_lo(ow[p]) - mu) * rstd), g1 * ((bf_hi(ow[p]) - mu) * rstd)); }
.LBB0_883:
	s_lshl_b32 s1, s1, 8
	v_mov_b32_e32 v125, v159
	v_mov_b32_e32 v124, v172
	s_ashr_i32 s2, s0, 1
	s_add_i32 s1, s1, s35
	s_lshl_b32 s0, s0, 8
	s_ashr_i32 s3, s2, 31
	v_add_u32_e32 v162, s1, v125
	s_ashr_i32 s1, s0, 31
	v_lshlrev_b32_e32 v126, 3, v124
	s_lshl_b64 s[48:49], s[2:3], 6
	v_ashrrev_i32_e32 v127, 31, v126
	s_or_b64 s[0:1], s[0:1], s[60:61]
	v_ashrrev_i32_e32 v163, 31, v162
	v_readlane_b32 s2, v248, 11
	v_lshl_add_u64 v[164:165], s[0:1], 0, v[126:127]
	v_lshlrev_b64 v[126:127], 9, v[162:163]
	v_readlane_b32 s3, v248, 12
	v_ashrrev_i32_e32 v125, 31, v124
	v_lshlrev_b64 v[166:167], 4, v[124:125]
	v_lshl_add_u64 v[126:127], s[2:3], 0, v[126:127]
	v_lshl_add_u64 v[126:127], v[126:127], 0, s[48:49]
	v_lshl_add_u64 v[124:125], v[126:127], 0, v[166:167]
	global_load_dwordx4 v[176:179], v[124:125], off
	v_lshlrev_b64 v[124:125], 12, v[162:163]
	v_lshl_add_u64 v[124:125], v[164:165], 0, v[124:125]
	v_readlane_b32 s4, v246, 17
	v_lshlrev_b64 v[170:171], 1, v[124:125]
	v_readlane_b32 s5, v246, 18
	s_mov_b32 s8, 0x3b000000
	v_readlane_b32 s6, v245, 8
	v_lshl_add_u64 v[124:125], s[4:5], 0, v[170:171]
	global_load_dwordx4 v[132:135], v[124:125], off
	s_nop 0
	global_load_dwordx4 v[124:127], v[124:125], off offset:256
	v_add_u32_e32 v216, 16, v162
	v_ashrrev_i32_e32 v217, 31, v216
	v_lshlrev_b64 v[218:219], 9, v[216:217]
	v_lshl_add_u64 v[218:219], s[2:3], 0, v[218:219]
	v_lshl_add_u64 v[218:219], v[218:219], 0, s[48:49]
	v_lshl_add_u64 v[218:219], v[218:219], 0, v[166:167]
	global_load_dwordx4 v[204:207], v[218:219], off
	v_lshlrev_b64 v[216:217], 12, v[216:217]
	v_lshl_add_u64 v[216:217], v[216:217], 0, v[164:165]
	v_lshlrev_b64 v[216:217], 1, v[216:217]
	v_lshl_add_u64 v[216:217], s[4:5], 0, v[216:217]
	global_load_dwordx4 v[208:211], v[216:217], off
	global_load_dwordx4 v[212:215], v[216:217], off offset:256
	v_readlane_b32 s7, v245, 9
	s_mov_b64 s[18:19], -1
	s_waitcnt vmcnt(3)
	v_add_f32_e32 v163, v176, v178
	v_mov_b32_e32 v169, v163
	v_add_f32_e32 v168, v177, v179
	s_nop 0
	v_permlane16_swap_b32_e32 v163, v169
	v_add_f32_e32 v169, v163, v169
	v_mov_b32_e32 v163, v168
	s_nop 1
	v_permlane16_swap_b32_e32 v168, v163
	v_add_f32_e32 v168, v168, v163
	v_mov_b32_e32 v177, v169
	v_mov_b32_e32 v176, v168
	s_nop 0
	v_permlane32_swap_b32_e32 v169, v177
	v_permlane32_swap_b32_e32 v168, v176
	v_pk_add_f32 v[168:169], v[168:169], v[176:177]
	s_nop 0
	v_pk_mul_f32 v[168:169], v[168:169], s[8:9] op_sel_hi:[1,0]
	s_nop 0
	v_fma_f32 v163, -v169, v169, v168
	v_max_f32_e32 v163, 0, v163
	v_add_f32_e32 v163, 0x358637bd, v163
	v_cmp_gt_f32_e32 vcc, s73, v163
	v_mul_f32_e32 v168, 0x4b800000, v163
	s_nop 0
	v_cndmask_b32_e32 v163, v163, v168, vcc
	v_rsq_f32_e32 v163, v163
	s_nop 0
	v_mul_f32_e32 v168, 0x45800000, v163
	v_cndmask_b32_e32 v163, v163, v168, vcc
	v_mul_f32_e32 v168, 0xbfb8aa3b, v128
	v_exp_f32_e32 v168, v168
	s_nop 0
	v_add_f32_e32 v168, 1.0, v168
	v_div_scale_f32 v175, s[0:1], v168, v168, v128
	v_rcp_f32_e32 v176, v175
	s_nop 0
	v_fma_f32 v177, -v175, v176, 1.0
	v_fmac_f32_e32 v176, v177, v176
	v_div_scale_f32 v177, vcc, v128, v168, v128
	v_mul_f32_e32 v178, v177, v176
	v_fma_f32 v179, -v175, v178, v177
	v_fmac_f32_e32 v178, v179, v176
	v_fma_f32 v175, -v175, v178, v177
	v_div_fmas_f32 v175, v175, v176, v178
	v_div_fixup_f32 v128, v175, v168, v128
	v_mul_f32_e32 v168, 0xbfb8aa3b, v129
	v_exp_f32_e32 v168, v168
	s_nop 0
	v_add_f32_e32 v168, 1.0, v168
	v_div_scale_f32 v175, s[0:1], v168, v168, v129
	v_rcp_f32_e32 v176, v175
	s_nop 0
	v_fma_f32 v177, -v175, v176, 1.0
	v_fmac_f32_e32 v176, v177, v176
	v_div_scale_f32 v177, vcc, v129, v168, v129
	v_mul_f32_e32 v178, v177, v176
	v_fma_f32 v179, -v175, v178, v177
	v_fmac_f32_e32 v178, v179, v176
	v_fma_f32 v175, -v175, v178, v177
	v_div_fmas_f32 v175, v175, v176, v178
	v_div_fixup_f32 v129, v175, v168, v129
	v_lshlrev_b32_e32 v168, 16, v132
	v_and_b32_e32 v132, 0xffff0000, v132
	v_sub_f32_e32 v168, v168, v169
	v_sub_f32_e32 v132, v132, v169
	v_mul_f32_e32 v168, v168, v163
	v_mul_f32_e32 v132, v132, v163
	v_mul_f32_e32 v128, v128, v168
	v_mul_f32_e32 v129, v129, v132
	v_cvt_pk_bf16_f32 v128, v128, v129
	v_mul_f32_e32 v129, 0xbfb8aa3b, v130
	v_exp_f32_e32 v129, v129
	s_nop 0
	v_add_f32_e32 v129, 1.0, v129
	v_div_scale_f32 v132, s[0:1], v129, v129, v130
	v_rcp_f32_e32 v168, v132
	s_nop 0
	v_fma_f32 v175, -v132, v168, 1.0
	v_fmac_f32_e32 v168, v175, v168
	v_div_scale_f32 v175, vcc, v130, v129, v130
	v_mul_f32_e32 v176, v175, v168
	v_fma_f32 v177, -v132, v176, v175
	v_fmac_f32_e32 v176, v177, v168
	v_fma_f32 v132, -v132, v176, v175
	v_div_fmas_f32 v132, v132, v168, v176
	v_div_fixup_f32 v129, v132, v129, v130
	v_mul_f32_e32 v130, 0xbfb8aa3b, v131
	v_exp_f32_e32 v130, v130
	s_nop 0
	v_add_f32_e32 v130, 1.0, v130
	v_div_scale_f32 v132, s[0:1], v130, v130, v131
	v_rcp_f32_e32 v168, v132
	s_nop 0
	v_fma_f32 v175, -v132, v168, 1.0
	v_fmac_f32_e32 v168, v175, v168
	v_div_scale_f32 v175, vcc, v131, v130, v131
	v_mul_f32_e32 v176, v175, v168
	v_fma_f32 v177, -v132, v176, v175
	v_fmac_f32_e32 v176, v177, v168
	v_fma_f32 v132, -v132, v176, v175
	v_div_fmas_f32 v132, v132, v168, v176
	v_div_fixup_f32 v130, v132, v130, v131
	v_lshlrev_b32_e32 v131, 16, v133
	v_sub_f32_e32 v131, v131, v169
	v_mul_f32_e32 v131, v131, v163
	v_mul_f32_e32 v129, v129, v131
	v_and_b32_e32 v131, 0xffff0000, v133
	v_sub_f32_e32 v131, v131, v169
	v_mul_f32_e32 v131, v131, v163
	v_mul_f32_e32 v130, v130, v131
	v_cvt_pk_bf16_f32 v129, v129, v130
	v_mul_f32_e32 v130, 0xbfb8aa3b, v120
	v_exp_f32_e32 v130, v130
	s_nop 0
	v_add_f32_e32 v130, 1.0, v130
	v_div_scale_f32 v131, s[0:1], v130, v130, v120
	v_rcp_f32_e32 v132, v131
	s_nop 0
; __device__ __forceinline__ unsigned cvt_pk_bf16(float lo, float hi) { unsigned r; asm volatile("v_cvt_pk_bf16_f32 %0, %1, %2" : "=v"(r) : "v"(lo), "v"(hi)); return r; }
; __device__ __forceinline__ float bf_lo(unsigned w) { return __uint_as_float(w << 16); }
; __device__ __forceinline__ float bf_hi(unsigned w) { return __uint_as_float(w & 0xffff0000u); }
; __device__ __forceinline__ float silu_f(float v) { return v / (1.0f + __expf(-v)); }
;     __device__ __forceinline__ void operator()(const Acc& acc, const Unit& u, int wr, int wc, int fr, int fq) const {
;     ...
; #pragma unroll
;                 for (int bj = 0; bj < 2; ++bj) { const u32x4 ov = bj == 0 ? o0 : o1; const unsigned ow[4] = {ov.x, ov.y, ov.z, ov.w}; unsigned r[4];
; #pragma unroll
;                     for (int p = 0; p < 4; ++p) { const f32x4 v = acc[ai][bj][m][p >> 1]; const float g0 = silu_f(v[(p & 1) * 2]), g1 = silu_f(v[(p & 1) * 2 + 1]);
;                         r[p] = cvt_pk_bf16(g0 * ((bf_lo(ow[p]) - mu) * rstd), g1 * ((bf_hi(ow[p]) - mu) * rstd)); }
;                     *(u32x4*)(U + off + bj * HALF) = (u32x4){r[0], r[1], r[2], r[3]}; }
	v_fma_f32 v133, -v131, v132, 1.0
	v_fmac_f32_e32 v132, v133, v132
	v_div_scale_f32 v133, vcc, v120, v130, v120
	v_mul_f32_e32 v168, v133, v132
	v_fma_f32 v175, -v131, v168, v133
	v_fmac_f32_e32 v168, v175, v132
	v_fma_f32 v131, -v131, v168, v133
	v_div_fmas_f32 v131, v131, v132, v168
	v_div_fixup_f32 v120, v131, v130, v120
	v_mul_f32_e32 v130, 0xbfb8aa3b, v121
	v_exp_f32_e32 v130, v130
	s_nop 0
	v_add_f32_e32 v130, 1.0, v130
	v_div_scale_f32 v131, s[0:1], v130, v130, v121
	v_rcp_f32_e32 v132, v131
	s_nop 0
	v_fma_f32 v133, -v131, v132, 1.0
	v_fmac_f32_e32 v132, v133, v132
	v_div_scale_f32 v133, vcc, v121, v130, v121
	v_mul_f32_e32 v168, v133, v132
	v_fma_f32 v175, -v131, v168, v133
	v_fmac_f32_e32 v168, v175, v132
	v_fma_f32 v131, -v131, v168, v133
	v_div_fmas_f32 v131, v131, v132, v168
	v_div_fixup_f32 v121, v131, v130, v121
	v_lshlrev_b32_e32 v130, 16, v134
	v_sub_f32_e32 v130, v130, v169
	v_mul_f32_e32 v130, v130, v163
	v_mul_f32_e32 v120, v120, v130
	v_and_b32_e32 v130, 0xffff0000, v134
	v_sub_f32_e32 v130, v130, v169
	v_mul_f32_e32 v130, v130, v163
	v_mul_f32_e32 v121, v121, v130
	v_cvt_pk_bf16_f32 v130, v120, v121
	v_mul_f32_e32 v120, 0xbfb8aa3b, v122
	v_exp_f32_e32 v120, v120
	s_nop 0
	v_add_f32_e32 v120, 1.0, v120
	v_div_scale_f32 v121, s[0:1], v120, v120, v122
	v_rcp_f32_e32 v131, v121
	s_nop 0
	v_fma_f32 v132, -v121, v131, 1.0
	v_fmac_f32_e32 v131, v132, v131
	v_div_scale_f32 v132, vcc, v122, v120, v122
	v_mul_f32_e32 v133, v132, v131
	v_fma_f32 v134, -v121, v133, v132
	v_fmac_f32_e32 v133, v134, v131
	v_fma_f32 v121, -v121, v133, v132
	v_div_fmas_f32 v121, v121, v131, v133
	v_div_fixup_f32 v120, v121, v120, v122
	v_mul_f32_e32 v121, 0xbfb8aa3b, v123
	v_exp_f32_e32 v121, v121
	s_nop 0
	v_add_f32_e32 v121, 1.0, v121
	v_div_scale_f32 v122, s[0:1], v121, v121, v123
	v_rcp_f32_e32 v131, v122
	s_nop 0
	v_fma_f32 v132, -v122, v131, 1.0
	v_fmac_f32_e32 v131, v132, v131
	v_div_scale_f32 v132, vcc, v123, v121, v123
	v_mul_f32_e32 v133, v132, v131
	v_fma_f32 v134, -v122, v133, v132
	v_fmac_f32_e32 v133, v134, v131
	v_fma_f32 v122, -v122, v133, v132
	v_div_fmas_f32 v122, v122, v131, v133
	v_div_fixup_f32 v121, v122, v121, v123
	v_lshlrev_b32_e32 v122, 16, v135
	v_sub_f32_e32 v122, v122, v169
	v_mul_f32_e32 v122, v122, v163
	v_mul_f32_e32 v120, v120, v122
	v_and_b32_e32 v122, 0xffff0000, v135
	v_sub_f32_e32 v122, v122, v169
	v_mul_f32_e32 v122, v122, v163
	v_mul_f32_e32 v121, v121, v122
	v_mul_f32_e32 v122, 0xbfb8aa3b, v116
	v_exp_f32_e32 v122, v122
	v_cvt_pk_bf16_f32 v131, v120, v121
	v_lshl_add_u64 v[120:121], s[6:7], 0, v[170:171]
	global_store_dwordx4 v[120:121], v[128:131], off
	v_add_f32_e32 v122, 1.0, v122
	v_div_scale_f32 v123, s[0:1], v122, v122, v116
	v_rcp_f32_e32 v128, v123
	s_nop 0
	v_fma_f32 v129, -v123, v128, 1.0
	v_fmac_f32_e32 v128, v129, v128
	v_div_scale_f32 v129, vcc, v116, v122, v116
	v_mul_f32_e32 v130, v129, v128
	v_fma_f32 v131, -v123, v130, v129
	v_fmac_f32_e32 v130, v131, v128
	v_fma_f32 v123, -v123, v130, v129
	v_div_fmas_f32 v123, v123, v128, v130
	v_div_fixup_f32 v116, v123, v122, v116
	v_mul_f32_e32 v122, 0xbfb8aa3b, v117
	v_exp_f32_e32 v122, v122
	s_nop 0
	v_add_f32_e32 v122, 1.0, v122
	v_div_scale_f32 v123, s[0:1], v122, v122, v117
	v_rcp_f32_e32 v128, v123
	s_nop 0
	v_fma_f32 v129, -v123, v128, 1.0
	v_fmac_f32_e32 v128, v129, v128
	v_div_scale_f32 v129, vcc, v117, v122, v117
	v_mul_f32_e32 v130, v129, v128
	v_fma_f32 v131, -v123, v130, v129
	v_fmac_f32_e32 v130, v131, v128
	v_fma_f32 v123, -v123, v130, v129
	v_div_fmas_f32 v123, v123, v128, v130
	v_div_fixup_f32 v117, v123, v122, v117
	v_lshlrev_b32_e32 v122, 16, v124
	v_sub_f32_e32 v122, v122, v169
	v_mul_f32_e32 v122, v122, v163
	v_mul_f32_e32 v116, v116, v122
	v_and_b32_e32 v122, 0xffff0000, v124
	v_sub_f32_e32 v122, v122, v169
	v_mul_f32_e32 v122, v122, v163
	v_mul_f32_e32 v117, v117, v122
	v_cvt_pk_bf16_f32 v116, v116, v117
	v_mul_f32_e32 v117, 0xbfb8aa3b, v118
	v_exp_f32_e32 v117, v117
	s_nop 0
	v_add_f32_e32 v117, 1.0, v117
	v_div_scale_f32 v122, s[0:1], v117, v117, v118
	v_rcp_f32_e32 v123, v122
	s_nop 0
	v_fma_f32 v124, -v122, v123, 1.0
	v_fmac_f32_e32 v123, v124, v123
	v_div_scale_f32 v124, vcc, v118, v117, v118
	v_mul_f32_e32 v128, v124, v123
	v_fma_f32 v129, -v122, v128, v124
	v_fmac_f32_e32 v128, v129, v123
	v_fma_f32 v122, -v122, v128, v124
	v_div_fmas_f32 v122, v122, v123, v128
	v_div_fixup_f32 v117, v122, v117, v118
	v_mul_f32_e32 v118, 0xbfb8aa3b, v119
	v_exp_f32_e32 v118, v118
	s_nop 0
	v_add_f32_e32 v118, 1.0, v118
	v_div_scale_f32 v122, s[0:1], v118, v118, v119
	v_rcp_f32_e32 v123, v122
	s_nop 0
	v_fma_f32 v124, -v122, v123, 1.0
	v_fmac_f32_e32 v123, v124, v123
	v_div_scale_f32 v124, vcc, v119, v118, v119
	v_mul_f32_e32 v128, v124, v123
	v_fma_f32 v129, -v122, v128, v124
	v_fmac_f32_e32 v128, v129, v123
	v_fma_f32 v122, -v122, v128, v124
	v_div_fmas_f32 v122, v122, v123, v128
	v_div_fixup_f32 v118, v122, v118, v119
	v_lshlrev_b32_e32 v119, 16, v125
	v_sub_f32_e32 v119, v119, v169
	v_mul_f32_e32 v119, v119, v163
	v_mul_f32_e32 v117, v117, v119
	v_and_b32_e32 v119, 0xffff0000, v125
	v_sub_f32_e32 v119, v119, v169
	v_mul_f32_e32 v119, v119, v163
	v_mul_f32_e32 v118, v118, v119
	v_cvt_pk_bf16_f32 v117, v117, v118
	v_mul_f32_e32 v118, 0xbfb8aa3b, v112
	v_exp_f32_e32 v118, v118
	s_nop 0
	v_add_f32_e32 v118, 1.0, v118
	v_div_scale_f32 v119, s[0:1], v118, v118, v112
	v_rcp_f32_e32 v122, v119
	s_nop 0
	v_fma_f32 v123, -v119, v122, 1.0
	v_fmac_f32_e32 v122, v123, v122
	v_div_scale_f32 v123, vcc, v112, v118, v112
	v_mul_f32_e32 v124, v123, v122
	v_fma_f32 v125, -v119, v124, v123
	v_fmac_f32_e32 v124, v125, v122
	v_fma_f32 v119, -v119, v124, v123
; __device__ __forceinline__ unsigned cvt_pk_bf16(float lo, float hi) { unsigned r; asm volatile("v_cvt_pk_bf16_f32 %0, %1, %2" : "=v"(r) : "v"(lo), "v"(hi)); return r; }
; __device__ __forceinline__ float bf_lo(unsigned w) { return __uint_as_float(w << 16); }
; __device__ __forceinline__ float bf_hi(unsigned w) { return __uint_as_float(w & 0xffff0000u); }
;     __device__ __forceinline__ void operator()(const Acc& acc, const Unit& u, int wr, int wc, int fr, int fq) const {
;     ...
;         for (int ai = 0; ai < 2; ++ai)
; #pragma unroll
;             for (int m = 0; m < 4; ++m) {
;                 const int row_in = ai * HALF + wr * 64 + m * 16 + fr, s = u.pm * BM + row_in;
;                 const f32x4 tq = ((const f32x4*)(stats + ((size_t)s * 8 + h) * 8))[fq];
;                 const size_t off = (size_t)s * RV + u.pn * BM + wc * 32 + 8 * fq;
;                 const u32x4 o0 = *(const u32x4*)(O + off), o1 = *(const u32x4*)(O + off + HALF);
;                 float s1 = tq[0] + tq[2], s2 = tq[1] + tq[3];
;                 { const auto r1 = __builtin_amdgcn_permlane16_swap(__float_as_uint(s1), __float_as_uint(s1), false, false); s1 = __uint_as_float(r1[0]) + __uint_as_float(r1[1]);
;                   const auto r2 = __builtin_amdgcn_permlane16_swap(__float_as_uint(s2), __float_as_uint(s2), false, false); s2 = __uint_as_float(r2[0]) + __uint_as_float(r2[1]);
;                   const auto r3 = __builtin_amdgcn_permlane32_swap(__float_as_uint(s1), __float_as_uint(s1), false, false); s1 = __uint_as_float(r3[0]) + __uint_as_float(r3[1]);
;                   const auto r4 = __builtin_amdgcn_permlane32_swap(__float_as_uint(s2), __float_as_uint(s2), false, false); s2 = __uint_as_float(r4[0]) + __uint_as_float(r4[1]); }
;                 const float mu = s1 * (1.0f / 512.0f), var = fmaxf(s2 * (1.0f / 512.0f) - mu * mu, 0.f), rstd = rsqrtf(var + EPS);
; #pragma unroll
;                 for (int bj = 0; bj < 2; ++bj) { const u32x4 ov = bj == 0 ? o0 : o1; const unsigned ow[4] = {ov.x, ov.y, ov.z, ov.w}; unsigned r[4];
; #pragma unroll
;                     for (int p = 0; p < 4; ++p) { const f32x4 v = acc[ai][bj][m][p >> 1]; const float g0 = silu_f(v[(p & 1) * 2]), g1 = silu_f(v[(p & 1) * 2 + 1]);
;                         r[p] = cvt_pk_bf16(g0 * ((bf_lo(ow[p]) - mu) * rstd), g1 * ((bf_hi(ow[p]) - mu) * rstd)); }
	v_div_fmas_f32 v119, v119, v122, v124
	v_div_fixup_f32 v112, v119, v118, v112
	v_mul_f32_e32 v118, 0xbfb8aa3b, v113
	v_exp_f32_e32 v118, v118
	s_nop 0
	v_add_f32_e32 v118, 1.0, v118
	v_div_scale_f32 v119, s[0:1], v118, v118, v113
	v_rcp_f32_e32 v122, v119
	s_nop 0
	v_fma_f32 v123, -v119, v122, 1.0
	v_fmac_f32_e32 v122, v123, v122
	v_div_scale_f32 v123, vcc, v113, v118, v113
	v_mul_f32_e32 v124, v123, v122
	v_fma_f32 v125, -v119, v124, v123
	v_fmac_f32_e32 v124, v125, v122
	v_fma_f32 v119, -v119, v124, v123
	v_div_fmas_f32 v119, v119, v122, v124
	v_div_fixup_f32 v113, v119, v118, v113
	v_lshlrev_b32_e32 v118, 16, v126
	v_sub_f32_e32 v118, v118, v169
	v_mul_f32_e32 v118, v118, v163
	v_mul_f32_e32 v112, v112, v118
	v_and_b32_e32 v118, 0xffff0000, v126
	v_sub_f32_e32 v118, v118, v169
	v_mul_f32_e32 v118, v118, v163
	v_mul_f32_e32 v113, v113, v118
	v_cvt_pk_bf16_f32 v118, v112, v113
	v_mul_f32_e32 v112, 0xbfb8aa3b, v114
	v_exp_f32_e32 v112, v112
	s_nop 0
	v_add_f32_e32 v112, 1.0, v112
	v_div_scale_f32 v113, s[0:1], v112, v112, v114
	v_rcp_f32_e32 v119, v113
	s_nop 0
	v_fma_f32 v122, -v113, v119, 1.0
	v_fmac_f32_e32 v119, v122, v119
	v_div_scale_f32 v122, vcc, v114, v112, v114
	v_mul_f32_e32 v123, v122, v119
	v_fma_f32 v124, -v113, v123, v122
	v_fmac_f32_e32 v123, v124, v119
	v_fma_f32 v113, -v113, v123, v122
	v_div_fmas_f32 v113, v113, v119, v123
	v_div_fixup_f32 v112, v113, v112, v114
	v_mul_f32_e32 v113, 0xbfb8aa3b, v115
	v_exp_f32_e32 v113, v113
	s_nop 0
	v_add_f32_e32 v113, 1.0, v113
	v_div_scale_f32 v114, s[0:1], v113, v113, v115
	v_rcp_f32_e32 v119, v114
	s_nop 0
	v_fma_f32 v122, -v114, v119, 1.0
	v_fmac_f32_e32 v119, v122, v119
	v_div_scale_f32 v122, vcc, v115, v113, v115
	v_mul_f32_e32 v123, v122, v119
	v_fma_f32 v124, -v114, v123, v122
	v_fmac_f32_e32 v123, v124, v119
	v_fma_f32 v114, -v114, v123, v122
	v_div_fmas_f32 v114, v114, v119, v123
	v_div_fixup_f32 v113, v114, v113, v115
	v_lshlrev_b32_e32 v114, 16, v127
	v_sub_f32_e32 v114, v114, v169
	v_mul_f32_e32 v114, v114, v163
	v_mul_f32_e32 v112, v112, v114
	v_and_b32_e32 v114, 0xffff0000, v127
	v_sub_f32_e32 v114, v114, v169
	v_mul_f32_e32 v114, v114, v163
	v_mul_f32_e32 v113, v113, v114
	v_cvt_pk_bf16_f32 v119, v112, v113
	v_add_u32_e32 v112, 16, v162
	v_ashrrev_i32_e32 v113, 31, v112
	v_lshlrev_b64 v[114:115], 9, v[112:113]
	v_lshl_add_u64 v[114:115], s[2:3], 0, v[114:115]
	v_lshl_add_u64 v[114:115], v[114:115], 0, s[48:49]
	global_store_dwordx4 v[120:121], v[116:119], off offset:256
	v_lshl_add_u64 v[114:115], v[114:115], 0, v[166:167]
	v_lshlrev_b64 v[112:113], 12, v[112:113]
	v_lshl_add_u64 v[112:113], v[112:113], 0, v[164:165]
	v_lshlrev_b64 v[122:123], 1, v[112:113]
	v_lshl_add_u64 v[112:113], s[4:5], 0, v[122:123]
	s_waitcnt vmcnt(2)
	v_mov_b32_e32 v124, v204
	v_mov_b32_e32 v125, v205
	v_mov_b32_e32 v126, v206
	v_mov_b32_e32 v127, v207
	v_mov_b32_e32 v116, v208
	v_mov_b32_e32 v117, v209
	v_mov_b32_e32 v118, v210
	v_mov_b32_e32 v119, v211
	v_mov_b32_e32 v112, v212
	v_mov_b32_e32 v113, v213
	v_mov_b32_e32 v114, v214
	v_mov_b32_e32 v115, v215
	v_add_u32_e32 v216, 32, v162
	v_ashrrev_i32_e32 v217, 31, v216
	v_lshlrev_b64 v[218:219], 9, v[216:217]
	v_lshl_add_u64 v[218:219], s[2:3], 0, v[218:219]
	v_lshl_add_u64 v[218:219], v[218:219], 0, s[48:49]
	v_lshl_add_u64 v[218:219], v[218:219], 0, v[166:167]
	global_load_dwordx4 v[192:195], v[218:219], off
	v_lshlrev_b64 v[216:217], 12, v[216:217]
	v_lshl_add_u64 v[216:217], v[216:217], 0, v[164:165]
	v_lshlrev_b64 v[216:217], 1, v[216:217]
	v_lshl_add_u64 v[216:217], s[4:5], 0, v[216:217]
	global_load_dwordx4 v[196:199], v[216:217], off
	global_load_dwordx4 v[200:203], v[216:217], off offset:256
	v_add_f32_e32 v120, v124, v126
	v_mov_b32_e32 v121, v120
	v_add_f32_e32 v124, v125, v127
	s_nop 0
	v_permlane16_swap_b32_e32 v120, v121
	v_add_f32_e32 v121, v120, v121
	v_mov_b32_e32 v120, v124
	s_nop 1
	v_permlane16_swap_b32_e32 v124, v120
	v_add_f32_e32 v120, v124, v120
	v_mov_b32_e32 v125, v121
	v_mov_b32_e32 v124, v120
	s_nop 0
	v_permlane32_swap_b32_e32 v121, v125
	v_permlane32_swap_b32_e32 v120, v124
	v_pk_add_f32 v[120:121], v[120:121], v[124:125]
	s_nop 0
	v_pk_mul_f32 v[120:121], v[120:121], s[8:9] op_sel_hi:[1,0]
	s_nop 0
	v_fma_f32 v120, -v121, v121, v120
	v_max_f32_e32 v120, 0, v120
	v_add_f32_e32 v120, 0x358637bd, v120
	v_cmp_gt_f32_e32 vcc, s73, v120
	v_mul_f32_e32 v124, 0x4b800000, v120
	s_nop 0
	v_cndmask_b32_e32 v120, v120, v124, vcc
	v_rsq_f32_e32 v120, v120
	s_nop 0
	v_mul_f32_e32 v124, 0x45800000, v120
	v_cndmask_b32_e32 v120, v120, v124, vcc
	v_mul_f32_e32 v124, 0xbfb8aa3b, v108
	v_exp_f32_e32 v124, v124
	s_nop 0
	v_add_f32_e32 v124, 1.0, v124
	v_div_scale_f32 v125, s[0:1], v124, v124, v108
	v_rcp_f32_e32 v126, v125
	s_nop 0
	v_fma_f32 v127, -v125, v126, 1.0
	v_fmac_f32_e32 v126, v127, v126
	v_div_scale_f32 v127, vcc, v108, v124, v108
	v_mul_f32_e32 v128, v127, v126
	v_fma_f32 v129, -v125, v128, v127
	v_fmac_f32_e32 v128, v129, v126
	v_fma_f32 v125, -v125, v128, v127
	v_div_fmas_f32 v125, v125, v126, v128
	v_div_fixup_f32 v108, v125, v124, v108
	v_mul_f32_e32 v124, 0xbfb8aa3b, v109
	v_exp_f32_e32 v124, v124
	s_nop 0
	v_add_f32_e32 v124, 1.0, v124
	v_div_scale_f32 v125, s[0:1], v124, v124, v109
	v_rcp_f32_e32 v126, v125
	s_nop 0
	v_fma_f32 v127, -v125, v126, 1.0
	v_fmac_f32_e32 v126, v127, v126
	v_div_scale_f32 v127, vcc, v109, v124, v109
	v_mul_f32_e32 v128, v127, v126
	v_fma_f32 v129, -v125, v128, v127
	v_fmac_f32_e32 v128, v129, v126
	v_fma_f32 v125, -v125, v128, v127
	v_div_fmas_f32 v125, v125, v126, v128
	v_div_fixup_f32 v109, v125, v124, v109
	v_lshlrev_b32_e32 v124, 16, v116
	v_and_b32_e32 v116, 0xffff0000, v116
; __device__ __forceinline__ unsigned cvt_pk_bf16(float lo, float hi) { unsigned r; asm volatile("v_cvt_pk_bf16_f32 %0, %1, %2" : "=v"(r) : "v"(lo), "v"(hi)); return r; }
; __device__ __forceinline__ float bf_lo(unsigned w) { return __uint_as_float(w << 16); }
; __device__ __forceinline__ float bf_hi(unsigned w) { return __uint_as_float(w & 0xffff0000u); }
; __device__ __forceinline__ float silu_f(float v) { return v / (1.0f + __expf(-v)); }
;     __device__ __forceinline__ void operator()(const Acc& acc, const Unit& u, int wr, int wc, int fr, int fq) const {
;     ...
; #pragma unroll
;                 for (int bj = 0; bj < 2; ++bj) { const u32x4 ov = bj == 0 ? o0 : o1; const unsigned ow[4] = {ov.x, ov.y, ov.z, ov.w}; unsigned r[4];
; #pragma unroll
;                     for (int p = 0; p < 4; ++p) { const f32x4 v = acc[ai][bj][m][p >> 1]; const float g0 = silu_f(v[(p & 1) * 2]), g1 = silu_f(v[(p & 1) * 2 + 1]);
;                         r[p] = cvt_pk_bf16(g0 * ((bf_lo(ow[p]) - mu) * rstd), g1 * ((bf_hi(ow[p]) - mu) * rstd)); }
;                     *(u32x4*)(U + off + bj * HALF) = (u32x4){r[0], r[1], r[2], r[3]}; }
	v_sub_f32_e32 v124, v124, v121
	v_sub_f32_e32 v116, v116, v121
	v_mul_f32_e32 v124, v124, v120
	v_mul_f32_e32 v116, v116, v120
	v_mul_f32_e32 v108, v108, v124
	v_mul_f32_e32 v109, v109, v116
	v_cvt_pk_bf16_f32 v108, v108, v109
	v_mul_f32_e32 v109, 0xbfb8aa3b, v110
	v_exp_f32_e32 v109, v109
	s_nop 0
	v_add_f32_e32 v109, 1.0, v109
	v_div_scale_f32 v116, s[0:1], v109, v109, v110
	v_rcp_f32_e32 v124, v116
	s_nop 0
	v_fma_f32 v125, -v116, v124, 1.0
	v_fmac_f32_e32 v124, v125, v124
	v_div_scale_f32 v125, vcc, v110, v109, v110
	v_mul_f32_e32 v126, v125, v124
	v_fma_f32 v127, -v116, v126, v125
	v_fmac_f32_e32 v126, v127, v124
	v_fma_f32 v116, -v116, v126, v125
	v_div_fmas_f32 v116, v116, v124, v126
	v_div_fixup_f32 v109, v116, v109, v110
	v_mul_f32_e32 v110, 0xbfb8aa3b, v111
	v_exp_f32_e32 v110, v110
	s_nop 0
	v_add_f32_e32 v110, 1.0, v110
	v_div_scale_f32 v116, s[0:1], v110, v110, v111
	v_rcp_f32_e32 v124, v116
	s_nop 0
	v_fma_f32 v125, -v116, v124, 1.0
	v_fmac_f32_e32 v124, v125, v124
	v_div_scale_f32 v125, vcc, v111, v110, v111
	v_mul_f32_e32 v126, v125, v124
	v_fma_f32 v127, -v116, v126, v125
	v_fmac_f32_e32 v126, v127, v124
	v_fma_f32 v116, -v116, v126, v125
	v_div_fmas_f32 v116, v116, v124, v126
	v_div_fixup_f32 v110, v116, v110, v111
	v_lshlrev_b32_e32 v111, 16, v117
	v_sub_f32_e32 v111, v111, v121
	v_mul_f32_e32 v111, v111, v120
	v_mul_f32_e32 v109, v109, v111
	v_and_b32_e32 v111, 0xffff0000, v117
	v_sub_f32_e32 v111, v111, v121
	v_mul_f32_e32 v111, v111, v120
	v_mul_f32_e32 v110, v110, v111
	v_cvt_pk_bf16_f32 v109, v109, v110
	v_mul_f32_e32 v110, 0xbfb8aa3b, v104
	v_exp_f32_e32 v110, v110
	s_nop 0
	v_add_f32_e32 v110, 1.0, v110
	v_div_scale_f32 v111, s[0:1], v110, v110, v104
	v_rcp_f32_e32 v116, v111
	s_nop 0
	v_fma_f32 v117, -v111, v116, 1.0
	v_fmac_f32_e32 v116, v117, v116
	v_div_scale_f32 v117, vcc, v104, v110, v104
	v_mul_f32_e32 v124, v117, v116
	v_fma_f32 v125, -v111, v124, v117
	v_fmac_f32_e32 v124, v125, v116
	v_fma_f32 v111, -v111, v124, v117
	v_div_fmas_f32 v111, v111, v116, v124
	v_div_fixup_f32 v104, v111, v110, v104
	v_mul_f32_e32 v110, 0xbfb8aa3b, v105
	v_exp_f32_e32 v110, v110
	s_nop 0
	v_add_f32_e32 v110, 1.0, v110
	v_div_scale_f32 v111, s[0:1], v110, v110, v105
	v_rcp_f32_e32 v116, v111
	s_nop 0
	v_fma_f32 v117, -v111, v116, 1.0
	v_fmac_f32_e32 v116, v117, v116
	v_div_scale_f32 v117, vcc, v105, v110, v105
	v_mul_f32_e32 v124, v117, v116
	v_fma_f32 v125, -v111, v124, v117
	v_fmac_f32_e32 v124, v125, v116
	v_fma_f32 v111, -v111, v124, v117
	v_div_fmas_f32 v111, v111, v116, v124
	v_div_fixup_f32 v105, v111, v110, v105
	v_lshlrev_b32_e32 v110, 16, v118
	v_sub_f32_e32 v110, v110, v121
	v_mul_f32_e32 v110, v110, v120
	v_mul_f32_e32 v104, v104, v110
	v_and_b32_e32 v110, 0xffff0000, v118
	v_sub_f32_e32 v110, v110, v121
	v_mul_f32_e32 v110, v110, v120
	v_mul_f32_e32 v105, v105, v110
	v_cvt_pk_bf16_f32 v110, v104, v105
	v_mul_f32_e32 v104, 0xbfb8aa3b, v106
	v_exp_f32_e32 v104, v104
	s_nop 0
	v_add_f32_e32 v104, 1.0, v104
	v_div_scale_f32 v105, s[0:1], v104, v104, v106
	v_rcp_f32_e32 v111, v105
	s_nop 0
	v_fma_f32 v116, -v105, v111, 1.0
	v_fmac_f32_e32 v111, v116, v111
	v_div_scale_f32 v116, vcc, v106, v104, v106
	v_mul_f32_e32 v117, v116, v111
	v_fma_f32 v118, -v105, v117, v116
	v_fmac_f32_e32 v117, v118, v111
	v_fma_f32 v105, -v105, v117, v116
	v_div_fmas_f32 v105, v105, v111, v117
	v_div_fixup_f32 v104, v105, v104, v106
	v_mul_f32_e32 v105, 0xbfb8aa3b, v107
	v_exp_f32_e32 v105, v105
	s_nop 0
	v_add_f32_e32 v105, 1.0, v105
	v_div_scale_f32 v106, s[0:1], v105, v105, v107
	v_rcp_f32_e32 v111, v106
	s_nop 0
	v_fma_f32 v116, -v106, v111, 1.0
	v_fmac_f32_e32 v111, v116, v111
	v_div_scale_f32 v116, vcc, v107, v105, v107
	v_mul_f32_e32 v117, v116, v111
	v_fma_f32 v118, -v106, v117, v116
	v_fmac_f32_e32 v117, v118, v111
	v_fma_f32 v106, -v106, v117, v116
	v_div_fmas_f32 v106, v106, v111, v117
	v_div_fixup_f32 v105, v106, v105, v107
	v_lshlrev_b32_e32 v106, 16, v119
	v_sub_f32_e32 v106, v106, v121
	v_mul_f32_e32 v106, v106, v120
	v_mul_f32_e32 v104, v104, v106
	v_and_b32_e32 v106, 0xffff0000, v119
	v_sub_f32_e32 v106, v106, v121
	v_mul_f32_e32 v106, v106, v120
	v_mul_f32_e32 v105, v105, v106
	v_mul_f32_e32 v106, 0xbfb8aa3b, v100
	v_exp_f32_e32 v106, v106
	v_cvt_pk_bf16_f32 v111, v104, v105
	v_lshl_add_u64 v[104:105], s[6:7], 0, v[122:123]
	global_store_dwordx4 v[104:105], v[108:111], off
	v_add_f32_e32 v106, 1.0, v106
	v_div_scale_f32 v107, s[0:1], v106, v106, v100
	v_rcp_f32_e32 v108, v107
	s_nop 0
	v_fma_f32 v109, -v107, v108, 1.0
	v_fmac_f32_e32 v108, v109, v108
	v_div_scale_f32 v109, vcc, v100, v106, v100
	v_mul_f32_e32 v110, v109, v108
	v_fma_f32 v111, -v107, v110, v109
	v_fmac_f32_e32 v110, v111, v108
	v_fma_f32 v107, -v107, v110, v109
	v_div_fmas_f32 v107, v107, v108, v110
	v_div_fixup_f32 v100, v107, v106, v100
	v_mul_f32_e32 v106, 0xbfb8aa3b, v101
	v_exp_f32_e32 v106, v106
	s_nop 0
	v_add_f32_e32 v106, 1.0, v106
	v_div_scale_f32 v107, s[0:1], v106, v106, v101
	v_rcp_f32_e32 v108, v107
	s_nop 0
	v_fma_f32 v109, -v107, v108, 1.0
	v_fmac_f32_e32 v108, v109, v108
	v_div_scale_f32 v109, vcc, v101, v106, v101
	v_mul_f32_e32 v110, v109, v108
	v_fma_f32 v111, -v107, v110, v109
	v_fmac_f32_e32 v110, v111, v108
	v_fma_f32 v107, -v107, v110, v109
	v_div_fmas_f32 v107, v107, v108, v110
	v_div_fixup_f32 v101, v107, v106, v101
	v_lshlrev_b32_e32 v106, 16, v112
	v_sub_f32_e32 v106, v106, v121
	v_mul_f32_e32 v106, v106, v120
	v_mul_f32_e32 v100, v100, v106
	v_and_b32_e32 v106, 0xffff0000, v112
	v_sub_f32_e32 v106, v106, v121
	v_mul_f32_e32 v106, v106, v120
	v_mul_f32_e32 v101, v101, v106
	v_cvt_pk_bf16_f32 v100, v100, v101
; __device__ __forceinline__ unsigned cvt_pk_bf16(float lo, float hi) { unsigned r; asm volatile("v_cvt_pk_bf16_f32 %0, %1, %2" : "=v"(r) : "v"(lo), "v"(hi)); return r; }
; __device__ __forceinline__ float bf_lo(unsigned w) { return __uint_as_float(w << 16); }
; __device__ __forceinline__ float bf_hi(unsigned w) { return __uint_as_float(w & 0xffff0000u); }
; __device__ __forceinline__ float silu_f(float v) { return v / (1.0f + __expf(-v)); }
;     __device__ __forceinline__ void operator()(const Acc& acc, const Unit& u, int wr, int wc, int fr, int fq) const {
;     ...
; #pragma unroll
;                 for (int bj = 0; bj < 2; ++bj) { const u32x4 ov = bj == 0 ? o0 : o1; const unsigned ow[4] = {ov.x, ov.y, ov.z, ov.w}; unsigned r[4];
; #pragma unroll
;                     for (int p = 0; p < 4; ++p) { const f32x4 v = acc[ai][bj][m][p >> 1]; const float g0 = silu_f(v[(p & 1) * 2]), g1 = silu_f(v[(p & 1) * 2 + 1]);
;                         r[p] = cvt_pk_bf16(g0 * ((bf_lo(ow[p]) - mu) * rstd), g1 * ((bf_hi(ow[p]) - mu) * rstd)); }
;                     *(u32x4*)(U + off + bj * HALF) = (u32x4){r[0], r[1], r[2], r[3]}; }
	v_mul_f32_e32 v101, 0xbfb8aa3b, v102
	v_exp_f32_e32 v101, v101
	s_nop 0
	v_add_f32_e32 v101, 1.0, v101
	v_div_scale_f32 v106, s[0:1], v101, v101, v102
	v_rcp_f32_e32 v107, v106
	s_nop 0
	v_fma_f32 v108, -v106, v107, 1.0
	v_fmac_f32_e32 v107, v108, v107
	v_div_scale_f32 v108, vcc, v102, v101, v102
	v_mul_f32_e32 v109, v108, v107
	v_fma_f32 v110, -v106, v109, v108
	v_fmac_f32_e32 v109, v110, v107
	v_fma_f32 v106, -v106, v109, v108
	v_div_fmas_f32 v106, v106, v107, v109
	v_div_fixup_f32 v101, v106, v101, v102
	v_mul_f32_e32 v102, 0xbfb8aa3b, v103
	v_exp_f32_e32 v102, v102
	s_nop 0
	v_add_f32_e32 v102, 1.0, v102
	v_div_scale_f32 v106, s[0:1], v102, v102, v103
	v_rcp_f32_e32 v107, v106
	s_nop 0
	v_fma_f32 v108, -v106, v107, 1.0
	v_fmac_f32_e32 v107, v108, v107
	v_div_scale_f32 v108, vcc, v103, v102, v103
	v_mul_f32_e32 v109, v108, v107
	v_fma_f32 v110, -v106, v109, v108
	v_fmac_f32_e32 v109, v110, v107
	v_fma_f32 v106, -v106, v109, v108
	v_div_fmas_f32 v106, v106, v107, v109
	v_div_fixup_f32 v102, v106, v102, v103
	v_lshlrev_b32_e32 v103, 16, v113
	v_sub_f32_e32 v103, v103, v121
	v_mul_f32_e32 v103, v103, v120
	v_mul_f32_e32 v101, v101, v103
	v_and_b32_e32 v103, 0xffff0000, v113
	v_sub_f32_e32 v103, v103, v121
	v_mul_f32_e32 v103, v103, v120
	v_mul_f32_e32 v102, v102, v103
	v_cvt_pk_bf16_f32 v101, v101, v102
	v_mul_f32_e32 v102, 0xbfb8aa3b, v96
	v_exp_f32_e32 v102, v102
	s_nop 0
	v_add_f32_e32 v102, 1.0, v102
	v_div_scale_f32 v103, s[0:1], v102, v102, v96
	v_rcp_f32_e32 v106, v103
	s_nop 0
	v_fma_f32 v107, -v103, v106, 1.0
	v_fmac_f32_e32 v106, v107, v106
	v_div_scale_f32 v107, vcc, v96, v102, v96
	v_mul_f32_e32 v108, v107, v106
	v_fma_f32 v109, -v103, v108, v107
	v_fmac_f32_e32 v108, v109, v106
	v_fma_f32 v103, -v103, v108, v107
	v_div_fmas_f32 v103, v103, v106, v108
	v_div_fixup_f32 v96, v103, v102, v96
	v_mul_f32_e32 v102, 0xbfb8aa3b, v97
	v_exp_f32_e32 v102, v102
	s_nop 0
	v_add_f32_e32 v102, 1.0, v102
	v_div_scale_f32 v103, s[0:1], v102, v102, v97
	v_rcp_f32_e32 v106, v103
	s_nop 0
	v_fma_f32 v107, -v103, v106, 1.0
	v_fmac_f32_e32 v106, v107, v106
	v_div_scale_f32 v107, vcc, v97, v102, v97
	v_mul_f32_e32 v108, v107, v106
	v_fma_f32 v109, -v103, v108, v107
	v_fmac_f32_e32 v108, v109, v106
	v_fma_f32 v103, -v103, v108, v107
	v_div_fmas_f32 v103, v103, v106, v108
	v_div_fixup_f32 v97, v103, v102, v97
	v_lshlrev_b32_e32 v102, 16, v114
	v_sub_f32_e32 v102, v102, v121
	v_mul_f32_e32 v102, v102, v120
	v_mul_f32_e32 v96, v96, v102
	v_and_b32_e32 v102, 0xffff0000, v114
	v_sub_f32_e32 v102, v102, v121
	v_mul_f32_e32 v102, v102, v120
	v_mul_f32_e32 v97, v97, v102
	v_cvt_pk_bf16_f32 v102, v96, v97
	v_mul_f32_e32 v96, 0xbfb8aa3b, v98
	v_exp_f32_e32 v96, v96
	s_nop 0
	v_add_f32_e32 v96, 1.0, v96
	v_div_scale_f32 v97, s[0:1], v96, v96, v98
	v_rcp_f32_e32 v103, v97
	s_nop 0
	v_fma_f32 v106, -v97, v103, 1.0
	v_fmac_f32_e32 v103, v106, v103
	v_div_scale_f32 v106, vcc, v98, v96, v98
	v_mul_f32_e32 v107, v106, v103
	v_fma_f32 v108, -v97, v107, v106
	v_fmac_f32_e32 v107, v108, v103
	v_fma_f32 v97, -v97, v107, v106
	v_div_fmas_f32 v97, v97, v103, v107
	v_div_fixup_f32 v96, v97, v96, v98
	v_mul_f32_e32 v97, 0xbfb8aa3b, v99
	v_exp_f32_e32 v97, v97
	s_nop 0
	v_add_f32_e32 v97, 1.0, v97
	v_div_scale_f32 v98, s[0:1], v97, v97, v99
	v_rcp_f32_e32 v103, v98
	s_nop 0
	v_fma_f32 v106, -v98, v103, 1.0
	v_fmac_f32_e32 v103, v106, v103
	v_div_scale_f32 v106, vcc, v99, v97, v99
	v_mul_f32_e32 v107, v106, v103
	v_fma_f32 v108, -v98, v107, v106
	v_fmac_f32_e32 v107, v108, v103
	v_fma_f32 v98, -v98, v107, v106
	v_div_fmas_f32 v98, v98, v103, v107
	v_div_fixup_f32 v97, v98, v97, v99
	v_lshlrev_b32_e32 v98, 16, v115
	v_sub_f32_e32 v98, v98, v121
	v_mul_f32_e32 v98, v98, v120
	v_mul_f32_e32 v96, v96, v98
	v_and_b32_e32 v98, 0xffff0000, v115
	v_sub_f32_e32 v98, v98, v121
	v_mul_f32_e32 v98, v98, v120
	v_mul_f32_e32 v97, v97, v98
	v_cvt_pk_bf16_f32 v103, v96, v97
	v_add_u32_e32 v96, 32, v162
	v_ashrrev_i32_e32 v97, 31, v96
	v_lshlrev_b64 v[98:99], 9, v[96:97]
	v_lshl_add_u64 v[98:99], s[2:3], 0, v[98:99]
	v_lshl_add_u64 v[98:99], v[98:99], 0, s[48:49]
	global_store_dwordx4 v[104:105], v[100:103], off offset:256
	v_lshl_add_u64 v[98:99], v[98:99], 0, v[166:167]
	v_lshlrev_b64 v[96:97], 12, v[96:97]
	v_lshl_add_u64 v[96:97], v[96:97], 0, v[164:165]
	v_lshlrev_b64 v[106:107], 1, v[96:97]
	v_lshl_add_u64 v[96:97], s[4:5], 0, v[106:107]
	s_waitcnt vmcnt(2)
; __device__ __forceinline__ unsigned cvt_pk_bf16(float lo, float hi) { unsigned r; asm volatile("v_cvt_pk_bf16_f32 %0, %1, %2" : "=v"(r) : "v"(lo), "v"(hi)); return r; }
; __device__ __forceinline__ float bf_lo(unsigned w) { return __uint_as_float(w << 16); }
; __device__ __forceinline__ float bf_hi(unsigned w) { return __uint_as_float(w & 0xffff0000u); }
;     __device__ __forceinline__ void operator()(const Acc& acc, const Unit& u, int wr, int wc, int fr, int fq) const {
;     ...
;         for (int ai = 0; ai < 2; ++ai)
; #pragma unroll
;             for (int m = 0; m < 4; ++m) {
;                 const int row_in = ai * HALF + wr * 64 + m * 16 + fr, s = u.pm * BM + row_in;
;                 const f32x4 tq = ((const f32x4*)(stats + ((size_t)s * 8 + h) * 8))[fq];
;                 const size_t off = (size_t)s * RV + u.pn * BM + wc * 32 + 8 * fq;
;                 const u32x4 o0 = *(const u32x4*)(O + off), o1 = *(const u32x4*)(O + off + HALF);
;                 float s1 = tq[0] + tq[2], s2 = tq[1] + tq[3];
;                 { const auto r1 = __builtin_amdgcn_permlane16_swap(__float_as_uint(s1), __float_as_uint(s1), false, false); s1 = __uint_as_float(r1[0]) + __uint_as_float(r1[1]);
;                   const auto r2 = __builtin_amdgcn_permlane16_swap(__float_as_uint(s2), __float_as_uint(s2), false, false); s2 = __uint_as_float(r2[0]) + __uint_as_float(r2[1]);
;                   const auto r3 = __builtin_amdgcn_permlane32_swap(__float_as_uint(s1), __float_as_uint(s1), false, false); s1 = __uint_as_float(r3[0]) + __uint_as_float(r3[1]);
;                   const auto r4 = __builtin_amdgcn_permlane32_swap(__float_as_uint(s2), __float_as_uint(s2), false, false); s2 = __uint_as_float(r4[0]) + __uint_as_float(r4[1]); }
;                 const float mu = s1 * (1.0f / 512.0f), var = fmaxf(s2 * (1.0f / 512.0f) - mu * mu, 0.f), rstd = rsqrtf(var + EPS);
; #pragma unroll
;                 for (int bj = 0; bj < 2; ++bj) { const u32x4 ov = bj == 0 ? o0 : o1; const unsigned ow[4] = {ov.x, ov.y, ov.z, ov.w}; unsigned r[4];
; #pragma unroll
;                     for (int p = 0; p < 4; ++p) { const f32x4 v = acc[ai][bj][m][p >> 1]; const float g0 = silu_f(v[(p & 1) * 2]), g1 = silu_f(v[(p & 1) * 2 + 1]);
;                         r[p] = cvt_pk_bf16(g0 * ((bf_lo(ow[p]) - mu) * rstd), g1 * ((bf_hi(ow[p]) - mu) * rstd)); }
	v_mov_b32_e32 v108, v192
	v_mov_b32_e32 v109, v193
	v_mov_b32_e32 v110, v194
	v_mov_b32_e32 v111, v195
	v_mov_b32_e32 v100, v196
	v_mov_b32_e32 v101, v197
	v_mov_b32_e32 v102, v198
	v_mov_b32_e32 v103, v199
	v_mov_b32_e32 v96, v200
	v_mov_b32_e32 v97, v201
	v_mov_b32_e32 v98, v202
	v_mov_b32_e32 v99, v203
	v_add_u32_e32 v216, 48, v162
	v_ashrrev_i32_e32 v217, 31, v216
	v_lshlrev_b64 v[218:219], 9, v[216:217]
	v_lshl_add_u64 v[218:219], s[2:3], 0, v[218:219]
	v_lshl_add_u64 v[218:219], v[218:219], 0, s[48:49]
	v_lshl_add_u64 v[218:219], v[218:219], 0, v[166:167]
	global_load_dwordx4 v[204:207], v[218:219], off
	v_lshlrev_b64 v[216:217], 12, v[216:217]
	v_lshl_add_u64 v[216:217], v[216:217], 0, v[164:165]
	v_lshlrev_b64 v[216:217], 1, v[216:217]
	v_lshl_add_u64 v[216:217], s[4:5], 0, v[216:217]
	global_load_dwordx4 v[208:211], v[216:217], off
	global_load_dwordx4 v[212:215], v[216:217], off offset:256
	v_add_f32_e32 v104, v108, v110
	v_mov_b32_e32 v105, v104
	v_add_f32_e32 v108, v109, v111
	s_nop 0
	v_permlane16_swap_b32_e32 v104, v105
	v_add_f32_e32 v105, v104, v105
	v_mov_b32_e32 v104, v108
	s_nop 1
	v_permlane16_swap_b32_e32 v108, v104
	v_add_f32_e32 v104, v108, v104
	v_mov_b32_e32 v109, v105
	v_mov_b32_e32 v108, v104
	s_nop 0
	v_permlane32_swap_b32_e32 v105, v109
	v_permlane32_swap_b32_e32 v104, v108
	v_pk_add_f32 v[104:105], v[104:105], v[108:109]
	s_nop 0
	v_pk_mul_f32 v[104:105], v[104:105], s[8:9] op_sel_hi:[1,0]
	s_nop 0
	v_fma_f32 v104, -v105, v105, v104
	v_max_f32_e32 v104, 0, v104
	v_add_f32_e32 v104, 0x358637bd, v104
	v_cmp_gt_f32_e32 vcc, s73, v104
	v_mul_f32_e32 v108, 0x4b800000, v104
	s_nop 0
	v_cndmask_b32_e32 v104, v104, v108, vcc
	v_rsq_f32_e32 v104, v104
	s_nop 0
	v_mul_f32_e32 v108, 0x45800000, v104
	v_cndmask_b32_e32 v104, v104, v108, vcc
	v_mul_f32_e32 v108, 0xbfb8aa3b, v92
	v_exp_f32_e32 v108, v108
	s_nop 0
	v_add_f32_e32 v108, 1.0, v108
	v_div_scale_f32 v109, s[0:1], v108, v108, v92
	v_rcp_f32_e32 v110, v109
	s_nop 0
	v_fma_f32 v111, -v109, v110, 1.0
	v_fmac_f32_e32 v110, v111, v110
	v_div_scale_f32 v111, vcc, v92, v108, v92
	v_mul_f32_e32 v112, v111, v110
	v_fma_f32 v113, -v109, v112, v111
	v_fmac_f32_e32 v112, v113, v110
	v_fma_f32 v109, -v109, v112, v111
	v_div_fmas_f32 v109, v109, v110, v112
	v_div_fixup_f32 v92, v109, v108, v92
	v_mul_f32_e32 v108, 0xbfb8aa3b, v93
	v_exp_f32_e32 v108, v108
	s_nop 0
	v_add_f32_e32 v108, 1.0, v108
	v_div_scale_f32 v109, s[0:1], v108, v108, v93
	v_rcp_f32_e32 v110, v109
	s_nop 0
	v_fma_f32 v111, -v109, v110, 1.0
	v_fmac_f32_e32 v110, v111, v110
	v_div_scale_f32 v111, vcc, v93, v108, v93
	v_mul_f32_e32 v112, v111, v110
	v_fma_f32 v113, -v109, v112, v111
	v_fmac_f32_e32 v112, v113, v110
	v_fma_f32 v109, -v109, v112, v111
	v_div_fmas_f32 v109, v109, v110, v112
	v_div_fixup_f32 v93, v109, v108, v93
	v_lshlrev_b32_e32 v108, 16, v100
	v_and_b32_e32 v100, 0xffff0000, v100
	v_sub_f32_e32 v108, v108, v105
	v_sub_f32_e32 v100, v100, v105
	v_mul_f32_e32 v108, v108, v104
	v_mul_f32_e32 v100, v100, v104
	v_mul_f32_e32 v92, v92, v108
	v_mul_f32_e32 v93, v93, v100
	v_cvt_pk_bf16_f32 v92, v92, v93
	v_mul_f32_e32 v93, 0xbfb8aa3b, v94
	v_exp_f32_e32 v93, v93
	s_nop 0
	v_add_f32_e32 v93, 1.0, v93
	v_div_scale_f32 v100, s[0:1], v93, v93, v94
	v_rcp_f32_e32 v108, v100
	s_nop 0
	v_fma_f32 v109, -v100, v108, 1.0
	v_fmac_f32_e32 v108, v109, v108
	v_div_scale_f32 v109, vcc, v94, v93, v94
	v_mul_f32_e32 v110, v109, v108
	v_fma_f32 v111, -v100, v110, v109
	v_fmac_f32_e32 v110, v111, v108
	v_fma_f32 v100, -v100, v110, v109
	v_div_fmas_f32 v100, v100, v108, v110
	v_div_fixup_f32 v93, v100, v93, v94
	v_mul_f32_e32 v94, 0xbfb8aa3b, v95
	v_exp_f32_e32 v94, v94
	s_nop 0
	v_add_f32_e32 v94, 1.0, v94
	v_div_scale_f32 v100, s[0:1], v94, v94, v95
	v_rcp_f32_e32 v108, v100
	s_nop 0
	v_fma_f32 v109, -v100, v108, 1.0
	v_fmac_f32_e32 v108, v109, v108
	v_div_scale_f32 v109, vcc, v95, v94, v95
	v_mul_f32_e32 v110, v109, v108
	v_fma_f32 v111, -v100, v110, v109
	v_fmac_f32_e32 v110, v111, v108
	v_fma_f32 v100, -v100, v110, v109
	v_div_fmas_f32 v100, v100, v108, v110
	v_div_fixup_f32 v94, v100, v94, v95
	v_lshlrev_b32_e32 v95, 16, v101
	v_sub_f32_e32 v95, v95, v105
	v_mul_f32_e32 v95, v95, v104
	v_mul_f32_e32 v93, v93, v95
	v_and_b32_e32 v95, 0xffff0000, v101
	v_sub_f32_e32 v95, v95, v105
	v_mul_f32_e32 v95, v95, v104
	v_mul_f32_e32 v94, v94, v95
	v_cvt_pk_bf16_f32 v93, v93, v94
	v_mul_f32_e32 v94, 0xbfb8aa3b, v88
	v_exp_f32_e32 v94, v94
	s_nop 0
	v_add_f32_e32 v94, 1.0, v94
	v_div_scale_f32 v95, s[0:1], v94, v94, v88
	v_rcp_f32_e32 v100, v95
	s_nop 0
	v_fma_f32 v101, -v95, v100, 1.0
	v_fmac_f32_e32 v100, v101, v100
	v_div_scale_f32 v101, vcc, v88, v94, v88
	v_mul_f32_e32 v108, v101, v100
	v_fma_f32 v109, -v95, v108, v101
	v_fmac_f32_e32 v108, v109, v100
	v_fma_f32 v95, -v95, v108, v101
	v_div_fmas_f32 v95, v95, v100, v108
	v_div_fixup_f32 v88, v95, v94, v88
	v_mul_f32_e32 v94, 0xbfb8aa3b, v89
	v_exp_f32_e32 v94, v94
	s_nop 0
	v_add_f32_e32 v94, 1.0, v94
	v_div_scale_f32 v95, s[0:1], v94, v94, v89
	v_rcp_f32_e32 v100, v95
	s_nop 0
	v_fma_f32 v101, -v95, v100, 1.0
	v_fmac_f32_e32 v100, v101, v100
	v_div_scale_f32 v101, vcc, v89, v94, v89
	v_mul_f32_e32 v108, v101, v100
	v_fma_f32 v109, -v95, v108, v101
	v_fmac_f32_e32 v108, v109, v100
	v_fma_f32 v95, -v95, v108, v101
	v_div_fmas_f32 v95, v95, v100, v108
	v_div_fixup_f32 v89, v95, v94, v89
	v_lshlrev_b32_e32 v94, 16, v102
	v_sub_f32_e32 v94, v94, v105
	v_mul_f32_e32 v94, v94, v104
	v_mul_f32_e32 v88, v88, v94
	v_and_b32_e32 v94, 0xffff0000, v102
	v_sub_f32_e32 v94, v94, v105
	v_mul_f32_e32 v94, v94, v104
	v_mul_f32_e32 v89, v89, v94
	v_cvt_pk_bf16_f32 v94, v88, v89
; __device__ __forceinline__ unsigned cvt_pk_bf16(float lo, float hi) { unsigned r; asm volatile("v_cvt_pk_bf16_f32 %0, %1, %2" : "=v"(r) : "v"(lo), "v"(hi)); return r; }
; __device__ __forceinline__ float bf_lo(unsigned w) { return __uint_as_float(w << 16); }
; __device__ __forceinline__ float bf_hi(unsigned w) { return __uint_as_float(w & 0xffff0000u); }
; __device__ __forceinline__ float silu_f(float v) { return v / (1.0f + __expf(-v)); }
;     __device__ __forceinline__ void operator()(const Acc& acc, const Unit& u, int wr, int wc, int fr, int fq) const {
;     ...
; #pragma unroll
;                 for (int bj = 0; bj < 2; ++bj) { const u32x4 ov = bj == 0 ? o0 : o1; const unsigned ow[4] = {ov.x, ov.y, ov.z, ov.w}; unsigned r[4];
; #pragma unroll
;                     for (int p = 0; p < 4; ++p) { const f32x4 v = acc[ai][bj][m][p >> 1]; const float g0 = silu_f(v[(p & 1) * 2]), g1 = silu_f(v[(p & 1) * 2 + 1]);
;                         r[p] = cvt_pk_bf16(g0 * ((bf_lo(ow[p]) - mu) * rstd), g1 * ((bf_hi(ow[p]) - mu) * rstd)); }
;                     *(u32x4*)(U + off + bj * HALF) = (u32x4){r[0], r[1], r[2], r[3]}; }
	v_mul_f32_e32 v88, 0xbfb8aa3b, v90
	v_exp_f32_e32 v88, v88
	s_nop 0
	v_add_f32_e32 v88, 1.0, v88
	v_div_scale_f32 v89, s[0:1], v88, v88, v90
	v_rcp_f32_e32 v95, v89
	s_nop 0
	v_fma_f32 v100, -v89, v95, 1.0
	v_fmac_f32_e32 v95, v100, v95
	v_div_scale_f32 v100, vcc, v90, v88, v90
	v_mul_f32_e32 v101, v100, v95
	v_fma_f32 v102, -v89, v101, v100
	v_fmac_f32_e32 v101, v102, v95
	v_fma_f32 v89, -v89, v101, v100
	v_div_fmas_f32 v89, v89, v95, v101
	v_div_fixup_f32 v88, v89, v88, v90
	v_mul_f32_e32 v89, 0xbfb8aa3b, v91
	v_exp_f32_e32 v89, v89
	s_nop 0
	v_add_f32_e32 v89, 1.0, v89
	v_div_scale_f32 v90, s[0:1], v89, v89, v91
	v_rcp_f32_e32 v95, v90
	s_nop 0
	v_fma_f32 v100, -v90, v95, 1.0
	v_fmac_f32_e32 v95, v100, v95
	v_div_scale_f32 v100, vcc, v91, v89, v91
	v_mul_f32_e32 v101, v100, v95
	v_fma_f32 v102, -v90, v101, v100
	v_fmac_f32_e32 v101, v102, v95
	v_fma_f32 v90, -v90, v101, v100
	v_div_fmas_f32 v90, v90, v95, v101
	v_div_fixup_f32 v89, v90, v89, v91
	v_lshlrev_b32_e32 v90, 16, v103
	v_sub_f32_e32 v90, v90, v105
	v_mul_f32_e32 v90, v90, v104
	v_mul_f32_e32 v88, v88, v90
	v_and_b32_e32 v90, 0xffff0000, v103
	v_sub_f32_e32 v90, v90, v105
	v_mul_f32_e32 v90, v90, v104
	v_mul_f32_e32 v89, v89, v90
	v_mul_f32_e32 v90, 0xbfb8aa3b, v84
	v_exp_f32_e32 v90, v90
	v_cvt_pk_bf16_f32 v95, v88, v89
	v_lshl_add_u64 v[88:89], s[6:7], 0, v[106:107]
	global_store_dwordx4 v[88:89], v[92:95], off
	v_add_f32_e32 v90, 1.0, v90
	v_div_scale_f32 v91, s[0:1], v90, v90, v84
	v_rcp_f32_e32 v92, v91
	s_nop 0
	v_fma_f32 v93, -v91, v92, 1.0
	v_fmac_f32_e32 v92, v93, v92
	v_div_scale_f32 v93, vcc, v84, v90, v84
	v_mul_f32_e32 v94, v93, v92
	v_fma_f32 v95, -v91, v94, v93
	v_fmac_f32_e32 v94, v95, v92
	v_fma_f32 v91, -v91, v94, v93
	v_div_fmas_f32 v91, v91, v92, v94
	v_div_fixup_f32 v84, v91, v90, v84
	v_mul_f32_e32 v90, 0xbfb8aa3b, v85
	v_exp_f32_e32 v90, v90
	s_nop 0
	v_add_f32_e32 v90, 1.0, v90
	v_div_scale_f32 v91, s[0:1], v90, v90, v85
	v_rcp_f32_e32 v92, v91
	s_nop 0
	v_fma_f32 v93, -v91, v92, 1.0
	v_fmac_f32_e32 v92, v93, v92
	v_div_scale_f32 v93, vcc, v85, v90, v85
	v_mul_f32_e32 v94, v93, v92
	v_fma_f32 v95, -v91, v94, v93
	v_fmac_f32_e32 v94, v95, v92
	v_fma_f32 v91, -v91, v94, v93
	v_div_fmas_f32 v91, v91, v92, v94
	v_div_fixup_f32 v85, v91, v90, v85
	v_lshlrev_b32_e32 v90, 16, v96
	v_sub_f32_e32 v90, v90, v105
	v_mul_f32_e32 v90, v90, v104
	v_mul_f32_e32 v84, v84, v90
	v_and_b32_e32 v90, 0xffff0000, v96
	v_sub_f32_e32 v90, v90, v105
	v_mul_f32_e32 v90, v90, v104
	v_mul_f32_e32 v85, v85, v90
	v_cvt_pk_bf16_f32 v84, v84, v85
	v_mul_f32_e32 v85, 0xbfb8aa3b, v86
	v_exp_f32_e32 v85, v85
	s_nop 0
	v_add_f32_e32 v85, 1.0, v85
	v_div_scale_f32 v90, s[0:1], v85, v85, v86
	v_rcp_f32_e32 v91, v90
	s_nop 0
	v_fma_f32 v92, -v90, v91, 1.0
	v_fmac_f32_e32 v91, v92, v91
	v_div_scale_f32 v92, vcc, v86, v85, v86
	v_mul_f32_e32 v93, v92, v91
	v_fma_f32 v94, -v90, v93, v92
	v_fmac_f32_e32 v93, v94, v91
	v_fma_f32 v90, -v90, v93, v92
	v_div_fmas_f32 v90, v90, v91, v93
	v_div_fixup_f32 v85, v90, v85, v86
	v_mul_f32_e32 v86, 0xbfb8aa3b, v87
	v_exp_f32_e32 v86, v86
	s_nop 0
	v_add_f32_e32 v86, 1.0, v86
	v_div_scale_f32 v90, s[0:1], v86, v86, v87
	v_rcp_f32_e32 v91, v90
	s_nop 0
	v_fma_f32 v92, -v90, v91, 1.0
	v_fmac_f32_e32 v91, v92, v91
	v_div_scale_f32 v92, vcc, v87, v86, v87
	v_mul_f32_e32 v93, v92, v91
	v_fma_f32 v94, -v90, v93, v92
	v_fmac_f32_e32 v93, v94, v91
	v_fma_f32 v90, -v90, v93, v92
	v_div_fmas_f32 v90, v90, v91, v93
	v_div_fixup_f32 v86, v90, v86, v87
	v_lshlrev_b32_e32 v87, 16, v97
	v_sub_f32_e32 v87, v87, v105
	v_mul_f32_e32 v87, v87, v104
	v_mul_f32_e32 v85, v85, v87
	v_and_b32_e32 v87, 0xffff0000, v97
	v_sub_f32_e32 v87, v87, v105
	v_mul_f32_e32 v87, v87, v104
	v_mul_f32_e32 v86, v86, v87
	v_cvt_pk_bf16_f32 v85, v85, v86
	v_mul_f32_e32 v86, 0xbfb8aa3b, v80
	v_exp_f32_e32 v86, v86
	s_nop 0
	v_add_f32_e32 v86, 1.0, v86
	v_div_scale_f32 v87, s[0:1], v86, v86, v80
	v_rcp_f32_e32 v90, v87
	s_nop 0
	v_fma_f32 v91, -v87, v90, 1.0
	v_fmac_f32_e32 v90, v91, v90
	v_div_scale_f32 v91, vcc, v80, v86, v80
	v_mul_f32_e32 v92, v91, v90
	v_fma_f32 v93, -v87, v92, v91
	v_fmac_f32_e32 v92, v93, v90
	v_fma_f32 v87, -v87, v92, v91
	v_div_fmas_f32 v87, v87, v90, v92
	v_div_fixup_f32 v80, v87, v86, v80
	v_mul_f32_e32 v86, 0xbfb8aa3b, v81
	v_exp_f32_e32 v86, v86
	s_nop 0
	v_add_f32_e32 v86, 1.0, v86
	v_div_scale_f32 v87, s[0:1], v86, v86, v81
	v_rcp_f32_e32 v90, v87
	s_nop 0
	v_fma_f32 v91, -v87, v90, 1.0
	v_fmac_f32_e32 v90, v91, v90
	v_div_scale_f32 v91, vcc, v81, v86, v81
	v_mul_f32_e32 v92, v91, v90
	v_fma_f32 v93, -v87, v92, v91
	v_fmac_f32_e32 v92, v93, v90
	v_fma_f32 v87, -v87, v92, v91
	v_div_fmas_f32 v87, v87, v90, v92
	v_div_fixup_f32 v81, v87, v86, v81
	v_lshlrev_b32_e32 v86, 16, v98
	v_sub_f32_e32 v86, v86, v105
	v_mul_f32_e32 v86, v86, v104
	v_mul_f32_e32 v80, v80, v86
	v_and_b32_e32 v86, 0xffff0000, v98
	v_sub_f32_e32 v86, v86, v105
	v_mul_f32_e32 v86, v86, v104
	v_mul_f32_e32 v81, v81, v86
	v_cvt_pk_bf16_f32 v86, v80, v81
	v_mul_f32_e32 v80, 0xbfb8aa3b, v82
	v_exp_f32_e32 v80, v80
	s_nop 0
	v_add_f32_e32 v80, 1.0, v80
	v_div_scale_f32 v81, s[0:1], v80, v80, v82
	v_rcp_f32_e32 v87, v81
	s_nop 0
	v_fma_f32 v90, -v81, v87, 1.0
	v_fmac_f32_e32 v87, v90, v87
	v_div_scale_f32 v90, vcc, v82, v80, v82
	v_mul_f32_e32 v91, v90, v87
	v_fma_f32 v92, -v81, v91, v90
	v_fmac_f32_e32 v91, v92, v87
	v_fma_f32 v81, -v81, v91, v90
	v_div_fmas_f32 v81, v81, v87, v91
	v_div_fixup_f32 v80, v81, v80, v82
	v_mul_f32_e32 v81, 0xbfb8aa3b, v83
	v_exp_f32_e32 v81, v81
	s_nop 0
	v_add_f32_e32 v81, 1.0, v81
	v_div_scale_f32 v82, s[0:1], v81, v81, v83
	v_rcp_f32_e32 v87, v82
	s_nop 0
	v_fma_f32 v90, -v82, v87, 1.0
	v_fmac_f32_e32 v87, v90, v87
	v_div_scale_f32 v90, vcc, v83, v81, v83
	v_mul_f32_e32 v91, v90, v87
	v_fma_f32 v92, -v82, v91, v90
	v_fmac_f32_e32 v91, v92, v87
	v_fma_f32 v82, -v82, v91, v90
	v_div_fmas_f32 v82, v82, v87, v91
	v_div_fixup_f32 v81, v82, v81, v83
	v_lshlrev_b32_e32 v82, 16, v99
	v_sub_f32_e32 v82, v82, v105
	v_mul_f32_e32 v82, v82, v104
	v_mul_f32_e32 v80, v80, v82
	v_and_b32_e32 v82, 0xffff0000, v99
	v_sub_f32_e32 v82, v82, v105
	v_mul_f32_e32 v82, v82, v104
	v_mul_f32_e32 v81, v81, v82
	v_cvt_pk_bf16_f32 v87, v80, v81
	v_add_u32_e32 v80, 48, v162
	v_ashrrev_i32_e32 v81, 31, v80
	v_lshlrev_b64 v[82:83], 9, v[80:81]
	v_lshl_add_u64 v[82:83], s[2:3], 0, v[82:83]
	v_lshl_add_u64 v[82:83], v[82:83], 0, s[48:49]
	global_store_dwordx4 v[88:89], v[84:87], off offset:256
	s_cmp_lg_u64 s[44:45], 0
	s_cbranch_scc0 .Llate_align_8
	s_barrier
; __device__ __forceinline__ unsigned cvt_pk_bf16(float lo, float hi) { unsigned r; asm volatile("v_cvt_pk_bf16_f32 %0, %1, %2" : "=v"(r) : "v"(lo), "v"(hi)); return r; }
; __device__ __forceinline__ float bf_lo(unsigned w) { return __uint_as_float(w << 16); }
; __device__ __forceinline__ float bf_hi(unsigned w) { return __uint_as_float(w & 0xffff0000u); }
;     __device__ __forceinline__ void operator()(const Acc& acc, const Unit& u, int wr, int wc, int fr, int fq) const {
;     ...
;         for (int ai = 0; ai < 2; ++ai)
; #pragma unroll
;             for (int m = 0; m < 4; ++m) {
;                 const int row_in = ai * HALF + wr * 64 + m * 16 + fr, s = u.pm * BM + row_in;
;                 const f32x4 tq = ((const f32x4*)(stats + ((size_t)s * 8 + h) * 8))[fq];
;                 const size_t off = (size_t)s * RV + u.pn * BM + wc * 32 + 8 * fq;
;                 const u32x4 o0 = *(const u32x4*)(O + off), o1 = *(const u32x4*)(O + off + HALF);
;                 float s1 = tq[0] + tq[2], s2 = tq[1] + tq[3];
;                 { const auto r1 = __builtin_amdgcn_permlane16_swap(__float_as_uint(s1), __float_as_uint(s1), false, false); s1 = __uint_as_float(r1[0]) + __uint_as_float(r1[1]);
;                   const auto r2 = __builtin_amdgcn_permlane16_swap(__float_as_uint(s2), __float_as_uint(s2), false, false); s2 = __uint_as_float(r2[0]) + __uint_as_float(r2[1]);
;                   const auto r3 = __builtin_amdgcn_permlane32_swap(__float_as_uint(s1), __float_as_uint(s1), false, false); s1 = __uint_as_float(r3[0]) + __uint_as_float(r3[1]);
;                   const auto r4 = __builtin_amdgcn_permlane32_swap(__float_as_uint(s2), __float_as_uint(s2), false, false); s2 = __uint_as_float(r4[0]) + __uint_as_float(r4[1]); }
;                 const float mu = s1 * (1.0f / 512.0f), var = fmaxf(s2 * (1.0f / 512.0f) - mu * mu, 0.f), rstd = rsqrtf(var + EPS);
; #pragma unroll
;                 for (int bj = 0; bj < 2; ++bj) { const u32x4 ov = bj == 0 ? o0 : o1; const unsigned ow[4] = {ov.x, ov.y, ov.z, ov.w}; unsigned r[4];
; #pragma unroll
;                     for (int p = 0; p < 4; ++p) { const f32x4 v = acc[ai][bj][m][p >> 1]; const float g0 = silu_f(v[(p & 1) * 2]), g1 = silu_f(v[(p & 1) * 2 + 1]);
;                         r[p] = cvt_pk_bf16(g0 * ((bf_lo(ow[p]) - mu) * rstd), g1 * ((bf_hi(ow[p]) - mu) * rstd)); }
.Llate_align_8:
	v_lshl_add_u64 v[82:83], v[82:83], 0, v[166:167]
	v_lshlrev_b64 v[80:81], 12, v[80:81]
	v_lshl_add_u64 v[80:81], v[80:81], 0, v[164:165]
	v_lshlrev_b64 v[90:91], 1, v[80:81]
	v_lshl_add_u64 v[80:81], s[4:5], 0, v[90:91]
	s_waitcnt vmcnt(2)
	v_mov_b32_e32 v92, v204
	v_mov_b32_e32 v93, v205
	v_mov_b32_e32 v94, v206
	v_mov_b32_e32 v95, v207
	v_mov_b32_e32 v84, v208
	v_mov_b32_e32 v85, v209
	v_mov_b32_e32 v86, v210
	v_mov_b32_e32 v87, v211
	v_mov_b32_e32 v80, v212
	v_mov_b32_e32 v81, v213
	v_mov_b32_e32 v82, v214
	v_mov_b32_e32 v83, v215
	v_add_u32_e32 v216, 0x80, v162
	v_ashrrev_i32_e32 v217, 31, v216
	v_lshlrev_b64 v[218:219], 9, v[216:217]
	v_lshl_add_u64 v[218:219], s[2:3], 0, v[218:219]
	v_lshl_add_u64 v[218:219], v[218:219], 0, s[48:49]
	v_lshl_add_u64 v[218:219], v[218:219], 0, v[166:167]
	global_load_dwordx4 v[192:195], v[218:219], off
	v_lshlrev_b64 v[216:217], 12, v[216:217]
	v_lshl_add_u64 v[216:217], v[216:217], 0, v[164:165]
	v_lshlrev_b64 v[216:217], 1, v[216:217]
	v_lshl_add_u64 v[216:217], s[4:5], 0, v[216:217]
	global_load_dwordx4 v[196:199], v[216:217], off
	global_load_dwordx4 v[200:203], v[216:217], off offset:256
	v_add_f32_e32 v88, v92, v94
	v_mov_b32_e32 v89, v88
	v_add_f32_e32 v92, v93, v95
	s_nop 0
	v_permlane16_swap_b32_e32 v88, v89
	v_add_f32_e32 v89, v88, v89
	v_mov_b32_e32 v88, v92
	s_nop 1
	v_permlane16_swap_b32_e32 v92, v88
	v_add_f32_e32 v88, v92, v88
	v_mov_b32_e32 v93, v89
	v_mov_b32_e32 v92, v88
	s_nop 0
	v_permlane32_swap_b32_e32 v89, v93
	v_permlane32_swap_b32_e32 v88, v92
	v_pk_add_f32 v[88:89], v[88:89], v[92:93]
	s_nop 0
	v_pk_mul_f32 v[88:89], v[88:89], s[8:9] op_sel_hi:[1,0]
	s_nop 0
	v_fma_f32 v88, -v89, v89, v88
	v_max_f32_e32 v88, 0, v88
	v_add_f32_e32 v88, 0x358637bd, v88
	v_cmp_gt_f32_e32 vcc, s73, v88
	v_mul_f32_e32 v92, 0x4b800000, v88
	s_nop 0
	v_cndmask_b32_e32 v88, v88, v92, vcc
	v_rsq_f32_e32 v88, v88
	s_nop 0
	v_mul_f32_e32 v92, 0x45800000, v88
	v_cndmask_b32_e32 v88, v88, v92, vcc
	v_mul_f32_e32 v92, 0xbfb8aa3b, v76
	v_exp_f32_e32 v92, v92
	s_nop 0
	v_add_f32_e32 v92, 1.0, v92
	v_div_scale_f32 v93, s[0:1], v92, v92, v76
	v_rcp_f32_e32 v94, v93
	s_nop 0
	v_fma_f32 v95, -v93, v94, 1.0
	v_fmac_f32_e32 v94, v95, v94
	v_div_scale_f32 v95, vcc, v76, v92, v76
	v_mul_f32_e32 v96, v95, v94
	v_fma_f32 v97, -v93, v96, v95
	v_fmac_f32_e32 v96, v97, v94
	v_fma_f32 v93, -v93, v96, v95
	v_div_fmas_f32 v93, v93, v94, v96
	v_div_fixup_f32 v76, v93, v92, v76
	v_mul_f32_e32 v92, 0xbfb8aa3b, v77
	v_exp_f32_e32 v92, v92
	s_nop 0
	v_add_f32_e32 v92, 1.0, v92
	v_div_scale_f32 v93, s[0:1], v92, v92, v77
	v_rcp_f32_e32 v94, v93
	s_nop 0
	v_fma_f32 v95, -v93, v94, 1.0
	v_fmac_f32_e32 v94, v95, v94
	v_div_scale_f32 v95, vcc, v77, v92, v77
	v_mul_f32_e32 v96, v95, v94
	v_fma_f32 v97, -v93, v96, v95
	v_fmac_f32_e32 v96, v97, v94
	v_fma_f32 v93, -v93, v96, v95
	v_div_fmas_f32 v93, v93, v94, v96
	v_div_fixup_f32 v77, v93, v92, v77
	v_lshlrev_b32_e32 v92, 16, v84
	v_and_b32_e32 v84, 0xffff0000, v84
	v_sub_f32_e32 v92, v92, v89
	v_sub_f32_e32 v84, v84, v89
	v_mul_f32_e32 v92, v92, v88
	v_mul_f32_e32 v84, v84, v88
	v_mul_f32_e32 v76, v76, v92
	v_mul_f32_e32 v77, v77, v84
	v_cvt_pk_bf16_f32 v76, v76, v77
	v_mul_f32_e32 v77, 0xbfb8aa3b, v78
	v_exp_f32_e32 v77, v77
	s_nop 0
	v_add_f32_e32 v77, 1.0, v77
	v_div_scale_f32 v84, s[0:1], v77, v77, v78
	v_rcp_f32_e32 v92, v84
	s_nop 0
	v_fma_f32 v93, -v84, v92, 1.0
	v_fmac_f32_e32 v92, v93, v92
	v_div_scale_f32 v93, vcc, v78, v77, v78
	v_mul_f32_e32 v94, v93, v92
	v_fma_f32 v95, -v84, v94, v93
	v_fmac_f32_e32 v94, v95, v92
	v_fma_f32 v84, -v84, v94, v93
	v_div_fmas_f32 v84, v84, v92, v94
	v_div_fixup_f32 v77, v84, v77, v78
	v_mul_f32_e32 v78, 0xbfb8aa3b, v79
	v_exp_f32_e32 v78, v78
	s_nop 0
	v_add_f32_e32 v78, 1.0, v78
	v_div_scale_f32 v84, s[0:1], v78, v78, v79
	v_rcp_f32_e32 v92, v84
	s_nop 0
	v_fma_f32 v93, -v84, v92, 1.0
	v_fmac_f32_e32 v92, v93, v92
	v_div_scale_f32 v93, vcc, v79, v78, v79
	v_mul_f32_e32 v94, v93, v92
	v_fma_f32 v95, -v84, v94, v93
	v_fmac_f32_e32 v94, v95, v92
	v_fma_f32 v84, -v84, v94, v93
	v_div_fmas_f32 v84, v84, v92, v94
	v_div_fixup_f32 v78, v84, v78, v79
	v_lshlrev_b32_e32 v79, 16, v85
	v_sub_f32_e32 v79, v79, v89
	v_mul_f32_e32 v79, v79, v88
	v_mul_f32_e32 v77, v77, v79
	v_and_b32_e32 v79, 0xffff0000, v85
	v_sub_f32_e32 v79, v79, v89
	v_mul_f32_e32 v79, v79, v88
	v_mul_f32_e32 v78, v78, v79
	v_cvt_pk_bf16_f32 v77, v77, v78
	v_mul_f32_e32 v78, 0xbfb8aa3b, v72
	v_exp_f32_e32 v78, v78
	s_nop 0
	v_add_f32_e32 v78, 1.0, v78
	v_div_scale_f32 v79, s[0:1], v78, v78, v72
	v_rcp_f32_e32 v84, v79
	s_nop 0
	v_fma_f32 v85, -v79, v84, 1.0
	v_fmac_f32_e32 v84, v85, v84
	v_div_scale_f32 v85, vcc, v72, v78, v72
	v_mul_f32_e32 v92, v85, v84
	v_fma_f32 v93, -v79, v92, v85
	v_fmac_f32_e32 v92, v93, v84
	v_fma_f32 v79, -v79, v92, v85
	v_div_fmas_f32 v79, v79, v84, v92
	v_div_fixup_f32 v72, v79, v78, v72
	v_mul_f32_e32 v78, 0xbfb8aa3b, v73
	v_exp_f32_e32 v78, v78
	s_nop 0
	v_add_f32_e32 v78, 1.0, v78
	v_div_scale_f32 v79, s[0:1], v78, v78, v73
	v_rcp_f32_e32 v84, v79
	s_nop 0
	v_fma_f32 v85, -v79, v84, 1.0
	v_fmac_f32_e32 v84, v85, v84
	v_div_scale_f32 v85, vcc, v73, v78, v73
	v_mul_f32_e32 v92, v85, v84
	v_fma_f32 v93, -v79, v92, v85
	v_fmac_f32_e32 v92, v93, v84
	v_fma_f32 v79, -v79, v92, v85
	v_div_fmas_f32 v79, v79, v84, v92
	v_div_fixup_f32 v73, v79, v78, v73
	v_lshlrev_b32_e32 v78, 16, v86
	v_sub_f32_e32 v78, v78, v89
	v_mul_f32_e32 v78, v78, v88
	v_mul_f32_e32 v72, v72, v78
	v_and_b32_e32 v78, 0xffff0000, v86
	v_sub_f32_e32 v78, v78, v89
	v_mul_f32_e32 v78, v78, v88
	v_mul_f32_e32 v73, v73, v78
	v_cvt_pk_bf16_f32 v78, v72, v73
	v_mul_f32_e32 v72, 0xbfb8aa3b, v74
; __device__ __forceinline__ unsigned cvt_pk_bf16(float lo, float hi) { unsigned r; asm volatile("v_cvt_pk_bf16_f32 %0, %1, %2" : "=v"(r) : "v"(lo), "v"(hi)); return r; }
; __device__ __forceinline__ float bf_lo(unsigned w) { return __uint_as_float(w << 16); }
; __device__ __forceinline__ float bf_hi(unsigned w) { return __uint_as_float(w & 0xffff0000u); }
; __device__ __forceinline__ float silu_f(float v) { return v / (1.0f + __expf(-v)); }
;     __device__ __forceinline__ void operator()(const Acc& acc, const Unit& u, int wr, int wc, int fr, int fq) const {
;     ...
; #pragma unroll
;                 for (int bj = 0; bj < 2; ++bj) { const u32x4 ov = bj == 0 ? o0 : o1; const unsigned ow[4] = {ov.x, ov.y, ov.z, ov.w}; unsigned r[4];
; #pragma unroll
;                     for (int p = 0; p < 4; ++p) { const f32x4 v = acc[ai][bj][m][p >> 1]; const float g0 = silu_f(v[(p & 1) * 2]), g1 = silu_f(v[(p & 1) * 2 + 1]);
;                         r[p] = cvt_pk_bf16(g0 * ((bf_lo(ow[p]) - mu) * rstd), g1 * ((bf_hi(ow[p]) - mu) * rstd)); }
;                     *(u32x4*)(U + off + bj * HALF) = (u32x4){r[0], r[1], r[2], r[3]}; }
	v_exp_f32_e32 v72, v72
	s_nop 0
	v_add_f32_e32 v72, 1.0, v72
	v_div_scale_f32 v73, s[0:1], v72, v72, v74
	v_rcp_f32_e32 v79, v73
	s_nop 0
	v_fma_f32 v84, -v73, v79, 1.0
	v_fmac_f32_e32 v79, v84, v79
	v_div_scale_f32 v84, vcc, v74, v72, v74
	v_mul_f32_e32 v85, v84, v79
	v_fma_f32 v86, -v73, v85, v84
	v_fmac_f32_e32 v85, v86, v79
	v_fma_f32 v73, -v73, v85, v84
	v_div_fmas_f32 v73, v73, v79, v85
	v_div_fixup_f32 v72, v73, v72, v74
	v_mul_f32_e32 v73, 0xbfb8aa3b, v75
	v_exp_f32_e32 v73, v73
	s_nop 0
	v_add_f32_e32 v73, 1.0, v73
	v_div_scale_f32 v74, s[0:1], v73, v73, v75
	v_rcp_f32_e32 v79, v74
	s_nop 0
	v_fma_f32 v84, -v74, v79, 1.0
	v_fmac_f32_e32 v79, v84, v79
	v_div_scale_f32 v84, vcc, v75, v73, v75
	v_mul_f32_e32 v85, v84, v79
	v_fma_f32 v86, -v74, v85, v84
	v_fmac_f32_e32 v85, v86, v79
	v_fma_f32 v74, -v74, v85, v84
	v_div_fmas_f32 v74, v74, v79, v85
	v_div_fixup_f32 v73, v74, v73, v75
	v_lshlrev_b32_e32 v74, 16, v87
	v_sub_f32_e32 v74, v74, v89
	v_mul_f32_e32 v74, v74, v88
	v_mul_f32_e32 v72, v72, v74
	v_and_b32_e32 v74, 0xffff0000, v87
	v_sub_f32_e32 v74, v74, v89
	v_mul_f32_e32 v74, v74, v88
	v_mul_f32_e32 v73, v73, v74
	v_mul_f32_e32 v74, 0xbfb8aa3b, v68
	v_exp_f32_e32 v74, v74
	v_cvt_pk_bf16_f32 v79, v72, v73
	v_lshl_add_u64 v[72:73], s[6:7], 0, v[90:91]
	global_store_dwordx4 v[72:73], v[76:79], off
	v_add_f32_e32 v74, 1.0, v74
	v_div_scale_f32 v75, s[0:1], v74, v74, v68
	v_rcp_f32_e32 v76, v75
	s_nop 0
	v_fma_f32 v77, -v75, v76, 1.0
	v_fmac_f32_e32 v76, v77, v76
	v_div_scale_f32 v77, vcc, v68, v74, v68
	v_mul_f32_e32 v78, v77, v76
	v_fma_f32 v79, -v75, v78, v77
	v_fmac_f32_e32 v78, v79, v76
	v_fma_f32 v75, -v75, v78, v77
	v_div_fmas_f32 v75, v75, v76, v78
	v_div_fixup_f32 v68, v75, v74, v68
	v_mul_f32_e32 v74, 0xbfb8aa3b, v69
	v_exp_f32_e32 v74, v74
	s_nop 0
	v_add_f32_e32 v74, 1.0, v74
	v_div_scale_f32 v75, s[0:1], v74, v74, v69
	v_rcp_f32_e32 v76, v75
	s_nop 0
	v_fma_f32 v77, -v75, v76, 1.0
	v_fmac_f32_e32 v76, v77, v76
	v_div_scale_f32 v77, vcc, v69, v74, v69
	v_mul_f32_e32 v78, v77, v76
	v_fma_f32 v79, -v75, v78, v77
	v_fmac_f32_e32 v78, v79, v76
	v_fma_f32 v75, -v75, v78, v77
	v_div_fmas_f32 v75, v75, v76, v78
	v_div_fixup_f32 v69, v75, v74, v69
	v_lshlrev_b32_e32 v74, 16, v80
	v_sub_f32_e32 v74, v74, v89
	v_mul_f32_e32 v74, v74, v88
	v_mul_f32_e32 v68, v68, v74
	v_and_b32_e32 v74, 0xffff0000, v80
	v_sub_f32_e32 v74, v74, v89
	v_mul_f32_e32 v74, v74, v88
	v_mul_f32_e32 v69, v69, v74
	v_cvt_pk_bf16_f32 v68, v68, v69
	v_mul_f32_e32 v69, 0xbfb8aa3b, v70
	v_exp_f32_e32 v69, v69
	s_nop 0
	v_add_f32_e32 v69, 1.0, v69
	v_div_scale_f32 v74, s[0:1], v69, v69, v70
	v_rcp_f32_e32 v75, v74
	s_nop 0
	v_fma_f32 v76, -v74, v75, 1.0
	v_fmac_f32_e32 v75, v76, v75
	v_div_scale_f32 v76, vcc, v70, v69, v70
	v_mul_f32_e32 v77, v76, v75
	v_fma_f32 v78, -v74, v77, v76
	v_fmac_f32_e32 v77, v78, v75
	v_fma_f32 v74, -v74, v77, v76
	v_div_fmas_f32 v74, v74, v75, v77
	v_div_fixup_f32 v69, v74, v69, v70
	v_mul_f32_e32 v70, 0xbfb8aa3b, v71
	v_exp_f32_e32 v70, v70
	s_nop 0
	v_add_f32_e32 v70, 1.0, v70
	v_div_scale_f32 v74, s[0:1], v70, v70, v71
	v_rcp_f32_e32 v75, v74
	s_nop 0
	v_fma_f32 v76, -v74, v75, 1.0
	v_fmac_f32_e32 v75, v76, v75
	v_div_scale_f32 v76, vcc, v71, v70, v71
	v_mul_f32_e32 v77, v76, v75
	v_fma_f32 v78, -v74, v77, v76
	v_fmac_f32_e32 v77, v78, v75
	v_fma_f32 v74, -v74, v77, v76
	v_div_fmas_f32 v74, v74, v75, v77
	v_div_fixup_f32 v70, v74, v70, v71
	v_lshlrev_b32_e32 v71, 16, v81
	v_sub_f32_e32 v71, v71, v89
	v_mul_f32_e32 v71, v71, v88
	v_mul_f32_e32 v69, v69, v71
	v_and_b32_e32 v71, 0xffff0000, v81
	v_sub_f32_e32 v71, v71, v89
	v_mul_f32_e32 v71, v71, v88
	v_mul_f32_e32 v70, v70, v71
	v_cvt_pk_bf16_f32 v69, v69, v70
	v_mul_f32_e32 v70, 0xbfb8aa3b, v64
	v_exp_f32_e32 v70, v70
	s_nop 0
	v_add_f32_e32 v70, 1.0, v70
	v_div_scale_f32 v71, s[0:1], v70, v70, v64
	v_rcp_f32_e32 v74, v71
	s_nop 0
	v_fma_f32 v75, -v71, v74, 1.0
	v_fmac_f32_e32 v74, v75, v74
	v_div_scale_f32 v75, vcc, v64, v70, v64
	v_mul_f32_e32 v76, v75, v74
	v_fma_f32 v77, -v71, v76, v75
	v_fmac_f32_e32 v76, v77, v74
	v_fma_f32 v71, -v71, v76, v75
	v_div_fmas_f32 v71, v71, v74, v76
	v_div_fixup_f32 v64, v71, v70, v64
	v_mul_f32_e32 v70, 0xbfb8aa3b, v65
	v_exp_f32_e32 v70, v70
	s_nop 0
	v_add_f32_e32 v70, 1.0, v70
	v_div_scale_f32 v71, s[0:1], v70, v70, v65
	v_rcp_f32_e32 v74, v71
	s_nop 0
	v_fma_f32 v75, -v71, v74, 1.0
	v_fmac_f32_e32 v74, v75, v74
	v_div_scale_f32 v75, vcc, v65, v70, v65
	v_mul_f32_e32 v76, v75, v74
	v_fma_f32 v77, -v71, v76, v75
	v_fmac_f32_e32 v76, v77, v74
	v_fma_f32 v71, -v71, v76, v75
	v_div_fmas_f32 v71, v71, v74, v76
	v_div_fixup_f32 v65, v71, v70, v65
	v_lshlrev_b32_e32 v70, 16, v82
	v_sub_f32_e32 v70, v70, v89
	v_mul_f32_e32 v70, v70, v88
	v_mul_f32_e32 v64, v64, v70
	v_and_b32_e32 v70, 0xffff0000, v82
	v_sub_f32_e32 v70, v70, v89
	v_mul_f32_e32 v70, v70, v88
	v_mul_f32_e32 v65, v65, v70
	v_cvt_pk_bf16_f32 v70, v64, v65
	v_mul_f32_e32 v64, 0xbfb8aa3b, v66
	v_exp_f32_e32 v64, v64
	s_nop 0
	v_add_f32_e32 v64, 1.0, v64
	v_div_scale_f32 v65, s[0:1], v64, v64, v66
	v_rcp_f32_e32 v71, v65
	s_nop 0
	v_fma_f32 v74, -v65, v71, 1.0
	v_fmac_f32_e32 v71, v74, v71
	v_div_scale_f32 v74, vcc, v66, v64, v66
	v_mul_f32_e32 v75, v74, v71
	v_fma_f32 v76, -v65, v75, v74
	v_fmac_f32_e32 v75, v76, v71
	v_fma_f32 v65, -v65, v75, v74
	v_div_fmas_f32 v65, v65, v71, v75
	v_div_fixup_f32 v64, v65, v64, v66
	v_mul_f32_e32 v65, 0xbfb8aa3b, v67
	v_exp_f32_e32 v65, v65
	s_nop 0
	v_add_f32_e32 v65, 1.0, v65
	v_div_scale_f32 v66, s[0:1], v65, v65, v67
	v_rcp_f32_e32 v71, v66
	s_nop 0
	v_fma_f32 v74, -v66, v71, 1.0
	v_fmac_f32_e32 v71, v74, v71
	v_div_scale_f32 v74, vcc, v67, v65, v67
	v_mul_f32_e32 v75, v74, v71
	v_fma_f32 v76, -v66, v75, v74
	v_fmac_f32_e32 v75, v76, v71
	v_fma_f32 v66, -v66, v75, v74
	v_div_fmas_f32 v66, v66, v71, v75
	v_div_fixup_f32 v65, v66, v65, v67
	v_lshlrev_b32_e32 v66, 16, v83
	v_sub_f32_e32 v66, v66, v89
	v_mul_f32_e32 v66, v66, v88
	v_mul_f32_e32 v64, v64, v66
	v_and_b32_e32 v66, 0xffff0000, v83
	v_sub_f32_e32 v66, v66, v89
	v_mul_f32_e32 v66, v66, v88
	v_mul_f32_e32 v65, v65, v66
	v_cvt_pk_bf16_f32 v71, v64, v65
	v_add_u32_e32 v64, 0x80, v162
	v_ashrrev_i32_e32 v65, 31, v64
	v_lshlrev_b64 v[66:67], 9, v[64:65]
	v_lshl_add_u64 v[66:67], s[2:3], 0, v[66:67]
	v_lshl_add_u64 v[66:67], v[66:67], 0, s[48:49]
	global_store_dwordx4 v[72:73], v[68:71], off offset:256
	v_lshl_add_u64 v[66:67], v[66:67], 0, v[166:167]
	v_lshlrev_b64 v[64:65], 12, v[64:65]
	v_lshl_add_u64 v[64:65], v[64:65], 0, v[164:165]
	v_lshlrev_b64 v[74:75], 1, v[64:65]
	v_lshl_add_u64 v[64:65], s[4:5], 0, v[74:75]
	s_waitcnt vmcnt(2)
; __device__ __forceinline__ unsigned cvt_pk_bf16(float lo, float hi) { unsigned r; asm volatile("v_cvt_pk_bf16_f32 %0, %1, %2" : "=v"(r) : "v"(lo), "v"(hi)); return r; }
; __device__ __forceinline__ float bf_lo(unsigned w) { return __uint_as_float(w << 16); }
; __device__ __forceinline__ float bf_hi(unsigned w) { return __uint_as_float(w & 0xffff0000u); }
;     __device__ __forceinline__ void operator()(const Acc& acc, const Unit& u, int wr, int wc, int fr, int fq) const {
;     ...
;                 const int row_in = ai * HALF + wr * 64 + m * 16 + fr, s = u.pm * BM + row_in;
;                 const f32x4 tq = ((const f32x4*)(stats + ((size_t)s * 8 + h) * 8))[fq];
;                 const size_t off = (size_t)s * RV + u.pn * BM + wc * 32 + 8 * fq;
;                 const u32x4 o0 = *(const u32x4*)(O + off), o1 = *(const u32x4*)(O + off + HALF);
;                 float s1 = tq[0] + tq[2], s2 = tq[1] + tq[3];
;                 { const auto r1 = __builtin_amdgcn_permlane16_swap(__float_as_uint(s1), __float_as_uint(s1), false, false); s1 = __uint_as_float(r1[0]) + __uint_as_float(r1[1]);
;                   const auto r2 = __builtin_amdgcn_permlane16_swap(__float_as_uint(s2), __float_as_uint(s2), false, false); s2 = __uint_as_float(r2[0]) + __uint_as_float(r2[1]);
;                   const auto r3 = __builtin_amdgcn_permlane32_swap(__float_as_uint(s1), __float_as_uint(s1), false, false); s1 = __uint_as_float(r3[0]) + __uint_as_float(r3[1]);
;                   const auto r4 = __builtin_amdgcn_permlane32_swap(__float_as_uint(s2), __float_as_uint(s2), false, false); s2 = __uint_as_float(r4[0]) + __uint_as_float(r4[1]); }
;                 const float mu = s1 * (1.0f / 512.0f), var = fmaxf(s2 * (1.0f / 512.0f) - mu * mu, 0.f), rstd = rsqrtf(var + EPS);
; #pragma unroll
;                 for (int bj = 0; bj < 2; ++bj) { const u32x4 ov = bj == 0 ? o0 : o1; const unsigned ow[4] = {ov.x, ov.y, ov.z, ov.w}; unsigned r[4];
; #pragma unroll
;                     for (int p = 0; p < 4; ++p) { const f32x4 v = acc[ai][bj][m][p >> 1]; const float g0 = silu_f(v[(p & 1) * 2]), g1 = silu_f(v[(p & 1) * 2 + 1]);
;                         r[p] = cvt_pk_bf16(g0 * ((bf_lo(ow[p]) - mu) * rstd), g1 * ((bf_hi(ow[p]) - mu) * rstd)); }
;                     *(u32x4*)(U + off + bj * HALF) = (u32x4){r[0], r[1], r[2], r[3]}; }
	v_mov_b32_e32 v76, v192
	v_mov_b32_e32 v77, v193
	v_mov_b32_e32 v78, v194
	v_mov_b32_e32 v79, v195
	v_mov_b32_e32 v68, v196
	v_mov_b32_e32 v69, v197
	v_mov_b32_e32 v70, v198
	v_mov_b32_e32 v71, v199
	v_mov_b32_e32 v64, v200
	v_mov_b32_e32 v65, v201
	v_mov_b32_e32 v66, v202
	v_mov_b32_e32 v67, v203
	v_add_u32_e32 v216, 0x90, v162
	v_ashrrev_i32_e32 v217, 31, v216
	v_lshlrev_b64 v[218:219], 9, v[216:217]
	v_lshl_add_u64 v[218:219], s[2:3], 0, v[218:219]
	v_lshl_add_u64 v[218:219], v[218:219], 0, s[48:49]
	v_lshl_add_u64 v[218:219], v[218:219], 0, v[166:167]
	global_load_dwordx4 v[204:207], v[218:219], off
	v_lshlrev_b64 v[216:217], 12, v[216:217]
	v_lshl_add_u64 v[216:217], v[216:217], 0, v[164:165]
	v_lshlrev_b64 v[216:217], 1, v[216:217]
	v_lshl_add_u64 v[216:217], s[4:5], 0, v[216:217]
	global_load_dwordx4 v[208:211], v[216:217], off
	global_load_dwordx4 v[212:215], v[216:217], off offset:256
	v_add_f32_e32 v72, v76, v78
	v_mov_b32_e32 v73, v72
	v_add_f32_e32 v76, v77, v79
	s_nop 0
	v_permlane16_swap_b32_e32 v72, v73
	v_add_f32_e32 v73, v72, v73
	v_mov_b32_e32 v72, v76
	s_nop 1
	v_permlane16_swap_b32_e32 v76, v72
	v_add_f32_e32 v72, v76, v72
	v_mov_b32_e32 v77, v73
	v_mov_b32_e32 v76, v72
	s_nop 0
	v_permlane32_swap_b32_e32 v73, v77
	v_permlane32_swap_b32_e32 v72, v76
	v_pk_add_f32 v[72:73], v[72:73], v[76:77]
	s_nop 0
	v_pk_mul_f32 v[72:73], v[72:73], s[8:9] op_sel_hi:[1,0]
	s_nop 0
	v_fma_f32 v72, -v73, v73, v72
	v_max_f32_e32 v72, 0, v72
	v_add_f32_e32 v72, 0x358637bd, v72
	v_cmp_gt_f32_e32 vcc, s73, v72
	v_mul_f32_e32 v76, 0x4b800000, v72
	s_nop 0
	v_cndmask_b32_e32 v72, v72, v76, vcc
	v_rsq_f32_e32 v72, v72
	s_nop 0
	v_mul_f32_e32 v76, 0x45800000, v72
	v_cndmask_b32_e32 v72, v72, v76, vcc
	v_mul_f32_e32 v76, 0xbfb8aa3b, v60
	v_exp_f32_e32 v76, v76
	s_nop 0
	v_add_f32_e32 v76, 1.0, v76
	v_div_scale_f32 v77, s[0:1], v76, v76, v60
	v_rcp_f32_e32 v78, v77
	s_nop 0
	v_fma_f32 v79, -v77, v78, 1.0
	v_fmac_f32_e32 v78, v79, v78
	v_div_scale_f32 v79, vcc, v60, v76, v60
	v_mul_f32_e32 v80, v79, v78
	v_fma_f32 v81, -v77, v80, v79
	v_fmac_f32_e32 v80, v81, v78
	v_fma_f32 v77, -v77, v80, v79
	v_div_fmas_f32 v77, v77, v78, v80
	v_div_fixup_f32 v60, v77, v76, v60
	v_mul_f32_e32 v76, 0xbfb8aa3b, v61
	v_exp_f32_e32 v76, v76
	s_nop 0
	v_add_f32_e32 v76, 1.0, v76
	v_div_scale_f32 v77, s[0:1], v76, v76, v61
	v_rcp_f32_e32 v78, v77
	s_nop 0
	v_fma_f32 v79, -v77, v78, 1.0
	v_fmac_f32_e32 v78, v79, v78
	v_div_scale_f32 v79, vcc, v61, v76, v61
	v_mul_f32_e32 v80, v79, v78
	v_fma_f32 v81, -v77, v80, v79
	v_fmac_f32_e32 v80, v81, v78
	v_fma_f32 v77, -v77, v80, v79
	v_div_fmas_f32 v77, v77, v78, v80
	v_div_fixup_f32 v61, v77, v76, v61
	v_lshlrev_b32_e32 v76, 16, v68
	v_and_b32_e32 v68, 0xffff0000, v68
	v_sub_f32_e32 v76, v76, v73
	v_sub_f32_e32 v68, v68, v73
	v_mul_f32_e32 v76, v76, v72
	v_mul_f32_e32 v68, v68, v72
	v_mul_f32_e32 v60, v60, v76
	v_mul_f32_e32 v61, v61, v68
	v_cvt_pk_bf16_f32 v60, v60, v61
	v_mul_f32_e32 v61, 0xbfb8aa3b, v62
	v_exp_f32_e32 v61, v61
	s_nop 0
	v_add_f32_e32 v61, 1.0, v61
	v_div_scale_f32 v68, s[0:1], v61, v61, v62
	v_rcp_f32_e32 v76, v68
	s_nop 0
	v_fma_f32 v77, -v68, v76, 1.0
	v_fmac_f32_e32 v76, v77, v76
	v_div_scale_f32 v77, vcc, v62, v61, v62
	v_mul_f32_e32 v78, v77, v76
	v_fma_f32 v79, -v68, v78, v77
	v_fmac_f32_e32 v78, v79, v76
	v_fma_f32 v68, -v68, v78, v77
	v_div_fmas_f32 v68, v68, v76, v78
	v_div_fixup_f32 v61, v68, v61, v62
	v_mul_f32_e32 v62, 0xbfb8aa3b, v63
	v_exp_f32_e32 v62, v62
	s_nop 0
	v_add_f32_e32 v62, 1.0, v62
	v_div_scale_f32 v68, s[0:1], v62, v62, v63
	v_rcp_f32_e32 v76, v68
	s_nop 0
	v_fma_f32 v77, -v68, v76, 1.0
	v_fmac_f32_e32 v76, v77, v76
	v_div_scale_f32 v77, vcc, v63, v62, v63
	v_mul_f32_e32 v78, v77, v76
	v_fma_f32 v79, -v68, v78, v77
	v_fmac_f32_e32 v78, v79, v76
	v_fma_f32 v68, -v68, v78, v77
	v_div_fmas_f32 v68, v68, v76, v78
	v_div_fixup_f32 v62, v68, v62, v63
	v_lshlrev_b32_e32 v63, 16, v69
	v_sub_f32_e32 v63, v63, v73
	v_mul_f32_e32 v63, v63, v72
	v_mul_f32_e32 v61, v61, v63
	v_and_b32_e32 v63, 0xffff0000, v69
	v_sub_f32_e32 v63, v63, v73
	v_mul_f32_e32 v63, v63, v72
	v_mul_f32_e32 v62, v62, v63
	v_cvt_pk_bf16_f32 v61, v61, v62
	v_mul_f32_e32 v62, 0xbfb8aa3b, v56
	v_exp_f32_e32 v62, v62
	s_nop 0
	v_add_f32_e32 v62, 1.0, v62
	v_div_scale_f32 v63, s[0:1], v62, v62, v56
	v_rcp_f32_e32 v68, v63
	s_nop 0
	v_fma_f32 v69, -v63, v68, 1.0
	v_fmac_f32_e32 v68, v69, v68
	v_div_scale_f32 v69, vcc, v56, v62, v56
	v_mul_f32_e32 v76, v69, v68
	v_fma_f32 v77, -v63, v76, v69
	v_fmac_f32_e32 v76, v77, v68
	v_fma_f32 v63, -v63, v76, v69
	v_div_fmas_f32 v63, v63, v68, v76
	v_div_fixup_f32 v56, v63, v62, v56
	v_mul_f32_e32 v62, 0xbfb8aa3b, v57
	v_exp_f32_e32 v62, v62
	s_nop 0
	v_add_f32_e32 v62, 1.0, v62
	v_div_scale_f32 v63, s[0:1], v62, v62, v57
	v_rcp_f32_e32 v68, v63
	s_nop 0
	v_fma_f32 v69, -v63, v68, 1.0
	v_fmac_f32_e32 v68, v69, v68
	v_div_scale_f32 v69, vcc, v57, v62, v57
	v_mul_f32_e32 v76, v69, v68
	v_fma_f32 v77, -v63, v76, v69
	v_fmac_f32_e32 v76, v77, v68
	v_fma_f32 v63, -v63, v76, v69
	v_div_fmas_f32 v63, v63, v68, v76
	v_div_fixup_f32 v57, v63, v62, v57
	v_lshlrev_b32_e32 v62, 16, v70
	v_sub_f32_e32 v62, v62, v73
	v_mul_f32_e32 v62, v62, v72
	v_mul_f32_e32 v56, v56, v62
	v_and_b32_e32 v62, 0xffff0000, v70
	v_sub_f32_e32 v62, v62, v73
	v_mul_f32_e32 v62, v62, v72
	v_mul_f32_e32 v57, v57, v62
	v_cvt_pk_bf16_f32 v62, v56, v57
	v_mul_f32_e32 v56, 0xbfb8aa3b, v58
	v_exp_f32_e32 v56, v56
	s_nop 0
	v_add_f32_e32 v56, 1.0, v56
	v_div_scale_f32 v57, s[0:1], v56, v56, v58
	v_rcp_f32_e32 v63, v57
	s_nop 0
	v_fma_f32 v68, -v57, v63, 1.0
	v_fmac_f32_e32 v63, v68, v63
	v_div_scale_f32 v68, vcc, v58, v56, v58
; __device__ __forceinline__ unsigned cvt_pk_bf16(float lo, float hi) { unsigned r; asm volatile("v_cvt_pk_bf16_f32 %0, %1, %2" : "=v"(r) : "v"(lo), "v"(hi)); return r; }
; __device__ __forceinline__ float bf_lo(unsigned w) { return __uint_as_float(w << 16); }
; __device__ __forceinline__ float bf_hi(unsigned w) { return __uint_as_float(w & 0xffff0000u); }
; __device__ __forceinline__ float silu_f(float v) { return v / (1.0f + __expf(-v)); }
;     __device__ __forceinline__ void operator()(const Acc& acc, const Unit& u, int wr, int wc, int fr, int fq) const {
;     ...
;                 const float mu = s1 * (1.0f / 512.0f), var = fmaxf(s2 * (1.0f / 512.0f) - mu * mu, 0.f), rstd = rsqrtf(var + EPS);
; #pragma unroll
;                 for (int bj = 0; bj < 2; ++bj) { const u32x4 ov = bj == 0 ? o0 : o1; const unsigned ow[4] = {ov.x, ov.y, ov.z, ov.w}; unsigned r[4];
; #pragma unroll
;                     for (int p = 0; p < 4; ++p) { const f32x4 v = acc[ai][bj][m][p >> 1]; const float g0 = silu_f(v[(p & 1) * 2]), g1 = silu_f(v[(p & 1) * 2 + 1]);
;                         r[p] = cvt_pk_bf16(g0 * ((bf_lo(ow[p]) - mu) * rstd), g1 * ((bf_hi(ow[p]) - mu) * rstd)); }
;                     *(u32x4*)(U + off + bj * HALF) = (u32x4){r[0], r[1], r[2], r[3]}; }
	v_mul_f32_e32 v69, v68, v63
	v_fma_f32 v70, -v57, v69, v68
	v_fmac_f32_e32 v69, v70, v63
	v_fma_f32 v57, -v57, v69, v68
	v_div_fmas_f32 v57, v57, v63, v69
	v_div_fixup_f32 v56, v57, v56, v58
	v_mul_f32_e32 v57, 0xbfb8aa3b, v59
	v_exp_f32_e32 v57, v57
	s_nop 0
	v_add_f32_e32 v57, 1.0, v57
	v_div_scale_f32 v58, s[0:1], v57, v57, v59
	v_rcp_f32_e32 v63, v58
	s_nop 0
	v_fma_f32 v68, -v58, v63, 1.0
	v_fmac_f32_e32 v63, v68, v63
	v_div_scale_f32 v68, vcc, v59, v57, v59
	v_mul_f32_e32 v69, v68, v63
	v_fma_f32 v70, -v58, v69, v68
	v_fmac_f32_e32 v69, v70, v63
	v_fma_f32 v58, -v58, v69, v68
	v_div_fmas_f32 v58, v58, v63, v69
	v_div_fixup_f32 v57, v58, v57, v59
	v_lshlrev_b32_e32 v58, 16, v71
	v_sub_f32_e32 v58, v58, v73
	v_mul_f32_e32 v58, v58, v72
	v_mul_f32_e32 v56, v56, v58
	v_and_b32_e32 v58, 0xffff0000, v71
	v_sub_f32_e32 v58, v58, v73
	v_mul_f32_e32 v58, v58, v72
	v_mul_f32_e32 v57, v57, v58
	v_mul_f32_e32 v58, 0xbfb8aa3b, v52
	v_exp_f32_e32 v58, v58
	v_cvt_pk_bf16_f32 v63, v56, v57
	v_lshl_add_u64 v[56:57], s[6:7], 0, v[74:75]
	global_store_dwordx4 v[56:57], v[60:63], off
	v_add_f32_e32 v58, 1.0, v58
	v_div_scale_f32 v59, s[0:1], v58, v58, v52
	v_rcp_f32_e32 v60, v59
	s_nop 0
	v_fma_f32 v61, -v59, v60, 1.0
	v_fmac_f32_e32 v60, v61, v60
	v_div_scale_f32 v61, vcc, v52, v58, v52
	v_mul_f32_e32 v62, v61, v60
	v_fma_f32 v63, -v59, v62, v61
	v_fmac_f32_e32 v62, v63, v60
	v_fma_f32 v59, -v59, v62, v61
	v_div_fmas_f32 v59, v59, v60, v62
	v_div_fixup_f32 v52, v59, v58, v52
	v_mul_f32_e32 v58, 0xbfb8aa3b, v53
	v_exp_f32_e32 v58, v58
	s_nop 0
	v_add_f32_e32 v58, 1.0, v58
	v_div_scale_f32 v59, s[0:1], v58, v58, v53
	v_rcp_f32_e32 v60, v59
	s_nop 0
	v_fma_f32 v61, -v59, v60, 1.0
	v_fmac_f32_e32 v60, v61, v60
	v_div_scale_f32 v61, vcc, v53, v58, v53
	v_mul_f32_e32 v62, v61, v60
	v_fma_f32 v63, -v59, v62, v61
	v_fmac_f32_e32 v62, v63, v60
	v_fma_f32 v59, -v59, v62, v61
	v_div_fmas_f32 v59, v59, v60, v62
	v_div_fixup_f32 v53, v59, v58, v53
	v_lshlrev_b32_e32 v58, 16, v64
	v_sub_f32_e32 v58, v58, v73
	v_mul_f32_e32 v58, v58, v72
	v_mul_f32_e32 v52, v52, v58
	v_and_b32_e32 v58, 0xffff0000, v64
	v_sub_f32_e32 v58, v58, v73
	v_mul_f32_e32 v58, v58, v72
	v_mul_f32_e32 v53, v53, v58
	v_cvt_pk_bf16_f32 v52, v52, v53
	v_mul_f32_e32 v53, 0xbfb8aa3b, v54
	v_exp_f32_e32 v53, v53
	s_nop 0
	v_add_f32_e32 v53, 1.0, v53
	v_div_scale_f32 v58, s[0:1], v53, v53, v54
	v_rcp_f32_e32 v59, v58
	s_nop 0
	v_fma_f32 v60, -v58, v59, 1.0
	v_fmac_f32_e32 v59, v60, v59
	v_div_scale_f32 v60, vcc, v54, v53, v54
	v_mul_f32_e32 v61, v60, v59
	v_fma_f32 v62, -v58, v61, v60
	v_fmac_f32_e32 v61, v62, v59
	v_fma_f32 v58, -v58, v61, v60
	v_div_fmas_f32 v58, v58, v59, v61
	v_div_fixup_f32 v53, v58, v53, v54
	v_mul_f32_e32 v54, 0xbfb8aa3b, v55
	v_exp_f32_e32 v54, v54
	s_nop 0
	v_add_f32_e32 v54, 1.0, v54
	v_div_scale_f32 v58, s[0:1], v54, v54, v55
	v_rcp_f32_e32 v59, v58
	s_nop 0
	v_fma_f32 v60, -v58, v59, 1.0
	v_fmac_f32_e32 v59, v60, v59
	v_div_scale_f32 v60, vcc, v55, v54, v55
	v_mul_f32_e32 v61, v60, v59
	v_fma_f32 v62, -v58, v61, v60
	v_fmac_f32_e32 v61, v62, v59
	v_fma_f32 v58, -v58, v61, v60
	v_div_fmas_f32 v58, v58, v59, v61
	v_div_fixup_f32 v54, v58, v54, v55
	v_lshlrev_b32_e32 v55, 16, v65
	v_sub_f32_e32 v55, v55, v73
	v_mul_f32_e32 v55, v55, v72
	v_mul_f32_e32 v53, v53, v55
	v_and_b32_e32 v55, 0xffff0000, v65
	v_sub_f32_e32 v55, v55, v73
	v_mul_f32_e32 v55, v55, v72
	v_mul_f32_e32 v54, v54, v55
	v_cvt_pk_bf16_f32 v53, v53, v54
	v_mul_f32_e32 v54, 0xbfb8aa3b, v48
	v_exp_f32_e32 v54, v54
	s_nop 0
	v_add_f32_e32 v54, 1.0, v54
	v_div_scale_f32 v55, s[0:1], v54, v54, v48
	v_rcp_f32_e32 v58, v55
	s_nop 0
	v_fma_f32 v59, -v55, v58, 1.0
	v_fmac_f32_e32 v58, v59, v58
	v_div_scale_f32 v59, vcc, v48, v54, v48
	v_mul_f32_e32 v60, v59, v58
	v_fma_f32 v61, -v55, v60, v59
	v_fmac_f32_e32 v60, v61, v58
	v_fma_f32 v55, -v55, v60, v59
	v_div_fmas_f32 v55, v55, v58, v60
	v_div_fixup_f32 v48, v55, v54, v48
	v_mul_f32_e32 v54, 0xbfb8aa3b, v49
	v_exp_f32_e32 v54, v54
	s_nop 0
	v_add_f32_e32 v54, 1.0, v54
	v_div_scale_f32 v55, s[0:1], v54, v54, v49
	v_rcp_f32_e32 v58, v55
	s_nop 0
	v_fma_f32 v59, -v55, v58, 1.0
	v_fmac_f32_e32 v58, v59, v58
	v_div_scale_f32 v59, vcc, v49, v54, v49
	v_mul_f32_e32 v60, v59, v58
	v_fma_f32 v61, -v55, v60, v59
	v_fmac_f32_e32 v60, v61, v58
	v_fma_f32 v55, -v55, v60, v59
	v_div_fmas_f32 v55, v55, v58, v60
	v_div_fixup_f32 v49, v55, v54, v49
	v_lshlrev_b32_e32 v54, 16, v66
	v_sub_f32_e32 v54, v54, v73
	v_mul_f32_e32 v54, v54, v72
	v_mul_f32_e32 v48, v48, v54
	v_and_b32_e32 v54, 0xffff0000, v66
	v_sub_f32_e32 v54, v54, v73
	v_mul_f32_e32 v54, v54, v72
	v_mul_f32_e32 v49, v49, v54
	v_cvt_pk_bf16_f32 v54, v48, v49
	v_mul_f32_e32 v48, 0xbfb8aa3b, v50
	v_exp_f32_e32 v48, v48
	s_nop 0
	v_add_f32_e32 v48, 1.0, v48
	v_div_scale_f32 v49, s[0:1], v48, v48, v50
	v_rcp_f32_e32 v55, v49
	s_nop 0
	v_fma_f32 v58, -v49, v55, 1.0
	v_fmac_f32_e32 v55, v58, v55
	v_div_scale_f32 v58, vcc, v50, v48, v50
	v_mul_f32_e32 v59, v58, v55
	v_fma_f32 v60, -v49, v59, v58
	v_fmac_f32_e32 v59, v60, v55
	v_fma_f32 v49, -v49, v59, v58
	v_div_fmas_f32 v49, v49, v55, v59
	v_div_fixup_f32 v48, v49, v48, v50
	v_mul_f32_e32 v49, 0xbfb8aa3b, v51
	v_exp_f32_e32 v49, v49
	s_nop 0
	v_add_f32_e32 v49, 1.0, v49
	v_div_scale_f32 v50, s[0:1], v49, v49, v51
	v_rcp_f32_e32 v55, v50
	s_nop 0
	v_fma_f32 v58, -v50, v55, 1.0
	v_fmac_f32_e32 v55, v58, v55
	v_div_scale_f32 v58, vcc, v51, v49, v51
	v_mul_f32_e32 v59, v58, v55
	v_fma_f32 v60, -v50, v59, v58
	v_fmac_f32_e32 v59, v60, v55
	v_fma_f32 v50, -v50, v59, v58
	v_div_fmas_f32 v50, v50, v55, v59
	v_div_fixup_f32 v49, v50, v49, v51
	v_lshlrev_b32_e32 v50, 16, v67
	v_sub_f32_e32 v50, v50, v73
	v_mul_f32_e32 v50, v50, v72
	v_mul_f32_e32 v48, v48, v50
	v_and_b32_e32 v50, 0xffff0000, v67
	v_sub_f32_e32 v50, v50, v73
	v_mul_f32_e32 v50, v50, v72
	v_mul_f32_e32 v49, v49, v50
	v_cvt_pk_bf16_f32 v55, v48, v49
	v_add_u32_e32 v48, 0x90, v162
	v_ashrrev_i32_e32 v49, 31, v48
	v_lshlrev_b64 v[50:51], 9, v[48:49]
	v_lshl_add_u64 v[50:51], s[2:3], 0, v[50:51]
	v_lshl_add_u64 v[50:51], v[50:51], 0, s[48:49]
	global_store_dwordx4 v[56:57], v[52:55], off offset:256
	v_lshl_add_u64 v[50:51], v[50:51], 0, v[166:167]
	v_lshlrev_b64 v[48:49], 12, v[48:49]
	v_lshl_add_u64 v[48:49], v[48:49], 0, v[164:165]
	v_lshlrev_b64 v[58:59], 1, v[48:49]
	v_lshl_add_u64 v[48:49], s[4:5], 0, v[58:59]
	s_waitcnt vmcnt(2)
; __device__ __forceinline__ unsigned cvt_pk_bf16(float lo, float hi) { unsigned r; asm volatile("v_cvt_pk_bf16_f32 %0, %1, %2" : "=v"(r) : "v"(lo), "v"(hi)); return r; }
; __device__ __forceinline__ float bf_lo(unsigned w) { return __uint_as_float(w << 16); }
; __device__ __forceinline__ float bf_hi(unsigned w) { return __uint_as_float(w & 0xffff0000u); }
;     __device__ __forceinline__ void operator()(const Acc& acc, const Unit& u, int wr, int wc, int fr, int fq) const {
;     ...
;                 const int row_in = ai * HALF + wr * 64 + m * 16 + fr, s = u.pm * BM + row_in;
;                 const f32x4 tq = ((const f32x4*)(stats + ((size_t)s * 8 + h) * 8))[fq];
;                 const size_t off = (size_t)s * RV + u.pn * BM + wc * 32 + 8 * fq;
;                 const u32x4 o0 = *(const u32x4*)(O + off), o1 = *(const u32x4*)(O + off + HALF);
;                 float s1 = tq[0] + tq[2], s2 = tq[1] + tq[3];
;                 { const auto r1 = __builtin_amdgcn_permlane16_swap(__float_as_uint(s1), __float_as_uint(s1), false, false); s1 = __uint_as_float(r1[0]) + __uint_as_float(r1[1]);
;                   const auto r2 = __builtin_amdgcn_permlane16_swap(__float_as_uint(s2), __float_as_uint(s2), false, false); s2 = __uint_as_float(r2[0]) + __uint_as_float(r2[1]);
;                   const auto r3 = __builtin_amdgcn_permlane32_swap(__float_as_uint(s1), __float_as_uint(s1), false, false); s1 = __uint_as_float(r3[0]) + __uint_as_float(r3[1]);
;                   const auto r4 = __builtin_amdgcn_permlane32_swap(__float_as_uint(s2), __float_as_uint(s2), false, false); s2 = __uint_as_float(r4[0]) + __uint_as_float(r4[1]); }
;                 const float mu = s1 * (1.0f / 512.0f), var = fmaxf(s2 * (1.0f / 512.0f) - mu * mu, 0.f), rstd = rsqrtf(var + EPS);
; #pragma unroll
;                 for (int bj = 0; bj < 2; ++bj) { const u32x4 ov = bj == 0 ? o0 : o1; const unsigned ow[4] = {ov.x, ov.y, ov.z, ov.w}; unsigned r[4];
; #pragma unroll
;                     for (int p = 0; p < 4; ++p) { const f32x4 v = acc[ai][bj][m][p >> 1]; const float g0 = silu_f(v[(p & 1) * 2]), g1 = silu_f(v[(p & 1) * 2 + 1]);
;                         r[p] = cvt_pk_bf16(g0 * ((bf_lo(ow[p]) - mu) * rstd), g1 * ((bf_hi(ow[p]) - mu) * rstd)); }
;                     *(u32x4*)(U + off + bj * HALF) = (u32x4){r[0], r[1], r[2], r[3]}; }
	v_mov_b32_e32 v60, v204
	v_mov_b32_e32 v61, v205
	v_mov_b32_e32 v62, v206
	v_mov_b32_e32 v63, v207
	v_mov_b32_e32 v52, v208
	v_mov_b32_e32 v53, v209
	v_mov_b32_e32 v54, v210
	v_mov_b32_e32 v55, v211
	v_mov_b32_e32 v48, v212
	v_mov_b32_e32 v49, v213
	v_mov_b32_e32 v50, v214
	v_mov_b32_e32 v51, v215
	v_add_u32_e32 v216, 0xa0, v162
	v_ashrrev_i32_e32 v217, 31, v216
	v_lshlrev_b64 v[218:219], 9, v[216:217]
	v_lshl_add_u64 v[218:219], s[2:3], 0, v[218:219]
	v_lshl_add_u64 v[218:219], v[218:219], 0, s[48:49]
	v_lshl_add_u64 v[218:219], v[218:219], 0, v[166:167]
	global_load_dwordx4 v[192:195], v[218:219], off
	v_lshlrev_b64 v[216:217], 12, v[216:217]
	v_lshl_add_u64 v[216:217], v[216:217], 0, v[164:165]
	v_lshlrev_b64 v[216:217], 1, v[216:217]
	v_lshl_add_u64 v[216:217], s[4:5], 0, v[216:217]
	global_load_dwordx4 v[196:199], v[216:217], off
	global_load_dwordx4 v[200:203], v[216:217], off offset:256
	v_add_f32_e32 v56, v60, v62
	v_mov_b32_e32 v57, v56
	v_add_f32_e32 v60, v61, v63
	s_nop 0
	v_permlane16_swap_b32_e32 v56, v57
	v_add_f32_e32 v57, v56, v57
	v_mov_b32_e32 v56, v60
	s_nop 1
	v_permlane16_swap_b32_e32 v60, v56
	v_add_f32_e32 v56, v60, v56
	v_mov_b32_e32 v61, v57
	v_mov_b32_e32 v60, v56
	s_nop 0
	v_permlane32_swap_b32_e32 v57, v61
	v_permlane32_swap_b32_e32 v56, v60
	v_pk_add_f32 v[56:57], v[56:57], v[60:61]
	s_nop 0
	v_pk_mul_f32 v[56:57], v[56:57], s[8:9] op_sel_hi:[1,0]
	s_nop 0
	v_fma_f32 v56, -v57, v57, v56
	v_max_f32_e32 v56, 0, v56
	v_add_f32_e32 v56, 0x358637bd, v56
	v_cmp_gt_f32_e32 vcc, s73, v56
	v_mul_f32_e32 v60, 0x4b800000, v56
	s_nop 0
	v_cndmask_b32_e32 v56, v56, v60, vcc
	v_rsq_f32_e32 v56, v56
	s_nop 0
	v_mul_f32_e32 v60, 0x45800000, v56
	v_cndmask_b32_e32 v56, v56, v60, vcc
	v_mul_f32_e32 v60, 0xbfb8aa3b, v44
	v_exp_f32_e32 v60, v60
	s_nop 0
	v_add_f32_e32 v60, 1.0, v60
	v_div_scale_f32 v61, s[0:1], v60, v60, v44
	v_rcp_f32_e32 v62, v61
	s_nop 0
	v_fma_f32 v63, -v61, v62, 1.0
	v_fmac_f32_e32 v62, v63, v62
	v_div_scale_f32 v63, vcc, v44, v60, v44
	v_mul_f32_e32 v64, v63, v62
	v_fma_f32 v65, -v61, v64, v63
	v_fmac_f32_e32 v64, v65, v62
	v_fma_f32 v61, -v61, v64, v63
	v_div_fmas_f32 v61, v61, v62, v64
	v_div_fixup_f32 v44, v61, v60, v44
	v_mul_f32_e32 v60, 0xbfb8aa3b, v45
	v_exp_f32_e32 v60, v60
	s_nop 0
	v_add_f32_e32 v60, 1.0, v60
	v_div_scale_f32 v61, s[0:1], v60, v60, v45
	v_rcp_f32_e32 v62, v61
	s_nop 0
	v_fma_f32 v63, -v61, v62, 1.0
	v_fmac_f32_e32 v62, v63, v62
	v_div_scale_f32 v63, vcc, v45, v60, v45
	v_mul_f32_e32 v64, v63, v62
	v_fma_f32 v65, -v61, v64, v63
	v_fmac_f32_e32 v64, v65, v62
	v_fma_f32 v61, -v61, v64, v63
	v_div_fmas_f32 v61, v61, v62, v64
	v_div_fixup_f32 v45, v61, v60, v45
	v_lshlrev_b32_e32 v60, 16, v52
	v_and_b32_e32 v52, 0xffff0000, v52
	v_sub_f32_e32 v60, v60, v57
	v_sub_f32_e32 v52, v52, v57
	v_mul_f32_e32 v60, v60, v56
	v_mul_f32_e32 v52, v52, v56
	v_mul_f32_e32 v44, v44, v60
	v_mul_f32_e32 v45, v45, v52
	v_cvt_pk_bf16_f32 v44, v44, v45
	v_mul_f32_e32 v45, 0xbfb8aa3b, v46
	v_exp_f32_e32 v45, v45
	s_nop 0
	v_add_f32_e32 v45, 1.0, v45
	v_div_scale_f32 v52, s[0:1], v45, v45, v46
	v_rcp_f32_e32 v60, v52
	s_nop 0
	v_fma_f32 v61, -v52, v60, 1.0
	v_fmac_f32_e32 v60, v61, v60
	v_div_scale_f32 v61, vcc, v46, v45, v46
	v_mul_f32_e32 v62, v61, v60
	v_fma_f32 v63, -v52, v62, v61
	v_fmac_f32_e32 v62, v63, v60
	v_fma_f32 v52, -v52, v62, v61
	v_div_fmas_f32 v52, v52, v60, v62
	v_div_fixup_f32 v45, v52, v45, v46
	v_mul_f32_e32 v46, 0xbfb8aa3b, v47
	v_exp_f32_e32 v46, v46
	s_nop 0
	v_add_f32_e32 v46, 1.0, v46
	v_div_scale_f32 v52, s[0:1], v46, v46, v47
	v_rcp_f32_e32 v60, v52
	s_nop 0
	v_fma_f32 v61, -v52, v60, 1.0
	v_fmac_f32_e32 v60, v61, v60
	v_div_scale_f32 v61, vcc, v47, v46, v47
	v_mul_f32_e32 v62, v61, v60
	v_fma_f32 v63, -v52, v62, v61
	v_fmac_f32_e32 v62, v63, v60
	v_fma_f32 v52, -v52, v62, v61
	v_div_fmas_f32 v52, v52, v60, v62
	v_div_fixup_f32 v46, v52, v46, v47
	v_lshlrev_b32_e32 v47, 16, v53
	v_sub_f32_e32 v47, v47, v57
	v_mul_f32_e32 v47, v47, v56
	v_mul_f32_e32 v45, v45, v47
	v_and_b32_e32 v47, 0xffff0000, v53
	v_sub_f32_e32 v47, v47, v57
	v_mul_f32_e32 v47, v47, v56
	v_mul_f32_e32 v46, v46, v47
	v_cvt_pk_bf16_f32 v45, v45, v46
	v_mul_f32_e32 v46, 0xbfb8aa3b, v40
	v_exp_f32_e32 v46, v46
	s_nop 0
	v_add_f32_e32 v46, 1.0, v46
	v_div_scale_f32 v47, s[0:1], v46, v46, v40
	v_rcp_f32_e32 v52, v47
	s_nop 0
	v_fma_f32 v53, -v47, v52, 1.0
	v_fmac_f32_e32 v52, v53, v52
	v_div_scale_f32 v53, vcc, v40, v46, v40
	v_mul_f32_e32 v60, v53, v52
	v_fma_f32 v61, -v47, v60, v53
	v_fmac_f32_e32 v60, v61, v52
	v_fma_f32 v47, -v47, v60, v53
	v_div_fmas_f32 v47, v47, v52, v60
	v_div_fixup_f32 v40, v47, v46, v40
	v_mul_f32_e32 v46, 0xbfb8aa3b, v41
	v_exp_f32_e32 v46, v46
	s_nop 0
	v_add_f32_e32 v46, 1.0, v46
	v_div_scale_f32 v47, s[0:1], v46, v46, v41
	v_rcp_f32_e32 v52, v47
	s_nop 0
	v_fma_f32 v53, -v47, v52, 1.0
	v_fmac_f32_e32 v52, v53, v52
	v_div_scale_f32 v53, vcc, v41, v46, v41
	v_mul_f32_e32 v60, v53, v52
	v_fma_f32 v61, -v47, v60, v53
	v_fmac_f32_e32 v60, v61, v52
	v_fma_f32 v47, -v47, v60, v53
	v_div_fmas_f32 v47, v47, v52, v60
	v_div_fixup_f32 v41, v47, v46, v41
	v_lshlrev_b32_e32 v46, 16, v54
	v_sub_f32_e32 v46, v46, v57
	v_mul_f32_e32 v46, v46, v56
	v_mul_f32_e32 v40, v40, v46
	v_and_b32_e32 v46, 0xffff0000, v54
	v_sub_f32_e32 v46, v46, v57
	v_mul_f32_e32 v46, v46, v56
	v_mul_f32_e32 v41, v41, v46
	v_cvt_pk_bf16_f32 v46, v40, v41
	v_mul_f32_e32 v40, 0xbfb8aa3b, v42
	v_exp_f32_e32 v40, v40
	s_nop 0
	v_add_f32_e32 v40, 1.0, v40
	v_div_scale_f32 v41, s[0:1], v40, v40, v42
	v_rcp_f32_e32 v47, v41
	s_nop 0
	v_fma_f32 v52, -v41, v47, 1.0
	v_fmac_f32_e32 v47, v52, v47
	v_div_scale_f32 v52, vcc, v42, v40, v42
; __device__ __forceinline__ unsigned cvt_pk_bf16(float lo, float hi) { unsigned r; asm volatile("v_cvt_pk_bf16_f32 %0, %1, %2" : "=v"(r) : "v"(lo), "v"(hi)); return r; }
; __device__ __forceinline__ float bf_lo(unsigned w) { return __uint_as_float(w << 16); }
; __device__ __forceinline__ float bf_hi(unsigned w) { return __uint_as_float(w & 0xffff0000u); }
; __device__ __forceinline__ float silu_f(float v) { return v / (1.0f + __expf(-v)); }
;     __device__ __forceinline__ void operator()(const Acc& acc, const Unit& u, int wr, int wc, int fr, int fq) const {
;     ...
;                 const float mu = s1 * (1.0f / 512.0f), var = fmaxf(s2 * (1.0f / 512.0f) - mu * mu, 0.f), rstd = rsqrtf(var + EPS);
; #pragma unroll
;                 for (int bj = 0; bj < 2; ++bj) { const u32x4 ov = bj == 0 ? o0 : o1; const unsigned ow[4] = {ov.x, ov.y, ov.z, ov.w}; unsigned r[4];
; #pragma unroll
;                     for (int p = 0; p < 4; ++p) { const f32x4 v = acc[ai][bj][m][p >> 1]; const float g0 = silu_f(v[(p & 1) * 2]), g1 = silu_f(v[(p & 1) * 2 + 1]);
;                         r[p] = cvt_pk_bf16(g0 * ((bf_lo(ow[p]) - mu) * rstd), g1 * ((bf_hi(ow[p]) - mu) * rstd)); }
;                     *(u32x4*)(U + off + bj * HALF) = (u32x4){r[0], r[1], r[2], r[3]}; }
	v_mul_f32_e32 v53, v52, v47
	v_fma_f32 v54, -v41, v53, v52
	v_fmac_f32_e32 v53, v54, v47
	v_fma_f32 v41, -v41, v53, v52
	v_div_fmas_f32 v41, v41, v47, v53
	v_div_fixup_f32 v40, v41, v40, v42
	v_mul_f32_e32 v41, 0xbfb8aa3b, v43
	v_exp_f32_e32 v41, v41
	s_nop 0
	v_add_f32_e32 v41, 1.0, v41
	v_div_scale_f32 v42, s[0:1], v41, v41, v43
	v_rcp_f32_e32 v47, v42
	s_nop 0
	v_fma_f32 v52, -v42, v47, 1.0
	v_fmac_f32_e32 v47, v52, v47
	v_div_scale_f32 v52, vcc, v43, v41, v43
	v_mul_f32_e32 v53, v52, v47
	v_fma_f32 v54, -v42, v53, v52
	v_fmac_f32_e32 v53, v54, v47
	v_fma_f32 v42, -v42, v53, v52
	v_div_fmas_f32 v42, v42, v47, v53
	v_div_fixup_f32 v41, v42, v41, v43
	v_lshlrev_b32_e32 v42, 16, v55
	v_sub_f32_e32 v42, v42, v57
	v_mul_f32_e32 v42, v42, v56
	v_mul_f32_e32 v40, v40, v42
	v_and_b32_e32 v42, 0xffff0000, v55
	v_sub_f32_e32 v42, v42, v57
	v_mul_f32_e32 v42, v42, v56
	v_mul_f32_e32 v41, v41, v42
	v_mul_f32_e32 v42, 0xbfb8aa3b, v36
	v_exp_f32_e32 v42, v42
	v_cvt_pk_bf16_f32 v47, v40, v41
	v_lshl_add_u64 v[40:41], s[6:7], 0, v[58:59]
	global_store_dwordx4 v[40:41], v[44:47], off
	v_add_f32_e32 v42, 1.0, v42
	v_div_scale_f32 v43, s[0:1], v42, v42, v36
	v_rcp_f32_e32 v44, v43
	s_nop 0
	v_fma_f32 v45, -v43, v44, 1.0
	v_fmac_f32_e32 v44, v45, v44
	v_div_scale_f32 v45, vcc, v36, v42, v36
	v_mul_f32_e32 v46, v45, v44
	v_fma_f32 v47, -v43, v46, v45
	v_fmac_f32_e32 v46, v47, v44
	v_fma_f32 v43, -v43, v46, v45
	v_div_fmas_f32 v43, v43, v44, v46
	v_div_fixup_f32 v36, v43, v42, v36
	v_mul_f32_e32 v42, 0xbfb8aa3b, v37
	v_exp_f32_e32 v42, v42
	s_nop 0
	v_add_f32_e32 v42, 1.0, v42
	v_div_scale_f32 v43, s[0:1], v42, v42, v37
	v_rcp_f32_e32 v44, v43
	s_nop 0
	v_fma_f32 v45, -v43, v44, 1.0
	v_fmac_f32_e32 v44, v45, v44
	v_div_scale_f32 v45, vcc, v37, v42, v37
	v_mul_f32_e32 v46, v45, v44
	v_fma_f32 v47, -v43, v46, v45
	v_fmac_f32_e32 v46, v47, v44
	v_fma_f32 v43, -v43, v46, v45
	v_div_fmas_f32 v43, v43, v44, v46
	v_div_fixup_f32 v37, v43, v42, v37
	v_lshlrev_b32_e32 v42, 16, v48
	v_sub_f32_e32 v42, v42, v57
	v_mul_f32_e32 v42, v42, v56
	v_mul_f32_e32 v36, v36, v42
	v_and_b32_e32 v42, 0xffff0000, v48
	v_sub_f32_e32 v42, v42, v57
	v_mul_f32_e32 v42, v42, v56
	v_mul_f32_e32 v37, v37, v42
	v_cvt_pk_bf16_f32 v36, v36, v37
	v_mul_f32_e32 v37, 0xbfb8aa3b, v38
	v_exp_f32_e32 v37, v37
	s_nop 0
	v_add_f32_e32 v37, 1.0, v37
	v_div_scale_f32 v42, s[0:1], v37, v37, v38
	v_rcp_f32_e32 v43, v42
	s_nop 0
	v_fma_f32 v44, -v42, v43, 1.0
	v_fmac_f32_e32 v43, v44, v43
	v_div_scale_f32 v44, vcc, v38, v37, v38
	v_mul_f32_e32 v45, v44, v43
	v_fma_f32 v46, -v42, v45, v44
	v_fmac_f32_e32 v45, v46, v43
	v_fma_f32 v42, -v42, v45, v44
	v_div_fmas_f32 v42, v42, v43, v45
	v_div_fixup_f32 v37, v42, v37, v38
	v_mul_f32_e32 v38, 0xbfb8aa3b, v39
	v_exp_f32_e32 v38, v38
	s_nop 0
	v_add_f32_e32 v38, 1.0, v38
	v_div_scale_f32 v42, s[0:1], v38, v38, v39
	v_rcp_f32_e32 v43, v42
	s_nop 0
	v_fma_f32 v44, -v42, v43, 1.0
	v_fmac_f32_e32 v43, v44, v43
	v_div_scale_f32 v44, vcc, v39, v38, v39
	v_mul_f32_e32 v45, v44, v43
	v_fma_f32 v46, -v42, v45, v44
	v_fmac_f32_e32 v45, v46, v43
	v_fma_f32 v42, -v42, v45, v44
	v_div_fmas_f32 v42, v42, v43, v45
	v_div_fixup_f32 v38, v42, v38, v39
	v_lshlrev_b32_e32 v39, 16, v49
	v_sub_f32_e32 v39, v39, v57
	v_mul_f32_e32 v39, v39, v56
	v_mul_f32_e32 v37, v37, v39
	v_and_b32_e32 v39, 0xffff0000, v49
	v_sub_f32_e32 v39, v39, v57
	v_mul_f32_e32 v39, v39, v56
	v_mul_f32_e32 v38, v38, v39
	v_cvt_pk_bf16_f32 v37, v37, v38
	v_mul_f32_e32 v38, 0xbfb8aa3b, v32
	v_exp_f32_e32 v38, v38
	s_nop 0
	v_add_f32_e32 v38, 1.0, v38
	v_div_scale_f32 v39, s[0:1], v38, v38, v32
	v_rcp_f32_e32 v42, v39
	s_nop 0
	v_fma_f32 v43, -v39, v42, 1.0
	v_fmac_f32_e32 v42, v43, v42
	v_div_scale_f32 v43, vcc, v32, v38, v32
	v_mul_f32_e32 v44, v43, v42
	v_fma_f32 v45, -v39, v44, v43
	v_fmac_f32_e32 v44, v45, v42
	v_fma_f32 v39, -v39, v44, v43
	v_div_fmas_f32 v39, v39, v42, v44
	v_div_fixup_f32 v32, v39, v38, v32
	v_mul_f32_e32 v38, 0xbfb8aa3b, v33
	v_exp_f32_e32 v38, v38
	s_nop 0
	v_add_f32_e32 v38, 1.0, v38
	v_div_scale_f32 v39, s[0:1], v38, v38, v33
	v_rcp_f32_e32 v42, v39
	s_nop 0
	v_fma_f32 v43, -v39, v42, 1.0
	v_fmac_f32_e32 v42, v43, v42
	v_div_scale_f32 v43, vcc, v33, v38, v33
	v_mul_f32_e32 v44, v43, v42
	v_fma_f32 v45, -v39, v44, v43
	v_fmac_f32_e32 v44, v45, v42
	v_fma_f32 v39, -v39, v44, v43
	v_div_fmas_f32 v39, v39, v42, v44
	v_div_fixup_f32 v33, v39, v38, v33
	v_lshlrev_b32_e32 v38, 16, v50
	v_sub_f32_e32 v38, v38, v57
	v_mul_f32_e32 v38, v38, v56
	v_mul_f32_e32 v32, v32, v38
	v_and_b32_e32 v38, 0xffff0000, v50
	v_sub_f32_e32 v38, v38, v57
	v_mul_f32_e32 v38, v38, v56
	v_mul_f32_e32 v33, v33, v38
	v_cvt_pk_bf16_f32 v38, v32, v33
	v_mul_f32_e32 v32, 0xbfb8aa3b, v34
	v_exp_f32_e32 v32, v32
	s_nop 0
	v_add_f32_e32 v32, 1.0, v32
	v_div_scale_f32 v33, s[0:1], v32, v32, v34
	v_rcp_f32_e32 v39, v33
	s_nop 0
	v_fma_f32 v42, -v33, v39, 1.0
	v_fmac_f32_e32 v39, v42, v39
	v_div_scale_f32 v42, vcc, v34, v32, v34
	v_mul_f32_e32 v43, v42, v39
	v_fma_f32 v44, -v33, v43, v42
	v_fmac_f32_e32 v43, v44, v39
	v_fma_f32 v33, -v33, v43, v42
	v_div_fmas_f32 v33, v33, v39, v43
	v_div_fixup_f32 v32, v33, v32, v34
	v_mul_f32_e32 v33, 0xbfb8aa3b, v35
	v_exp_f32_e32 v33, v33
	s_nop 0
	v_add_f32_e32 v33, 1.0, v33
	v_div_scale_f32 v34, s[0:1], v33, v33, v35
	v_rcp_f32_e32 v39, v34
	s_nop 0
	v_fma_f32 v42, -v34, v39, 1.0
	v_fmac_f32_e32 v39, v42, v39
	v_div_scale_f32 v42, vcc, v35, v33, v35
	v_mul_f32_e32 v43, v42, v39
	v_fma_f32 v44, -v34, v43, v42
	v_fmac_f32_e32 v43, v44, v39
	v_fma_f32 v34, -v34, v43, v42
	v_div_fmas_f32 v34, v34, v39, v43
	v_div_fixup_f32 v33, v34, v33, v35
	v_lshlrev_b32_e32 v34, 16, v51
	v_sub_f32_e32 v34, v34, v57
	v_mul_f32_e32 v34, v34, v56
	v_mul_f32_e32 v32, v32, v34
	v_and_b32_e32 v34, 0xffff0000, v51
	v_sub_f32_e32 v34, v34, v57
	v_mul_f32_e32 v34, v34, v56
	v_mul_f32_e32 v33, v33, v34
	v_cvt_pk_bf16_f32 v39, v32, v33
	v_add_u32_e32 v32, 0xa0, v162
	v_ashrrev_i32_e32 v33, 31, v32
	v_lshlrev_b64 v[34:35], 9, v[32:33]
	v_lshl_add_u64 v[34:35], s[2:3], 0, v[34:35]
	v_lshl_add_u64 v[34:35], v[34:35], 0, s[48:49]
	global_store_dwordx4 v[40:41], v[36:39], off offset:256
	v_lshl_add_u64 v[34:35], v[34:35], 0, v[166:167]
	v_lshlrev_b64 v[32:33], 12, v[32:33]
	v_lshl_add_u64 v[32:33], v[32:33], 0, v[164:165]
	v_lshlrev_b64 v[42:43], 1, v[32:33]
	v_lshl_add_u64 v[32:33], s[4:5], 0, v[42:43]
	s_waitcnt vmcnt(2)
; __device__ __forceinline__ unsigned cvt_pk_bf16(float lo, float hi) { unsigned r; asm volatile("v_cvt_pk_bf16_f32 %0, %1, %2" : "=v"(r) : "v"(lo), "v"(hi)); return r; }
; __device__ __forceinline__ float bf_lo(unsigned w) { return __uint_as_float(w << 16); }
; __device__ __forceinline__ float bf_hi(unsigned w) { return __uint_as_float(w & 0xffff0000u); }
;     __device__ __forceinline__ void operator()(const Acc& acc, const Unit& u, int wr, int wc, int fr, int fq) const {
;     ...
;                 const int row_in = ai * HALF + wr * 64 + m * 16 + fr, s = u.pm * BM + row_in;
;                 const f32x4 tq = ((const f32x4*)(stats + ((size_t)s * 8 + h) * 8))[fq];
;                 const size_t off = (size_t)s * RV + u.pn * BM + wc * 32 + 8 * fq;
;                 const u32x4 o0 = *(const u32x4*)(O + off), o1 = *(const u32x4*)(O + off + HALF);
;                 float s1 = tq[0] + tq[2], s2 = tq[1] + tq[3];
;                 { const auto r1 = __builtin_amdgcn_permlane16_swap(__float_as_uint(s1), __float_as_uint(s1), false, false); s1 = __uint_as_float(r1[0]) + __uint_as_float(r1[1]);
;                   const auto r2 = __builtin_amdgcn_permlane16_swap(__float_as_uint(s2), __float_as_uint(s2), false, false); s2 = __uint_as_float(r2[0]) + __uint_as_float(r2[1]);
;                   const auto r3 = __builtin_amdgcn_permlane32_swap(__float_as_uint(s1), __float_as_uint(s1), false, false); s1 = __uint_as_float(r3[0]) + __uint_as_float(r3[1]);
;                   const auto r4 = __builtin_amdgcn_permlane32_swap(__float_as_uint(s2), __float_as_uint(s2), false, false); s2 = __uint_as_float(r4[0]) + __uint_as_float(r4[1]); }
;                 const float mu = s1 * (1.0f / 512.0f), var = fmaxf(s2 * (1.0f / 512.0f) - mu * mu, 0.f), rstd = rsqrtf(var + EPS);
; #pragma unroll
;                 for (int bj = 0; bj < 2; ++bj) { const u32x4 ov = bj == 0 ? o0 : o1; const unsigned ow[4] = {ov.x, ov.y, ov.z, ov.w}; unsigned r[4];
; #pragma unroll
;                     for (int p = 0; p < 4; ++p) { const f32x4 v = acc[ai][bj][m][p >> 1]; const float g0 = silu_f(v[(p & 1) * 2]), g1 = silu_f(v[(p & 1) * 2 + 1]);
;                         r[p] = cvt_pk_bf16(g0 * ((bf_lo(ow[p]) - mu) * rstd), g1 * ((bf_hi(ow[p]) - mu) * rstd)); }
;                     *(u32x4*)(U + off + bj * HALF) = (u32x4){r[0], r[1], r[2], r[3]}; }
	v_mov_b32_e32 v44, v192
	v_mov_b32_e32 v45, v193
	v_mov_b32_e32 v46, v194
	v_mov_b32_e32 v47, v195
	v_mov_b32_e32 v36, v196
	v_mov_b32_e32 v37, v197
	v_mov_b32_e32 v38, v198
	v_mov_b32_e32 v39, v199
	v_mov_b32_e32 v32, v200
	v_mov_b32_e32 v33, v201
	v_mov_b32_e32 v34, v202
	v_mov_b32_e32 v35, v203
	v_add_u32_e32 v216, 0xb0, v162
	v_ashrrev_i32_e32 v217, 31, v216
	v_lshlrev_b64 v[218:219], 9, v[216:217]
	v_lshl_add_u64 v[218:219], s[2:3], 0, v[218:219]
	v_lshl_add_u64 v[218:219], v[218:219], 0, s[48:49]
	v_lshl_add_u64 v[218:219], v[218:219], 0, v[166:167]
	global_load_dwordx4 v[204:207], v[218:219], off
	v_lshlrev_b64 v[216:217], 12, v[216:217]
	v_lshl_add_u64 v[216:217], v[216:217], 0, v[164:165]
	v_lshlrev_b64 v[216:217], 1, v[216:217]
	v_lshl_add_u64 v[216:217], s[4:5], 0, v[216:217]
	global_load_dwordx4 v[208:211], v[216:217], off
	global_load_dwordx4 v[212:215], v[216:217], off offset:256
	v_add_f32_e32 v40, v44, v46
	v_mov_b32_e32 v41, v40
	v_add_f32_e32 v44, v45, v47
	s_nop 0
	v_permlane16_swap_b32_e32 v40, v41
	v_add_f32_e32 v41, v40, v41
	v_mov_b32_e32 v40, v44
	s_nop 1
	v_permlane16_swap_b32_e32 v44, v40
	v_add_f32_e32 v40, v44, v40
	v_mov_b32_e32 v45, v41
	v_mov_b32_e32 v44, v40
	s_nop 0
	v_permlane32_swap_b32_e32 v41, v45
	v_permlane32_swap_b32_e32 v40, v44
	v_pk_add_f32 v[40:41], v[40:41], v[44:45]
	s_nop 0
	v_pk_mul_f32 v[40:41], v[40:41], s[8:9] op_sel_hi:[1,0]
	s_nop 0
	v_fma_f32 v40, -v41, v41, v40
	v_max_f32_e32 v40, 0, v40
	v_add_f32_e32 v40, 0x358637bd, v40
	v_cmp_gt_f32_e32 vcc, s73, v40
	v_mul_f32_e32 v44, 0x4b800000, v40
	s_nop 0
	v_cndmask_b32_e32 v40, v40, v44, vcc
	v_rsq_f32_e32 v40, v40
	s_nop 0
	v_mul_f32_e32 v44, 0x45800000, v40
	v_cndmask_b32_e32 v40, v40, v44, vcc
	v_mul_f32_e32 v44, 0xbfb8aa3b, v28
	v_exp_f32_e32 v44, v44
	s_nop 0
	v_add_f32_e32 v44, 1.0, v44
	v_div_scale_f32 v45, s[0:1], v44, v44, v28
	v_rcp_f32_e32 v46, v45
	s_nop 0
	v_fma_f32 v47, -v45, v46, 1.0
	v_fmac_f32_e32 v46, v47, v46
	v_div_scale_f32 v47, vcc, v28, v44, v28
	v_mul_f32_e32 v48, v47, v46
	v_fma_f32 v49, -v45, v48, v47
	v_fmac_f32_e32 v48, v49, v46
	v_fma_f32 v45, -v45, v48, v47
	v_div_fmas_f32 v45, v45, v46, v48
	v_div_fixup_f32 v28, v45, v44, v28
	v_mul_f32_e32 v44, 0xbfb8aa3b, v29
	v_exp_f32_e32 v44, v44
	s_nop 0
	v_add_f32_e32 v44, 1.0, v44
	v_div_scale_f32 v45, s[0:1], v44, v44, v29
	v_rcp_f32_e32 v46, v45
	s_nop 0
	v_fma_f32 v47, -v45, v46, 1.0
	v_fmac_f32_e32 v46, v47, v46
	v_div_scale_f32 v47, vcc, v29, v44, v29
	v_mul_f32_e32 v48, v47, v46
	v_fma_f32 v49, -v45, v48, v47
	v_fmac_f32_e32 v48, v49, v46
	v_fma_f32 v45, -v45, v48, v47
	v_div_fmas_f32 v45, v45, v46, v48
	v_div_fixup_f32 v29, v45, v44, v29
	v_lshlrev_b32_e32 v44, 16, v36
	v_and_b32_e32 v36, 0xffff0000, v36
	v_sub_f32_e32 v44, v44, v41
	v_sub_f32_e32 v36, v36, v41
	v_mul_f32_e32 v44, v44, v40
	v_mul_f32_e32 v36, v36, v40
	v_mul_f32_e32 v28, v28, v44
	v_mul_f32_e32 v29, v29, v36
	v_cvt_pk_bf16_f32 v28, v28, v29
	v_mul_f32_e32 v29, 0xbfb8aa3b, v30
	v_exp_f32_e32 v29, v29
	s_nop 0
	v_add_f32_e32 v29, 1.0, v29
	v_div_scale_f32 v36, s[0:1], v29, v29, v30
	v_rcp_f32_e32 v44, v36
	s_nop 0
	v_fma_f32 v45, -v36, v44, 1.0
	v_fmac_f32_e32 v44, v45, v44
	v_div_scale_f32 v45, vcc, v30, v29, v30
	v_mul_f32_e32 v46, v45, v44
	v_fma_f32 v47, -v36, v46, v45
	v_fmac_f32_e32 v46, v47, v44
	v_fma_f32 v36, -v36, v46, v45
	v_div_fmas_f32 v36, v36, v44, v46
	v_div_fixup_f32 v29, v36, v29, v30
	v_mul_f32_e32 v30, 0xbfb8aa3b, v31
	v_exp_f32_e32 v30, v30
	s_nop 0
	v_add_f32_e32 v30, 1.0, v30
	v_div_scale_f32 v36, s[0:1], v30, v30, v31
	v_rcp_f32_e32 v44, v36
	s_nop 0
	v_fma_f32 v45, -v36, v44, 1.0
	v_fmac_f32_e32 v44, v45, v44
	v_div_scale_f32 v45, vcc, v31, v30, v31
	v_mul_f32_e32 v46, v45, v44
	v_fma_f32 v47, -v36, v46, v45
	v_fmac_f32_e32 v46, v47, v44
	v_fma_f32 v36, -v36, v46, v45
	v_div_fmas_f32 v36, v36, v44, v46
	v_div_fixup_f32 v30, v36, v30, v31
	v_lshlrev_b32_e32 v31, 16, v37
	v_sub_f32_e32 v31, v31, v41
	v_mul_f32_e32 v31, v31, v40
	v_mul_f32_e32 v29, v29, v31
	v_and_b32_e32 v31, 0xffff0000, v37
	v_sub_f32_e32 v31, v31, v41
	v_mul_f32_e32 v31, v31, v40
	v_mul_f32_e32 v30, v30, v31
	v_cvt_pk_bf16_f32 v29, v29, v30
	v_mul_f32_e32 v30, 0xbfb8aa3b, v24
	v_exp_f32_e32 v30, v30
	s_nop 0
	v_add_f32_e32 v30, 1.0, v30
	v_div_scale_f32 v31, s[0:1], v30, v30, v24
	v_rcp_f32_e32 v36, v31
	s_nop 0
	v_fma_f32 v37, -v31, v36, 1.0
	v_fmac_f32_e32 v36, v37, v36
	v_div_scale_f32 v37, vcc, v24, v30, v24
	v_mul_f32_e32 v44, v37, v36
	v_fma_f32 v45, -v31, v44, v37
	v_fmac_f32_e32 v44, v45, v36
	v_fma_f32 v31, -v31, v44, v37
	v_div_fmas_f32 v31, v31, v36, v44
	v_div_fixup_f32 v24, v31, v30, v24
	v_mul_f32_e32 v30, 0xbfb8aa3b, v25
	v_exp_f32_e32 v30, v30
	s_nop 0
	v_add_f32_e32 v30, 1.0, v30
	v_div_scale_f32 v31, s[0:1], v30, v30, v25
	v_rcp_f32_e32 v36, v31
	s_nop 0
	v_fma_f32 v37, -v31, v36, 1.0
	v_fmac_f32_e32 v36, v37, v36
	v_div_scale_f32 v37, vcc, v25, v30, v25
	v_mul_f32_e32 v44, v37, v36
	v_fma_f32 v45, -v31, v44, v37
	v_fmac_f32_e32 v44, v45, v36
	v_fma_f32 v31, -v31, v44, v37
	v_div_fmas_f32 v31, v31, v36, v44
	v_div_fixup_f32 v25, v31, v30, v25
	v_lshlrev_b32_e32 v30, 16, v38
	v_sub_f32_e32 v30, v30, v41
	v_mul_f32_e32 v30, v30, v40
	v_mul_f32_e32 v24, v24, v30
	v_and_b32_e32 v30, 0xffff0000, v38
	v_sub_f32_e32 v30, v30, v41
	v_mul_f32_e32 v30, v30, v40
	v_mul_f32_e32 v25, v25, v30
	v_cvt_pk_bf16_f32 v30, v24, v25
	v_mul_f32_e32 v24, 0xbfb8aa3b, v26
	v_exp_f32_e32 v24, v24
	s_nop 0
	v_add_f32_e32 v24, 1.0, v24
	v_div_scale_f32 v25, s[0:1], v24, v24, v26
	v_rcp_f32_e32 v31, v25
	s_nop 0
	v_fma_f32 v36, -v25, v31, 1.0
	v_fmac_f32_e32 v31, v36, v31
	v_div_scale_f32 v36, vcc, v26, v24, v26
; __device__ __forceinline__ unsigned cvt_pk_bf16(float lo, float hi) { unsigned r; asm volatile("v_cvt_pk_bf16_f32 %0, %1, %2" : "=v"(r) : "v"(lo), "v"(hi)); return r; }
; __device__ __forceinline__ float bf_lo(unsigned w) { return __uint_as_float(w << 16); }
; __device__ __forceinline__ float bf_hi(unsigned w) { return __uint_as_float(w & 0xffff0000u); }
; __device__ __forceinline__ float silu_f(float v) { return v / (1.0f + __expf(-v)); }
;     __device__ __forceinline__ void operator()(const Acc& acc, const Unit& u, int wr, int wc, int fr, int fq) const {
;     ...
;                 const float mu = s1 * (1.0f / 512.0f), var = fmaxf(s2 * (1.0f / 512.0f) - mu * mu, 0.f), rstd = rsqrtf(var + EPS);
; #pragma unroll
;                 for (int bj = 0; bj < 2; ++bj) { const u32x4 ov = bj == 0 ? o0 : o1; const unsigned ow[4] = {ov.x, ov.y, ov.z, ov.w}; unsigned r[4];
; #pragma unroll
;                     for (int p = 0; p < 4; ++p) { const f32x4 v = acc[ai][bj][m][p >> 1]; const float g0 = silu_f(v[(p & 1) * 2]), g1 = silu_f(v[(p & 1) * 2 + 1]);
;                         r[p] = cvt_pk_bf16(g0 * ((bf_lo(ow[p]) - mu) * rstd), g1 * ((bf_hi(ow[p]) - mu) * rstd)); }
;                     *(u32x4*)(U + off + bj * HALF) = (u32x4){r[0], r[1], r[2], r[3]}; }
	v_mul_f32_e32 v37, v36, v31
	v_fma_f32 v38, -v25, v37, v36
	v_fmac_f32_e32 v37, v38, v31
	v_fma_f32 v25, -v25, v37, v36
	v_div_fmas_f32 v25, v25, v31, v37
	v_div_fixup_f32 v24, v25, v24, v26
	v_mul_f32_e32 v25, 0xbfb8aa3b, v27
	v_exp_f32_e32 v25, v25
	s_nop 0
	v_add_f32_e32 v25, 1.0, v25
	v_div_scale_f32 v26, s[0:1], v25, v25, v27
	v_rcp_f32_e32 v31, v26
	s_nop 0
	v_fma_f32 v36, -v26, v31, 1.0
	v_fmac_f32_e32 v31, v36, v31
	v_div_scale_f32 v36, vcc, v27, v25, v27
	v_mul_f32_e32 v37, v36, v31
	v_fma_f32 v38, -v26, v37, v36
	v_fmac_f32_e32 v37, v38, v31
	v_fma_f32 v26, -v26, v37, v36
	v_div_fmas_f32 v26, v26, v31, v37
	v_div_fixup_f32 v25, v26, v25, v27
	v_lshlrev_b32_e32 v26, 16, v39
	v_sub_f32_e32 v26, v26, v41
	v_mul_f32_e32 v26, v26, v40
	v_mul_f32_e32 v24, v24, v26
	v_and_b32_e32 v26, 0xffff0000, v39
	v_sub_f32_e32 v26, v26, v41
	v_mul_f32_e32 v26, v26, v40
	v_mul_f32_e32 v25, v25, v26
	v_mul_f32_e32 v26, 0xbfb8aa3b, v20
	v_exp_f32_e32 v26, v26
	v_cvt_pk_bf16_f32 v31, v24, v25
	v_lshl_add_u64 v[24:25], s[6:7], 0, v[42:43]
	global_store_dwordx4 v[24:25], v[28:31], off
	v_add_f32_e32 v26, 1.0, v26
	v_div_scale_f32 v27, s[0:1], v26, v26, v20
	v_rcp_f32_e32 v28, v27
	s_nop 0
	v_fma_f32 v29, -v27, v28, 1.0
	v_fmac_f32_e32 v28, v29, v28
	v_div_scale_f32 v29, vcc, v20, v26, v20
	v_mul_f32_e32 v30, v29, v28
	v_fma_f32 v31, -v27, v30, v29
	v_fmac_f32_e32 v30, v31, v28
	v_fma_f32 v27, -v27, v30, v29
	v_div_fmas_f32 v27, v27, v28, v30
	v_div_fixup_f32 v20, v27, v26, v20
	v_mul_f32_e32 v26, 0xbfb8aa3b, v21
	v_exp_f32_e32 v26, v26
	s_nop 0
	v_add_f32_e32 v26, 1.0, v26
	v_div_scale_f32 v27, s[0:1], v26, v26, v21
	v_rcp_f32_e32 v28, v27
	s_nop 0
	v_fma_f32 v29, -v27, v28, 1.0
	v_fmac_f32_e32 v28, v29, v28
	v_div_scale_f32 v29, vcc, v21, v26, v21
	v_mul_f32_e32 v30, v29, v28
	v_fma_f32 v31, -v27, v30, v29
	v_fmac_f32_e32 v30, v31, v28
	v_fma_f32 v27, -v27, v30, v29
	v_div_fmas_f32 v27, v27, v28, v30
	v_div_fixup_f32 v21, v27, v26, v21
	v_lshlrev_b32_e32 v26, 16, v32
	v_sub_f32_e32 v26, v26, v41
	v_mul_f32_e32 v26, v26, v40
	v_mul_f32_e32 v20, v20, v26
	v_and_b32_e32 v26, 0xffff0000, v32
	v_sub_f32_e32 v26, v26, v41
	v_mul_f32_e32 v26, v26, v40
	v_mul_f32_e32 v21, v21, v26
	v_cvt_pk_bf16_f32 v20, v20, v21
	v_mul_f32_e32 v21, 0xbfb8aa3b, v22
	v_exp_f32_e32 v21, v21
	s_nop 0
	v_add_f32_e32 v21, 1.0, v21
	v_div_scale_f32 v26, s[0:1], v21, v21, v22
	v_rcp_f32_e32 v27, v26
	s_nop 0
	v_fma_f32 v28, -v26, v27, 1.0
	v_fmac_f32_e32 v27, v28, v27
	v_div_scale_f32 v28, vcc, v22, v21, v22
	v_mul_f32_e32 v29, v28, v27
	v_fma_f32 v30, -v26, v29, v28
	v_fmac_f32_e32 v29, v30, v27
	v_fma_f32 v26, -v26, v29, v28
	v_div_fmas_f32 v26, v26, v27, v29
	v_div_fixup_f32 v21, v26, v21, v22
	v_mul_f32_e32 v22, 0xbfb8aa3b, v23
	v_exp_f32_e32 v22, v22
	s_nop 0
	v_add_f32_e32 v22, 1.0, v22
	v_div_scale_f32 v26, s[0:1], v22, v22, v23
	v_rcp_f32_e32 v27, v26
	s_nop 0
	v_fma_f32 v28, -v26, v27, 1.0
	v_fmac_f32_e32 v27, v28, v27
	v_div_scale_f32 v28, vcc, v23, v22, v23
	v_mul_f32_e32 v29, v28, v27
	v_fma_f32 v30, -v26, v29, v28
	v_fmac_f32_e32 v29, v30, v27
	v_fma_f32 v26, -v26, v29, v28
	v_div_fmas_f32 v26, v26, v27, v29
	v_div_fixup_f32 v22, v26, v22, v23
	v_lshlrev_b32_e32 v23, 16, v33
	v_sub_f32_e32 v23, v23, v41
	v_mul_f32_e32 v23, v23, v40
	v_mul_f32_e32 v21, v21, v23
	v_and_b32_e32 v23, 0xffff0000, v33
	v_sub_f32_e32 v23, v23, v41
	v_mul_f32_e32 v23, v23, v40
	v_mul_f32_e32 v22, v22, v23
	v_cvt_pk_bf16_f32 v21, v21, v22
	v_mul_f32_e32 v22, 0xbfb8aa3b, v16
	v_exp_f32_e32 v22, v22
	s_nop 0
	v_add_f32_e32 v22, 1.0, v22
	v_div_scale_f32 v23, s[0:1], v22, v22, v16
	v_rcp_f32_e32 v26, v23
	s_nop 0
	v_fma_f32 v27, -v23, v26, 1.0
	v_fmac_f32_e32 v26, v27, v26
	v_div_scale_f32 v27, vcc, v16, v22, v16
	v_mul_f32_e32 v28, v27, v26
	v_fma_f32 v29, -v23, v28, v27
	v_fmac_f32_e32 v28, v29, v26
	v_fma_f32 v23, -v23, v28, v27
	v_div_fmas_f32 v23, v23, v26, v28
	v_div_fixup_f32 v16, v23, v22, v16
	v_mul_f32_e32 v22, 0xbfb8aa3b, v17
	v_exp_f32_e32 v22, v22
	s_nop 0
	v_add_f32_e32 v22, 1.0, v22
	v_div_scale_f32 v23, s[0:1], v22, v22, v17
	v_rcp_f32_e32 v26, v23
	s_nop 0
	v_fma_f32 v27, -v23, v26, 1.0
	v_fmac_f32_e32 v26, v27, v26
	v_div_scale_f32 v27, vcc, v17, v22, v17
	v_mul_f32_e32 v28, v27, v26
	v_fma_f32 v29, -v23, v28, v27
	v_fmac_f32_e32 v28, v29, v26
	v_fma_f32 v23, -v23, v28, v27
	v_div_fmas_f32 v23, v23, v26, v28
	v_div_fixup_f32 v17, v23, v22, v17
	v_lshlrev_b32_e32 v22, 16, v34
	v_sub_f32_e32 v22, v22, v41
	v_mul_f32_e32 v22, v22, v40
	v_mul_f32_e32 v16, v16, v22
	v_and_b32_e32 v22, 0xffff0000, v34
	v_sub_f32_e32 v22, v22, v41
	v_mul_f32_e32 v22, v22, v40
	v_mul_f32_e32 v17, v17, v22
	v_cvt_pk_bf16_f32 v22, v16, v17
	v_mul_f32_e32 v16, 0xbfb8aa3b, v18
	v_exp_f32_e32 v16, v16
	s_nop 0
	v_add_f32_e32 v16, 1.0, v16
	v_div_scale_f32 v17, s[0:1], v16, v16, v18
	v_rcp_f32_e32 v23, v17
	s_nop 0
	v_fma_f32 v26, -v17, v23, 1.0
	v_fmac_f32_e32 v23, v26, v23
	v_div_scale_f32 v26, vcc, v18, v16, v18
	v_mul_f32_e32 v27, v26, v23
	v_fma_f32 v28, -v17, v27, v26
	v_fmac_f32_e32 v27, v28, v23
	v_fma_f32 v17, -v17, v27, v26
	v_div_fmas_f32 v17, v17, v23, v27
	v_div_fixup_f32 v16, v17, v16, v18
	v_mul_f32_e32 v17, 0xbfb8aa3b, v19
	v_exp_f32_e32 v17, v17
	s_nop 0
	v_add_f32_e32 v17, 1.0, v17
	v_div_scale_f32 v18, s[0:1], v17, v17, v19
	v_rcp_f32_e32 v23, v18
	s_nop 0
	v_fma_f32 v26, -v18, v23, 1.0
	v_fmac_f32_e32 v23, v26, v23
	v_div_scale_f32 v26, vcc, v19, v17, v19
	v_mul_f32_e32 v27, v26, v23
	v_fma_f32 v28, -v18, v27, v26
	v_fmac_f32_e32 v27, v28, v23
	v_fma_f32 v18, -v18, v27, v26
	v_div_fmas_f32 v18, v18, v23, v27
	v_div_fixup_f32 v17, v18, v17, v19
	v_lshlrev_b32_e32 v18, 16, v35
	v_sub_f32_e32 v18, v18, v41
	v_mul_f32_e32 v18, v18, v40
	v_mul_f32_e32 v16, v16, v18
	v_and_b32_e32 v18, 0xffff0000, v35
	v_sub_f32_e32 v18, v18, v41
	v_mul_f32_e32 v18, v18, v40
	v_mul_f32_e32 v17, v17, v18
	v_cvt_pk_bf16_f32 v23, v16, v17
	v_add_u32_e32 v16, 0xb0, v162
	v_ashrrev_i32_e32 v17, 31, v16
	v_lshlrev_b64 v[18:19], 9, v[16:17]
	v_lshl_add_u64 v[18:19], s[2:3], 0, v[18:19]
	v_lshl_add_u64 v[18:19], v[18:19], 0, s[48:49]
	global_store_dwordx4 v[24:25], v[20:23], off offset:256
	v_lshl_add_u64 v[18:19], v[18:19], 0, v[166:167]
	v_lshlrev_b64 v[16:17], 12, v[16:17]
	v_lshl_add_u64 v[16:17], v[16:17], 0, v[164:165]
	v_lshlrev_b64 v[26:27], 1, v[16:17]
	v_lshl_add_u64 v[16:17], s[4:5], 0, v[26:27]
	s_waitcnt vmcnt(2)
; __device__ __forceinline__ unsigned cvt_pk_bf16(float lo, float hi) { unsigned r; asm volatile("v_cvt_pk_bf16_f32 %0, %1, %2" : "=v"(r) : "v"(lo), "v"(hi)); return r; }
; __device__ __forceinline__ float bf_lo(unsigned w) { return __uint_as_float(w << 16); }
; __device__ __forceinline__ float bf_hi(unsigned w) { return __uint_as_float(w & 0xffff0000u); }
;     __device__ __forceinline__ void operator()(const Acc& acc, const Unit& u, int wr, int wc, int fr, int fq) const {
;     ...
;                 const int row_in = ai * HALF + wr * 64 + m * 16 + fr, s = u.pm * BM + row_in;
;                 const f32x4 tq = ((const f32x4*)(stats + ((size_t)s * 8 + h) * 8))[fq];
;                 const size_t off = (size_t)s * RV + u.pn * BM + wc * 32 + 8 * fq;
;                 const u32x4 o0 = *(const u32x4*)(O + off), o1 = *(const u32x4*)(O + off + HALF);
;                 float s1 = tq[0] + tq[2], s2 = tq[1] + tq[3];
;                 { const auto r1 = __builtin_amdgcn_permlane16_swap(__float_as_uint(s1), __float_as_uint(s1), false, false); s1 = __uint_as_float(r1[0]) + __uint_as_float(r1[1]);
;                   const auto r2 = __builtin_amdgcn_permlane16_swap(__float_as_uint(s2), __float_as_uint(s2), false, false); s2 = __uint_as_float(r2[0]) + __uint_as_float(r2[1]);
;                   const auto r3 = __builtin_amdgcn_permlane32_swap(__float_as_uint(s1), __float_as_uint(s1), false, false); s1 = __uint_as_float(r3[0]) + __uint_as_float(r3[1]);
;                   const auto r4 = __builtin_amdgcn_permlane32_swap(__float_as_uint(s2), __float_as_uint(s2), false, false); s2 = __uint_as_float(r4[0]) + __uint_as_float(r4[1]); }
;                 const float mu = s1 * (1.0f / 512.0f), var = fmaxf(s2 * (1.0f / 512.0f) - mu * mu, 0.f), rstd = rsqrtf(var + EPS);
; #pragma unroll
;                 for (int bj = 0; bj < 2; ++bj) { const u32x4 ov = bj == 0 ? o0 : o1; const unsigned ow[4] = {ov.x, ov.y, ov.z, ov.w}; unsigned r[4];
; #pragma unroll
;                     for (int p = 0; p < 4; ++p) { const f32x4 v = acc[ai][bj][m][p >> 1]; const float g0 = silu_f(v[(p & 1) * 2]), g1 = silu_f(v[(p & 1) * 2 + 1]);
;                         r[p] = cvt_pk_bf16(g0 * ((bf_lo(ow[p]) - mu) * rstd), g1 * ((bf_hi(ow[p]) - mu) * rstd)); }
;                     *(u32x4*)(U + off + bj * HALF) = (u32x4){r[0], r[1], r[2], r[3]}; }
	v_mov_b32_e32 v28, v204
	v_mov_b32_e32 v29, v205
	v_mov_b32_e32 v30, v206
	v_mov_b32_e32 v31, v207
	v_mov_b32_e32 v20, v208
	v_mov_b32_e32 v21, v209
	v_mov_b32_e32 v22, v210
	v_mov_b32_e32 v23, v211
	v_mov_b32_e32 v16, v212
	v_mov_b32_e32 v17, v213
	v_mov_b32_e32 v18, v214
	v_mov_b32_e32 v19, v215
	v_add_f32_e32 v24, v28, v30
	v_mov_b32_e32 v25, v24
	v_add_f32_e32 v28, v29, v31
	s_nop 0
	v_permlane16_swap_b32_e32 v24, v25
	v_add_f32_e32 v25, v24, v25
	v_mov_b32_e32 v24, v28
	s_nop 1
	v_permlane16_swap_b32_e32 v28, v24
	v_add_f32_e32 v24, v28, v24
	v_mov_b32_e32 v29, v25
	v_mov_b32_e32 v28, v24
	s_nop 0
	v_permlane32_swap_b32_e32 v25, v29
	v_permlane32_swap_b32_e32 v24, v28
	v_pk_add_f32 v[24:25], v[24:25], v[28:29]
	s_nop 0
	v_pk_mul_f32 v[24:25], v[24:25], s[8:9] op_sel_hi:[1,0]
	s_nop 0
	v_fma_f32 v24, -v25, v25, v24
	v_max_f32_e32 v24, 0, v24
	v_add_f32_e32 v24, 0x358637bd, v24
	v_cmp_gt_f32_e32 vcc, s73, v24
	v_mul_f32_e32 v28, 0x4b800000, v24
	s_nop 0
	v_cndmask_b32_e32 v24, v24, v28, vcc
	v_rsq_f32_e32 v24, v24
	s_nop 0
	v_mul_f32_e32 v28, 0x45800000, v24
	v_cndmask_b32_e32 v24, v24, v28, vcc
	v_mul_f32_e32 v28, 0xbfb8aa3b, v12
	v_exp_f32_e32 v28, v28
	s_nop 0
	v_add_f32_e32 v28, 1.0, v28
	v_div_scale_f32 v29, s[0:1], v28, v28, v12
	v_rcp_f32_e32 v30, v29
	s_nop 0
	v_fma_f32 v31, -v29, v30, 1.0
	v_fmac_f32_e32 v30, v31, v30
	v_div_scale_f32 v31, vcc, v12, v28, v12
	v_mul_f32_e32 v32, v31, v30
	v_fma_f32 v33, -v29, v32, v31
	v_fmac_f32_e32 v32, v33, v30
	v_fma_f32 v29, -v29, v32, v31
	v_div_fmas_f32 v29, v29, v30, v32
	v_div_fixup_f32 v12, v29, v28, v12
	v_mul_f32_e32 v28, 0xbfb8aa3b, v13
	v_exp_f32_e32 v28, v28
	s_nop 0
	v_add_f32_e32 v28, 1.0, v28
	v_div_scale_f32 v29, s[0:1], v28, v28, v13
	v_rcp_f32_e32 v30, v29
	s_nop 0
	v_fma_f32 v31, -v29, v30, 1.0
	v_fmac_f32_e32 v30, v31, v30
	v_div_scale_f32 v31, vcc, v13, v28, v13
	v_mul_f32_e32 v32, v31, v30
	v_fma_f32 v33, -v29, v32, v31
	v_fmac_f32_e32 v32, v33, v30
	v_fma_f32 v29, -v29, v32, v31
	v_div_fmas_f32 v29, v29, v30, v32
	v_div_fixup_f32 v13, v29, v28, v13
	v_lshlrev_b32_e32 v28, 16, v20
	v_and_b32_e32 v20, 0xffff0000, v20
	v_sub_f32_e32 v28, v28, v25
	v_sub_f32_e32 v20, v20, v25
	v_mul_f32_e32 v28, v28, v24
	v_mul_f32_e32 v20, v20, v24
	v_mul_f32_e32 v12, v12, v28
	v_mul_f32_e32 v13, v13, v20
	v_cvt_pk_bf16_f32 v12, v12, v13
	v_mul_f32_e32 v13, 0xbfb8aa3b, v14
	v_exp_f32_e32 v13, v13
	s_nop 0
	v_add_f32_e32 v13, 1.0, v13
	v_div_scale_f32 v20, s[0:1], v13, v13, v14
	v_rcp_f32_e32 v28, v20
	s_nop 0
	v_fma_f32 v29, -v20, v28, 1.0
	v_fmac_f32_e32 v28, v29, v28
	v_div_scale_f32 v29, vcc, v14, v13, v14
	v_mul_f32_e32 v30, v29, v28
	v_fma_f32 v31, -v20, v30, v29
	v_fmac_f32_e32 v30, v31, v28
	v_fma_f32 v20, -v20, v30, v29
	v_div_fmas_f32 v20, v20, v28, v30
	v_div_fixup_f32 v13, v20, v13, v14
	v_mul_f32_e32 v14, 0xbfb8aa3b, v15
	v_exp_f32_e32 v14, v14
	s_nop 0
	v_add_f32_e32 v14, 1.0, v14
	v_div_scale_f32 v20, s[0:1], v14, v14, v15
	v_rcp_f32_e32 v28, v20
	s_nop 0
	v_fma_f32 v29, -v20, v28, 1.0
	v_fmac_f32_e32 v28, v29, v28
	v_div_scale_f32 v29, vcc, v15, v14, v15
	v_mul_f32_e32 v30, v29, v28
	v_fma_f32 v31, -v20, v30, v29
	v_fmac_f32_e32 v30, v31, v28
	v_fma_f32 v20, -v20, v30, v29
	v_div_fmas_f32 v20, v20, v28, v30
	v_div_fixup_f32 v14, v20, v14, v15
	v_lshlrev_b32_e32 v15, 16, v21
	v_sub_f32_e32 v15, v15, v25
	v_mul_f32_e32 v15, v15, v24
	v_mul_f32_e32 v13, v13, v15
	v_and_b32_e32 v15, 0xffff0000, v21
	v_sub_f32_e32 v15, v15, v25
	v_mul_f32_e32 v15, v15, v24
	v_mul_f32_e32 v14, v14, v15
	v_cvt_pk_bf16_f32 v13, v13, v14
	v_mul_f32_e32 v14, 0xbfb8aa3b, v8
	v_exp_f32_e32 v14, v14
	s_nop 0
	v_add_f32_e32 v14, 1.0, v14
	v_div_scale_f32 v15, s[0:1], v14, v14, v8
	v_rcp_f32_e32 v20, v15
	s_nop 0
	v_fma_f32 v21, -v15, v20, 1.0
	v_fmac_f32_e32 v20, v21, v20
	v_div_scale_f32 v21, vcc, v8, v14, v8
	v_mul_f32_e32 v28, v21, v20
	v_fma_f32 v29, -v15, v28, v21
	v_fmac_f32_e32 v28, v29, v20
	v_fma_f32 v15, -v15, v28, v21
	v_div_fmas_f32 v15, v15, v20, v28
	v_div_fixup_f32 v8, v15, v14, v8
	v_mul_f32_e32 v14, 0xbfb8aa3b, v9
	v_exp_f32_e32 v14, v14
	s_nop 0
	v_add_f32_e32 v14, 1.0, v14
	v_div_scale_f32 v15, s[0:1], v14, v14, v9
	v_rcp_f32_e32 v20, v15
	s_nop 0
	v_fma_f32 v21, -v15, v20, 1.0
	v_fmac_f32_e32 v20, v21, v20
	v_div_scale_f32 v21, vcc, v9, v14, v9
	v_mul_f32_e32 v28, v21, v20
	v_fma_f32 v29, -v15, v28, v21
	v_fmac_f32_e32 v28, v29, v20
	v_fma_f32 v15, -v15, v28, v21
	v_div_fmas_f32 v15, v15, v20, v28
	v_div_fixup_f32 v9, v15, v14, v9
	v_lshlrev_b32_e32 v14, 16, v22
	v_sub_f32_e32 v14, v14, v25
	v_mul_f32_e32 v14, v14, v24
	v_mul_f32_e32 v8, v8, v14
	v_and_b32_e32 v14, 0xffff0000, v22
	v_sub_f32_e32 v14, v14, v25
	v_mul_f32_e32 v14, v14, v24
	v_mul_f32_e32 v9, v9, v14
	v_cvt_pk_bf16_f32 v14, v8, v9
	v_mul_f32_e32 v8, 0xbfb8aa3b, v10
	v_exp_f32_e32 v8, v8
	s_nop 0
	v_add_f32_e32 v8, 1.0, v8
	v_div_scale_f32 v9, s[0:1], v8, v8, v10
	v_rcp_f32_e32 v15, v9
	s_nop 0
	v_fma_f32 v20, -v9, v15, 1.0
	v_fmac_f32_e32 v15, v20, v15
	v_div_scale_f32 v20, vcc, v10, v8, v10
	v_mul_f32_e32 v21, v20, v15
	v_fma_f32 v22, -v9, v21, v20
	v_fmac_f32_e32 v21, v22, v15
	v_fma_f32 v9, -v9, v21, v20
	v_div_fmas_f32 v9, v9, v15, v21
	v_div_fixup_f32 v8, v9, v8, v10
	v_mul_f32_e32 v9, 0xbfb8aa3b, v11
	v_exp_f32_e32 v9, v9
	s_nop 0
	v_add_f32_e32 v9, 1.0, v9
	v_div_scale_f32 v10, s[0:1], v9, v9, v11
	v_rcp_f32_e32 v15, v10
	s_nop 0
	v_fma_f32 v20, -v10, v15, 1.0
	v_fmac_f32_e32 v15, v20, v15
; __device__ __forceinline__ unsigned cvt_pk_bf16(float lo, float hi) { unsigned r; asm volatile("v_cvt_pk_bf16_f32 %0, %1, %2" : "=v"(r) : "v"(lo), "v"(hi)); return r; }
; __device__ __forceinline__ float bf_lo(unsigned w) { return __uint_as_float(w << 16); }
; __device__ __forceinline__ float bf_hi(unsigned w) { return __uint_as_float(w & 0xffff0000u); }
; __device__ __forceinline__ float silu_f(float v) { return v / (1.0f + __expf(-v)); }
; #define PG8_BAR __builtin_amdgcn_s_barrier()
; template <class Epi, class Map>
; __device__ __forceinline__ void gemm_phase(LAS unsigned char* lds, const Gemm g, const Sched<Map>& S, const Epi& E) {
;     ...
;         if (wr == 0) PG8_BAR;
;         E(acc, cur, wr, wc, fr, fq);
;         if (!has_next) break;
; #pragma unroll
;         for (int a = 0; a < 2; ++a)
; #pragma unroll
;             for (int b = 0; b < 2; ++b)
; #pragma unroll
;                 for (int m = 0; m < 4; ++m)
; #pragma unroll
;                     for (int n = 0; n < 2; ++n) acc[a][b][m][n] = (f32x4){0.f, 0.f, 0.f, 0.f};
;         cur = nxt; cA = nA; cB = nB; ++ui;
;         if (wr == 1) PG8_BAR;
;     __device__ __forceinline__ void operator()(const Acc& acc, const Unit& u, int wr, int wc, int fr, int fq) const {
;     ...
;                 const float mu = s1 * (1.0f / 512.0f), var = fmaxf(s2 * (1.0f / 512.0f) - mu * mu, 0.f), rstd = rsqrtf(var + EPS);
; #pragma unroll
;                 for (int bj = 0; bj < 2; ++bj) { const u32x4 ov = bj == 0 ? o0 : o1; const unsigned ow[4] = {ov.x, ov.y, ov.z, ov.w}; unsigned r[4];
; #pragma unroll
;                     for (int p = 0; p < 4; ++p) { const f32x4 v = acc[ai][bj][m][p >> 1]; const float g0 = silu_f(v[(p & 1) * 2]), g1 = silu_f(v[(p & 1) * 2 + 1]);
;                         r[p] = cvt_pk_bf16(g0 * ((bf_lo(ow[p]) - mu) * rstd), g1 * ((bf_hi(ow[p]) - mu) * rstd)); }
;                     *(u32x4*)(U + off + bj * HALF) = (u32x4){r[0], r[1], r[2], r[3]}; }
	v_div_scale_f32 v20, vcc, v11, v9, v11
	v_mul_f32_e32 v21, v20, v15
	v_fma_f32 v22, -v10, v21, v20
	v_fmac_f32_e32 v21, v22, v15
	v_fma_f32 v10, -v10, v21, v20
	v_div_fmas_f32 v10, v10, v15, v21
	v_div_fixup_f32 v9, v10, v9, v11
	v_lshlrev_b32_e32 v10, 16, v23
	v_sub_f32_e32 v10, v10, v25
	v_mul_f32_e32 v10, v10, v24
	v_mul_f32_e32 v8, v8, v10
	v_and_b32_e32 v10, 0xffff0000, v23
	v_sub_f32_e32 v10, v10, v25
	v_mul_f32_e32 v10, v10, v24
	v_mul_f32_e32 v9, v9, v10
	v_mul_f32_e32 v10, 0xbfb8aa3b, v4
	v_exp_f32_e32 v10, v10
	v_cvt_pk_bf16_f32 v15, v8, v9
	v_lshl_add_u64 v[8:9], s[6:7], 0, v[26:27]
	global_store_dwordx4 v[8:9], v[12:15], off
	v_add_f32_e32 v10, 1.0, v10
	v_div_scale_f32 v11, s[0:1], v10, v10, v4
	v_rcp_f32_e32 v12, v11
	s_nop 0
	v_fma_f32 v13, -v11, v12, 1.0
	v_fmac_f32_e32 v12, v13, v12
	v_div_scale_f32 v13, vcc, v4, v10, v4
	v_mul_f32_e32 v14, v13, v12
	v_fma_f32 v15, -v11, v14, v13
	v_fmac_f32_e32 v14, v15, v12
	v_fma_f32 v11, -v11, v14, v13
	v_div_fmas_f32 v11, v11, v12, v14
	v_div_fixup_f32 v4, v11, v10, v4
	v_mul_f32_e32 v10, 0xbfb8aa3b, v5
	v_exp_f32_e32 v10, v10
	s_nop 0
	v_add_f32_e32 v10, 1.0, v10
	v_div_scale_f32 v11, s[0:1], v10, v10, v5
	v_rcp_f32_e32 v12, v11
	s_nop 0
	v_fma_f32 v13, -v11, v12, 1.0
	v_fmac_f32_e32 v12, v13, v12
	v_div_scale_f32 v13, vcc, v5, v10, v5
	v_mul_f32_e32 v14, v13, v12
	v_fma_f32 v15, -v11, v14, v13
	v_fmac_f32_e32 v14, v15, v12
	v_fma_f32 v11, -v11, v14, v13
	v_div_fmas_f32 v11, v11, v12, v14
	v_div_fixup_f32 v5, v11, v10, v5
	v_lshlrev_b32_e32 v10, 16, v16
	v_sub_f32_e32 v10, v10, v25
	v_mul_f32_e32 v10, v10, v24
	v_mul_f32_e32 v4, v4, v10
	v_and_b32_e32 v10, 0xffff0000, v16
	v_sub_f32_e32 v10, v10, v25
	v_mul_f32_e32 v10, v10, v24
	v_mul_f32_e32 v5, v5, v10
	v_cvt_pk_bf16_f32 v4, v4, v5
	v_mul_f32_e32 v5, 0xbfb8aa3b, v6
	v_exp_f32_e32 v5, v5
	s_nop 0
	v_add_f32_e32 v5, 1.0, v5
	v_div_scale_f32 v10, s[0:1], v5, v5, v6
	v_rcp_f32_e32 v11, v10
	s_nop 0
	v_fma_f32 v12, -v10, v11, 1.0
	v_fmac_f32_e32 v11, v12, v11
	v_div_scale_f32 v12, vcc, v6, v5, v6
	v_mul_f32_e32 v13, v12, v11
	v_fma_f32 v14, -v10, v13, v12
	v_fmac_f32_e32 v13, v14, v11
	v_fma_f32 v10, -v10, v13, v12
	v_div_fmas_f32 v10, v10, v11, v13
	v_div_fixup_f32 v5, v10, v5, v6
	v_mul_f32_e32 v6, 0xbfb8aa3b, v7
	v_exp_f32_e32 v6, v6
	s_nop 0
	v_add_f32_e32 v6, 1.0, v6
	v_div_scale_f32 v10, s[0:1], v6, v6, v7
	v_rcp_f32_e32 v11, v10
	s_nop 0
	v_fma_f32 v12, -v10, v11, 1.0
	v_fmac_f32_e32 v11, v12, v11
	v_div_scale_f32 v12, vcc, v7, v6, v7
	v_mul_f32_e32 v13, v12, v11
	v_fma_f32 v14, -v10, v13, v12
	v_fmac_f32_e32 v13, v14, v11
	v_fma_f32 v10, -v10, v13, v12
	v_div_fmas_f32 v10, v10, v11, v13
	v_div_fixup_f32 v6, v10, v6, v7
	v_lshlrev_b32_e32 v7, 16, v17
	v_sub_f32_e32 v7, v7, v25
	v_mul_f32_e32 v7, v7, v24
	v_mul_f32_e32 v5, v5, v7
	v_and_b32_e32 v7, 0xffff0000, v17
	v_sub_f32_e32 v7, v7, v25
	v_mul_f32_e32 v7, v7, v24
	v_mul_f32_e32 v6, v6, v7
	v_cvt_pk_bf16_f32 v5, v5, v6
	v_mul_f32_e32 v6, 0xbfb8aa3b, v0
	v_exp_f32_e32 v6, v6
	s_nop 0
	v_add_f32_e32 v6, 1.0, v6
	v_div_scale_f32 v7, s[0:1], v6, v6, v0
	v_rcp_f32_e32 v10, v7
	s_nop 0
	v_fma_f32 v11, -v7, v10, 1.0
	v_fmac_f32_e32 v10, v11, v10
	v_div_scale_f32 v11, vcc, v0, v6, v0
	v_mul_f32_e32 v12, v11, v10
	v_fma_f32 v13, -v7, v12, v11
	v_fmac_f32_e32 v12, v13, v10
	v_fma_f32 v7, -v7, v12, v11
	v_div_fmas_f32 v7, v7, v10, v12
	v_div_fixup_f32 v0, v7, v6, v0
	v_mul_f32_e32 v6, 0xbfb8aa3b, v1
	v_exp_f32_e32 v6, v6
	s_nop 0
	v_add_f32_e32 v6, 1.0, v6
	v_div_scale_f32 v7, s[0:1], v6, v6, v1
	v_rcp_f32_e32 v10, v7
	s_nop 0
	v_fma_f32 v11, -v7, v10, 1.0
	v_fmac_f32_e32 v10, v11, v10
	v_div_scale_f32 v11, vcc, v1, v6, v1
	v_mul_f32_e32 v12, v11, v10
	v_fma_f32 v13, -v7, v12, v11
	v_fmac_f32_e32 v12, v13, v10
	v_fma_f32 v7, -v7, v12, v11
	v_div_fmas_f32 v7, v7, v10, v12
	v_div_fixup_f32 v1, v7, v6, v1
	v_lshlrev_b32_e32 v6, 16, v18
	v_sub_f32_e32 v6, v6, v25
	v_mul_f32_e32 v6, v6, v24
	v_mul_f32_e32 v0, v0, v6
	v_and_b32_e32 v6, 0xffff0000, v18
	v_sub_f32_e32 v6, v6, v25
	v_mul_f32_e32 v6, v6, v24
	v_mul_f32_e32 v1, v1, v6
	v_cvt_pk_bf16_f32 v6, v0, v1
	v_mul_f32_e32 v0, 0xbfb8aa3b, v2
	v_exp_f32_e32 v0, v0
	s_nop 0
	v_add_f32_e32 v0, 1.0, v0
	v_div_scale_f32 v1, s[0:1], v0, v0, v2
	v_rcp_f32_e32 v7, v1
	s_nop 0
	v_fma_f32 v10, -v1, v7, 1.0
	v_fmac_f32_e32 v7, v10, v7
	v_div_scale_f32 v10, vcc, v2, v0, v2
	v_mul_f32_e32 v11, v10, v7
	v_fma_f32 v12, -v1, v11, v10
	v_fmac_f32_e32 v11, v12, v7
	v_fma_f32 v1, -v1, v11, v10
	v_div_fmas_f32 v1, v1, v7, v11
	v_div_fixup_f32 v0, v1, v0, v2
	v_mul_f32_e32 v1, 0xbfb8aa3b, v3
	v_exp_f32_e32 v1, v1
	s_nop 0
	v_add_f32_e32 v1, 1.0, v1
	v_div_scale_f32 v2, s[0:1], v1, v1, v3
	v_rcp_f32_e32 v7, v2
	s_nop 0
	v_fma_f32 v10, -v2, v7, 1.0
	v_fmac_f32_e32 v7, v10, v7
	v_div_scale_f32 v10, vcc, v3, v1, v3
	v_mul_f32_e32 v11, v10, v7
	v_fma_f32 v12, -v2, v11, v10
	v_fmac_f32_e32 v11, v12, v7
	v_fma_f32 v2, -v2, v11, v10
	v_div_fmas_f32 v2, v2, v7, v11
	v_div_fixup_f32 v1, v2, v1, v3
	v_lshlrev_b32_e32 v2, 16, v19
	v_sub_f32_e32 v2, v2, v25
	v_mul_f32_e32 v2, v2, v24
	v_mul_f32_e32 v0, v0, v2
	v_and_b32_e32 v2, 0xffff0000, v19
	v_sub_f32_e32 v2, v2, v25
	v_mul_f32_e32 v2, v2, v24
	s_andn2_b64 vcc, exec, s[40:41]
	v_mul_f32_e32 v1, v1, v2
	v_cvt_pk_bf16_f32 v7, v0, v1
	global_store_dwordx4 v[8:9], v[4:7], off offset:256
	s_cbranch_vccnz .LBB0_872
	s_andn2_b64 vcc, exec, s[42:43]
	s_cbranch_vccnz .LBB0_871
	s_barrier
	s_branch .LBB0_871

; #define PG8_BAR __builtin_amdgcn_s_barrier()
; template <class Epi, class Map>
; __device__ __forceinline__ void gemm_phase(LAS unsigned char* lds, const Gemm g, const Sched<Map>& S, const Epi& E) {
;     ...
;         if (wr == 0) PG8_BAR;
;     __device__ __forceinline__ void operator()(const Acc& acc, const Unit& u, int wr, int wc, int fr, int fq) const {
;     ...
;         const int row0 = u.pm * BM + wr * 64 + fr, col0 = u.pn * BM + wc * 32 + 4 * fq;
;         const float* gp = gate + (size_t)(u.pm >> 6) * gate_bstride + col0;
;         f32x4 gv[2][2];
; #pragma unroll
;         for (int bj = 0; bj < 2; ++bj)
; #pragma unroll
;             for (int n = 0; n < 2; ++n) gv[bj][n] = *(const f32x4*)(gp + bj * HALF + n * 16);
; #pragma unroll
;         for (int aim = 0; aim < 4; ++aim) { const int ai = aim >> 1, m0 = (aim & 1) * 2;
;             f32x4 bs[2][2][2];
; #pragma unroll
;             for (int mm = 0; mm < 2; ++mm) { const size_t off = (size_t)(row0 + ai * HALF + (m0 + mm) * 16) * D + col0;
; #pragma unroll
;                 for (int bj = 0; bj < 2; ++bj)
; #pragma unroll
;                     for (int n = 0; n < 2; ++n) bs[mm][bj][n] = *(const f32x4*)(base + off + bj * HALF + n * 16); }
; #pragma unroll
;             for (int mm = 0; mm < 2; ++mm) { const size_t off = (size_t)(row0 + ai * HALF + (m0 + mm) * 16) * D + col0;
; #pragma unroll
;                 for (int bj = 0; bj < 2; ++bj)
; #pragma unroll
;                     for (int n = 0; n < 2; ++n) *(f32x4*)(out + off + bj * HALF + n * 16) = bs[mm][bj][n] + gv[bj][n] * acc[ai][bj][m0 + mm][n]; }
;             asm volatile("" ::: "memory"); }
.LBB0_955:
	v_mov_b32_e32 v168, v159
	v_mov_b32_e32 v64, v172
	s_lshl_b32 s15, s15, 8
	s_or_b32 s15, s15, s6
	s_lshl_b32 s14, s14, 8
	v_lshl_add_u32 v64, v64, 2, s15
	s_add_i32 s14, s14, s5
	v_ashrrev_i32_e32 v65, 31, v64
	v_add_u32_e32 v170, s14, v168
	v_lshlrev_b64 v[166:167], 2, v[64:65]
	v_ashrrev_i32_e32 v171, 31, v170
	v_lshl_add_u64 v[168:169], s[18:19], 0, v[166:167]
	v_lshlrev_b64 v[170:171], 13, v[170:171]
	v_lshl_add_u64 v[64:65], s[24:25], 0, v[166:167]
	v_lshl_add_u64 v[180:181], v[168:169], 0, v[170:171]
	s_mov_b64 s[14:15], 0x20000
	global_load_dwordx4 v[108:111], v[64:65], off
	global_load_dwordx4 v[72:75], v[64:65], off offset:64
	global_load_dwordx4 v[68:71], v[64:65], off offset:512
	s_nop 0
	global_load_dwordx4 v[64:67], v[64:65], off offset:576
	s_nop 0
	global_load_dwordx4 v[176:179], v[180:181], off
	global_load_dwordx4 v[192:195], v[180:181], off offset:64
	global_load_dwordx4 v[196:199], v[180:181], off offset:512
	global_load_dwordx4 v[200:203], v[180:181], off offset:576
	v_lshl_add_u64 v[180:181], v[170:171], 0, s[14:15]
	v_lshl_add_u64 v[216:217], v[168:169], 0, v[180:181]
	global_load_dwordx4 v[204:207], v[216:217], off
	global_load_dwordx4 v[208:211], v[216:217], off offset:64
	global_load_dwordx4 v[212:215], v[216:217], off offset:512
	s_nop 0
	global_load_dwordx4 v[216:219], v[216:217], off offset:576
	s_mov_b64 s[14:15], 0x40000
	s_mov_b64 s[36:37], -1
	s_andn2_b64 vcc, exec, s[38:39]
	s_waitcnt vmcnt(0)
	v_pk_fma_f32 v[140:141], v[140:141], v[108:109], v[176:177]
	v_lshl_add_u64 v[176:177], s[20:21], 0, v[170:171]
	v_lshl_add_u64 v[176:177], v[176:177], 0, v[166:167]
	v_pk_fma_f32 v[126:127], v[126:127], v[70:71], v[198:199]
	v_pk_fma_f32 v[124:125], v[124:125], v[68:69], v[196:197]
	global_store_dwordx4 v[176:177], v[124:127], off offset:512
	v_pk_fma_f32 v[122:123], v[122:123], v[66:67], v[202:203]
	v_pk_fma_f32 v[120:121], v[120:121], v[64:65], v[200:201]
	v_lshl_add_u64 v[124:125], s[20:21], 0, v[180:181]
	global_store_dwordx4 v[176:177], v[120:123], off offset:576
	v_lshl_add_u64 v[124:125], v[124:125], 0, v[166:167]
	v_pk_fma_f32 v[142:143], v[142:143], v[110:111], v[178:179]
	v_pk_fma_f32 v[122:123], v[134:135], v[110:111], v[206:207]
	v_pk_fma_f32 v[120:121], v[132:133], v[108:109], v[204:205]
	v_pk_fma_f32 v[138:139], v[138:139], v[74:75], v[194:195]
	v_pk_fma_f32 v[136:137], v[136:137], v[72:73], v[192:193]
	global_store_dwordx4 v[124:125], v[120:123], off
	v_pk_fma_f32 v[118:119], v[118:119], v[70:71], v[214:215]
	v_pk_fma_f32 v[116:117], v[116:117], v[68:69], v[212:213]
	v_pk_fma_f32 v[122:123], v[130:131], v[74:75], v[210:211]
	v_pk_fma_f32 v[120:121], v[128:129], v[72:73], v[208:209]
	v_pk_fma_f32 v[114:115], v[114:115], v[66:67], v[218:219]
	v_pk_fma_f32 v[112:113], v[112:113], v[64:65], v[216:217]
	global_store_dwordx4 v[176:177], v[140:143], off
	global_store_dwordx4 v[176:177], v[136:139], off offset:64
	global_store_dwordx4 v[124:125], v[120:123], off offset:64
	s_cmp_lg_u64 s[28:29], 0
	s_cbranch_scc0 .Llate_align_9
	s_barrier
.Llate_align_9:
	global_store_dwordx4 v[124:125], v[116:119], off offset:512
	global_store_dwordx4 v[124:125], v[112:115], off offset:576
	v_lshl_add_u64 v[176:177], v[170:171], 0, s[14:15]
	v_lshl_add_u64 v[124:125], v[168:169], 0, v[176:177]
	s_mov_b64 s[14:15], 0x60000
	global_load_dwordx4 v[112:115], v[124:125], off
	global_load_dwordx4 v[116:119], v[124:125], off offset:64
	global_load_dwordx4 v[120:123], v[124:125], off offset:512
	s_nop 0
	global_load_dwordx4 v[124:127], v[124:125], off offset:576
	v_lshl_add_u64 v[178:179], v[170:171], 0, s[14:15]
	v_lshl_add_u64 v[140:141], v[168:169], 0, v[178:179]
	global_load_dwordx4 v[128:131], v[140:141], off
	global_load_dwordx4 v[132:135], v[140:141], off offset:64
	global_load_dwordx4 v[136:139], v[140:141], off offset:512
	s_nop 0
	global_load_dwordx4 v[140:143], v[140:141], off offset:576
	s_mov_b64 s[14:15], 0x100000
	s_waitcnt vmcnt(7)
	v_pk_fma_f32 v[104:105], v[104:105], v[108:109], v[112:113]
	v_lshl_add_u64 v[112:113], s[20:21], 0, v[176:177]
	v_lshl_add_u64 v[112:113], v[112:113], 0, v[166:167]
	s_waitcnt vmcnt(5)
	v_pk_fma_f32 v[90:91], v[90:91], v[70:71], v[122:123]
	v_pk_fma_f32 v[88:89], v[88:89], v[68:69], v[120:121]
	global_store_dwordx4 v[112:113], v[88:91], off offset:512
	s_waitcnt vmcnt(5)
	v_pk_fma_f32 v[86:87], v[86:87], v[66:67], v[126:127]
	v_pk_fma_f32 v[84:85], v[84:85], v[64:65], v[124:125]
	v_lshl_add_u64 v[88:89], s[20:21], 0, v[178:179]
	global_store_dwordx4 v[112:113], v[84:87], off offset:576
	v_lshl_add_u64 v[88:89], v[88:89], 0, v[166:167]
	v_pk_fma_f32 v[106:107], v[106:107], v[110:111], v[114:115]
	s_waitcnt vmcnt(5)
	v_pk_fma_f32 v[86:87], v[98:99], v[110:111], v[130:131]
	v_pk_fma_f32 v[84:85], v[96:97], v[108:109], v[128:129]
	v_pk_fma_f32 v[102:103], v[102:103], v[74:75], v[118:119]
	v_pk_fma_f32 v[100:101], v[100:101], v[72:73], v[116:117]
	global_store_dwordx4 v[88:89], v[84:87], off
	s_waitcnt vmcnt(4)
	v_pk_fma_f32 v[82:83], v[82:83], v[70:71], v[138:139]
	v_pk_fma_f32 v[80:81], v[80:81], v[68:69], v[136:137]
	v_pk_fma_f32 v[86:87], v[94:95], v[74:75], v[134:135]
	v_pk_fma_f32 v[84:85], v[92:93], v[72:73], v[132:133]
	s_waitcnt vmcnt(3)
;     __device__ __forceinline__ void operator()(const Acc& acc, const Unit& u, int wr, int wc, int fr, int fq) const {
;     ...
;         for (int aim = 0; aim < 4; ++aim) { const int ai = aim >> 1, m0 = (aim & 1) * 2;
;             f32x4 bs[2][2][2];
; #pragma unroll
;             for (int mm = 0; mm < 2; ++mm) { const size_t off = (size_t)(row0 + ai * HALF + (m0 + mm) * 16) * D + col0;
; #pragma unroll
;                 for (int bj = 0; bj < 2; ++bj)
; #pragma unroll
;                     for (int n = 0; n < 2; ++n) bs[mm][bj][n] = *(const f32x4*)(base + off + bj * HALF + n * 16); }
; #pragma unroll
;             for (int mm = 0; mm < 2; ++mm) { const size_t off = (size_t)(row0 + ai * HALF + (m0 + mm) * 16) * D + col0;
; #pragma unroll
;                 for (int bj = 0; bj < 2; ++bj)
; #pragma unroll
;                     for (int n = 0; n < 2; ++n) *(f32x4*)(out + off + bj * HALF + n * 16) = bs[mm][bj][n] + gv[bj][n] * acc[ai][bj][m0 + mm][n]; }
;             asm volatile("" ::: "memory"); }
	v_pk_fma_f32 v[78:79], v[78:79], v[66:67], v[142:143]
	v_pk_fma_f32 v[76:77], v[76:77], v[64:65], v[140:141]
	global_store_dwordx4 v[112:113], v[104:107], off
	global_store_dwordx4 v[112:113], v[100:103], off offset:64
	global_store_dwordx4 v[88:89], v[84:87], off offset:64
	global_store_dwordx4 v[88:89], v[80:83], off offset:512
	global_store_dwordx4 v[88:89], v[76:79], off offset:576
	v_lshl_add_u64 v[112:113], v[170:171], 0, s[14:15]
	v_lshl_add_u64 v[88:89], v[168:169], 0, v[112:113]
	s_mov_b64 s[14:15], 0x120000
	global_load_dwordx4 v[76:79], v[88:89], off
	global_load_dwordx4 v[80:83], v[88:89], off offset:64
	global_load_dwordx4 v[84:87], v[88:89], off offset:512
	s_nop 0
	global_load_dwordx4 v[88:91], v[88:89], off offset:576
	v_lshl_add_u64 v[114:115], v[170:171], 0, s[14:15]
	v_lshl_add_u64 v[104:105], v[168:169], 0, v[114:115]
	global_load_dwordx4 v[92:95], v[104:105], off
	global_load_dwordx4 v[96:99], v[104:105], off offset:64
	global_load_dwordx4 v[100:103], v[104:105], off offset:512
	s_nop 0
	global_load_dwordx4 v[104:107], v[104:105], off offset:576
	s_mov_b64 s[14:15], 0x140000
	s_waitcnt vmcnt(7)
	v_pk_fma_f32 v[60:61], v[60:61], v[108:109], v[76:77]
	v_lshl_add_u64 v[76:77], s[20:21], 0, v[112:113]
	v_lshl_add_u64 v[76:77], v[76:77], 0, v[166:167]
	s_waitcnt vmcnt(5)
	v_pk_fma_f32 v[46:47], v[46:47], v[70:71], v[86:87]
	v_pk_fma_f32 v[44:45], v[44:45], v[68:69], v[84:85]
	global_store_dwordx4 v[76:77], v[44:47], off offset:512
	s_waitcnt vmcnt(5)
	v_pk_fma_f32 v[42:43], v[42:43], v[66:67], v[90:91]
	v_pk_fma_f32 v[40:41], v[40:41], v[64:65], v[88:89]
	v_lshl_add_u64 v[44:45], s[20:21], 0, v[114:115]
	global_store_dwordx4 v[76:77], v[40:43], off offset:576
	v_lshl_add_u64 v[44:45], v[44:45], 0, v[166:167]
	v_pk_fma_f32 v[62:63], v[62:63], v[110:111], v[78:79]
	s_waitcnt vmcnt(5)
	v_pk_fma_f32 v[42:43], v[54:55], v[110:111], v[94:95]
	v_pk_fma_f32 v[40:41], v[52:53], v[108:109], v[92:93]
	v_pk_fma_f32 v[58:59], v[58:59], v[74:75], v[82:83]
	v_pk_fma_f32 v[56:57], v[56:57], v[72:73], v[80:81]
	global_store_dwordx4 v[44:45], v[40:43], off
	s_waitcnt vmcnt(4)
	v_pk_fma_f32 v[38:39], v[38:39], v[70:71], v[102:103]
	v_pk_fma_f32 v[36:37], v[36:37], v[68:69], v[100:101]
	v_pk_fma_f32 v[42:43], v[50:51], v[74:75], v[98:99]
	v_pk_fma_f32 v[40:41], v[48:49], v[72:73], v[96:97]
	s_waitcnt vmcnt(3)
	v_pk_fma_f32 v[34:35], v[34:35], v[66:67], v[106:107]
	v_pk_fma_f32 v[32:33], v[32:33], v[64:65], v[104:105]
	global_store_dwordx4 v[76:77], v[60:63], off
	global_store_dwordx4 v[76:77], v[56:59], off offset:64
	global_store_dwordx4 v[44:45], v[40:43], off offset:64
	global_store_dwordx4 v[44:45], v[36:39], off offset:512
	global_store_dwordx4 v[44:45], v[32:35], off offset:576
	v_lshl_add_u64 v[76:77], v[170:171], 0, s[14:15]
	s_mov_b64 s[14:15], 0x160000
	v_lshl_add_u64 v[44:45], v[168:169], 0, v[76:77]
	v_lshl_add_u64 v[78:79], v[170:171], 0, s[14:15]
	global_load_dwordx4 v[32:35], v[44:45], off
	global_load_dwordx4 v[36:39], v[44:45], off offset:64
	global_load_dwordx4 v[40:43], v[44:45], off offset:512
	s_nop 0
	global_load_dwordx4 v[44:47], v[44:45], off offset:576
	v_lshl_add_u64 v[60:61], v[168:169], 0, v[78:79]
	global_load_dwordx4 v[48:51], v[60:61], off
	global_load_dwordx4 v[52:55], v[60:61], off offset:64
	global_load_dwordx4 v[56:59], v[60:61], off offset:512
	s_nop 0
	global_load_dwordx4 v[60:63], v[60:61], off offset:576
	s_waitcnt vmcnt(7)
	v_pk_fma_f32 v[28:29], v[28:29], v[108:109], v[32:33]
	v_lshl_add_u64 v[32:33], s[20:21], 0, v[76:77]
	v_lshl_add_u64 v[32:33], v[32:33], 0, v[166:167]
	s_waitcnt vmcnt(5)
	v_pk_fma_f32 v[18:19], v[18:19], v[70:71], v[42:43]
	v_pk_fma_f32 v[16:17], v[16:17], v[68:69], v[40:41]
	global_store_dwordx4 v[32:33], v[16:19], off offset:512
	s_waitcnt vmcnt(5)
	v_pk_fma_f32 v[14:15], v[14:15], v[66:67], v[46:47]
	v_pk_fma_f32 v[12:13], v[12:13], v[64:65], v[44:45]
	v_lshl_add_u64 v[16:17], s[20:21], 0, v[78:79]
	v_pk_fma_f32 v[30:31], v[30:31], v[110:111], v[34:35]
	v_pk_fma_f32 v[26:27], v[26:27], v[74:75], v[38:39]
	v_pk_fma_f32 v[24:25], v[24:25], v[72:73], v[36:37]
	global_store_dwordx4 v[32:33], v[12:15], off offset:576
	v_lshl_add_u64 v[16:17], v[16:17], 0, v[166:167]
	s_waitcnt vmcnt(4)
	v_pk_fma_f32 v[10:11], v[10:11], v[74:75], v[54:55]
	v_pk_fma_f32 v[14:15], v[22:23], v[110:111], v[50:51]
	v_pk_fma_f32 v[12:13], v[20:21], v[108:109], v[48:49]
	v_pk_fma_f32 v[8:9], v[8:9], v[72:73], v[52:53]
	s_waitcnt vmcnt(3)
	v_pk_fma_f32 v[6:7], v[6:7], v[70:71], v[58:59]
	v_pk_fma_f32 v[4:5], v[4:5], v[68:69], v[56:57]
	s_waitcnt vmcnt(2)
	v_pk_fma_f32 v[2:3], v[2:3], v[66:67], v[62:63]
	v_pk_fma_f32 v[0:1], v[0:1], v[64:65], v[60:61]
	global_store_dwordx4 v[32:33], v[28:31], off
	global_store_dwordx4 v[32:33], v[24:27], off offset:64
	global_store_dwordx4 v[16:17], v[12:15], off
	global_store_dwordx4 v[16:17], v[8:11], off offset:64
	global_store_dwordx4 v[16:17], v[4:7], off offset:512
	global_store_dwordx4 v[16:17], v[0:3], off offset:576
	s_cbranch_vccnz .LBB0_944
	s_andn2_b64 vcc, exec, s[16:17]
	s_cbranch_vccnz .LBB0_943
	s_barrier
	s_branch .LBB0_943

; __device__ __forceinline__ unsigned cvt_pk_bf16(float lo, float hi) { unsigned r; asm volatile("v_cvt_pk_bf16_f32 %0, %1, %2" : "=v"(r) : "v"(lo), "v"(hi)); return r; }
; __device__ __forceinline__ float silu_f(float v) { return v / (1.0f + __expf(-v)); }
; #define PG8_BAR __builtin_amdgcn_s_barrier()
; template <class Epi, class Map>
; __device__ __forceinline__ void gemm_phase(LAS unsigned char* lds, const Gemm g, const Sched<Map>& S, const Epi& E) {
;     ...
;         if (wr == 0) PG8_BAR;
;     __device__ __forceinline__ void operator()(const Acc& acc, const Unit& u, int wr, int wc, int fr, int fq) const {
;     ...
;             for (int m = 0; m < 4; ++m) { bf16_t* rowp = base + (size_t)(ai * HALF + m * 16) * ldc;
; #pragma unroll
;                 for (int bj = 0; bj < 2; ++bj) { f32x4 v0 = acc[ai][bj][m][0], v1 = acc[ai][bj][m][1];
;                     if (ACT == 1) {
; #pragma unroll
;                         for (int j = 0; j < 4; ++j) { v0[j] = silu_f(v0[j]); v1[j] = silu_f(v1[j]); } }
;                     if (ACT == 2) {
; #pragma unroll
;                         for (int j = 0; j < 4; ++j) { const float a = fmaxf(v0[j], 0.f), b = fmaxf(v1[j], 0.f); v0[j] = a * a; v1[j] = b * b; } }
;                     u32x4 w; w.x = cvt_pk_bf16(v0[0], v0[1]); w.y = cvt_pk_bf16(v0[2], v0[3]); w.z = cvt_pk_bf16(v1[0], v1[1]); w.w = cvt_pk_bf16(v1[2], v1[3]);
;                     *(u32x4*)(rowp + bj * HALF) = w; } }
.LBB0_1091:
	v_mov_b32_e32 v138, v140
	v_mov_b32_e32 v159, v141
	s_lshl_b64 s[12:13], s[60:61], 1
	v_readlane_b32 s14, v245, 30
	v_add_u32_e32 v138, s5, v138
	v_max_f32_e32 v120, v120, v120
	v_readlane_b32 s15, v245, 31
	s_add_u32 s12, s14, s12
	v_ashrrev_i32_e32 v139, 31, v138
	v_max_f32_e32 v120, 0, v120
	v_max_f32_e32 v121, v121, v121
	v_max_f32_e32 v122, v122, v122
	s_addc_u32 s13, s15, s13
	v_lshlrev_b64 v[138:139], 14, v[138:139]
	v_lshlrev_b32_e32 v160, 3, v159
	v_mul_f32_e32 v159, v120, v120
	v_max_f32_e32 v120, v125, v125
	v_max_f32_e32 v121, 0, v121
	v_max_f32_e32 v122, 0, v122
	v_lshl_add_u64 v[138:139], s[12:13], 0, v[138:139]
	s_mov_b32 s21, s61
	v_max_f32_e32 v124, v124, v124
	v_max_f32_e32 v120, 0, v120
	v_mul_f32_e32 v125, v121, v121
	v_max_f32_e32 v121, v126, v126
	v_mul_f32_e32 v126, v122, v122
	v_max_f32_e32 v122, v127, v127
	v_max_f32_e32 v123, v123, v123
	v_lshl_add_u64 v[138:139], v[138:139], 0, s[20:21]
	v_ashrrev_i32_e32 v161, 31, v160
	v_max_f32_e32 v124, 0, v124
	v_mul_f32_e32 v120, v120, v120
	v_max_f32_e32 v121, 0, v121
	v_max_f32_e32 v122, 0, v122
	v_max_f32_e32 v123, 0, v123
	v_max_f32_e32 v112, v112, v112
	v_lshl_add_u64 v[138:139], v[160:161], 1, v[138:139]
	v_mul_f32_e32 v124, v124, v124
	v_mul_f32_e32 v121, v121, v121
	v_mul_f32_e32 v122, v122, v122
	v_mul_f32_e32 v123, v123, v123
	v_cvt_pk_bf16_f32 v120, v124, v120
	v_max_f32_e32 v112, 0, v112
	v_max_f32_e32 v113, v113, v113
	v_max_f32_e32 v114, v114, v114
	v_cvt_pk_bf16_f32 v121, v121, v122
	v_cvt_pk_bf16_f32 v122, v159, v125
	v_cvt_pk_bf16_f32 v123, v126, v123
	global_store_dwordx4 v[138:139], v[120:123], off
	v_max_f32_e32 v113, 0, v113
	v_max_f32_e32 v114, 0, v114
	v_mul_f32_e32 v120, v112, v112
	v_max_f32_e32 v112, v117, v117
	v_max_f32_e32 v116, v116, v116
	v_max_f32_e32 v112, 0, v112
	v_mul_f32_e32 v117, v113, v113
	v_max_f32_e32 v113, v118, v118
	v_mul_f32_e32 v118, v114, v114
	v_max_f32_e32 v114, v119, v119
	v_max_f32_e32 v115, v115, v115
	v_max_f32_e32 v116, 0, v116
	v_mul_f32_e32 v112, v112, v112
	v_max_f32_e32 v113, 0, v113
	v_max_f32_e32 v114, 0, v114
	v_max_f32_e32 v115, 0, v115
	v_max_f32_e32 v104, v104, v104
	v_mul_f32_e32 v116, v116, v116
	v_mul_f32_e32 v113, v113, v113
	v_mul_f32_e32 v114, v114, v114
	v_mul_f32_e32 v115, v115, v115
	v_cvt_pk_bf16_f32 v112, v116, v112
	v_max_f32_e32 v104, 0, v104
	v_max_f32_e32 v105, v105, v105
	v_max_f32_e32 v106, v106, v106
	v_cvt_pk_bf16_f32 v113, v113, v114
	v_cvt_pk_bf16_f32 v114, v120, v117
	v_cvt_pk_bf16_f32 v115, v118, v115
	global_store_dwordx4 v[138:139], v[112:115], off offset:256
	v_max_f32_e32 v108, v108, v108
	v_max_f32_e32 v105, 0, v105
	v_mul_f32_e32 v112, v104, v104
	v_max_f32_e32 v104, v109, v109
	v_max_f32_e32 v106, 0, v106
	v_max_f32_e32 v108, 0, v108
	v_max_f32_e32 v104, 0, v104
	v_mul_f32_e32 v109, v105, v105
	v_max_f32_e32 v105, v110, v110
	v_mul_f32_e32 v110, v106, v106
	v_max_f32_e32 v106, v111, v111
	v_mul_f32_e32 v108, v108, v108
	v_mul_f32_e32 v104, v104, v104
	v_max_f32_e32 v105, 0, v105
	v_max_f32_e32 v106, 0, v106
	v_max_f32_e32 v107, v107, v107
	s_mov_b32 s12, 0x40000
	v_mul_f32_e32 v105, v105, v105
	v_max_f32_e32 v107, 0, v107
	v_mul_f32_e32 v106, v106, v106
	v_cvt_pk_bf16_f32 v104, v108, v104
	v_add_co_u32_e32 v108, vcc, s12, v138
	v_max_f32_e32 v96, v96, v96
	v_mul_f32_e32 v107, v107, v107
	v_cvt_pk_bf16_f32 v105, v105, v106
	v_cvt_pk_bf16_f32 v106, v112, v109
	v_addc_co_u32_e32 v109, vcc, 0, v139, vcc
	v_max_f32_e32 v96, 0, v96
	v_max_f32_e32 v97, v97, v97
	v_max_f32_e32 v98, v98, v98
	v_cvt_pk_bf16_f32 v107, v110, v107
	global_store_dwordx4 v[108:109], v[104:107], off
	v_max_f32_e32 v97, 0, v97
	v_max_f32_e32 v98, 0, v98
	v_mul_f32_e32 v104, v96, v96
	v_max_f32_e32 v96, v101, v101
	v_max_f32_e32 v100, v100, v100
	v_max_f32_e32 v96, 0, v96
	v_mul_f32_e32 v101, v97, v97
	v_max_f32_e32 v97, v102, v102
	v_mul_f32_e32 v102, v98, v98
	v_max_f32_e32 v98, v103, v103
	v_max_f32_e32 v99, v99, v99
	v_max_f32_e32 v100, 0, v100
	v_mul_f32_e32 v96, v96, v96
	v_max_f32_e32 v97, 0, v97
	v_max_f32_e32 v98, 0, v98
	v_max_f32_e32 v99, 0, v99
	v_max_f32_e32 v88, v88, v88
	v_mul_f32_e32 v100, v100, v100
	v_mul_f32_e32 v97, v97, v97
	v_mul_f32_e32 v98, v98, v98
	v_mul_f32_e32 v99, v99, v99
	v_cvt_pk_bf16_f32 v96, v100, v96
	v_max_f32_e32 v88, 0, v88
	v_max_f32_e32 v89, v89, v89
	v_max_f32_e32 v90, v90, v90
	v_cvt_pk_bf16_f32 v97, v97, v98
	v_cvt_pk_bf16_f32 v98, v104, v101
	v_cvt_pk_bf16_f32 v99, v102, v99
	global_store_dwordx4 v[108:109], v[96:99], off offset:256
	v_max_f32_e32 v92, v92, v92
	v_max_f32_e32 v89, 0, v89
	v_mul_f32_e32 v96, v88, v88
	v_max_f32_e32 v88, v93, v93
	v_max_f32_e32 v90, 0, v90
	v_max_f32_e32 v92, 0, v92
	v_max_f32_e32 v88, 0, v88
	v_mul_f32_e32 v93, v89, v89
	v_max_f32_e32 v89, v94, v94
	v_mul_f32_e32 v94, v90, v90
	v_max_f32_e32 v90, v95, v95
	v_mul_f32_e32 v92, v92, v92
	v_mul_f32_e32 v88, v88, v88
	v_max_f32_e32 v89, 0, v89
	v_max_f32_e32 v90, 0, v90
	v_max_f32_e32 v91, v91, v91
	s_mov_b32 s12, 0x80000
	v_mul_f32_e32 v89, v89, v89
	v_max_f32_e32 v91, 0, v91
	v_mul_f32_e32 v90, v90, v90
	v_cvt_pk_bf16_f32 v88, v92, v88
	v_add_co_u32_e32 v92, vcc, s12, v138
	v_max_f32_e32 v80, v80, v80
	v_mul_f32_e32 v91, v91, v91
	v_cvt_pk_bf16_f32 v89, v89, v90
	v_cvt_pk_bf16_f32 v90, v96, v93
	v_addc_co_u32_e32 v93, vcc, 0, v139, vcc
	v_max_f32_e32 v80, 0, v80
	v_max_f32_e32 v81, v81, v81
	v_max_f32_e32 v82, v82, v82
	v_cvt_pk_bf16_f32 v91, v94, v91
	global_store_dwordx4 v[92:93], v[88:91], off
	v_max_f32_e32 v81, 0, v81
	v_max_f32_e32 v82, 0, v82
	v_mul_f32_e32 v88, v80, v80
	v_max_f32_e32 v80, v85, v85
	v_max_f32_e32 v84, v84, v84
	v_max_f32_e32 v80, 0, v80
	v_mul_f32_e32 v85, v81, v81
	v_max_f32_e32 v81, v86, v86
	v_mul_f32_e32 v86, v82, v82
	v_max_f32_e32 v82, v87, v87
	v_max_f32_e32 v83, v83, v83
	v_max_f32_e32 v84, 0, v84
	v_mul_f32_e32 v80, v80, v80
	v_max_f32_e32 v81, 0, v81
	v_max_f32_e32 v82, 0, v82
	v_max_f32_e32 v83, 0, v83
	v_max_f32_e32 v72, v72, v72
	v_mul_f32_e32 v84, v84, v84
	v_mul_f32_e32 v81, v81, v81
	v_mul_f32_e32 v82, v82, v82
	v_mul_f32_e32 v83, v83, v83
	v_cvt_pk_bf16_f32 v80, v84, v80
	v_max_f32_e32 v72, 0, v72
	v_max_f32_e32 v73, v73, v73
	v_max_f32_e32 v74, v74, v74
	v_cvt_pk_bf16_f32 v81, v81, v82
	v_cvt_pk_bf16_f32 v82, v88, v85
	v_cvt_pk_bf16_f32 v83, v86, v83
	global_store_dwordx4 v[92:93], v[80:83], off offset:256
	s_cmp_lg_u64 s[18:19], 0
	s_cbranch_scc0 .Llate_align_10
	s_barrier
; __device__ __forceinline__ unsigned cvt_pk_bf16(float lo, float hi) { unsigned r; asm volatile("v_cvt_pk_bf16_f32 %0, %1, %2" : "=v"(r) : "v"(lo), "v"(hi)); return r; }
; __device__ __forceinline__ float silu_f(float v) { return v / (1.0f + __expf(-v)); }
;     __device__ __forceinline__ void operator()(const Acc& acc, const Unit& u, int wr, int wc, int fr, int fq) const {
;     ...
;             for (int m = 0; m < 4; ++m) { bf16_t* rowp = base + (size_t)(ai * HALF + m * 16) * ldc;
; #pragma unroll
;                 for (int bj = 0; bj < 2; ++bj) { f32x4 v0 = acc[ai][bj][m][0], v1 = acc[ai][bj][m][1];
;                     if (ACT == 1) {
; #pragma unroll
;                         for (int j = 0; j < 4; ++j) { v0[j] = silu_f(v0[j]); v1[j] = silu_f(v1[j]); } }
;                     if (ACT == 2) {
; #pragma unroll
;                         for (int j = 0; j < 4; ++j) { const float a = fmaxf(v0[j], 0.f), b = fmaxf(v1[j], 0.f); v0[j] = a * a; v1[j] = b * b; } }
;                     u32x4 w; w.x = cvt_pk_bf16(v0[0], v0[1]); w.y = cvt_pk_bf16(v0[2], v0[3]); w.z = cvt_pk_bf16(v1[0], v1[1]); w.w = cvt_pk_bf16(v1[2], v1[3]);
;                     *(u32x4*)(rowp + bj * HALF) = w; } }
.Llate_align_10:
	v_max_f32_e32 v76, v76, v76
	v_max_f32_e32 v73, 0, v73
	v_mul_f32_e32 v80, v72, v72
	v_max_f32_e32 v72, v77, v77
	v_max_f32_e32 v74, 0, v74
	v_max_f32_e32 v76, 0, v76
	v_max_f32_e32 v72, 0, v72
	v_mul_f32_e32 v77, v73, v73
	v_max_f32_e32 v73, v78, v78
	v_mul_f32_e32 v78, v74, v74
	v_max_f32_e32 v74, v79, v79
	v_mul_f32_e32 v76, v76, v76
	v_mul_f32_e32 v72, v72, v72
	v_max_f32_e32 v73, 0, v73
	v_max_f32_e32 v74, 0, v74
	v_max_f32_e32 v75, v75, v75
	s_mov_b32 s12, 0xc0000
	v_mul_f32_e32 v73, v73, v73
	v_max_f32_e32 v75, 0, v75
	v_mul_f32_e32 v74, v74, v74
	v_cvt_pk_bf16_f32 v72, v76, v72
	v_add_co_u32_e32 v76, vcc, s12, v138
	v_max_f32_e32 v64, v64, v64
	v_mul_f32_e32 v75, v75, v75
	v_cvt_pk_bf16_f32 v73, v73, v74
	v_cvt_pk_bf16_f32 v74, v80, v77
	v_addc_co_u32_e32 v77, vcc, 0, v139, vcc
	v_max_f32_e32 v64, 0, v64
	v_max_f32_e32 v65, v65, v65
	v_max_f32_e32 v66, v66, v66
	v_cvt_pk_bf16_f32 v75, v78, v75
	global_store_dwordx4 v[76:77], v[72:75], off
	v_max_f32_e32 v65, 0, v65
	v_max_f32_e32 v66, 0, v66
	v_mul_f32_e32 v72, v64, v64
	v_max_f32_e32 v64, v69, v69
	v_max_f32_e32 v68, v68, v68
	v_max_f32_e32 v64, 0, v64
	v_mul_f32_e32 v69, v65, v65
	v_max_f32_e32 v65, v70, v70
	v_mul_f32_e32 v70, v66, v66
	v_max_f32_e32 v66, v71, v71
	v_max_f32_e32 v67, v67, v67
	v_max_f32_e32 v68, 0, v68
	v_mul_f32_e32 v64, v64, v64
	v_max_f32_e32 v65, 0, v65
	v_max_f32_e32 v66, 0, v66
	v_max_f32_e32 v67, 0, v67
	v_max_f32_e32 v56, v56, v56
	v_mul_f32_e32 v68, v68, v68
	v_mul_f32_e32 v65, v65, v65
	v_mul_f32_e32 v66, v66, v66
	v_mul_f32_e32 v67, v67, v67
	v_cvt_pk_bf16_f32 v64, v68, v64
	v_max_f32_e32 v56, 0, v56
	v_max_f32_e32 v57, v57, v57
	v_max_f32_e32 v58, v58, v58
	v_cvt_pk_bf16_f32 v65, v65, v66
	v_cvt_pk_bf16_f32 v66, v72, v69
	v_cvt_pk_bf16_f32 v67, v70, v67
	global_store_dwordx4 v[76:77], v[64:67], off offset:256
	v_max_f32_e32 v60, v60, v60
	v_max_f32_e32 v57, 0, v57
	v_mul_f32_e32 v64, v56, v56
	v_max_f32_e32 v56, v61, v61
	v_max_f32_e32 v58, 0, v58
	v_max_f32_e32 v60, 0, v60
	v_max_f32_e32 v56, 0, v56
	v_mul_f32_e32 v61, v57, v57
	v_max_f32_e32 v57, v62, v62
	v_mul_f32_e32 v62, v58, v58
	v_max_f32_e32 v58, v63, v63
	v_mul_f32_e32 v60, v60, v60
	v_mul_f32_e32 v56, v56, v56
	v_max_f32_e32 v57, 0, v57
	v_max_f32_e32 v58, 0, v58
	v_max_f32_e32 v59, v59, v59
	s_mov_b32 s12, 0x200000
	v_mul_f32_e32 v57, v57, v57
	v_max_f32_e32 v59, 0, v59
	v_mul_f32_e32 v58, v58, v58
	v_cvt_pk_bf16_f32 v56, v60, v56
	v_add_co_u32_e32 v60, vcc, s12, v138
	v_max_f32_e32 v48, v48, v48
	v_mul_f32_e32 v59, v59, v59
	v_cvt_pk_bf16_f32 v57, v57, v58
	v_cvt_pk_bf16_f32 v58, v64, v61
	v_addc_co_u32_e32 v61, vcc, 0, v139, vcc
	v_max_f32_e32 v48, 0, v48
	v_max_f32_e32 v49, v49, v49
	v_max_f32_e32 v50, v50, v50
	v_cvt_pk_bf16_f32 v59, v62, v59
	global_store_dwordx4 v[60:61], v[56:59], off
	v_max_f32_e32 v49, 0, v49
	v_max_f32_e32 v50, 0, v50
	v_mul_f32_e32 v56, v48, v48
	v_max_f32_e32 v48, v53, v53
	v_max_f32_e32 v52, v52, v52
	v_max_f32_e32 v48, 0, v48
	v_mul_f32_e32 v53, v49, v49
	v_max_f32_e32 v49, v54, v54
	v_mul_f32_e32 v54, v50, v50
	v_max_f32_e32 v50, v55, v55
	v_max_f32_e32 v51, v51, v51
	v_max_f32_e32 v52, 0, v52
	v_mul_f32_e32 v48, v48, v48
	v_max_f32_e32 v49, 0, v49
	v_max_f32_e32 v50, 0, v50
	v_max_f32_e32 v51, 0, v51
	v_max_f32_e32 v40, v40, v40
	v_mul_f32_e32 v52, v52, v52
	v_mul_f32_e32 v49, v49, v49
	v_mul_f32_e32 v50, v50, v50
	v_mul_f32_e32 v51, v51, v51
	v_cvt_pk_bf16_f32 v48, v52, v48
	v_max_f32_e32 v40, 0, v40
	v_max_f32_e32 v41, v41, v41
	v_max_f32_e32 v42, v42, v42
	v_cvt_pk_bf16_f32 v49, v49, v50
	v_cvt_pk_bf16_f32 v50, v56, v53
	v_cvt_pk_bf16_f32 v51, v54, v51
	global_store_dwordx4 v[60:61], v[48:51], off offset:256
	v_max_f32_e32 v44, v44, v44
	v_max_f32_e32 v41, 0, v41
	v_mul_f32_e32 v48, v40, v40
	v_max_f32_e32 v40, v45, v45
	v_max_f32_e32 v42, 0, v42
	v_max_f32_e32 v44, 0, v44
	v_max_f32_e32 v40, 0, v40
	v_mul_f32_e32 v45, v41, v41
	v_max_f32_e32 v41, v46, v46
	v_mul_f32_e32 v46, v42, v42
	v_max_f32_e32 v42, v47, v47
	v_mul_f32_e32 v44, v44, v44
	v_mul_f32_e32 v40, v40, v40
	v_max_f32_e32 v41, 0, v41
	v_max_f32_e32 v42, 0, v42
	v_max_f32_e32 v43, v43, v43
	s_mov_b32 s12, 0x240000
	v_mul_f32_e32 v41, v41, v41
	v_max_f32_e32 v43, 0, v43
	v_mul_f32_e32 v42, v42, v42
	v_cvt_pk_bf16_f32 v40, v44, v40
	v_add_co_u32_e32 v44, vcc, s12, v138
	v_max_f32_e32 v32, v32, v32
	v_mul_f32_e32 v43, v43, v43
	v_cvt_pk_bf16_f32 v41, v41, v42
	v_cvt_pk_bf16_f32 v42, v48, v45
	v_addc_co_u32_e32 v45, vcc, 0, v139, vcc
	v_max_f32_e32 v32, 0, v32
	v_max_f32_e32 v33, v33, v33
	v_max_f32_e32 v34, v34, v34
; __device__ __forceinline__ unsigned cvt_pk_bf16(float lo, float hi) { unsigned r; asm volatile("v_cvt_pk_bf16_f32 %0, %1, %2" : "=v"(r) : "v"(lo), "v"(hi)); return r; }
; __device__ __forceinline__ float silu_f(float v) { return v / (1.0f + __expf(-v)); }
; #define PG8_BAR __builtin_amdgcn_s_barrier()
; template <class Epi, class Map>
; __device__ __forceinline__ void gemm_phase(LAS unsigned char* lds, const Gemm g, const Sched<Map>& S, const Epi& E) {
;     ...
;         if (!has_next) break;
; #pragma unroll
;         for (int a = 0; a < 2; ++a)
; #pragma unroll
;             for (int b = 0; b < 2; ++b)
; #pragma unroll
;                 for (int m = 0; m < 4; ++m)
; #pragma unroll
;                     for (int n = 0; n < 2; ++n) acc[a][b][m][n] = (f32x4){0.f, 0.f, 0.f, 0.f};
;         cur = nxt; cA = nA; cB = nB; ++ui;
;         if (wr == 1) PG8_BAR;
;     __device__ __forceinline__ void operator()(const Acc& acc, const Unit& u, int wr, int wc, int fr, int fq) const {
;     ...
;             for (int m = 0; m < 4; ++m) { bf16_t* rowp = base + (size_t)(ai * HALF + m * 16) * ldc;
; #pragma unroll
;                 for (int bj = 0; bj < 2; ++bj) { f32x4 v0 = acc[ai][bj][m][0], v1 = acc[ai][bj][m][1];
;                     if (ACT == 1) {
; #pragma unroll
;                         for (int j = 0; j < 4; ++j) { v0[j] = silu_f(v0[j]); v1[j] = silu_f(v1[j]); } }
;                     if (ACT == 2) {
; #pragma unroll
;                         for (int j = 0; j < 4; ++j) { const float a = fmaxf(v0[j], 0.f), b = fmaxf(v1[j], 0.f); v0[j] = a * a; v1[j] = b * b; } }
;                     u32x4 w; w.x = cvt_pk_bf16(v0[0], v0[1]); w.y = cvt_pk_bf16(v0[2], v0[3]); w.z = cvt_pk_bf16(v1[0], v1[1]); w.w = cvt_pk_bf16(v1[2], v1[3]);
;                     *(u32x4*)(rowp + bj * HALF) = w; } }
	v_cvt_pk_bf16_f32 v43, v46, v43
	global_store_dwordx4 v[44:45], v[40:43], off
	v_max_f32_e32 v33, 0, v33
	v_max_f32_e32 v34, 0, v34
	v_mul_f32_e32 v40, v32, v32
	v_max_f32_e32 v32, v37, v37
	v_max_f32_e32 v36, v36, v36
	v_max_f32_e32 v32, 0, v32
	v_mul_f32_e32 v37, v33, v33
	v_max_f32_e32 v33, v38, v38
	v_mul_f32_e32 v38, v34, v34
	v_max_f32_e32 v34, v39, v39
	v_max_f32_e32 v35, v35, v35
	v_max_f32_e32 v36, 0, v36
	v_mul_f32_e32 v32, v32, v32
	v_max_f32_e32 v33, 0, v33
	v_max_f32_e32 v34, 0, v34
	v_max_f32_e32 v35, 0, v35
	v_max_f32_e32 v24, v24, v24
	v_mul_f32_e32 v36, v36, v36
	v_mul_f32_e32 v33, v33, v33
	v_mul_f32_e32 v34, v34, v34
	v_mul_f32_e32 v35, v35, v35
	v_cvt_pk_bf16_f32 v32, v36, v32
	v_max_f32_e32 v24, 0, v24
	v_max_f32_e32 v25, v25, v25
	v_max_f32_e32 v26, v26, v26
	v_cvt_pk_bf16_f32 v33, v33, v34
	v_cvt_pk_bf16_f32 v34, v40, v37
	v_cvt_pk_bf16_f32 v35, v38, v35
	global_store_dwordx4 v[44:45], v[32:35], off offset:256
	v_max_f32_e32 v28, v28, v28
	v_max_f32_e32 v25, 0, v25
	v_mul_f32_e32 v32, v24, v24
	v_max_f32_e32 v24, v29, v29
	v_max_f32_e32 v26, 0, v26
	v_max_f32_e32 v28, 0, v28
	v_max_f32_e32 v24, 0, v24
	v_mul_f32_e32 v29, v25, v25
	v_max_f32_e32 v25, v30, v30
	v_mul_f32_e32 v30, v26, v26
	v_max_f32_e32 v26, v31, v31
	v_mul_f32_e32 v28, v28, v28
	v_mul_f32_e32 v24, v24, v24
	v_max_f32_e32 v25, 0, v25
	v_max_f32_e32 v26, 0, v26
	v_max_f32_e32 v27, v27, v27
	s_mov_b32 s12, 0x280000
	v_mul_f32_e32 v25, v25, v25
	v_max_f32_e32 v27, 0, v27
	v_mul_f32_e32 v26, v26, v26
	v_cvt_pk_bf16_f32 v24, v28, v24
	v_add_co_u32_e32 v28, vcc, s12, v138
	v_max_f32_e32 v16, v16, v16
	v_mul_f32_e32 v27, v27, v27
	v_cvt_pk_bf16_f32 v25, v25, v26
	v_cvt_pk_bf16_f32 v26, v32, v29
	v_addc_co_u32_e32 v29, vcc, 0, v139, vcc
	v_max_f32_e32 v16, 0, v16
	v_max_f32_e32 v17, v17, v17
	v_max_f32_e32 v18, v18, v18
	v_cvt_pk_bf16_f32 v27, v30, v27
	global_store_dwordx4 v[28:29], v[24:27], off
	v_max_f32_e32 v17, 0, v17
	v_max_f32_e32 v18, 0, v18
	v_mul_f32_e32 v24, v16, v16
	v_max_f32_e32 v16, v21, v21
	v_max_f32_e32 v20, v20, v20
	v_max_f32_e32 v16, 0, v16
	v_mul_f32_e32 v21, v17, v17
	v_max_f32_e32 v17, v22, v22
	v_mul_f32_e32 v22, v18, v18
	v_max_f32_e32 v18, v23, v23
	v_max_f32_e32 v19, v19, v19
	v_max_f32_e32 v20, 0, v20
	v_mul_f32_e32 v16, v16, v16
	v_max_f32_e32 v17, 0, v17
	v_max_f32_e32 v18, 0, v18
	v_max_f32_e32 v19, 0, v19
	v_max_f32_e32 v8, v8, v8
	v_mul_f32_e32 v20, v20, v20
	v_mul_f32_e32 v17, v17, v17
	v_mul_f32_e32 v18, v18, v18
	v_mul_f32_e32 v19, v19, v19
	v_cvt_pk_bf16_f32 v16, v20, v16
	v_max_f32_e32 v8, 0, v8
	v_max_f32_e32 v9, v9, v9
	v_max_f32_e32 v10, v10, v10
	v_cvt_pk_bf16_f32 v17, v17, v18
	v_cvt_pk_bf16_f32 v18, v24, v21
	v_cvt_pk_bf16_f32 v19, v22, v19
	global_store_dwordx4 v[28:29], v[16:19], off offset:256
	v_max_f32_e32 v12, v12, v12
	v_max_f32_e32 v9, 0, v9
	v_mul_f32_e32 v16, v8, v8
	v_max_f32_e32 v8, v13, v13
	v_max_f32_e32 v10, 0, v10
	v_max_f32_e32 v12, 0, v12
	v_max_f32_e32 v8, 0, v8
	v_mul_f32_e32 v13, v9, v9
	v_max_f32_e32 v9, v14, v14
	v_mul_f32_e32 v14, v10, v10
	v_max_f32_e32 v10, v15, v15
	v_mul_f32_e32 v12, v12, v12
	v_mul_f32_e32 v8, v8, v8
	v_max_f32_e32 v9, 0, v9
	v_max_f32_e32 v10, 0, v10
	v_max_f32_e32 v11, v11, v11
	s_mov_b32 s12, 0x2c0000
	v_mul_f32_e32 v9, v9, v9
	v_max_f32_e32 v11, 0, v11
	v_mul_f32_e32 v10, v10, v10
	v_cvt_pk_bf16_f32 v8, v12, v8
	v_add_co_u32_e32 v12, vcc, s12, v138
	v_max_f32_e32 v0, v0, v0
	v_max_f32_e32 v1, v1, v1
	v_max_f32_e32 v2, v2, v2
	v_mul_f32_e32 v11, v11, v11
	v_cvt_pk_bf16_f32 v9, v9, v10
	v_cvt_pk_bf16_f32 v10, v16, v13
	v_addc_co_u32_e32 v13, vcc, 0, v139, vcc
	v_max_f32_e32 v0, 0, v0
	v_max_f32_e32 v1, 0, v1
	v_max_f32_e32 v2, 0, v2
	v_cvt_pk_bf16_f32 v11, v14, v11
	global_store_dwordx4 v[12:13], v[8:11], off
	v_max_f32_e32 v3, v3, v3
	v_max_f32_e32 v4, v4, v4
	v_mul_f32_e32 v8, v0, v0
	v_max_f32_e32 v0, v5, v5
	v_mul_f32_e32 v5, v1, v1
	v_max_f32_e32 v1, v6, v6
	v_mul_f32_e32 v6, v2, v2
	v_max_f32_e32 v2, v7, v7
	v_max_f32_e32 v0, 0, v0
	v_max_f32_e32 v1, 0, v1
	v_max_f32_e32 v2, 0, v2
	v_max_f32_e32 v3, 0, v3
	v_max_f32_e32 v4, 0, v4
	v_mul_f32_e32 v0, v0, v0
	v_mul_f32_e32 v1, v1, v1
	v_mul_f32_e32 v2, v2, v2
	v_mul_f32_e32 v3, v3, v3
	s_andn2_b64 vcc, exec, s[38:39]
	s_mov_b64 s[30:31], -1
	v_mul_f32_e32 v4, v4, v4
	v_cvt_pk_bf16_f32 v0, v4, v0
	v_cvt_pk_bf16_f32 v1, v1, v2
	v_cvt_pk_bf16_f32 v2, v8, v5
	v_cvt_pk_bf16_f32 v3, v6, v3
	global_store_dwordx4 v[12:13], v[0:3], off offset:256
	s_cbranch_vccnz .LBB0_1080
	s_andn2_b64 vcc, exec, s[16:17]
	s_cbranch_vccnz .LBB0_1079
	s_barrier
	s_branch .LBB0_1079

; __device__ __forceinline__ unsigned cvt_pk_bf16(float lo, float hi) { unsigned r; asm volatile("v_cvt_pk_bf16_f32 %0, %1, %2" : "=v"(r) : "v"(lo), "v"(hi)); return r; }
; #define PG8_BAR __builtin_amdgcn_s_barrier()
; template <class Epi, class Map>
; __device__ __forceinline__ void gemm_phase(LAS unsigned char* lds, const Gemm g, const Sched<Map>& S, const Epi& E) {
;     ...
;         if (wr == 0) PG8_BAR;
;     __device__ __forceinline__ void operator()(const Acc& acc, const Unit& u, int wr, int wc, int fr, int fq) const {
;     ...
;         const int col0 = u.pn * BM + wc * 32 + 8 * fq;
;         const float* gp = gate + (size_t)(u.pm >> 6) * gate_bstride + col0;
;         f32x4 gv[2][2];
; #pragma unroll
;         for (int bj = 0; bj < 2; ++bj) { gv[bj][0] = *(const f32x4*)(gp + bj * HALF); gv[bj][1] = *(const f32x4*)(gp + bj * HALF + 4); }
;         bf16_t* base = Y + (size_t)(u.pm * BM + wr * 64 + fr) * D + col0;
; #pragma unroll
;         for (int ai = 0; ai < 2; ++ai)
; #pragma unroll
;             for (int m = 0; m < 4; ++m) { bf16_t* rowp = base + (size_t)(ai * HALF + m * 16) * D;
; #pragma unroll
;                 for (int bj = 0; bj < 2; ++bj) { const f32x4 v0 = acc[ai][bj][m][0] * gv[bj][0], v1 = acc[ai][bj][m][1] * gv[bj][1];
;                     u32x4 w; w.x = cvt_pk_bf16(v0[0], v0[1]); w.y = cvt_pk_bf16(v0[2], v0[3]); w.z = cvt_pk_bf16(v1[0], v1[1]); w.w = cvt_pk_bf16(v1[2], v1[3]);
;                     *(u32x4*)(rowp + bj * HALF) = w; } }
.LBB0_1164:
	s_lshl_b32 s28, s36, 8
	v_mov_b32_e32 v175, v159
	v_mov_b32_e32 v104, v172
	s_or_b32 s28, s28, s8
	s_nop 0
	v_lshl_add_u32 v170, v104, 3, s28
	s_ashr_i32 s28, s33, 6
	s_mul_hi_i32 s29, s28, 0xc000
	s_mul_i32 s28, s28, 0xc000
	s_add_u32 s28, s0, s28
	s_addc_u32 s29, s1, s29
	v_ashrrev_i32_e32 v171, 31, v170
	v_lshl_add_u64 v[108:109], v[170:171], 2, s[28:29]
	global_load_dwordx4 v[112:115], v[108:109], off offset:16
	global_load_dwordx4 v[116:119], v[108:109], off
	global_load_dwordx4 v[104:107], v[108:109], off offset:528
	s_nop 0
	global_load_dwordx4 v[108:111], v[108:109], off offset:512
	s_lshl_b32 s28, s33, 8
	s_add_i32 s28, s28, s7
	v_add_u32_e32 v176, s28, v175
	v_ashrrev_i32_e32 v177, 31, v176
	v_readlane_b32 s28, v245, 21
	v_lshlrev_b64 v[176:177], 12, v[176:177]
	v_readlane_b32 s29, v245, 22
	s_waitcnt vmcnt(0)
	v_pk_mul_f32 v[142:143], v[142:143], v[118:119]
	v_lshl_add_u64 v[176:177], s[28:29], 0, v[176:177]
	v_lshl_add_u64 v[170:171], v[170:171], 1, v[176:177]
	v_pk_mul_f32 v[140:141], v[140:141], v[116:117]
	v_pk_mul_f32 v[176:177], v[138:139], v[114:115]
	v_pk_mul_f32 v[138:139], v[136:137], v[112:113]
	v_cvt_pk_bf16_f32 v136, v140, v141
	v_cvt_pk_bf16_f32 v137, v142, v143
	v_pk_mul_f32 v[126:127], v[126:127], v[110:111]
	v_cvt_pk_bf16_f32 v138, v138, v139
	v_cvt_pk_bf16_f32 v139, v176, v177
	global_store_dwordx4 v[170:171], v[136:139], off
	v_pk_mul_f32 v[124:125], v[124:125], v[108:109]
	s_mov_b32 s28, 0x10000
	v_pk_mul_f32 v[136:137], v[122:123], v[106:107]
	v_pk_mul_f32 v[122:123], v[120:121], v[104:105]
	v_cvt_pk_bf16_f32 v120, v124, v125
	v_cvt_pk_bf16_f32 v121, v126, v127
	v_pk_mul_f32 v[124:125], v[130:131], v[114:115]
	v_cvt_pk_bf16_f32 v122, v122, v123
	v_cvt_pk_bf16_f32 v123, v136, v137
	global_store_dwordx4 v[170:171], v[120:123], off offset:256
	v_pk_mul_f32 v[126:127], v[128:129], v[112:113]
	v_pk_mul_f32 v[94:95], v[94:95], v[110:111]
	v_pk_mul_f32 v[122:123], v[134:135], v[118:119]
	v_pk_mul_f32 v[120:121], v[132:133], v[116:117]
	v_pk_mul_f32 v[92:93], v[92:93], v[108:109]
	v_cvt_pk_bf16_f32 v120, v120, v121
	v_cvt_pk_bf16_f32 v121, v122, v123
	v_cvt_pk_bf16_f32 v122, v126, v127
	v_cvt_pk_bf16_f32 v123, v124, v125
	v_add_co_u32_e32 v124, vcc, s28, v170
	s_mov_b32 s28, 0x20000
	s_nop 0
	v_addc_co_u32_e32 v125, vcc, 0, v171, vcc
	global_store_dwordx4 v[124:125], v[120:123], off
	v_pk_mul_f32 v[86:87], v[86:87], v[110:111]
	v_pk_mul_f32 v[84:85], v[84:85], v[108:109]
	v_pk_mul_f32 v[120:121], v[90:91], v[106:107]
	v_pk_mul_f32 v[90:91], v[88:89], v[104:105]
	v_cvt_pk_bf16_f32 v88, v92, v93
	v_cvt_pk_bf16_f32 v89, v94, v95
	v_pk_mul_f32 v[92:93], v[98:99], v[114:115]
	v_cvt_pk_bf16_f32 v90, v90, v91
	v_cvt_pk_bf16_f32 v91, v120, v121
	global_store_dwordx4 v[124:125], v[88:91], off offset:256
	v_pk_mul_f32 v[94:95], v[96:97], v[112:113]
	v_pk_mul_f32 v[76:77], v[76:77], v[116:117]
	v_pk_mul_f32 v[90:91], v[102:103], v[118:119]
	v_pk_mul_f32 v[88:89], v[100:101], v[116:117]
	v_pk_mul_f32 v[78:79], v[78:79], v[118:119]
	v_cvt_pk_bf16_f32 v88, v88, v89
	v_cvt_pk_bf16_f32 v89, v90, v91
	v_cvt_pk_bf16_f32 v90, v94, v95
	v_cvt_pk_bf16_f32 v91, v92, v93
	v_add_co_u32_e32 v92, vcc, s28, v170
	s_mov_b32 s28, 0x30000
	s_nop 0
	v_addc_co_u32_e32 v93, vcc, 0, v171, vcc
	global_store_dwordx4 v[92:93], v[88:91], off
	v_pk_mul_f32 v[70:71], v[70:71], v[110:111]
	v_pk_mul_f32 v[68:69], v[68:69], v[108:109]
	v_pk_mul_f32 v[88:89], v[82:83], v[106:107]
	v_pk_mul_f32 v[82:83], v[80:81], v[104:105]
	v_cvt_pk_bf16_f32 v80, v84, v85
	v_cvt_pk_bf16_f32 v81, v86, v87
	v_pk_mul_f32 v[60:61], v[60:61], v[116:117]
	v_cvt_pk_bf16_f32 v82, v82, v83
	v_cvt_pk_bf16_f32 v83, v88, v89
	global_store_dwordx4 v[92:93], v[80:83], off offset:256
	s_cmp_lg_u64 s[18:19], 0
	s_cbranch_scc0 .Llate_align_11
	s_barrier
; __device__ __forceinline__ unsigned cvt_pk_bf16(float lo, float hi) { unsigned r; asm volatile("v_cvt_pk_bf16_f32 %0, %1, %2" : "=v"(r) : "v"(lo), "v"(hi)); return r; }
; #define PG8_BAR __builtin_amdgcn_s_barrier()
; template <class Epi, class Map>
; __device__ __forceinline__ void gemm_phase(LAS unsigned char* lds, const Gemm g, const Sched<Map>& S, const Epi& E) {
;     ...
;         if (!has_next) break;
; #pragma unroll
;         for (int a = 0; a < 2; ++a)
; #pragma unroll
;             for (int b = 0; b < 2; ++b)
; #pragma unroll
;                 for (int m = 0; m < 4; ++m)
; #pragma unroll
;                     for (int n = 0; n < 2; ++n) acc[a][b][m][n] = (f32x4){0.f, 0.f, 0.f, 0.f};
;         cur = nxt; cA = nA; cB = nB; ++ui;
;         if (wr == 1) PG8_BAR;
;     __device__ __forceinline__ void operator()(const Acc& acc, const Unit& u, int wr, int wc, int fr, int fq) const {
;     ...
;             for (int m = 0; m < 4; ++m) { bf16_t* rowp = base + (size_t)(ai * HALF + m * 16) * D;
; #pragma unroll
;                 for (int bj = 0; bj < 2; ++bj) { const f32x4 v0 = acc[ai][bj][m][0] * gv[bj][0], v1 = acc[ai][bj][m][1] * gv[bj][1];
;                     u32x4 w; w.x = cvt_pk_bf16(v0[0], v0[1]); w.y = cvt_pk_bf16(v0[2], v0[3]); w.z = cvt_pk_bf16(v1[0], v1[1]); w.w = cvt_pk_bf16(v1[2], v1[3]);
;                     *(u32x4*)(rowp + bj * HALF) = w; } }
.Llate_align_11:
	v_pk_mul_f32 v[62:63], v[62:63], v[118:119]
	v_pk_mul_f32 v[54:55], v[54:55], v[110:111]
	v_pk_mul_f32 v[80:81], v[74:75], v[114:115]
	v_pk_mul_f32 v[74:75], v[72:73], v[112:113]
	v_cvt_pk_bf16_f32 v72, v76, v77
	v_add_co_u32_e32 v76, vcc, s28, v170
	v_cvt_pk_bf16_f32 v73, v78, v79
	v_cvt_pk_bf16_f32 v74, v74, v75
	v_cvt_pk_bf16_f32 v75, v80, v81
	s_mov_b32 s28, 0x80000
	s_nop 0
	v_addc_co_u32_e32 v77, vcc, 0, v171, vcc
	global_store_dwordx4 v[76:77], v[72:75], off
	v_pk_mul_f32 v[52:53], v[52:53], v[108:109]
	v_pk_mul_f32 v[38:39], v[38:39], v[110:111]
	v_pk_mul_f32 v[72:73], v[66:67], v[106:107]
	v_pk_mul_f32 v[66:67], v[64:65], v[104:105]
	v_cvt_pk_bf16_f32 v64, v68, v69
	v_cvt_pk_bf16_f32 v65, v70, v71
	v_pk_mul_f32 v[36:37], v[36:37], v[108:109]
	v_cvt_pk_bf16_f32 v66, v66, v67
	v_cvt_pk_bf16_f32 v67, v72, v73
	global_store_dwordx4 v[76:77], v[64:67], off offset:256
	v_pk_mul_f32 v[22:23], v[22:23], v[110:111]
	v_pk_mul_f32 v[20:21], v[20:21], v[108:109]
	v_pk_mul_f32 v[64:65], v[58:59], v[114:115]
	v_pk_mul_f32 v[58:59], v[56:57], v[112:113]
	v_cvt_pk_bf16_f32 v56, v60, v61
	v_add_co_u32_e32 v60, vcc, s28, v170
	v_cvt_pk_bf16_f32 v57, v62, v63
	v_cvt_pk_bf16_f32 v58, v58, v59
	v_cvt_pk_bf16_f32 v59, v64, v65
	s_mov_b32 s28, 0x90000
	s_nop 0
	v_addc_co_u32_e32 v61, vcc, 0, v171, vcc
	global_store_dwordx4 v[60:61], v[56:59], off
	v_pk_mul_f32 v[6:7], v[6:7], v[110:111]
	v_pk_mul_f32 v[4:5], v[4:5], v[108:109]
	v_pk_mul_f32 v[56:57], v[46:47], v[106:107]
	v_pk_mul_f32 v[46:47], v[44:45], v[104:105]
	v_cvt_pk_bf16_f32 v44, v52, v53
	v_cvt_pk_bf16_f32 v45, v54, v55
	s_nop 0
	v_cvt_pk_bf16_f32 v46, v46, v47
	v_cvt_pk_bf16_f32 v47, v56, v57
	global_store_dwordx4 v[60:61], v[44:47], off offset:256
	s_nop 1
	v_pk_mul_f32 v[44:45], v[50:51], v[118:119]
	v_pk_mul_f32 v[46:47], v[48:49], v[116:117]
	v_pk_mul_f32 v[48:49], v[42:43], v[114:115]
	v_pk_mul_f32 v[42:43], v[40:41], v[112:113]
	v_cvt_pk_bf16_f32 v40, v46, v47
	v_cvt_pk_bf16_f32 v41, v44, v45
	v_add_co_u32_e32 v44, vcc, s28, v170
	v_cvt_pk_bf16_f32 v42, v42, v43
	v_cvt_pk_bf16_f32 v43, v48, v49
	s_mov_b32 s28, 0xa0000
	s_nop 0
	v_addc_co_u32_e32 v45, vcc, 0, v171, vcc
	global_store_dwordx4 v[44:45], v[40:43], off
	s_nop 1
	v_pk_mul_f32 v[40:41], v[30:31], v[106:107]
	v_pk_mul_f32 v[30:31], v[28:29], v[104:105]
	v_cvt_pk_bf16_f32 v28, v36, v37
	v_cvt_pk_bf16_f32 v29, v38, v39
	s_nop 0
	v_cvt_pk_bf16_f32 v30, v30, v31
	v_cvt_pk_bf16_f32 v31, v40, v41
	global_store_dwordx4 v[44:45], v[28:31], off offset:256
	s_nop 1
	v_pk_mul_f32 v[28:29], v[34:35], v[118:119]
	v_pk_mul_f32 v[30:31], v[32:33], v[116:117]
	v_pk_mul_f32 v[32:33], v[26:27], v[114:115]
	v_pk_mul_f32 v[26:27], v[24:25], v[112:113]
	v_cvt_pk_bf16_f32 v24, v30, v31
	v_cvt_pk_bf16_f32 v25, v28, v29
	v_add_co_u32_e32 v28, vcc, s28, v170
	v_cvt_pk_bf16_f32 v26, v26, v27
	v_cvt_pk_bf16_f32 v27, v32, v33
	s_mov_b32 s28, 0xb0000
	s_nop 0
	v_addc_co_u32_e32 v29, vcc, 0, v171, vcc
	global_store_dwordx4 v[28:29], v[24:27], off
	s_nop 1
	v_pk_mul_f32 v[24:25], v[14:15], v[106:107]
	v_pk_mul_f32 v[14:15], v[12:13], v[104:105]
	v_cvt_pk_bf16_f32 v12, v20, v21
	v_cvt_pk_bf16_f32 v13, v22, v23
	s_nop 0
	v_cvt_pk_bf16_f32 v14, v14, v15
	v_cvt_pk_bf16_f32 v15, v24, v25
	global_store_dwordx4 v[28:29], v[12:15], off offset:256
	s_nop 1
	v_pk_mul_f32 v[12:13], v[18:19], v[118:119]
	v_pk_mul_f32 v[14:15], v[16:17], v[116:117]
	v_pk_mul_f32 v[16:17], v[10:11], v[114:115]
	v_pk_mul_f32 v[10:11], v[8:9], v[112:113]
	v_cvt_pk_bf16_f32 v8, v14, v15
	v_cvt_pk_bf16_f32 v9, v12, v13
	v_add_co_u32_e32 v12, vcc, s28, v170
	v_cvt_pk_bf16_f32 v10, v10, v11
	v_cvt_pk_bf16_f32 v11, v16, v17
	s_mov_b64 s[28:29], -1
	s_nop 0
	v_addc_co_u32_e32 v13, vcc, 0, v171, vcc
	global_store_dwordx4 v[12:13], v[8:11], off
	s_andn2_b64 vcc, exec, s[40:41]
	s_nop 0
	v_pk_mul_f32 v[8:9], v[2:3], v[106:107]
	v_pk_mul_f32 v[2:3], v[0:1], v[104:105]
	v_cvt_pk_bf16_f32 v0, v4, v5
	v_cvt_pk_bf16_f32 v1, v6, v7
	s_nop 0
	v_cvt_pk_bf16_f32 v2, v2, v3
	v_cvt_pk_bf16_f32 v3, v8, v9
	global_store_dwordx4 v[12:13], v[0:3], off offset:256
	s_cbranch_vccnz .LBB0_1153
	s_andn2_b64 vcc, exec, s[16:17]
	s_cbranch_vccnz .LBB0_1152
	s_barrier
	s_branch .LBB0_1152

; #define PG8_BAR __builtin_amdgcn_s_barrier()
; template <class Epi, class Map>
; __device__ __forceinline__ void gemm_phase(LAS unsigned char* lds, const Gemm g, const Sched<Map>& S, const Epi& E) {
;     ...
;         if (wr == 0) PG8_BAR;
;     __device__ __forceinline__ void operator()(const Acc& acc, const Unit& u, int wr, int wc, int fr, int fq) const {
;     ...
;         const int row0 = u.pm * BM + wr * 64 + fr, col0 = u.pn * BM + wc * 32 + 4 * fq;
;         const float* gp = gate + (size_t)(u.pm >> 6) * gate_bstride + col0;
;         f32x4 gv[2][2];
; #pragma unroll
;         for (int bj = 0; bj < 2; ++bj)
; #pragma unroll
;             for (int n = 0; n < 2; ++n) gv[bj][n] = *(const f32x4*)(gp + bj * HALF + n * 16);
; #pragma unroll
;         for (int aim = 0; aim < 4; ++aim) { const int ai = aim >> 1, m0 = (aim & 1) * 2;
;             f32x4 bs[2][2][2];
; #pragma unroll
;             for (int mm = 0; mm < 2; ++mm) { const size_t off = (size_t)(row0 + ai * HALF + (m0 + mm) * 16) * D + col0;
; #pragma unroll
;                 for (int bj = 0; bj < 2; ++bj)
; #pragma unroll
;                     for (int n = 0; n < 2; ++n) bs[mm][bj][n] = *(const f32x4*)(base + off + bj * HALF + n * 16); }
; #pragma unroll
;             for (int mm = 0; mm < 2; ++mm) { const size_t off = (size_t)(row0 + ai * HALF + (m0 + mm) * 16) * D + col0;
; #pragma unroll
;                 for (int bj = 0; bj < 2; ++bj)
; #pragma unroll
;                     for (int n = 0; n < 2; ++n) *(f32x4*)(out + off + bj * HALF + n * 16) = bs[mm][bj][n] + gv[bj][n] * acc[ai][bj][m0 + mm][n]; }
;             asm volatile("" ::: "memory"); }
.LBB0_1186:
	v_mov_b32_e32 v168, v159
	v_mov_b32_e32 v64, v172
	s_lshl_b32 s28, s36, 8
	s_or_b32 s28, s28, s8
	v_lshl_add_u32 v64, v64, 2, s28
	s_ashr_i32 s28, s33, 6
	s_mul_hi_i32 s29, s28, 0xc000
	s_mul_i32 s28, s28, 0xc000
	s_add_u32 s28, s0, s28
	v_ashrrev_i32_e32 v65, 31, v64
	s_addc_u32 s29, s1, s29
	v_lshlrev_b64 v[166:167], 2, v[64:65]
	v_lshl_add_u64 v[64:65], s[28:29], 0, v[166:167]
	s_lshl_b32 s28, s33, 8
	s_add_i32 s28, s28, s7
	v_add_u32_e32 v170, s28, v168
	v_readlane_b32 s28, v245, 51
	v_readlane_b32 s29, v245, 52
	v_ashrrev_i32_e32 v171, 31, v170
	v_lshlrev_b64 v[170:171], 13, v[170:171]
	v_lshl_add_u64 v[168:169], s[28:29], 0, v[166:167]
	v_lshl_add_u64 v[180:181], v[168:169], 0, v[170:171]
	s_mov_b64 s[30:31], 0x20000
	global_load_dwordx4 v[108:111], v[64:65], off
	global_load_dwordx4 v[72:75], v[64:65], off offset:64
	global_load_dwordx4 v[68:71], v[64:65], off offset:512
	s_nop 0
	global_load_dwordx4 v[64:67], v[64:65], off offset:576
	s_nop 0
	global_load_dwordx4 v[176:179], v[180:181], off
	global_load_dwordx4 v[192:195], v[180:181], off offset:64
	global_load_dwordx4 v[196:199], v[180:181], off offset:512
	global_load_dwordx4 v[200:203], v[180:181], off offset:576
	v_lshl_add_u64 v[180:181], v[170:171], 0, s[30:31]
	v_lshl_add_u64 v[216:217], v[168:169], 0, v[180:181]
	global_load_dwordx4 v[204:207], v[216:217], off
	global_load_dwordx4 v[208:211], v[216:217], off offset:64
	global_load_dwordx4 v[212:215], v[216:217], off offset:512
	s_nop 0
	global_load_dwordx4 v[216:219], v[216:217], off offset:576
	s_mov_b64 s[30:31], 0x40000
	s_andn2_b64 vcc, exec, s[38:39]
	s_waitcnt vmcnt(0)
	v_pk_fma_f32 v[140:141], v[140:141], v[108:109], v[176:177]
	v_lshl_add_u64 v[176:177], s[28:29], 0, v[170:171]
	v_lshl_add_u64 v[176:177], v[176:177], 0, v[166:167]
	v_pk_fma_f32 v[126:127], v[126:127], v[70:71], v[198:199]
	v_pk_fma_f32 v[124:125], v[124:125], v[68:69], v[196:197]
	global_store_dwordx4 v[176:177], v[124:127], off offset:512
	v_pk_fma_f32 v[122:123], v[122:123], v[66:67], v[202:203]
	v_pk_fma_f32 v[120:121], v[120:121], v[64:65], v[200:201]
	v_lshl_add_u64 v[124:125], s[28:29], 0, v[180:181]
	global_store_dwordx4 v[176:177], v[120:123], off offset:576
	v_lshl_add_u64 v[124:125], v[124:125], 0, v[166:167]
	v_pk_fma_f32 v[142:143], v[142:143], v[110:111], v[178:179]
	v_pk_fma_f32 v[122:123], v[134:135], v[110:111], v[206:207]
	v_pk_fma_f32 v[120:121], v[132:133], v[108:109], v[204:205]
	v_pk_fma_f32 v[138:139], v[138:139], v[74:75], v[194:195]
	v_pk_fma_f32 v[136:137], v[136:137], v[72:73], v[192:193]
	global_store_dwordx4 v[124:125], v[120:123], off
	v_pk_fma_f32 v[118:119], v[118:119], v[70:71], v[214:215]
	v_pk_fma_f32 v[116:117], v[116:117], v[68:69], v[212:213]
	v_pk_fma_f32 v[122:123], v[130:131], v[74:75], v[210:211]
	v_pk_fma_f32 v[120:121], v[128:129], v[72:73], v[208:209]
	v_pk_fma_f32 v[114:115], v[114:115], v[66:67], v[218:219]
	v_pk_fma_f32 v[112:113], v[112:113], v[64:65], v[216:217]
	global_store_dwordx4 v[176:177], v[140:143], off
	global_store_dwordx4 v[176:177], v[136:139], off offset:64
	global_store_dwordx4 v[124:125], v[120:123], off offset:64
	s_cmp_lg_u64 s[18:19], 0
	s_cbranch_scc0 .Llate_align_12
	s_barrier
